# all 520 flat_load/flat_store/flat_atomic of the GEMM epilogues rewritten as global_* (addresses are always workspace/global memory), so they no longer tick lgkmcnt or take the flat path; on top of v56
# speedup vs baseline: 1.0035x; 1.0035x over previous
; #define PG8_BAR __builtin_amdgcn_s_barrier()
; DI u32x4 pack8(f32x4 a, f32x4 b) { u32x4 w; w.x = pk2(a[0], a[1]); w.y = pk2(a[2], a[3]); w.z = pk2(b[0], b[1]); w.w = pk2(b[2], b[3]); return w; }
; template <class Epi, class Sched, bool ALIGN_EPI = false, bool SP2 = false>
; __device__ __forceinline__ void gemm_phase(PG8_LAS unsigned char* lds, const Gemm g, const Sched& S, const Epi& E) {
;     ...
;         if (!has_next) break;
; #pragma unroll
;         for (int a = 0; a < 2; ++a)
; #pragma unroll
;             for (int b = 0; b < 2; ++b)
; #pragma unroll
;                 for (int m = 0; m < 4; ++m)
; #pragma unroll
;                     for (int n = 0; n < 2; ++n) acc[a][b][m][n] = (f32x4){0.f, 0.f, 0.f, 0.f};
;         cur = nxt; cA = nA; cB = nB; ++ui;
;         if constexpr (ALIGN_EPI) { if (wr == 1) PG8_BAR; }
;     DI void operator()(AccRef acc, const Unit& u, int wr, int wc, int fr, int fq) const {
;         unsigned char* w_ = ws; asm volatile("" : "+s"(w_)); bf16_t* E = (bf16_t*)(w_ + WS_E);
;         const int row0 = u.pm * 256 + wr * 64 + fr, c0 = u.pn * 256 + wc * 32 + 8 * fq;
; #pragma unroll
;         for (int ai = 0; ai < 2; ++ai)
; #pragma unroll
;             for (int m = 0; m < 4; ++m) { int row_ = row0 + ai * 128 + m * 16; asm volatile("" : "+v"(row_) :: "memory"); const size_t off = (size_t)row_ * DM + c0;
; #pragma unroll
;                 for (int bj = 0; bj < 2; ++bj) *(u32x4*)(E + off + bj * 128) = pack8(acc[ai][bj][m][0], acc[ai][bj][m][1]); }
.LBB0_39:
	v_lshl_add_u32 v152, s84, 8, v144
	v_lshl_or_b32 v148, s83, 8, v146
	s_mov_b64 s[48:49], s[0:1]
	v_ashrrev_i32_e32 v149, 31, v148
	v_mov_b32_e32 v150, v152
	v_cvt_pk_bf16_f32 v122, v122, v123
	v_lshl_add_u64 v[148:149], v[148:149], 1, s[48:49]
	v_ashrrev_i32_e32 v151, 31, v150
	v_lshl_add_u64 v[148:149], v[148:149], 0, s[72:73]
	v_lshlrev_b64 v[150:151], 11, v[150:151]
	v_lshl_add_u64 v[150:151], v[148:149], 0, v[150:151]
	v_cvt_pk_bf16_f32 v123, v124, v125
	v_cvt_pk_bf16_f32 v124, v126, v127
	v_cvt_pk_bf16_f32 v125, v128, v129
	v_cvt_pk_bf16_f32 v118, v118, v119
	v_cvt_pk_bf16_f32 v119, v120, v121
	v_cvt_pk_bf16_f32 v120, v114, v115
	v_cvt_pk_bf16_f32 v121, v116, v117
	global_store_dwordx4 v[150:151], v[122:125], off
	global_store_dwordx4 v[150:151], v[118:121], off offset:256
	v_or_b32_e32 v114, 16, v152
	v_cvt_pk_bf16_f32 v110, v110, v111
	v_ashrrev_i32_e32 v115, 31, v114
	v_lshlrev_b64 v[114:115], 11, v[114:115]
	v_lshl_add_u64 v[114:115], v[148:149], 0, v[114:115]
	v_cvt_pk_bf16_f32 v111, v112, v113
	v_cvt_pk_bf16_f32 v112, v106, v107
	v_cvt_pk_bf16_f32 v113, v108, v109
	v_cvt_pk_bf16_f32 v102, v102, v103
	v_cvt_pk_bf16_f32 v103, v104, v105
	v_cvt_pk_bf16_f32 v104, v98, v99
	v_cvt_pk_bf16_f32 v105, v100, v101
	global_store_dwordx4 v[114:115], v[110:113], off
	global_store_dwordx4 v[114:115], v[102:105], off offset:256
	v_or_b32_e32 v98, 32, v152
	v_cvt_pk_bf16_f32 v94, v94, v95
	v_ashrrev_i32_e32 v99, 31, v98
	v_lshlrev_b64 v[98:99], 11, v[98:99]
	v_lshl_add_u64 v[98:99], v[148:149], 0, v[98:99]
	v_cvt_pk_bf16_f32 v95, v96, v97
	v_cvt_pk_bf16_f32 v96, v90, v91
	v_cvt_pk_bf16_f32 v97, v92, v93
	v_cvt_pk_bf16_f32 v86, v86, v87
	v_cvt_pk_bf16_f32 v87, v88, v89
	v_cvt_pk_bf16_f32 v88, v82, v83
	v_cvt_pk_bf16_f32 v89, v84, v85
	global_store_dwordx4 v[98:99], v[94:97], off
	global_store_dwordx4 v[98:99], v[86:89], off offset:256
	v_or_b32_e32 v82, 48, v152
	v_cvt_pk_bf16_f32 v78, v78, v79
	v_ashrrev_i32_e32 v83, 31, v82
	v_lshlrev_b64 v[82:83], 11, v[82:83]
	v_lshl_add_u64 v[82:83], v[148:149], 0, v[82:83]
	v_cvt_pk_bf16_f32 v79, v80, v81
	v_cvt_pk_bf16_f32 v80, v74, v75
	v_cvt_pk_bf16_f32 v81, v76, v77
	v_cvt_pk_bf16_f32 v70, v70, v71
	v_cvt_pk_bf16_f32 v71, v72, v73
	v_cvt_pk_bf16_f32 v72, v66, v67
	v_cvt_pk_bf16_f32 v73, v68, v69
	global_store_dwordx4 v[82:83], v[78:81], off
	global_store_dwordx4 v[82:83], v[70:73], off offset:256
	v_add_u32_e32 v66, 0x80, v152
	v_cvt_pk_bf16_f32 v62, v62, v63
	v_ashrrev_i32_e32 v67, 31, v66
	v_lshlrev_b64 v[66:67], 11, v[66:67]
	v_lshl_add_u64 v[66:67], v[148:149], 0, v[66:67]
	v_cvt_pk_bf16_f32 v63, v64, v65
	v_cvt_pk_bf16_f32 v64, v58, v59
	v_cvt_pk_bf16_f32 v65, v60, v61
	v_cvt_pk_bf16_f32 v54, v54, v55
	v_cvt_pk_bf16_f32 v55, v56, v57
	v_cvt_pk_bf16_f32 v56, v50, v51
	v_cvt_pk_bf16_f32 v57, v52, v53
	global_store_dwordx4 v[66:67], v[62:65], off
	global_store_dwordx4 v[66:67], v[54:57], off offset:256
	v_add_u32_e32 v50, 0x90, v152
	v_cvt_pk_bf16_f32 v46, v46, v47
	v_ashrrev_i32_e32 v51, 31, v50
	v_lshlrev_b64 v[50:51], 11, v[50:51]
	v_lshl_add_u64 v[50:51], v[148:149], 0, v[50:51]
	v_cvt_pk_bf16_f32 v47, v48, v49
	v_cvt_pk_bf16_f32 v48, v42, v43
	v_cvt_pk_bf16_f32 v49, v44, v45
	v_cvt_pk_bf16_f32 v38, v38, v39
	v_cvt_pk_bf16_f32 v39, v40, v41
	v_cvt_pk_bf16_f32 v40, v34, v35
	v_cvt_pk_bf16_f32 v41, v36, v37
	global_store_dwordx4 v[50:51], v[46:49], off
	global_store_dwordx4 v[50:51], v[38:41], off offset:256
	v_add_u32_e32 v34, 0xa0, v152
	v_cvt_pk_bf16_f32 v30, v30, v31
	v_ashrrev_i32_e32 v35, 31, v34
	v_lshlrev_b64 v[34:35], 11, v[34:35]
	v_lshl_add_u64 v[34:35], v[148:149], 0, v[34:35]
	v_cvt_pk_bf16_f32 v31, v32, v33
	v_cvt_pk_bf16_f32 v32, v26, v27
	v_cvt_pk_bf16_f32 v33, v28, v29
	v_cvt_pk_bf16_f32 v22, v22, v23
	v_cvt_pk_bf16_f32 v23, v24, v25
	v_cvt_pk_bf16_f32 v24, v18, v19
	v_cvt_pk_bf16_f32 v25, v20, v21
	global_store_dwordx4 v[34:35], v[30:33], off
	global_store_dwordx4 v[34:35], v[22:25], off offset:256
	v_add_u32_e32 v18, 0xb0, v152
	v_cvt_pk_bf16_f32 v14, v14, v15
	v_ashrrev_i32_e32 v19, 31, v18
	v_lshlrev_b64 v[18:19], 11, v[18:19]
	v_lshl_add_u64 v[18:19], v[148:149], 0, v[18:19]
	v_cvt_pk_bf16_f32 v15, v16, v17
	v_cvt_pk_bf16_f32 v16, v10, v11
	v_cvt_pk_bf16_f32 v17, v12, v13
	v_cvt_pk_bf16_f32 v6, v6, v7
	v_cvt_pk_bf16_f32 v7, v8, v9
	v_cvt_pk_bf16_f32 v8, v2, v3
	v_cvt_pk_bf16_f32 v9, v4, v5
	s_and_b64 vcc, exec, s[40:41]
	s_mov_b64 s[40:41], -1
	global_store_dwordx4 v[18:19], v[14:17], off
	global_store_dwordx4 v[18:19], v[6:9], off offset:256
	s_cbranch_vccnz .LBB0_23
	s_andn2_b64 vcc, exec, s[8:9]
	s_cbranch_vccnz .LBB0_22
	s_barrier
	s_branch .LBB0_22

;     DI void operator()(AccRef acc, const Unit& u, int wr, int wc, int fr, int fq) const {
;         unsigned char* w_ = ws; asm volatile("" : "+s"(w_)); float* Y = (float*)(w_ + WS_Y); bf16_t* YG = (bf16_t*)(w_ + WS_X1B); const float* ST = (const float*)(w_ + WS_ST1); float* ST2 = (float*)(w_ + WS_ST2);
;         const int row0 = u.pm * 256 + wr * 64 + fr, c0 = u.pn * 256 + wc * 32 + 8 * fq;
;         f32x4 yb[2][2][2]; f32x2 sb[2];
;         { int r0_ = row0; asm volatile("" : "+v"(r0_) :: "memory"); const size_t o0 = (size_t)r0_ * DM + c0; sb[0] = *(const f32x2*)(ST + (size_t)r0_ * 2);
; #pragma unroll
;           for (int bj = 0; bj < 2; ++bj)
; #pragma unroll
;             for (int n = 0; n < 2; ++n) yb[0][bj][n] = *(const f32x4*)(Y + o0 + bj * 128 + 4 * n); }
; #pragma unroll
;         for (int it = 0; it < 8; ++it) { const int ai = it >> 2, m = it & 3, cur = it & 1;
;             if (it + 1 < 8) { int rn_ = row0 + ((it + 1) >> 2) * 128 + ((it + 1) & 3) * 16; asm volatile("" : "+v"(rn_) :: "memory"); const size_t on = (size_t)rn_ * DM + c0; sb[cur ^ 1] = *(const f32x2*)(ST + (size_t)rn_ * 2);
; #pragma unroll
;                 for (int bj = 0; bj < 2; ++bj)
; #pragma unroll
;                     for (int n = 0; n < 2; ++n) yb[cur ^ 1][bj][n] = *(const f32x4*)(Y + on + bj * 128 + 4 * n); }
;             int row = row0 + ai * 128 + m * 16; asm volatile("" : "+v"(row)); const size_t off = (size_t)row * DM + c0; float s1 = 0.f, s2 = 0.f;
;             const float mean = sb[cur].x * (1.f / DM); const float rstd = __builtin_amdgcn_rsqf(fmaxf(sb[cur].y * (1.f / DM) - mean * mean, 0.f) + LN_EPS);
; #pragma unroll
;             for (int bj = 0; bj < 2; ++bj) { f32x4 y[2];
; #pragma unroll
;                 for (int n = 0; n < 2; ++n) { const int cc = c0 + bj * 128 + 4 * n; const f32x4 gv = *(const f32x4*)(G + cc), bv = *(const f32x4*)(Bv + cc);
;                     const f32x4 x1 = (yb[cur][bj][n] - mean) * rstd * gv + bv;
;                     y[n] = x1 * ALPHA + acc[ai][bj][m][n]; *(f32x4*)(Y + off + bj * 128 + 4 * n) = y[n];
;                     s1 += (y[n][0] + y[n][1]) + (y[n][2] + y[n][3]); s2 += (y[n][0] * y[n][0] + y[n][1] * y[n][1]) + (y[n][2] * y[n][2] + y[n][3] * y[n][3]); }
;                 const f32x4 g0 = *(const f32x4*)(G2 + c0 + bj * 128), g1 = *(const f32x4*)(G2 + c0 + bj * 128 + 4);
.LBB0_68:
	s_mov_b64 s[58:59], s[0:1]
	s_add_u32 s64, s58, 0xe600000
	s_addc_u32 s65, s59, 0
	v_lshl_add_u32 v184, s61, 8, v178
	s_add_u32 s14, s58, 0x3540000
	v_mov_b32_e32 v134, v184
	s_addc_u32 s15, s59, 0
	v_lshl_or_b32 v166, s60, 8, v180
	v_ashrrev_i32_e32 v167, 31, v166
	v_ashrrev_i32_e32 v135, 31, v134
	v_lshl_add_u64 v[136:137], v[134:135], 3, s[14:15]
	v_lshlrev_b64 v[134:135], 12, v[134:135]
	v_lshl_add_u64 v[134:135], s[64:65], 0, v[134:135]
	v_lshlrev_b64 v[164:165], 2, v[166:167]
	v_lshl_add_u64 v[134:135], v[134:135], 0, v[164:165]
	global_load_dwordx2 v[176:177], v[136:137], off
	global_load_dwordx4 v[186:189], v[134:135], off
	global_load_dwordx4 v[190:193], v[134:135], off offset:16
	global_load_dwordx4 v[208:211], v[134:135], off offset:512
	global_load_dwordx4 v[212:215], v[134:135], off offset:528
	v_or_b32_e32 v170, 16, v184
	v_mov_b32_e32 v134, v170
	v_lshl_add_u64 v[168:169], s[64:65], 0, v[164:165]
	v_ashrrev_i32_e32 v135, 31, v134
	v_lshl_add_u64 v[136:137], v[134:135], 3, s[14:15]
	v_lshlrev_b64 v[134:135], 12, v[134:135]
	v_lshl_add_u64 v[134:135], v[168:169], 0, v[134:135]
	v_mov_b32_e32 v172, v184
	v_lshl_add_u64 v[160:161], s[10:11], 0, v[164:165]
	v_lshl_add_u64 v[162:163], s[48:49], 0, v[164:165]
	global_load_dwordx2 v[174:175], v[136:137], off
	global_load_dwordx4 v[146:149], v[134:135], off
	global_load_dwordx4 v[142:145], v[134:135], off offset:16
	global_load_dwordx4 v[138:141], v[134:135], off offset:512
	s_nop 0
	global_load_dwordx4 v[134:137], v[134:135], off offset:528
	global_load_dwordx4 v[216:219], v[160:161], off
	global_load_dwordx4 v[220:223], v[162:163], off
	v_ashrrev_i32_e32 v173, 31, v172
	v_lshlrev_b64 v[182:183], 12, v[172:173]
	v_lshl_add_u64 v[182:183], v[168:169], 0, v[182:183]
	v_lshl_add_u64 v[164:165], s[50:51], 0, v[164:165]
	s_add_u32 s60, s58, 0x17600000
	v_lshlrev_b64 v[200:201], 10, v[172:173]
	s_addc_u32 s61, s59, 0
	v_lshl_add_u64 v[200:201], v[200:201], 0, v[166:167]
	v_lshl_add_u64 v[200:201], v[200:201], 1, s[60:61]
	s_add_u32 s58, s58, 0x3580000
	s_addc_u32 s59, s59, 0
	s_waitcnt vmcnt(0) lgkmcnt(0)
	v_pk_mul_f32 v[176:177], v[176:177], s[36:37] op_sel_hi:[1,0]
	s_nop 0
	v_fma_f32 v171, -v176, v176, v177
	v_max_f32_e32 v171, 0, v171
	v_add_f32_e32 v171, 0x3727c5ac, v171
	v_rsq_f32_e32 v198, v171
	v_sub_f32_e32 v187, v187, v176
	v_sub_f32_e32 v186, v186, v176
	v_sub_f32_e32 v189, v189, v176
	v_sub_f32_e32 v188, v188, v176
	v_pk_mul_f32 v[188:189], v[188:189], v[198:199] op_sel_hi:[1,0]
	v_pk_mul_f32 v[186:187], v[186:187], v[198:199] op_sel_hi:[1,0]
	v_sub_f32_e32 v191, v191, v176
	v_sub_f32_e32 v190, v190, v176
	v_sub_f32_e32 v193, v193, v176
	v_sub_f32_e32 v192, v192, v176
	v_pk_mul_f32 v[192:193], v[192:193], v[198:199] op_sel_hi:[1,0]
	v_pk_mul_f32 v[190:191], v[190:191], v[198:199] op_sel_hi:[1,0]
	v_sub_f32_e32 v203, v209, v176
	v_sub_f32_e32 v202, v208, v176
	v_pk_fma_f32 v[186:187], v[186:187], v[216:217], v[220:221]
	v_pk_fma_f32 v[188:189], v[188:189], v[218:219], v[222:223]
	v_pk_fma_f32 v[126:127], v[186:187], s[30:31], v[126:127] op_sel_hi:[1,0,1]
	v_pk_fma_f32 v[128:129], v[188:189], s[30:31], v[128:129] op_sel_hi:[1,0,1]
	global_store_dwordx4 v[182:183], v[126:129], off
	global_load_dwordx4 v[186:189], v[160:161], off offset:16
	global_load_dwordx4 v[216:219], v[162:163], off offset:16
	v_sub_f32_e32 v205, v211, v176
	v_sub_f32_e32 v204, v210, v176
	v_pk_mul_f32 v[204:205], v[204:205], v[198:199] op_sel_hi:[1,0]
	v_pk_mul_f32 v[202:203], v[202:203], v[198:199] op_sel_hi:[1,0]
	v_sub_f32_e32 v177, v215, v176
	s_waitcnt vmcnt(0)
	v_pk_fma_f32 v[186:187], v[190:191], v[186:187], v[216:217]
	v_pk_fma_f32 v[188:189], v[192:193], v[188:189], v[218:219]
	v_pk_fma_f32 v[122:123], v[186:187], s[30:31], v[122:123] op_sel_hi:[1,0,1]
	v_pk_fma_f32 v[124:125], v[188:189], s[30:31], v[124:125] op_sel_hi:[1,0,1]
	global_store_dwordx4 v[182:183], v[122:125], off offset:16
	global_load_dwordx4 v[186:189], v[164:165], off
	global_load_dwordx4 v[190:193], v[164:165], off offset:16
	s_waitcnt vmcnt(0)
	v_pk_mul_f32 v[188:189], v[128:129], v[188:189]
	v_pk_mul_f32 v[186:187], v[126:127], v[186:187]
	v_pk_mul_f32 v[192:193], v[192:193], v[124:125]
	v_pk_mul_f32 v[190:191], v[190:191], v[122:123]
	v_cvt_pk_bf16_f32 v186, v186, v187
	v_cvt_pk_bf16_f32 v187, v188, v189
	v_cvt_pk_bf16_f32 v188, v190, v191
	v_cvt_pk_bf16_f32 v189, v192, v193
	global_store_dwordx4 v[200:201], v[186:189], off
	global_load_dwordx4 v[186:189], v[160:161], off offset:512
	s_nop 0
	global_load_dwordx4 v[190:193], v[162:163], off offset:512
	s_waitcnt vmcnt(0)
	v_pk_fma_f32 v[186:187], v[202:203], v[186:187], v[190:191]
	v_pk_fma_f32 v[188:189], v[204:205], v[188:189], v[192:193]
	v_pk_fma_f32 v[118:119], v[186:187], s[30:31], v[118:119] op_sel_hi:[1,0,1]
	v_pk_fma_f32 v[120:121], v[188:189], s[30:31], v[120:121] op_sel_hi:[1,0,1]
	global_store_dwordx4 v[182:183], v[118:121], off offset:512
	global_load_dwordx4 v[186:189], v[160:161], off offset:528
	global_load_dwordx4 v[190:193], v[162:163], off offset:528
	v_sub_f32_e32 v203, v213, v176
	v_sub_f32_e32 v202, v212, v176
	v_sub_f32_e32 v176, v214, v176
	v_pk_mul_f32 v[176:177], v[176:177], v[198:199] op_sel_hi:[1,0]
	v_pk_mul_f32 v[198:199], v[202:203], v[198:199] op_sel_hi:[1,0]
	s_waitcnt vmcnt(0)
; DI u32x4 pack8(f32x4 a, f32x4 b) { u32x4 w; w.x = pk2(a[0], a[1]); w.y = pk2(a[2], a[3]); w.z = pk2(b[0], b[1]); w.w = pk2(b[2], b[3]); return w; }
;     DI void operator()(AccRef acc, const Unit& u, int wr, int wc, int fr, int fq) const {
;     ...
;         for (int it = 0; it < 8; ++it) { const int ai = it >> 2, m = it & 3, cur = it & 1;
;             if (it + 1 < 8) { int rn_ = row0 + ((it + 1) >> 2) * 128 + ((it + 1) & 3) * 16; asm volatile("" : "+v"(rn_) :: "memory"); const size_t on = (size_t)rn_ * DM + c0; sb[cur ^ 1] = *(const f32x2*)(ST + (size_t)rn_ * 2);
; #pragma unroll
;                 for (int bj = 0; bj < 2; ++bj)
; #pragma unroll
;                     for (int n = 0; n < 2; ++n) yb[cur ^ 1][bj][n] = *(const f32x4*)(Y + on + bj * 128 + 4 * n); }
;             int row = row0 + ai * 128 + m * 16; asm volatile("" : "+v"(row)); const size_t off = (size_t)row * DM + c0; float s1 = 0.f, s2 = 0.f;
;             const float mean = sb[cur].x * (1.f / DM); const float rstd = __builtin_amdgcn_rsqf(fmaxf(sb[cur].y * (1.f / DM) - mean * mean, 0.f) + LN_EPS);
; #pragma unroll
;             for (int bj = 0; bj < 2; ++bj) { f32x4 y[2];
; #pragma unroll
;                 for (int n = 0; n < 2; ++n) { const int cc = c0 + bj * 128 + 4 * n; const f32x4 gv = *(const f32x4*)(G + cc), bv = *(const f32x4*)(Bv + cc);
;                     const f32x4 x1 = (yb[cur][bj][n] - mean) * rstd * gv + bv;
;                     y[n] = x1 * ALPHA + acc[ai][bj][m][n]; *(f32x4*)(Y + off + bj * 128 + 4 * n) = y[n];
;                     s1 += (y[n][0] + y[n][1]) + (y[n][2] + y[n][3]); s2 += (y[n][0] * y[n][0] + y[n][1] * y[n][1]) + (y[n][2] * y[n][2] + y[n][3] * y[n][3]); }
;                 const f32x4 g0 = *(const f32x4*)(G2 + c0 + bj * 128), g1 = *(const f32x4*)(G2 + c0 + bj * 128 + 4);
;                 *(u32x4*)(YG + off + bj * 128) = pack8(y[0] * g0, y[1] * g1); }
;             s1 += __shfl_xor(s1, 16); s1 += __shfl_xor(s1, 32); s2 += __shfl_xor(s2, 16); s2 += __shfl_xor(s2, 32);
;             if (fq == 0) { unsafeAtomicAdd(ST2 + (size_t)row * 2, s1); unsafeAtomicAdd(ST2 + (size_t)row * 2 + 1, s2); } }
	v_pk_fma_f32 v[176:177], v[176:177], v[188:189], v[192:193]
	v_pk_fma_f32 v[186:187], v[198:199], v[186:187], v[190:191]
	v_pk_fma_f32 v[188:189], v[176:177], s[30:31], v[116:117] op_sel_hi:[1,0,1]
	v_pk_fma_f32 v[186:187], v[186:187], s[30:31], v[114:115] op_sel_hi:[1,0,1]
	global_store_dwordx4 v[182:183], v[186:189], off offset:528
	global_load_dwordx4 v[190:193], v[164:165], off offset:512
	global_load_dwordx4 v[208:211], v[164:165], off offset:528
	v_and_b32_e32 v115, 64, v230
	v_xor_b32_e32 v114, 16, v230
	v_add_u32_e32 v115, 64, v115
	v_xor_b32_e32 v116, 32, v230
	v_cmp_lt_i32_e32 vcc, v114, v115
	v_mul_f32_e32 v117, v128, v128
	v_fmac_f32_e32 v117, v129, v129
	v_cndmask_b32_e32 v114, v230, v114, vcc
	v_cmp_lt_i32_e32 vcc, v116, v115
	v_lshlrev_b32_e32 v183, 2, v114
	v_add_f32_e32 v114, v126, v127
	v_cndmask_b32_e32 v115, v230, v116, vcc
	v_mul_f32_e32 v116, v127, v127
	v_lshlrev_b32_e32 v182, 2, v115
	v_add_f32_e32 v115, v129, v128
	v_fmac_f32_e32 v116, v126, v126
	v_add_f32_e32 v114, v114, v115
	v_add_f32_e32 v115, v116, v117
	v_add_f32_e32 v116, v122, v123
	v_add_f32_e32 v117, v125, v124
	v_mul_f32_e32 v123, v123, v123
	v_mul_f32_e32 v124, v124, v124
	v_add_f32_e32 v114, 0, v114
	v_add_f32_e32 v116, v116, v117
	v_fmac_f32_e32 v123, v122, v122
	v_fmac_f32_e32 v124, v125, v125
	v_add_f32_e32 v114, v114, v116
	v_add_f32_e32 v116, v123, v124
	v_add_f32_e32 v115, v115, v116
	v_add_f32_e32 v116, v118, v119
	v_add_f32_e32 v117, v121, v120
	v_mul_f32_e32 v122, v119, v119
	v_mul_f32_e32 v123, v120, v120
	v_add_f32_e32 v116, v116, v117
	v_fmac_f32_e32 v122, v118, v118
	v_fmac_f32_e32 v123, v121, v121
	v_add_f32_e32 v114, v114, v116
	v_add_f32_e32 v116, v122, v123
	v_add_f32_e32 v115, v115, v116
	v_add_f32_e32 v116, v186, v187
	v_add_f32_e32 v117, v189, v188
	v_mul_f32_e32 v122, v187, v187
	v_mul_f32_e32 v123, v188, v188
	v_add_f32_e32 v116, v116, v117
	v_fmac_f32_e32 v122, v186, v186
	v_fmac_f32_e32 v123, v189, v189
	v_add_f32_e32 v114, v114, v116
	v_add_f32_e32 v116, v122, v123
	v_add_f32_e32 v116, v115, v116
	ds_bpermute_b32 v117, v183, v114
	ds_bpermute_b32 v122, v183, v116
	s_waitcnt lgkmcnt(0)
	v_add_f32_e32 v114, v114, v117
	v_add_f32_e32 v116, v116, v122
	ds_bpermute_b32 v115, v182, v114
	ds_bpermute_b32 v117, v182, v116
	s_waitcnt vmcnt(0)
	v_pk_mul_f32 v[120:121], v[120:121], v[192:193]
	v_pk_mul_f32 v[118:119], v[118:119], v[190:191]
	v_pk_mul_f32 v[122:123], v[210:211], v[188:189]
	v_pk_mul_f32 v[124:125], v[208:209], v[186:187]
	v_cvt_pk_bf16_f32 v118, v118, v119
	v_cvt_pk_bf16_f32 v119, v120, v121
	v_cvt_pk_bf16_f32 v120, v124, v125
	v_cvt_pk_bf16_f32 v121, v122, v123
	global_store_dwordx4 v[200:201], v[118:121], off offset:256
	s_and_saveexec_b64 vcc, s[40:41]
	s_cbranch_execz .LBB0_70
	s_waitcnt lgkmcnt(0)
	v_add_f32_e32 v116, v116, v117
	v_add_f32_e32 v117, v114, v115
	v_lshl_add_u64 v[114:115], v[172:173], 3, s[58:59]
	global_atomic_add_f32 v[114:115], v117, off
	global_atomic_add_f32 v[114:115], v116, off offset:4
.LBB0_70:
	s_or_b64 exec, exec, vcc
	v_or_b32_e32 v172, 32, v184
	v_mov_b32_e32 v114, v172
	v_pk_mul_f32 v[174:175], v[174:175], s[36:37] op_sel_hi:[1,0]
	s_waitcnt lgkmcnt(0)
	v_ashrrev_i32_e32 v115, 31, v114
	v_lshl_add_u64 v[116:117], v[114:115], 3, s[14:15]
	v_lshlrev_b64 v[114:115], 12, v[114:115]
	v_lshl_add_u64 v[114:115], v[168:169], 0, v[114:115]
	global_load_dwordx2 v[176:177], v[116:117], off
	global_load_dwordx4 v[126:129], v[114:115], off
	global_load_dwordx4 v[122:125], v[114:115], off offset:16
	global_load_dwordx4 v[118:121], v[114:115], off offset:512
	s_nop 0
	global_load_dwordx4 v[114:117], v[114:115], off offset:528
	global_load_dwordx4 v[186:189], v[160:161], off
	global_load_dwordx4 v[190:193], v[162:163], off
	v_fma_f32 v171, -v174, v174, v175
	v_max_f32_e32 v171, 0, v171
	v_add_f32_e32 v171, 0x3727c5ac, v171
	v_rsq_f32_e32 v198, v171
	v_sub_f32_e32 v147, v147, v174
	v_sub_f32_e32 v146, v146, v174
	v_sub_f32_e32 v149, v149, v174
	v_sub_f32_e32 v148, v148, v174
	v_pk_mul_f32 v[148:149], v[148:149], v[198:199] op_sel_hi:[1,0]
	v_pk_mul_f32 v[146:147], v[146:147], v[198:199] op_sel_hi:[1,0]
	v_ashrrev_i32_e32 v171, 31, v170
	v_lshlrev_b64 v[200:201], 12, v[170:171]
	v_lshl_add_u64 v[200:201], v[168:169], 0, v[200:201]
	v_sub_f32_e32 v143, v143, v174
	v_sub_f32_e32 v142, v142, v174
	v_sub_f32_e32 v145, v145, v174
	v_sub_f32_e32 v144, v144, v174
	v_pk_mul_f32 v[144:145], v[144:145], v[198:199] op_sel_hi:[1,0]
	v_pk_mul_f32 v[142:143], v[142:143], v[198:199] op_sel_hi:[1,0]
	v_sub_f32_e32 v139, v139, v174
	v_sub_f32_e32 v138, v138, v174
	v_sub_f32_e32 v141, v141, v174
	v_sub_f32_e32 v140, v140, v174
	v_pk_mul_f32 v[140:141], v[140:141], v[198:199] op_sel_hi:[1,0]
	v_pk_mul_f32 v[138:139], v[138:139], v[198:199] op_sel_hi:[1,0]
	v_sub_f32_e32 v135, v135, v174
	v_sub_f32_e32 v134, v134, v174
	v_sub_f32_e32 v137, v137, v174
	v_sub_f32_e32 v136, v136, v174
	v_pk_mul_f32 v[136:137], v[136:137], v[198:199] op_sel_hi:[1,0]
	v_pk_mul_f32 v[134:135], v[134:135], v[198:199] op_sel_hi:[1,0]
	s_waitcnt vmcnt(0)
	v_pk_fma_f32 v[146:147], v[146:147], v[186:187], v[190:191]
	v_pk_fma_f32 v[148:149], v[148:149], v[188:189], v[192:193]
	v_pk_fma_f32 v[110:111], v[146:147], s[30:31], v[110:111] op_sel_hi:[1,0,1]
	v_pk_fma_f32 v[112:113], v[148:149], s[30:31], v[112:113] op_sel_hi:[1,0,1]
	global_store_dwordx4 v[200:201], v[110:113], off
	global_load_dwordx4 v[146:149], v[160:161], off offset:16
	global_load_dwordx4 v[186:189], v[162:163], off offset:16
	s_waitcnt vmcnt(0)
; DI u32x4 pack8(f32x4 a, f32x4 b) { u32x4 w; w.x = pk2(a[0], a[1]); w.y = pk2(a[2], a[3]); w.z = pk2(b[0], b[1]); w.w = pk2(b[2], b[3]); return w; }
;     DI void operator()(AccRef acc, const Unit& u, int wr, int wc, int fr, int fq) const {
;     ...
;         for (int it = 0; it < 8; ++it) { const int ai = it >> 2, m = it & 3, cur = it & 1;
;             if (it + 1 < 8) { int rn_ = row0 + ((it + 1) >> 2) * 128 + ((it + 1) & 3) * 16; asm volatile("" : "+v"(rn_) :: "memory"); const size_t on = (size_t)rn_ * DM + c0; sb[cur ^ 1] = *(const f32x2*)(ST + (size_t)rn_ * 2);
; #pragma unroll
;                 for (int bj = 0; bj < 2; ++bj)
; #pragma unroll
;                     for (int n = 0; n < 2; ++n) yb[cur ^ 1][bj][n] = *(const f32x4*)(Y + on + bj * 128 + 4 * n); }
;             int row = row0 + ai * 128 + m * 16; asm volatile("" : "+v"(row)); const size_t off = (size_t)row * DM + c0; float s1 = 0.f, s2 = 0.f;
;             const float mean = sb[cur].x * (1.f / DM); const float rstd = __builtin_amdgcn_rsqf(fmaxf(sb[cur].y * (1.f / DM) - mean * mean, 0.f) + LN_EPS);
; #pragma unroll
;             for (int bj = 0; bj < 2; ++bj) { f32x4 y[2];
; #pragma unroll
;                 for (int n = 0; n < 2; ++n) { const int cc = c0 + bj * 128 + 4 * n; const f32x4 gv = *(const f32x4*)(G + cc), bv = *(const f32x4*)(Bv + cc);
;                     const f32x4 x1 = (yb[cur][bj][n] - mean) * rstd * gv + bv;
;                     y[n] = x1 * ALPHA + acc[ai][bj][m][n]; *(f32x4*)(Y + off + bj * 128 + 4 * n) = y[n];
;                     s1 += (y[n][0] + y[n][1]) + (y[n][2] + y[n][3]); s2 += (y[n][0] * y[n][0] + y[n][1] * y[n][1]) + (y[n][2] * y[n][2] + y[n][3] * y[n][3]); }
;                 const f32x4 g0 = *(const f32x4*)(G2 + c0 + bj * 128), g1 = *(const f32x4*)(G2 + c0 + bj * 128 + 4);
;                 *(u32x4*)(YG + off + bj * 128) = pack8(y[0] * g0, y[1] * g1); }
;             s1 += __shfl_xor(s1, 16); s1 += __shfl_xor(s1, 32); s2 += __shfl_xor(s2, 16); s2 += __shfl_xor(s2, 32);
;             if (fq == 0) { unsafeAtomicAdd(ST2 + (size_t)row * 2, s1); unsafeAtomicAdd(ST2 + (size_t)row * 2 + 1, s2); } }
	v_pk_fma_f32 v[142:143], v[142:143], v[146:147], v[186:187]
	v_pk_fma_f32 v[144:145], v[144:145], v[148:149], v[188:189]
	v_pk_fma_f32 v[106:107], v[142:143], s[30:31], v[106:107] op_sel_hi:[1,0,1]
	v_pk_fma_f32 v[108:109], v[144:145], s[30:31], v[108:109] op_sel_hi:[1,0,1]
	global_store_dwordx4 v[200:201], v[106:109], off offset:16
	global_load_dwordx4 v[142:145], v[164:165], off
	global_load_dwordx4 v[146:149], v[164:165], off offset:16
	v_lshlrev_b64 v[186:187], 10, v[170:171]
	v_lshl_add_u64 v[186:187], v[186:187], 0, v[166:167]
	v_lshl_add_u64 v[186:187], v[186:187], 1, s[60:61]
	s_waitcnt vmcnt(0)
	v_pk_mul_f32 v[144:145], v[112:113], v[144:145]
	v_pk_mul_f32 v[142:143], v[110:111], v[142:143]
	v_pk_mul_f32 v[148:149], v[148:149], v[108:109]
	v_pk_mul_f32 v[146:147], v[146:147], v[106:107]
	v_cvt_pk_bf16_f32 v142, v142, v143
	v_cvt_pk_bf16_f32 v143, v144, v145
	v_cvt_pk_bf16_f32 v144, v146, v147
	v_cvt_pk_bf16_f32 v145, v148, v149
	global_store_dwordx4 v[186:187], v[142:145], off
	global_load_dwordx4 v[142:145], v[160:161], off offset:512
	s_nop 0
	global_load_dwordx4 v[146:149], v[162:163], off offset:512
	s_waitcnt vmcnt(0)
	v_pk_fma_f32 v[138:139], v[138:139], v[142:143], v[146:147]
	v_pk_fma_f32 v[140:141], v[140:141], v[144:145], v[148:149]
	v_pk_fma_f32 v[102:103], v[138:139], s[30:31], v[102:103] op_sel_hi:[1,0,1]
	v_pk_fma_f32 v[104:105], v[140:141], s[30:31], v[104:105] op_sel_hi:[1,0,1]
	global_store_dwordx4 v[200:201], v[102:105], off offset:512
	global_load_dwordx4 v[138:141], v[160:161], off offset:528
	global_load_dwordx4 v[142:145], v[162:163], off offset:528
	s_waitcnt vmcnt(0)
	v_pk_fma_f32 v[134:135], v[134:135], v[138:139], v[142:143]
	v_pk_fma_f32 v[136:137], v[136:137], v[140:141], v[144:145]
	v_pk_fma_f32 v[134:135], v[134:135], s[30:31], v[98:99] op_sel_hi:[1,0,1]
	v_pk_fma_f32 v[136:137], v[136:137], s[30:31], v[100:101] op_sel_hi:[1,0,1]
	global_store_dwordx4 v[200:201], v[134:137], off offset:528
	global_load_dwordx4 v[138:141], v[164:165], off offset:512
	global_load_dwordx4 v[142:145], v[164:165], off offset:528
	v_mul_f32_e32 v100, v111, v111
	v_mul_f32_e32 v101, v112, v112
	v_add_f32_e32 v98, v110, v111
	v_add_f32_e32 v99, v113, v112
	v_fmac_f32_e32 v100, v110, v110
	v_fmac_f32_e32 v101, v113, v113
	v_add_f32_e32 v98, v98, v99
	v_add_f32_e32 v99, v100, v101
	v_add_f32_e32 v100, v106, v107
	v_add_f32_e32 v101, v109, v108
	v_mul_f32_e32 v107, v107, v107
	v_mul_f32_e32 v108, v108, v108
	v_add_f32_e32 v98, 0, v98
	v_add_f32_e32 v100, v100, v101
	v_fmac_f32_e32 v107, v106, v106
	v_fmac_f32_e32 v108, v109, v109
	v_add_f32_e32 v98, v98, v100
	v_add_f32_e32 v100, v107, v108
	v_add_f32_e32 v99, v99, v100
	v_add_f32_e32 v100, v102, v103
	v_add_f32_e32 v101, v105, v104
	v_mul_f32_e32 v106, v103, v103
	v_mul_f32_e32 v107, v104, v104
	v_add_f32_e32 v100, v100, v101
	v_fmac_f32_e32 v106, v102, v102
	v_fmac_f32_e32 v107, v105, v105
	v_add_f32_e32 v98, v98, v100
	v_add_f32_e32 v100, v106, v107
	v_add_f32_e32 v99, v99, v100
	v_add_f32_e32 v100, v134, v135
	v_add_f32_e32 v101, v137, v136
	v_mul_f32_e32 v106, v135, v135
	v_mul_f32_e32 v107, v136, v136
	v_add_f32_e32 v100, v100, v101
	v_fmac_f32_e32 v106, v134, v134
	v_fmac_f32_e32 v107, v137, v137
	v_add_f32_e32 v98, v98, v100
	v_add_f32_e32 v100, v106, v107
	v_add_f32_e32 v100, v99, v100
	ds_bpermute_b32 v101, v183, v98
	ds_bpermute_b32 v106, v183, v100
	s_waitcnt lgkmcnt(0)
	v_add_f32_e32 v98, v98, v101
	v_add_f32_e32 v100, v100, v106
	ds_bpermute_b32 v99, v182, v98
	ds_bpermute_b32 v101, v182, v100
	s_waitcnt vmcnt(0)
	v_pk_mul_f32 v[104:105], v[104:105], v[140:141]
	v_pk_mul_f32 v[102:103], v[102:103], v[138:139]
	v_pk_mul_f32 v[106:107], v[144:145], v[136:137]
	v_pk_mul_f32 v[108:109], v[142:143], v[134:135]
	v_cvt_pk_bf16_f32 v102, v102, v103
	v_cvt_pk_bf16_f32 v103, v104, v105
	v_cvt_pk_bf16_f32 v104, v108, v109
	v_cvt_pk_bf16_f32 v105, v106, v107
	global_store_dwordx4 v[186:187], v[102:105], off offset:256
	s_and_saveexec_b64 vcc, s[40:41]
	s_cbranch_execz .LBB0_72
	s_waitcnt lgkmcnt(0)
	v_add_f32_e32 v100, v100, v101
	v_add_f32_e32 v101, v98, v99
	v_lshl_add_u64 v[98:99], v[170:171], 3, s[58:59]
	global_atomic_add_f32 v[98:99], v101, off
	global_atomic_add_f32 v[98:99], v100, off offset:4
; DI u32x4 pack8(f32x4 a, f32x4 b) { u32x4 w; w.x = pk2(a[0], a[1]); w.y = pk2(a[2], a[3]); w.z = pk2(b[0], b[1]); w.w = pk2(b[2], b[3]); return w; }
;     DI void operator()(AccRef acc, const Unit& u, int wr, int wc, int fr, int fq) const {
;     ...
;         for (int it = 0; it < 8; ++it) { const int ai = it >> 2, m = it & 3, cur = it & 1;
;             if (it + 1 < 8) { int rn_ = row0 + ((it + 1) >> 2) * 128 + ((it + 1) & 3) * 16; asm volatile("" : "+v"(rn_) :: "memory"); const size_t on = (size_t)rn_ * DM + c0; sb[cur ^ 1] = *(const f32x2*)(ST + (size_t)rn_ * 2);
; #pragma unroll
;                 for (int bj = 0; bj < 2; ++bj)
; #pragma unroll
;                     for (int n = 0; n < 2; ++n) yb[cur ^ 1][bj][n] = *(const f32x4*)(Y + on + bj * 128 + 4 * n); }
;             int row = row0 + ai * 128 + m * 16; asm volatile("" : "+v"(row)); const size_t off = (size_t)row * DM + c0; float s1 = 0.f, s2 = 0.f;
;             const float mean = sb[cur].x * (1.f / DM); const float rstd = __builtin_amdgcn_rsqf(fmaxf(sb[cur].y * (1.f / DM) - mean * mean, 0.f) + LN_EPS);
; #pragma unroll
;             for (int bj = 0; bj < 2; ++bj) { f32x4 y[2];
; #pragma unroll
;                 for (int n = 0; n < 2; ++n) { const int cc = c0 + bj * 128 + 4 * n; const f32x4 gv = *(const f32x4*)(G + cc), bv = *(const f32x4*)(Bv + cc);
;                     const f32x4 x1 = (yb[cur][bj][n] - mean) * rstd * gv + bv;
;                     y[n] = x1 * ALPHA + acc[ai][bj][m][n]; *(f32x4*)(Y + off + bj * 128 + 4 * n) = y[n];
;                     s1 += (y[n][0] + y[n][1]) + (y[n][2] + y[n][3]); s2 += (y[n][0] * y[n][0] + y[n][1] * y[n][1]) + (y[n][2] * y[n][2] + y[n][3] * y[n][3]); }
;                 const f32x4 g0 = *(const f32x4*)(G2 + c0 + bj * 128), g1 = *(const f32x4*)(G2 + c0 + bj * 128 + 4);
;                 *(u32x4*)(YG + off + bj * 128) = pack8(y[0] * g0, y[1] * g1); }
;             s1 += __shfl_xor(s1, 16); s1 += __shfl_xor(s1, 32); s2 += __shfl_xor(s2, 16); s2 += __shfl_xor(s2, 32);
;             if (fq == 0) { unsafeAtomicAdd(ST2 + (size_t)row * 2, s1); unsafeAtomicAdd(ST2 + (size_t)row * 2 + 1, s2); } }
.LBB0_72:
	s_or_b64 exec, exec, vcc
	v_or_b32_e32 v134, 48, v184
	v_mov_b32_e32 v98, v134
	v_pk_mul_f32 v[146:147], v[176:177], s[36:37] op_sel_hi:[1,0]
	s_waitcnt lgkmcnt(0)
	v_ashrrev_i32_e32 v99, 31, v98
	v_lshl_add_u64 v[100:101], v[98:99], 3, s[14:15]
	v_lshlrev_b64 v[98:99], 12, v[98:99]
	v_lshl_add_u64 v[98:99], v[168:169], 0, v[98:99]
	global_load_dwordx2 v[136:137], v[100:101], off
	global_load_dwordx4 v[110:113], v[98:99], off
	global_load_dwordx4 v[106:109], v[98:99], off offset:16
	global_load_dwordx4 v[102:105], v[98:99], off offset:512
	s_nop 0
	global_load_dwordx4 v[98:101], v[98:99], off offset:528
	global_load_dwordx4 v[138:141], v[160:161], off
	global_load_dwordx4 v[142:145], v[162:163], off
	v_fma_f32 v135, -v146, v146, v147
	v_max_f32_e32 v135, 0, v135
	v_add_f32_e32 v135, 0x3727c5ac, v135
	v_rsq_f32_e32 v148, v135
	v_sub_f32_e32 v127, v127, v146
	v_sub_f32_e32 v126, v126, v146
	v_sub_f32_e32 v129, v129, v146
	v_sub_f32_e32 v128, v128, v146
	v_pk_mul_f32 v[128:129], v[128:129], v[148:149] op_sel_hi:[1,0]
	v_pk_mul_f32 v[126:127], v[126:127], v[148:149] op_sel_hi:[1,0]
	v_ashrrev_i32_e32 v173, 31, v172
	v_lshlrev_b64 v[170:171], 12, v[172:173]
	v_lshl_add_u64 v[170:171], v[168:169], 0, v[170:171]
	v_sub_f32_e32 v123, v123, v146
	v_sub_f32_e32 v122, v122, v146
	v_sub_f32_e32 v125, v125, v146
	v_sub_f32_e32 v124, v124, v146
	v_pk_mul_f32 v[124:125], v[124:125], v[148:149] op_sel_hi:[1,0]
	v_pk_mul_f32 v[122:123], v[122:123], v[148:149] op_sel_hi:[1,0]
	v_sub_f32_e32 v119, v119, v146
	v_sub_f32_e32 v118, v118, v146
	v_sub_f32_e32 v121, v121, v146
	v_sub_f32_e32 v120, v120, v146
	v_pk_mul_f32 v[120:121], v[120:121], v[148:149] op_sel_hi:[1,0]
	v_pk_mul_f32 v[118:119], v[118:119], v[148:149] op_sel_hi:[1,0]
	v_sub_f32_e32 v115, v115, v146
	v_sub_f32_e32 v114, v114, v146
	v_sub_f32_e32 v117, v117, v146
	v_sub_f32_e32 v116, v116, v146
	v_pk_mul_f32 v[116:117], v[116:117], v[148:149] op_sel_hi:[1,0]
	v_pk_mul_f32 v[114:115], v[114:115], v[148:149] op_sel_hi:[1,0]
	s_waitcnt vmcnt(0)
	v_pk_fma_f32 v[126:127], v[126:127], v[138:139], v[142:143]
	v_pk_fma_f32 v[128:129], v[128:129], v[140:141], v[144:145]
	v_pk_fma_f32 v[94:95], v[126:127], s[30:31], v[94:95] op_sel_hi:[1,0,1]
	v_pk_fma_f32 v[96:97], v[128:129], s[30:31], v[96:97] op_sel_hi:[1,0,1]
	global_store_dwordx4 v[170:171], v[94:97], off
	global_load_dwordx4 v[126:129], v[160:161], off offset:16
	global_load_dwordx4 v[138:141], v[162:163], off offset:16
	s_waitcnt vmcnt(0)
	v_pk_fma_f32 v[122:123], v[122:123], v[126:127], v[138:139]
	v_pk_fma_f32 v[124:125], v[124:125], v[128:129], v[140:141]
	v_pk_fma_f32 v[90:91], v[122:123], s[30:31], v[90:91] op_sel_hi:[1,0,1]
	v_pk_fma_f32 v[92:93], v[124:125], s[30:31], v[92:93] op_sel_hi:[1,0,1]
	global_store_dwordx4 v[170:171], v[90:93], off offset:16
	global_load_dwordx4 v[122:125], v[164:165], off
	global_load_dwordx4 v[126:129], v[164:165], off offset:16
	v_lshlrev_b64 v[138:139], 10, v[172:173]
	v_lshl_add_u64 v[138:139], v[138:139], 0, v[166:167]
	v_lshl_add_u64 v[138:139], v[138:139], 1, s[60:61]
	s_waitcnt vmcnt(0)
	v_pk_mul_f32 v[124:125], v[96:97], v[124:125]
	v_pk_mul_f32 v[122:123], v[94:95], v[122:123]
	v_pk_mul_f32 v[128:129], v[128:129], v[92:93]
	v_pk_mul_f32 v[126:127], v[126:127], v[90:91]
	v_cvt_pk_bf16_f32 v122, v122, v123
	v_cvt_pk_bf16_f32 v123, v124, v125
	v_cvt_pk_bf16_f32 v124, v126, v127
	v_cvt_pk_bf16_f32 v125, v128, v129
	global_store_dwordx4 v[138:139], v[122:125], off
	global_load_dwordx4 v[122:125], v[160:161], off offset:512
	s_nop 0
	global_load_dwordx4 v[126:129], v[162:163], off offset:512
	s_waitcnt vmcnt(0)
	v_pk_fma_f32 v[118:119], v[118:119], v[122:123], v[126:127]
	v_pk_fma_f32 v[120:121], v[120:121], v[124:125], v[128:129]
	v_pk_fma_f32 v[86:87], v[118:119], s[30:31], v[86:87] op_sel_hi:[1,0,1]
	v_pk_fma_f32 v[88:89], v[120:121], s[30:31], v[88:89] op_sel_hi:[1,0,1]
	global_store_dwordx4 v[170:171], v[86:89], off offset:512
	global_load_dwordx4 v[118:121], v[160:161], off offset:528
	global_load_dwordx4 v[122:125], v[162:163], off offset:528
	s_waitcnt vmcnt(0)
	v_pk_fma_f32 v[114:115], v[114:115], v[118:119], v[122:123]
	v_pk_fma_f32 v[116:117], v[116:117], v[120:121], v[124:125]
	v_pk_fma_f32 v[114:115], v[114:115], s[30:31], v[82:83] op_sel_hi:[1,0,1]
	v_pk_fma_f32 v[116:117], v[116:117], s[30:31], v[84:85] op_sel_hi:[1,0,1]
	global_store_dwordx4 v[170:171], v[114:117], off offset:528
	global_load_dwordx4 v[118:121], v[164:165], off offset:512
	global_load_dwordx4 v[122:125], v[164:165], off offset:528
	v_mul_f32_e32 v84, v95, v95
	v_mul_f32_e32 v85, v96, v96
	v_add_f32_e32 v82, v94, v95
	v_add_f32_e32 v83, v97, v96
	v_fmac_f32_e32 v84, v94, v94
	v_fmac_f32_e32 v85, v97, v97
	v_add_f32_e32 v82, v82, v83
	v_add_f32_e32 v83, v84, v85
	v_add_f32_e32 v84, v90, v91
	v_add_f32_e32 v85, v93, v92
	v_mul_f32_e32 v91, v91, v91
	v_mul_f32_e32 v92, v92, v92
	v_add_f32_e32 v82, 0, v82
	v_add_f32_e32 v84, v84, v85
	v_fmac_f32_e32 v91, v90, v90
	v_fmac_f32_e32 v92, v93, v93
	v_add_f32_e32 v82, v82, v84
	v_add_f32_e32 v84, v91, v92
	v_add_f32_e32 v83, v83, v84
	v_add_f32_e32 v84, v86, v87
	v_add_f32_e32 v85, v89, v88
	v_mul_f32_e32 v90, v87, v87
	v_mul_f32_e32 v91, v88, v88
	v_add_f32_e32 v84, v84, v85
	v_fmac_f32_e32 v90, v86, v86
	v_fmac_f32_e32 v91, v89, v89
	v_add_f32_e32 v82, v82, v84
	v_add_f32_e32 v84, v90, v91
	v_add_f32_e32 v83, v83, v84
	v_add_f32_e32 v84, v114, v115
	v_add_f32_e32 v85, v117, v116
	v_mul_f32_e32 v90, v115, v115
	v_mul_f32_e32 v91, v116, v116
	v_add_f32_e32 v84, v84, v85
	v_fmac_f32_e32 v90, v114, v114
	v_fmac_f32_e32 v91, v117, v117
	v_add_f32_e32 v82, v82, v84
	v_add_f32_e32 v84, v90, v91
	v_add_f32_e32 v84, v83, v84
	ds_bpermute_b32 v85, v183, v82
	ds_bpermute_b32 v90, v183, v84
	s_waitcnt lgkmcnt(0)
	v_add_f32_e32 v82, v82, v85
	v_add_f32_e32 v84, v84, v90
	ds_bpermute_b32 v83, v182, v82
	ds_bpermute_b32 v85, v182, v84
	s_waitcnt vmcnt(0)
	v_pk_mul_f32 v[88:89], v[88:89], v[120:121]
	v_pk_mul_f32 v[86:87], v[86:87], v[118:119]
	v_pk_mul_f32 v[90:91], v[124:125], v[116:117]
	v_pk_mul_f32 v[92:93], v[122:123], v[114:115]
	v_cvt_pk_bf16_f32 v86, v86, v87
	v_cvt_pk_bf16_f32 v87, v88, v89
	v_cvt_pk_bf16_f32 v88, v92, v93
	v_cvt_pk_bf16_f32 v89, v90, v91
	global_store_dwordx4 v[138:139], v[86:89], off offset:256
	s_and_saveexec_b64 vcc, s[40:41]
	s_cbranch_execz .LBB0_74
	s_waitcnt lgkmcnt(0)
	v_add_f32_e32 v84, v84, v85
	v_add_f32_e32 v85, v82, v83
	v_lshl_add_u64 v[82:83], v[172:173], 3, s[58:59]
	global_atomic_add_f32 v[82:83], v85, off
	global_atomic_add_f32 v[82:83], v84, off offset:4
; DI u32x4 pack8(f32x4 a, f32x4 b) { u32x4 w; w.x = pk2(a[0], a[1]); w.y = pk2(a[2], a[3]); w.z = pk2(b[0], b[1]); w.w = pk2(b[2], b[3]); return w; }
;     DI void operator()(AccRef acc, const Unit& u, int wr, int wc, int fr, int fq) const {
;     ...
;         for (int it = 0; it < 8; ++it) { const int ai = it >> 2, m = it & 3, cur = it & 1;
;             if (it + 1 < 8) { int rn_ = row0 + ((it + 1) >> 2) * 128 + ((it + 1) & 3) * 16; asm volatile("" : "+v"(rn_) :: "memory"); const size_t on = (size_t)rn_ * DM + c0; sb[cur ^ 1] = *(const f32x2*)(ST + (size_t)rn_ * 2);
; #pragma unroll
;                 for (int bj = 0; bj < 2; ++bj)
; #pragma unroll
;                     for (int n = 0; n < 2; ++n) yb[cur ^ 1][bj][n] = *(const f32x4*)(Y + on + bj * 128 + 4 * n); }
;             int row = row0 + ai * 128 + m * 16; asm volatile("" : "+v"(row)); const size_t off = (size_t)row * DM + c0; float s1 = 0.f, s2 = 0.f;
;             const float mean = sb[cur].x * (1.f / DM); const float rstd = __builtin_amdgcn_rsqf(fmaxf(sb[cur].y * (1.f / DM) - mean * mean, 0.f) + LN_EPS);
; #pragma unroll
;             for (int bj = 0; bj < 2; ++bj) { f32x4 y[2];
; #pragma unroll
;                 for (int n = 0; n < 2; ++n) { const int cc = c0 + bj * 128 + 4 * n; const f32x4 gv = *(const f32x4*)(G + cc), bv = *(const f32x4*)(Bv + cc);
;                     const f32x4 x1 = (yb[cur][bj][n] - mean) * rstd * gv + bv;
;                     y[n] = x1 * ALPHA + acc[ai][bj][m][n]; *(f32x4*)(Y + off + bj * 128 + 4 * n) = y[n];
;                     s1 += (y[n][0] + y[n][1]) + (y[n][2] + y[n][3]); s2 += (y[n][0] * y[n][0] + y[n][1] * y[n][1]) + (y[n][2] * y[n][2] + y[n][3] * y[n][3]); }
;                 const f32x4 g0 = *(const f32x4*)(G2 + c0 + bj * 128), g1 = *(const f32x4*)(G2 + c0 + bj * 128 + 4);
;                 *(u32x4*)(YG + off + bj * 128) = pack8(y[0] * g0, y[1] * g1); }
;             s1 += __shfl_xor(s1, 16); s1 += __shfl_xor(s1, 32); s2 += __shfl_xor(s2, 16); s2 += __shfl_xor(s2, 32);
;             if (fq == 0) { unsafeAtomicAdd(ST2 + (size_t)row * 2, s1); unsafeAtomicAdd(ST2 + (size_t)row * 2 + 1, s2); } }
.LBB0_74:
	s_or_b64 exec, exec, vcc
	v_add_u32_e32 v116, 0x80, v184
	v_mov_b32_e32 v82, v116
	v_pk_mul_f32 v[126:127], v[136:137], s[36:37] op_sel_hi:[1,0]
	s_waitcnt lgkmcnt(0)
	v_ashrrev_i32_e32 v83, 31, v82
	v_lshl_add_u64 v[84:85], v[82:83], 3, s[14:15]
	v_lshlrev_b64 v[82:83], 12, v[82:83]
	v_lshl_add_u64 v[82:83], v[168:169], 0, v[82:83]
	global_load_dwordx2 v[114:115], v[84:85], off
	global_load_dwordx4 v[94:97], v[82:83], off
	global_load_dwordx4 v[90:93], v[82:83], off offset:16
	global_load_dwordx4 v[86:89], v[82:83], off offset:512
	s_nop 0
	global_load_dwordx4 v[82:85], v[82:83], off offset:528
	global_load_dwordx4 v[118:121], v[160:161], off
	global_load_dwordx4 v[122:125], v[162:163], off
	v_fma_f32 v117, -v126, v126, v127
	v_max_f32_e32 v117, 0, v117
	v_add_f32_e32 v117, 0x3727c5ac, v117
	v_rsq_f32_e32 v128, v117
	v_sub_f32_e32 v111, v111, v126
	v_sub_f32_e32 v110, v110, v126
	v_sub_f32_e32 v113, v113, v126
	v_sub_f32_e32 v112, v112, v126
	v_pk_mul_f32 v[112:113], v[112:113], v[128:129] op_sel_hi:[1,0]
	v_pk_mul_f32 v[110:111], v[110:111], v[128:129] op_sel_hi:[1,0]
	v_ashrrev_i32_e32 v135, 31, v134
	v_lshlrev_b64 v[136:137], 12, v[134:135]
	v_lshl_add_u64 v[136:137], v[168:169], 0, v[136:137]
	v_sub_f32_e32 v107, v107, v126
	v_sub_f32_e32 v106, v106, v126
	v_sub_f32_e32 v109, v109, v126
	v_sub_f32_e32 v108, v108, v126
	v_pk_mul_f32 v[108:109], v[108:109], v[128:129] op_sel_hi:[1,0]
	v_pk_mul_f32 v[106:107], v[106:107], v[128:129] op_sel_hi:[1,0]
	v_sub_f32_e32 v103, v103, v126
	v_sub_f32_e32 v102, v102, v126
	v_sub_f32_e32 v105, v105, v126
	v_sub_f32_e32 v104, v104, v126
	v_pk_mul_f32 v[104:105], v[104:105], v[128:129] op_sel_hi:[1,0]
	v_pk_mul_f32 v[102:103], v[102:103], v[128:129] op_sel_hi:[1,0]
	v_sub_f32_e32 v99, v99, v126
	v_sub_f32_e32 v98, v98, v126
	v_sub_f32_e32 v101, v101, v126
	v_sub_f32_e32 v100, v100, v126
	v_pk_mul_f32 v[100:101], v[100:101], v[128:129] op_sel_hi:[1,0]
	v_pk_mul_f32 v[98:99], v[98:99], v[128:129] op_sel_hi:[1,0]
	s_waitcnt vmcnt(0)
	v_pk_fma_f32 v[110:111], v[110:111], v[118:119], v[122:123]
	v_pk_fma_f32 v[112:113], v[112:113], v[120:121], v[124:125]
	v_pk_fma_f32 v[78:79], v[110:111], s[30:31], v[78:79] op_sel_hi:[1,0,1]
	v_pk_fma_f32 v[80:81], v[112:113], s[30:31], v[80:81] op_sel_hi:[1,0,1]
	global_store_dwordx4 v[136:137], v[78:81], off
	global_load_dwordx4 v[110:113], v[160:161], off offset:16
	global_load_dwordx4 v[118:121], v[162:163], off offset:16
	s_waitcnt vmcnt(0)
	v_pk_fma_f32 v[106:107], v[106:107], v[110:111], v[118:119]
	v_pk_fma_f32 v[108:109], v[108:109], v[112:113], v[120:121]
	v_pk_fma_f32 v[74:75], v[106:107], s[30:31], v[74:75] op_sel_hi:[1,0,1]
	v_pk_fma_f32 v[76:77], v[108:109], s[30:31], v[76:77] op_sel_hi:[1,0,1]
	global_store_dwordx4 v[136:137], v[74:77], off offset:16
	global_load_dwordx4 v[106:109], v[164:165], off
	global_load_dwordx4 v[110:113], v[164:165], off offset:16
	v_lshlrev_b64 v[118:119], 10, v[134:135]
	v_lshl_add_u64 v[118:119], v[118:119], 0, v[166:167]
	v_lshl_add_u64 v[118:119], v[118:119], 1, s[60:61]
	s_waitcnt vmcnt(0)
	v_pk_mul_f32 v[108:109], v[80:81], v[108:109]
	v_pk_mul_f32 v[106:107], v[78:79], v[106:107]
	v_pk_mul_f32 v[112:113], v[112:113], v[76:77]
	v_pk_mul_f32 v[110:111], v[110:111], v[74:75]
	v_cvt_pk_bf16_f32 v106, v106, v107
	v_cvt_pk_bf16_f32 v107, v108, v109
	v_cvt_pk_bf16_f32 v108, v110, v111
	v_cvt_pk_bf16_f32 v109, v112, v113
	global_store_dwordx4 v[118:119], v[106:109], off
	global_load_dwordx4 v[106:109], v[160:161], off offset:512
	s_nop 0
	global_load_dwordx4 v[110:113], v[162:163], off offset:512
	s_waitcnt vmcnt(0)
	v_pk_fma_f32 v[102:103], v[102:103], v[106:107], v[110:111]
	v_pk_fma_f32 v[104:105], v[104:105], v[108:109], v[112:113]
	v_pk_fma_f32 v[70:71], v[102:103], s[30:31], v[70:71] op_sel_hi:[1,0,1]
	v_pk_fma_f32 v[72:73], v[104:105], s[30:31], v[72:73] op_sel_hi:[1,0,1]
	global_store_dwordx4 v[136:137], v[70:73], off offset:512
	global_load_dwordx4 v[102:105], v[160:161], off offset:528
	global_load_dwordx4 v[106:109], v[162:163], off offset:528
	s_waitcnt vmcnt(0)
	v_pk_fma_f32 v[98:99], v[98:99], v[102:103], v[106:107]
	v_pk_fma_f32 v[100:101], v[100:101], v[104:105], v[108:109]
	v_pk_fma_f32 v[98:99], v[98:99], s[30:31], v[66:67] op_sel_hi:[1,0,1]
	v_pk_fma_f32 v[100:101], v[100:101], s[30:31], v[68:69] op_sel_hi:[1,0,1]
	global_store_dwordx4 v[136:137], v[98:101], off offset:528
	global_load_dwordx4 v[102:105], v[164:165], off offset:512
	global_load_dwordx4 v[106:109], v[164:165], off offset:528
	v_mul_f32_e32 v68, v79, v79
	v_mul_f32_e32 v69, v80, v80
	v_add_f32_e32 v66, v78, v79
	v_add_f32_e32 v67, v81, v80
	v_fmac_f32_e32 v68, v78, v78
	v_fmac_f32_e32 v69, v81, v81
	v_add_f32_e32 v66, v66, v67
	v_add_f32_e32 v67, v68, v69
	v_add_f32_e32 v68, v74, v75
	v_add_f32_e32 v69, v77, v76
	v_mul_f32_e32 v75, v75, v75
	v_mul_f32_e32 v76, v76, v76
	v_add_f32_e32 v66, 0, v66
	v_add_f32_e32 v68, v68, v69
	v_fmac_f32_e32 v75, v74, v74
	v_fmac_f32_e32 v76, v77, v77
	v_add_f32_e32 v66, v66, v68
	v_add_f32_e32 v68, v75, v76
	v_add_f32_e32 v67, v67, v68
	v_add_f32_e32 v68, v70, v71
	v_add_f32_e32 v69, v73, v72
	v_mul_f32_e32 v74, v71, v71
	v_mul_f32_e32 v75, v72, v72
	v_add_f32_e32 v68, v68, v69
	v_fmac_f32_e32 v74, v70, v70
	v_fmac_f32_e32 v75, v73, v73
	v_add_f32_e32 v66, v66, v68
	v_add_f32_e32 v68, v74, v75
	v_add_f32_e32 v67, v67, v68
	v_add_f32_e32 v68, v98, v99
	v_add_f32_e32 v69, v101, v100
	v_mul_f32_e32 v74, v99, v99
	v_mul_f32_e32 v75, v100, v100
	v_add_f32_e32 v68, v68, v69
	v_fmac_f32_e32 v74, v98, v98
	v_fmac_f32_e32 v75, v101, v101
	v_add_f32_e32 v66, v66, v68
	v_add_f32_e32 v68, v74, v75
	v_add_f32_e32 v68, v67, v68
	ds_bpermute_b32 v69, v183, v66
	ds_bpermute_b32 v74, v183, v68
	s_waitcnt lgkmcnt(0)
	v_add_f32_e32 v66, v66, v69
	v_add_f32_e32 v68, v68, v74
	ds_bpermute_b32 v67, v182, v66
	ds_bpermute_b32 v69, v182, v68
	s_waitcnt vmcnt(0)
	v_pk_mul_f32 v[72:73], v[72:73], v[104:105]
	v_pk_mul_f32 v[70:71], v[70:71], v[102:103]
	v_pk_mul_f32 v[74:75], v[108:109], v[100:101]
	v_pk_mul_f32 v[76:77], v[106:107], v[98:99]
	v_cvt_pk_bf16_f32 v70, v70, v71
	v_cvt_pk_bf16_f32 v71, v72, v73
	v_cvt_pk_bf16_f32 v72, v76, v77
	v_cvt_pk_bf16_f32 v73, v74, v75
	global_store_dwordx4 v[118:119], v[70:73], off offset:256
	s_and_saveexec_b64 vcc, s[40:41]
	s_cbranch_execz .LBB0_76
	s_waitcnt lgkmcnt(0)
	v_add_f32_e32 v68, v68, v69
	v_add_f32_e32 v69, v66, v67
	v_lshl_add_u64 v[66:67], v[134:135], 3, s[58:59]
	global_atomic_add_f32 v[66:67], v69, off
	global_atomic_add_f32 v[66:67], v68, off offset:4
; DI u32x4 pack8(f32x4 a, f32x4 b) { u32x4 w; w.x = pk2(a[0], a[1]); w.y = pk2(a[2], a[3]); w.z = pk2(b[0], b[1]); w.w = pk2(b[2], b[3]); return w; }
;     DI void operator()(AccRef acc, const Unit& u, int wr, int wc, int fr, int fq) const {
;     ...
;         for (int it = 0; it < 8; ++it) { const int ai = it >> 2, m = it & 3, cur = it & 1;
;             if (it + 1 < 8) { int rn_ = row0 + ((it + 1) >> 2) * 128 + ((it + 1) & 3) * 16; asm volatile("" : "+v"(rn_) :: "memory"); const size_t on = (size_t)rn_ * DM + c0; sb[cur ^ 1] = *(const f32x2*)(ST + (size_t)rn_ * 2);
; #pragma unroll
;                 for (int bj = 0; bj < 2; ++bj)
; #pragma unroll
;                     for (int n = 0; n < 2; ++n) yb[cur ^ 1][bj][n] = *(const f32x4*)(Y + on + bj * 128 + 4 * n); }
;             int row = row0 + ai * 128 + m * 16; asm volatile("" : "+v"(row)); const size_t off = (size_t)row * DM + c0; float s1 = 0.f, s2 = 0.f;
;             const float mean = sb[cur].x * (1.f / DM); const float rstd = __builtin_amdgcn_rsqf(fmaxf(sb[cur].y * (1.f / DM) - mean * mean, 0.f) + LN_EPS);
; #pragma unroll
;             for (int bj = 0; bj < 2; ++bj) { f32x4 y[2];
; #pragma unroll
;                 for (int n = 0; n < 2; ++n) { const int cc = c0 + bj * 128 + 4 * n; const f32x4 gv = *(const f32x4*)(G + cc), bv = *(const f32x4*)(Bv + cc);
;                     const f32x4 x1 = (yb[cur][bj][n] - mean) * rstd * gv + bv;
;                     y[n] = x1 * ALPHA + acc[ai][bj][m][n]; *(f32x4*)(Y + off + bj * 128 + 4 * n) = y[n];
;                     s1 += (y[n][0] + y[n][1]) + (y[n][2] + y[n][3]); s2 += (y[n][0] * y[n][0] + y[n][1] * y[n][1]) + (y[n][2] * y[n][2] + y[n][3] * y[n][3]); }
;                 const f32x4 g0 = *(const f32x4*)(G2 + c0 + bj * 128), g1 = *(const f32x4*)(G2 + c0 + bj * 128 + 4);
;                 *(u32x4*)(YG + off + bj * 128) = pack8(y[0] * g0, y[1] * g1); }
;             s1 += __shfl_xor(s1, 16); s1 += __shfl_xor(s1, 32); s2 += __shfl_xor(s2, 16); s2 += __shfl_xor(s2, 32);
;             if (fq == 0) { unsafeAtomicAdd(ST2 + (size_t)row * 2, s1); unsafeAtomicAdd(ST2 + (size_t)row * 2 + 1, s2); } }
.LBB0_76:
	s_or_b64 exec, exec, vcc
	v_or_b32_e32 v98, 16, v116
	v_mov_b32_e32 v66, v98
	v_mov_b32_e32 v102, v116
	s_waitcnt lgkmcnt(0)
	v_ashrrev_i32_e32 v67, 31, v66
	v_lshl_add_u64 v[68:69], v[66:67], 3, s[14:15]
	v_lshlrev_b64 v[66:67], 12, v[66:67]
	v_lshl_add_u64 v[66:67], v[168:169], 0, v[66:67]
	global_load_dwordx2 v[100:101], v[68:69], off
	global_load_dwordx4 v[78:81], v[66:67], off
	global_load_dwordx4 v[74:77], v[66:67], off offset:16
	global_load_dwordx4 v[70:73], v[66:67], off offset:512
	s_nop 0
	global_load_dwordx4 v[66:69], v[66:67], off offset:528
	global_load_dwordx4 v[104:107], v[160:161], off
	global_load_dwordx4 v[108:111], v[162:163], off
	v_pk_mul_f32 v[112:113], v[114:115], s[36:37] op_sel_hi:[1,0]
	v_ashrrev_i32_e32 v103, 31, v102
	v_fma_f32 v99, -v112, v112, v113
	v_max_f32_e32 v99, 0, v99
	v_add_f32_e32 v99, 0x3727c5ac, v99
	v_rsq_f32_e32 v114, v99
	v_sub_f32_e32 v95, v95, v112
	v_sub_f32_e32 v94, v94, v112
	v_sub_f32_e32 v97, v97, v112
	v_sub_f32_e32 v96, v96, v112
	v_pk_mul_f32 v[96:97], v[96:97], v[114:115] op_sel_hi:[1,0]
	v_pk_mul_f32 v[94:95], v[94:95], v[114:115] op_sel_hi:[1,0]
	v_lshlrev_b64 v[118:119], 12, v[102:103]
	v_lshl_add_u64 v[118:119], v[168:169], 0, v[118:119]
	v_sub_f32_e32 v91, v91, v112
	v_sub_f32_e32 v90, v90, v112
	v_sub_f32_e32 v93, v93, v112
	v_sub_f32_e32 v92, v92, v112
	v_pk_mul_f32 v[92:93], v[92:93], v[114:115] op_sel_hi:[1,0]
	v_pk_mul_f32 v[90:91], v[90:91], v[114:115] op_sel_hi:[1,0]
	v_sub_f32_e32 v87, v87, v112
	v_sub_f32_e32 v86, v86, v112
	v_sub_f32_e32 v89, v89, v112
	v_sub_f32_e32 v88, v88, v112
	v_pk_mul_f32 v[88:89], v[88:89], v[114:115] op_sel_hi:[1,0]
	v_pk_mul_f32 v[86:87], v[86:87], v[114:115] op_sel_hi:[1,0]
	v_sub_f32_e32 v83, v83, v112
	v_sub_f32_e32 v82, v82, v112
	v_sub_f32_e32 v85, v85, v112
	v_sub_f32_e32 v84, v84, v112
	v_pk_mul_f32 v[84:85], v[84:85], v[114:115] op_sel_hi:[1,0]
	v_pk_mul_f32 v[82:83], v[82:83], v[114:115] op_sel_hi:[1,0]
	s_waitcnt vmcnt(0)
	v_pk_fma_f32 v[94:95], v[94:95], v[104:105], v[108:109]
	v_pk_fma_f32 v[96:97], v[96:97], v[106:107], v[110:111]
	v_pk_fma_f32 v[62:63], v[94:95], s[30:31], v[62:63] op_sel_hi:[1,0,1]
	v_pk_fma_f32 v[64:65], v[96:97], s[30:31], v[64:65] op_sel_hi:[1,0,1]
	global_store_dwordx4 v[118:119], v[62:65], off
	global_load_dwordx4 v[94:97], v[160:161], off offset:16
	global_load_dwordx4 v[104:107], v[162:163], off offset:16
	s_waitcnt vmcnt(0)
	v_pk_fma_f32 v[90:91], v[90:91], v[94:95], v[104:105]
	v_pk_fma_f32 v[92:93], v[92:93], v[96:97], v[106:107]
	v_pk_fma_f32 v[58:59], v[90:91], s[30:31], v[58:59] op_sel_hi:[1,0,1]
	v_pk_fma_f32 v[60:61], v[92:93], s[30:31], v[60:61] op_sel_hi:[1,0,1]
	global_store_dwordx4 v[118:119], v[58:61], off offset:16
	global_load_dwordx4 v[90:93], v[164:165], off
	global_load_dwordx4 v[94:97], v[164:165], off offset:16
	v_lshlrev_b64 v[104:105], 10, v[102:103]
	v_lshl_add_u64 v[104:105], v[104:105], 0, v[166:167]
	v_lshl_add_u64 v[104:105], v[104:105], 1, s[60:61]
	s_waitcnt vmcnt(0)
	v_pk_mul_f32 v[92:93], v[64:65], v[92:93]
	v_pk_mul_f32 v[90:91], v[62:63], v[90:91]
	v_pk_mul_f32 v[96:97], v[96:97], v[60:61]
	v_pk_mul_f32 v[94:95], v[94:95], v[58:59]
	v_cvt_pk_bf16_f32 v90, v90, v91
	v_cvt_pk_bf16_f32 v91, v92, v93
	v_cvt_pk_bf16_f32 v92, v94, v95
	v_cvt_pk_bf16_f32 v93, v96, v97
	global_store_dwordx4 v[104:105], v[90:93], off
	global_load_dwordx4 v[90:93], v[160:161], off offset:512
	s_nop 0
	global_load_dwordx4 v[94:97], v[162:163], off offset:512
	s_waitcnt vmcnt(0)
	v_pk_fma_f32 v[86:87], v[86:87], v[90:91], v[94:95]
	v_pk_fma_f32 v[88:89], v[88:89], v[92:93], v[96:97]
	v_pk_fma_f32 v[54:55], v[86:87], s[30:31], v[54:55] op_sel_hi:[1,0,1]
	v_pk_fma_f32 v[56:57], v[88:89], s[30:31], v[56:57] op_sel_hi:[1,0,1]
	global_store_dwordx4 v[118:119], v[54:57], off offset:512
	global_load_dwordx4 v[86:89], v[160:161], off offset:528
	global_load_dwordx4 v[90:93], v[162:163], off offset:528
	s_waitcnt vmcnt(0)
	v_pk_fma_f32 v[82:83], v[82:83], v[86:87], v[90:91]
	v_pk_fma_f32 v[84:85], v[84:85], v[88:89], v[92:93]
	v_pk_fma_f32 v[82:83], v[82:83], s[30:31], v[50:51] op_sel_hi:[1,0,1]
	v_pk_fma_f32 v[84:85], v[84:85], s[30:31], v[52:53] op_sel_hi:[1,0,1]
	global_store_dwordx4 v[118:119], v[82:85], off offset:528
	global_load_dwordx4 v[86:89], v[164:165], off offset:512
	global_load_dwordx4 v[90:93], v[164:165], off offset:528
	v_mul_f32_e32 v52, v63, v63
	v_mul_f32_e32 v53, v64, v64
	v_add_f32_e32 v50, v62, v63
	v_add_f32_e32 v51, v65, v64
	v_fmac_f32_e32 v52, v62, v62
	v_fmac_f32_e32 v53, v65, v65
	v_add_f32_e32 v50, v50, v51
	v_add_f32_e32 v51, v52, v53
	v_add_f32_e32 v52, v58, v59
	v_add_f32_e32 v53, v61, v60
	v_mul_f32_e32 v59, v59, v59
	v_mul_f32_e32 v60, v60, v60
	v_add_f32_e32 v50, 0, v50
	v_add_f32_e32 v52, v52, v53
	v_fmac_f32_e32 v59, v58, v58
	v_fmac_f32_e32 v60, v61, v61
	v_add_f32_e32 v50, v50, v52
	v_add_f32_e32 v52, v59, v60
	v_add_f32_e32 v51, v51, v52
	v_add_f32_e32 v52, v54, v55
	v_add_f32_e32 v53, v57, v56
	v_mul_f32_e32 v58, v55, v55
	v_mul_f32_e32 v59, v56, v56
	v_add_f32_e32 v52, v52, v53
	v_fmac_f32_e32 v58, v54, v54
	v_fmac_f32_e32 v59, v57, v57
	v_add_f32_e32 v50, v50, v52
	v_add_f32_e32 v52, v58, v59
	v_add_f32_e32 v51, v51, v52
	v_add_f32_e32 v52, v82, v83
	v_add_f32_e32 v53, v85, v84
	v_mul_f32_e32 v58, v83, v83
	v_mul_f32_e32 v59, v84, v84
	v_add_f32_e32 v52, v52, v53
	v_fmac_f32_e32 v58, v82, v82
	v_fmac_f32_e32 v59, v85, v85
	v_add_f32_e32 v50, v50, v52
	v_add_f32_e32 v52, v58, v59
	v_add_f32_e32 v52, v51, v52
	ds_bpermute_b32 v53, v183, v50
	ds_bpermute_b32 v58, v183, v52
	s_waitcnt lgkmcnt(0)
	v_add_f32_e32 v50, v50, v53
	v_add_f32_e32 v52, v52, v58
	ds_bpermute_b32 v51, v182, v50
	ds_bpermute_b32 v53, v182, v52
	s_waitcnt vmcnt(0)
	v_pk_mul_f32 v[56:57], v[56:57], v[88:89]
	v_pk_mul_f32 v[54:55], v[54:55], v[86:87]
	v_pk_mul_f32 v[58:59], v[92:93], v[84:85]
	v_pk_mul_f32 v[60:61], v[90:91], v[82:83]
	v_cvt_pk_bf16_f32 v54, v54, v55
	v_cvt_pk_bf16_f32 v55, v56, v57
	v_cvt_pk_bf16_f32 v56, v60, v61
	v_cvt_pk_bf16_f32 v57, v58, v59
	global_store_dwordx4 v[104:105], v[54:57], off offset:256
	s_and_saveexec_b64 vcc, s[40:41]
	s_cbranch_execz .LBB0_78
	s_waitcnt lgkmcnt(0)
	v_add_f32_e32 v52, v52, v53
	v_add_f32_e32 v53, v50, v51
	v_lshl_add_u64 v[50:51], v[102:103], 3, s[58:59]
	global_atomic_add_f32 v[50:51], v53, off
	global_atomic_add_f32 v[50:51], v52, off offset:4
; DI u32x4 pack8(f32x4 a, f32x4 b) { u32x4 w; w.x = pk2(a[0], a[1]); w.y = pk2(a[2], a[3]); w.z = pk2(b[0], b[1]); w.w = pk2(b[2], b[3]); return w; }
;     DI void operator()(AccRef acc, const Unit& u, int wr, int wc, int fr, int fq) const {
;     ...
;         for (int it = 0; it < 8; ++it) { const int ai = it >> 2, m = it & 3, cur = it & 1;
;             if (it + 1 < 8) { int rn_ = row0 + ((it + 1) >> 2) * 128 + ((it + 1) & 3) * 16; asm volatile("" : "+v"(rn_) :: "memory"); const size_t on = (size_t)rn_ * DM + c0; sb[cur ^ 1] = *(const f32x2*)(ST + (size_t)rn_ * 2);
; #pragma unroll
;                 for (int bj = 0; bj < 2; ++bj)
; #pragma unroll
;                     for (int n = 0; n < 2; ++n) yb[cur ^ 1][bj][n] = *(const f32x4*)(Y + on + bj * 128 + 4 * n); }
;             int row = row0 + ai * 128 + m * 16; asm volatile("" : "+v"(row)); const size_t off = (size_t)row * DM + c0; float s1 = 0.f, s2 = 0.f;
;             const float mean = sb[cur].x * (1.f / DM); const float rstd = __builtin_amdgcn_rsqf(fmaxf(sb[cur].y * (1.f / DM) - mean * mean, 0.f) + LN_EPS);
; #pragma unroll
;             for (int bj = 0; bj < 2; ++bj) { f32x4 y[2];
; #pragma unroll
;                 for (int n = 0; n < 2; ++n) { const int cc = c0 + bj * 128 + 4 * n; const f32x4 gv = *(const f32x4*)(G + cc), bv = *(const f32x4*)(Bv + cc);
;                     const f32x4 x1 = (yb[cur][bj][n] - mean) * rstd * gv + bv;
;                     y[n] = x1 * ALPHA + acc[ai][bj][m][n]; *(f32x4*)(Y + off + bj * 128 + 4 * n) = y[n];
;                     s1 += (y[n][0] + y[n][1]) + (y[n][2] + y[n][3]); s2 += (y[n][0] * y[n][0] + y[n][1] * y[n][1]) + (y[n][2] * y[n][2] + y[n][3] * y[n][3]); }
;                 const f32x4 g0 = *(const f32x4*)(G2 + c0 + bj * 128), g1 = *(const f32x4*)(G2 + c0 + bj * 128 + 4);
;                 *(u32x4*)(YG + off + bj * 128) = pack8(y[0] * g0, y[1] * g1); }
;             s1 += __shfl_xor(s1, 16); s1 += __shfl_xor(s1, 32); s2 += __shfl_xor(s2, 16); s2 += __shfl_xor(s2, 32);
;             if (fq == 0) { unsafeAtomicAdd(ST2 + (size_t)row * 2, s1); unsafeAtomicAdd(ST2 + (size_t)row * 2 + 1, s2); } }
.LBB0_78:
	s_or_b64 exec, exec, vcc
	v_or_b32_e32 v82, 32, v116
	v_mov_b32_e32 v50, v82
	v_pk_mul_f32 v[94:95], v[100:101], s[36:37] op_sel_hi:[1,0]
	s_waitcnt lgkmcnt(0)
	v_ashrrev_i32_e32 v51, 31, v50
	v_lshl_add_u64 v[52:53], v[50:51], 3, s[14:15]
	v_lshlrev_b64 v[50:51], 12, v[50:51]
	v_lshl_add_u64 v[50:51], v[168:169], 0, v[50:51]
	global_load_dwordx2 v[84:85], v[52:53], off
	global_load_dwordx4 v[62:65], v[50:51], off
	global_load_dwordx4 v[58:61], v[50:51], off offset:16
	global_load_dwordx4 v[54:57], v[50:51], off offset:512
	s_nop 0
	global_load_dwordx4 v[50:53], v[50:51], off offset:528
	global_load_dwordx4 v[86:89], v[160:161], off
	global_load_dwordx4 v[90:93], v[162:163], off
	v_fma_f32 v83, -v94, v94, v95
	v_max_f32_e32 v83, 0, v83
	v_add_f32_e32 v83, 0x3727c5ac, v83
	v_rsq_f32_e32 v96, v83
	v_sub_f32_e32 v79, v79, v94
	v_sub_f32_e32 v78, v78, v94
	v_sub_f32_e32 v81, v81, v94
	v_sub_f32_e32 v80, v80, v94
	v_pk_mul_f32 v[80:81], v[80:81], v[96:97] op_sel_hi:[1,0]
	v_pk_mul_f32 v[78:79], v[78:79], v[96:97] op_sel_hi:[1,0]
	v_ashrrev_i32_e32 v99, 31, v98
	v_lshlrev_b64 v[100:101], 12, v[98:99]
	v_lshl_add_u64 v[100:101], v[168:169], 0, v[100:101]
	v_sub_f32_e32 v75, v75, v94
	v_sub_f32_e32 v74, v74, v94
	v_sub_f32_e32 v77, v77, v94
	v_sub_f32_e32 v76, v76, v94
	v_pk_mul_f32 v[76:77], v[76:77], v[96:97] op_sel_hi:[1,0]
	v_pk_mul_f32 v[74:75], v[74:75], v[96:97] op_sel_hi:[1,0]
	v_sub_f32_e32 v71, v71, v94
	v_sub_f32_e32 v70, v70, v94
	v_sub_f32_e32 v73, v73, v94
	v_sub_f32_e32 v72, v72, v94
	v_pk_mul_f32 v[72:73], v[72:73], v[96:97] op_sel_hi:[1,0]
	v_pk_mul_f32 v[70:71], v[70:71], v[96:97] op_sel_hi:[1,0]
	v_sub_f32_e32 v67, v67, v94
	v_sub_f32_e32 v66, v66, v94
	v_sub_f32_e32 v69, v69, v94
	v_sub_f32_e32 v68, v68, v94
	v_pk_mul_f32 v[68:69], v[68:69], v[96:97] op_sel_hi:[1,0]
	v_pk_mul_f32 v[66:67], v[66:67], v[96:97] op_sel_hi:[1,0]
	s_waitcnt vmcnt(0)
	v_pk_fma_f32 v[78:79], v[78:79], v[86:87], v[90:91]
	v_pk_fma_f32 v[80:81], v[80:81], v[88:89], v[92:93]
	v_pk_fma_f32 v[46:47], v[78:79], s[30:31], v[46:47] op_sel_hi:[1,0,1]
	v_pk_fma_f32 v[48:49], v[80:81], s[30:31], v[48:49] op_sel_hi:[1,0,1]
	global_store_dwordx4 v[100:101], v[46:49], off
	global_load_dwordx4 v[78:81], v[160:161], off offset:16
	global_load_dwordx4 v[86:89], v[162:163], off offset:16
	s_waitcnt vmcnt(0)
	v_pk_fma_f32 v[74:75], v[74:75], v[78:79], v[86:87]
	v_pk_fma_f32 v[76:77], v[76:77], v[80:81], v[88:89]
	v_pk_fma_f32 v[42:43], v[74:75], s[30:31], v[42:43] op_sel_hi:[1,0,1]
	v_pk_fma_f32 v[44:45], v[76:77], s[30:31], v[44:45] op_sel_hi:[1,0,1]
	global_store_dwordx4 v[100:101], v[42:45], off offset:16
	global_load_dwordx4 v[74:77], v[164:165], off
	global_load_dwordx4 v[78:81], v[164:165], off offset:16
	v_lshlrev_b64 v[86:87], 10, v[98:99]
	v_lshl_add_u64 v[86:87], v[86:87], 0, v[166:167]
	v_lshl_add_u64 v[86:87], v[86:87], 1, s[60:61]
	s_waitcnt vmcnt(0)
	v_pk_mul_f32 v[76:77], v[48:49], v[76:77]
	v_pk_mul_f32 v[74:75], v[46:47], v[74:75]
	v_pk_mul_f32 v[80:81], v[80:81], v[44:45]
	v_pk_mul_f32 v[78:79], v[78:79], v[42:43]
	v_cvt_pk_bf16_f32 v74, v74, v75
	v_cvt_pk_bf16_f32 v75, v76, v77
	v_cvt_pk_bf16_f32 v76, v78, v79
	v_cvt_pk_bf16_f32 v77, v80, v81
	global_store_dwordx4 v[86:87], v[74:77], off
	global_load_dwordx4 v[74:77], v[160:161], off offset:512
	s_nop 0
	global_load_dwordx4 v[78:81], v[162:163], off offset:512
	s_waitcnt vmcnt(0)
	v_pk_fma_f32 v[70:71], v[70:71], v[74:75], v[78:79]
	v_pk_fma_f32 v[72:73], v[72:73], v[76:77], v[80:81]
	v_pk_fma_f32 v[38:39], v[70:71], s[30:31], v[38:39] op_sel_hi:[1,0,1]
	v_pk_fma_f32 v[40:41], v[72:73], s[30:31], v[40:41] op_sel_hi:[1,0,1]
	global_store_dwordx4 v[100:101], v[38:41], off offset:512
	global_load_dwordx4 v[70:73], v[160:161], off offset:528
	global_load_dwordx4 v[74:77], v[162:163], off offset:528
	s_waitcnt vmcnt(0)
	v_pk_fma_f32 v[66:67], v[66:67], v[70:71], v[74:75]
	v_pk_fma_f32 v[68:69], v[68:69], v[72:73], v[76:77]
	v_pk_fma_f32 v[66:67], v[66:67], s[30:31], v[34:35] op_sel_hi:[1,0,1]
	v_pk_fma_f32 v[68:69], v[68:69], s[30:31], v[36:37] op_sel_hi:[1,0,1]
	global_store_dwordx4 v[100:101], v[66:69], off offset:528
	global_load_dwordx4 v[70:73], v[164:165], off offset:512
	global_load_dwordx4 v[74:77], v[164:165], off offset:528
	v_mul_f32_e32 v36, v47, v47
	v_mul_f32_e32 v37, v48, v48
	v_add_f32_e32 v34, v46, v47
	v_add_f32_e32 v35, v49, v48
	v_fmac_f32_e32 v36, v46, v46
	v_fmac_f32_e32 v37, v49, v49
	v_add_f32_e32 v34, v34, v35
	v_add_f32_e32 v35, v36, v37
	v_add_f32_e32 v36, v42, v43
	v_add_f32_e32 v37, v45, v44
	v_mul_f32_e32 v43, v43, v43
	v_mul_f32_e32 v44, v44, v44
	v_add_f32_e32 v34, 0, v34
	v_add_f32_e32 v36, v36, v37
	v_fmac_f32_e32 v43, v42, v42
	v_fmac_f32_e32 v44, v45, v45
	v_add_f32_e32 v34, v34, v36
	v_add_f32_e32 v36, v43, v44
	v_add_f32_e32 v35, v35, v36
	v_add_f32_e32 v36, v38, v39
	v_add_f32_e32 v37, v41, v40
	v_mul_f32_e32 v42, v39, v39
	v_mul_f32_e32 v43, v40, v40
	v_add_f32_e32 v36, v36, v37
	v_fmac_f32_e32 v42, v38, v38
	v_fmac_f32_e32 v43, v41, v41
	v_add_f32_e32 v34, v34, v36
	v_add_f32_e32 v36, v42, v43
	v_add_f32_e32 v35, v35, v36
	v_add_f32_e32 v36, v66, v67
	v_add_f32_e32 v37, v69, v68
	v_mul_f32_e32 v42, v67, v67
	v_mul_f32_e32 v43, v68, v68
	v_add_f32_e32 v36, v36, v37
	v_fmac_f32_e32 v42, v66, v66
	v_fmac_f32_e32 v43, v69, v69
	v_add_f32_e32 v34, v34, v36
	v_add_f32_e32 v36, v42, v43
	v_add_f32_e32 v36, v35, v36
	ds_bpermute_b32 v37, v183, v34
	ds_bpermute_b32 v42, v183, v36
	s_waitcnt lgkmcnt(0)
	v_add_f32_e32 v34, v34, v37
	v_add_f32_e32 v36, v36, v42
	ds_bpermute_b32 v35, v182, v34
	ds_bpermute_b32 v37, v182, v36
	s_waitcnt vmcnt(0)
	v_pk_mul_f32 v[40:41], v[40:41], v[72:73]
	v_pk_mul_f32 v[38:39], v[38:39], v[70:71]
	v_pk_mul_f32 v[42:43], v[76:77], v[68:69]
	v_pk_mul_f32 v[44:45], v[74:75], v[66:67]
	v_cvt_pk_bf16_f32 v38, v38, v39
	v_cvt_pk_bf16_f32 v39, v40, v41
	v_cvt_pk_bf16_f32 v40, v44, v45
	v_cvt_pk_bf16_f32 v41, v42, v43
	global_store_dwordx4 v[86:87], v[38:41], off offset:256
	s_and_saveexec_b64 vcc, s[40:41]
	s_cbranch_execz .LBB0_80
	s_waitcnt lgkmcnt(0)
	v_add_f32_e32 v36, v36, v37
	v_add_f32_e32 v37, v34, v35
	v_lshl_add_u64 v[34:35], v[98:99], 3, s[58:59]
	global_atomic_add_f32 v[34:35], v37, off
	global_atomic_add_f32 v[34:35], v36, off offset:4
; DI u32x4 pack8(f32x4 a, f32x4 b) { u32x4 w; w.x = pk2(a[0], a[1]); w.y = pk2(a[2], a[3]); w.z = pk2(b[0], b[1]); w.w = pk2(b[2], b[3]); return w; }
;     DI void operator()(AccRef acc, const Unit& u, int wr, int wc, int fr, int fq) const {
;     ...
;         for (int it = 0; it < 8; ++it) { const int ai = it >> 2, m = it & 3, cur = it & 1;
;             if (it + 1 < 8) { int rn_ = row0 + ((it + 1) >> 2) * 128 + ((it + 1) & 3) * 16; asm volatile("" : "+v"(rn_) :: "memory"); const size_t on = (size_t)rn_ * DM + c0; sb[cur ^ 1] = *(const f32x2*)(ST + (size_t)rn_ * 2);
; #pragma unroll
;                 for (int bj = 0; bj < 2; ++bj)
; #pragma unroll
;                     for (int n = 0; n < 2; ++n) yb[cur ^ 1][bj][n] = *(const f32x4*)(Y + on + bj * 128 + 4 * n); }
;             int row = row0 + ai * 128 + m * 16; asm volatile("" : "+v"(row)); const size_t off = (size_t)row * DM + c0; float s1 = 0.f, s2 = 0.f;
;             const float mean = sb[cur].x * (1.f / DM); const float rstd = __builtin_amdgcn_rsqf(fmaxf(sb[cur].y * (1.f / DM) - mean * mean, 0.f) + LN_EPS);
; #pragma unroll
;             for (int bj = 0; bj < 2; ++bj) { f32x4 y[2];
; #pragma unroll
;                 for (int n = 0; n < 2; ++n) { const int cc = c0 + bj * 128 + 4 * n; const f32x4 gv = *(const f32x4*)(G + cc), bv = *(const f32x4*)(Bv + cc);
;                     const f32x4 x1 = (yb[cur][bj][n] - mean) * rstd * gv + bv;
;                     y[n] = x1 * ALPHA + acc[ai][bj][m][n]; *(f32x4*)(Y + off + bj * 128 + 4 * n) = y[n];
;                     s1 += (y[n][0] + y[n][1]) + (y[n][2] + y[n][3]); s2 += (y[n][0] * y[n][0] + y[n][1] * y[n][1]) + (y[n][2] * y[n][2] + y[n][3] * y[n][3]); }
;                 const f32x4 g0 = *(const f32x4*)(G2 + c0 + bj * 128), g1 = *(const f32x4*)(G2 + c0 + bj * 128 + 4);
;                 *(u32x4*)(YG + off + bj * 128) = pack8(y[0] * g0, y[1] * g1); }
;             s1 += __shfl_xor(s1, 16); s1 += __shfl_xor(s1, 32); s2 += __shfl_xor(s2, 16); s2 += __shfl_xor(s2, 32);
;             if (fq == 0) { unsafeAtomicAdd(ST2 + (size_t)row * 2, s1); unsafeAtomicAdd(ST2 + (size_t)row * 2 + 1, s2); } }
.LBB0_80:
	s_or_b64 exec, exec, vcc
	v_or_b32_e32 v66, 48, v116
	v_mov_b32_e32 v34, v66
	v_pk_mul_f32 v[78:79], v[84:85], s[36:37] op_sel_hi:[1,0]
	s_waitcnt lgkmcnt(0)
	v_ashrrev_i32_e32 v35, 31, v34
	v_lshl_add_u64 v[36:37], v[34:35], 3, s[14:15]
	v_lshlrev_b64 v[34:35], 12, v[34:35]
	v_lshl_add_u64 v[34:35], v[168:169], 0, v[34:35]
	global_load_dwordx2 v[68:69], v[36:37], off
	global_load_dwordx4 v[46:49], v[34:35], off
	global_load_dwordx4 v[42:45], v[34:35], off offset:16
	global_load_dwordx4 v[38:41], v[34:35], off offset:512
	s_nop 0
	global_load_dwordx4 v[34:37], v[34:35], off offset:528
	global_load_dwordx4 v[70:73], v[160:161], off
	global_load_dwordx4 v[74:77], v[162:163], off
	v_fma_f32 v67, -v78, v78, v79
	v_max_f32_e32 v67, 0, v67
	v_add_f32_e32 v67, 0x3727c5ac, v67
	v_rsq_f32_e32 v80, v67
	v_sub_f32_e32 v63, v63, v78
	v_sub_f32_e32 v62, v62, v78
	v_sub_f32_e32 v65, v65, v78
	v_sub_f32_e32 v64, v64, v78
	v_pk_mul_f32 v[64:65], v[64:65], v[80:81] op_sel_hi:[1,0]
	v_pk_mul_f32 v[62:63], v[62:63], v[80:81] op_sel_hi:[1,0]
	v_ashrrev_i32_e32 v83, 31, v82
	v_lshlrev_b64 v[84:85], 12, v[82:83]
	v_lshl_add_u64 v[84:85], v[168:169], 0, v[84:85]
	v_sub_f32_e32 v59, v59, v78
	v_sub_f32_e32 v58, v58, v78
	v_sub_f32_e32 v61, v61, v78
	v_sub_f32_e32 v60, v60, v78
	v_pk_mul_f32 v[60:61], v[60:61], v[80:81] op_sel_hi:[1,0]
	v_pk_mul_f32 v[58:59], v[58:59], v[80:81] op_sel_hi:[1,0]
	v_sub_f32_e32 v55, v55, v78
	v_sub_f32_e32 v54, v54, v78
	v_sub_f32_e32 v57, v57, v78
	v_sub_f32_e32 v56, v56, v78
	v_pk_mul_f32 v[56:57], v[56:57], v[80:81] op_sel_hi:[1,0]
	v_pk_mul_f32 v[54:55], v[54:55], v[80:81] op_sel_hi:[1,0]
	v_sub_f32_e32 v51, v51, v78
	v_sub_f32_e32 v50, v50, v78
	v_sub_f32_e32 v53, v53, v78
	v_sub_f32_e32 v52, v52, v78
	v_pk_mul_f32 v[52:53], v[52:53], v[80:81] op_sel_hi:[1,0]
	v_pk_mul_f32 v[50:51], v[50:51], v[80:81] op_sel_hi:[1,0]
	s_waitcnt vmcnt(0)
	v_pk_fma_f32 v[62:63], v[62:63], v[70:71], v[74:75]
	v_pk_fma_f32 v[64:65], v[64:65], v[72:73], v[76:77]
	v_pk_fma_f32 v[30:31], v[62:63], s[30:31], v[30:31] op_sel_hi:[1,0,1]
	v_pk_fma_f32 v[32:33], v[64:65], s[30:31], v[32:33] op_sel_hi:[1,0,1]
	global_store_dwordx4 v[84:85], v[30:33], off
	global_load_dwordx4 v[62:65], v[160:161], off offset:16
	global_load_dwordx4 v[70:73], v[162:163], off offset:16
	s_waitcnt vmcnt(0)
	v_pk_fma_f32 v[58:59], v[58:59], v[62:63], v[70:71]
	v_pk_fma_f32 v[60:61], v[60:61], v[64:65], v[72:73]
	v_pk_fma_f32 v[26:27], v[58:59], s[30:31], v[26:27] op_sel_hi:[1,0,1]
	v_pk_fma_f32 v[28:29], v[60:61], s[30:31], v[28:29] op_sel_hi:[1,0,1]
	global_store_dwordx4 v[84:85], v[26:29], off offset:16
	global_load_dwordx4 v[58:61], v[164:165], off
	global_load_dwordx4 v[62:65], v[164:165], off offset:16
	v_lshlrev_b64 v[70:71], 10, v[82:83]
	v_lshl_add_u64 v[70:71], v[70:71], 0, v[166:167]
	v_lshl_add_u64 v[70:71], v[70:71], 1, s[60:61]
	s_waitcnt vmcnt(0)
	v_pk_mul_f32 v[60:61], v[32:33], v[60:61]
	v_pk_mul_f32 v[58:59], v[30:31], v[58:59]
	v_pk_mul_f32 v[64:65], v[64:65], v[28:29]
	v_pk_mul_f32 v[62:63], v[62:63], v[26:27]
	v_cvt_pk_bf16_f32 v58, v58, v59
	v_cvt_pk_bf16_f32 v59, v60, v61
	v_cvt_pk_bf16_f32 v60, v62, v63
	v_cvt_pk_bf16_f32 v61, v64, v65
	global_store_dwordx4 v[70:71], v[58:61], off
	global_load_dwordx4 v[58:61], v[160:161], off offset:512
	s_nop 0
	global_load_dwordx4 v[62:65], v[162:163], off offset:512
	s_waitcnt vmcnt(0)
	v_pk_fma_f32 v[54:55], v[54:55], v[58:59], v[62:63]
	v_pk_fma_f32 v[56:57], v[56:57], v[60:61], v[64:65]
	v_pk_fma_f32 v[22:23], v[54:55], s[30:31], v[22:23] op_sel_hi:[1,0,1]
	v_pk_fma_f32 v[24:25], v[56:57], s[30:31], v[24:25] op_sel_hi:[1,0,1]
	global_store_dwordx4 v[84:85], v[22:25], off offset:512
	global_load_dwordx4 v[54:57], v[160:161], off offset:528
	global_load_dwordx4 v[58:61], v[162:163], off offset:528
	s_waitcnt vmcnt(0)
	v_pk_fma_f32 v[50:51], v[50:51], v[54:55], v[58:59]
	v_pk_fma_f32 v[52:53], v[52:53], v[56:57], v[60:61]
	v_pk_fma_f32 v[50:51], v[50:51], s[30:31], v[18:19] op_sel_hi:[1,0,1]
	v_pk_fma_f32 v[52:53], v[52:53], s[30:31], v[20:21] op_sel_hi:[1,0,1]
	global_store_dwordx4 v[84:85], v[50:53], off offset:528
	global_load_dwordx4 v[54:57], v[164:165], off offset:512
	global_load_dwordx4 v[58:61], v[164:165], off offset:528
	v_mul_f32_e32 v20, v31, v31
	v_mul_f32_e32 v21, v32, v32
	v_add_f32_e32 v18, v30, v31
	v_add_f32_e32 v19, v33, v32
	v_fmac_f32_e32 v20, v30, v30
	v_fmac_f32_e32 v21, v33, v33
	v_add_f32_e32 v18, v18, v19
	v_add_f32_e32 v19, v20, v21
	v_add_f32_e32 v20, v26, v27
	v_add_f32_e32 v21, v29, v28
	v_mul_f32_e32 v27, v27, v27
	v_mul_f32_e32 v28, v28, v28
	v_add_f32_e32 v18, 0, v18
	v_add_f32_e32 v20, v20, v21
	v_fmac_f32_e32 v27, v26, v26
	v_fmac_f32_e32 v28, v29, v29
	v_add_f32_e32 v18, v18, v20
	v_add_f32_e32 v20, v27, v28
	v_add_f32_e32 v19, v19, v20
	v_add_f32_e32 v20, v22, v23
	v_add_f32_e32 v21, v25, v24
	v_mul_f32_e32 v26, v23, v23
	v_mul_f32_e32 v27, v24, v24
	v_add_f32_e32 v20, v20, v21
	v_fmac_f32_e32 v26, v22, v22
	v_fmac_f32_e32 v27, v25, v25
	v_add_f32_e32 v18, v18, v20
	v_add_f32_e32 v20, v26, v27
	v_add_f32_e32 v19, v19, v20
	v_add_f32_e32 v20, v50, v51
	v_add_f32_e32 v21, v53, v52
	v_mul_f32_e32 v26, v51, v51
	v_mul_f32_e32 v27, v52, v52
	v_add_f32_e32 v20, v20, v21
	v_fmac_f32_e32 v26, v50, v50
	v_fmac_f32_e32 v27, v53, v53
	v_add_f32_e32 v18, v18, v20
	v_add_f32_e32 v20, v26, v27
	v_add_f32_e32 v20, v19, v20
	ds_bpermute_b32 v21, v183, v18
	ds_bpermute_b32 v26, v183, v20
	s_waitcnt lgkmcnt(0)
	v_add_f32_e32 v18, v18, v21
	v_add_f32_e32 v20, v20, v26
	ds_bpermute_b32 v19, v182, v18
	ds_bpermute_b32 v21, v182, v20
	s_waitcnt vmcnt(0)
	v_pk_mul_f32 v[24:25], v[24:25], v[56:57]
	v_pk_mul_f32 v[22:23], v[22:23], v[54:55]
	v_pk_mul_f32 v[26:27], v[60:61], v[52:53]
	v_pk_mul_f32 v[28:29], v[58:59], v[50:51]
	v_cvt_pk_bf16_f32 v22, v22, v23
	v_cvt_pk_bf16_f32 v23, v24, v25
	v_cvt_pk_bf16_f32 v24, v28, v29
	v_cvt_pk_bf16_f32 v25, v26, v27
	global_store_dwordx4 v[70:71], v[22:25], off offset:256
	s_and_saveexec_b64 s[14:15], s[40:41]
	s_cbranch_execz .LBB0_82
	s_waitcnt lgkmcnt(0)
	v_add_f32_e32 v20, v20, v21
	v_add_f32_e32 v21, v18, v19
	v_lshl_add_u64 v[18:19], v[82:83], 3, s[58:59]
	global_atomic_add_f32 v[18:19], v21, off
	global_atomic_add_f32 v[18:19], v20, off offset:4
; DI u32x4 pack8(f32x4 a, f32x4 b) { u32x4 w; w.x = pk2(a[0], a[1]); w.y = pk2(a[2], a[3]); w.z = pk2(b[0], b[1]); w.w = pk2(b[2], b[3]); return w; }
;     DI void operator()(AccRef acc, const Unit& u, int wr, int wc, int fr, int fq) const {
;     ...
;             int row = row0 + ai * 128 + m * 16; asm volatile("" : "+v"(row)); const size_t off = (size_t)row * DM + c0; float s1 = 0.f, s2 = 0.f;
;             const float mean = sb[cur].x * (1.f / DM); const float rstd = __builtin_amdgcn_rsqf(fmaxf(sb[cur].y * (1.f / DM) - mean * mean, 0.f) + LN_EPS);
; #pragma unroll
;             for (int bj = 0; bj < 2; ++bj) { f32x4 y[2];
; #pragma unroll
;                 for (int n = 0; n < 2; ++n) { const int cc = c0 + bj * 128 + 4 * n; const f32x4 gv = *(const f32x4*)(G + cc), bv = *(const f32x4*)(Bv + cc);
;                     const f32x4 x1 = (yb[cur][bj][n] - mean) * rstd * gv + bv;
;                     y[n] = x1 * ALPHA + acc[ai][bj][m][n]; *(f32x4*)(Y + off + bj * 128 + 4 * n) = y[n];
;                     s1 += (y[n][0] + y[n][1]) + (y[n][2] + y[n][3]); s2 += (y[n][0] * y[n][0] + y[n][1] * y[n][1]) + (y[n][2] * y[n][2] + y[n][3] * y[n][3]); }
;                 const f32x4 g0 = *(const f32x4*)(G2 + c0 + bj * 128), g1 = *(const f32x4*)(G2 + c0 + bj * 128 + 4);
;                 *(u32x4*)(YG + off + bj * 128) = pack8(y[0] * g0, y[1] * g1); }
;             s1 += __shfl_xor(s1, 16); s1 += __shfl_xor(s1, 32); s2 += __shfl_xor(s2, 16); s2 += __shfl_xor(s2, 32);
;             if (fq == 0) { unsafeAtomicAdd(ST2 + (size_t)row * 2, s1); unsafeAtomicAdd(ST2 + (size_t)row * 2 + 1, s2); } }
.LBB0_82:
	s_or_b64 exec, exec, s[14:15]
	global_load_dwordx4 v[26:29], v[160:161], off
	global_load_dwordx4 v[30:33], v[162:163], off
	v_pk_mul_f32 v[24:25], v[68:69], s[36:37] op_sel_hi:[1,0]
	v_ashrrev_i32_e32 v67, 31, v66
	v_fma_f32 v20, -v24, v24, v25
	v_max_f32_e32 v20, 0, v20
	v_add_f32_e32 v20, 0x3727c5ac, v20
	v_rsq_f32_e32 v22, v20
	v_sub_f32_e32 v47, v47, v24
	v_sub_f32_e32 v46, v46, v24
	v_sub_f32_e32 v49, v49, v24
	v_sub_f32_e32 v48, v48, v24
	v_pk_mul_f32 v[48:49], v[48:49], v[22:23] op_sel_hi:[1,0]
	v_pk_mul_f32 v[46:47], v[46:47], v[22:23] op_sel_hi:[1,0]
	s_waitcnt lgkmcnt(0)
	v_lshlrev_b64 v[20:21], 12, v[66:67]
	v_lshl_add_u64 v[20:21], v[168:169], 0, v[20:21]
	v_sub_f32_e32 v43, v43, v24
	v_sub_f32_e32 v42, v42, v24
	v_sub_f32_e32 v45, v45, v24
	v_sub_f32_e32 v44, v44, v24
	v_lshlrev_b64 v[18:19], 10, v[66:67]
	v_lshl_add_u64 v[18:19], v[18:19], 0, v[166:167]
	v_lshl_add_u64 v[18:19], v[18:19], 1, s[60:61]
	s_waitcnt vmcnt(0)
	v_pk_fma_f32 v[26:27], v[46:47], v[26:27], v[30:31]
	v_pk_fma_f32 v[28:29], v[48:49], v[28:29], v[32:33]
	v_pk_fma_f32 v[14:15], v[26:27], s[30:31], v[14:15] op_sel_hi:[1,0,1]
	v_pk_fma_f32 v[16:17], v[28:29], s[30:31], v[16:17] op_sel_hi:[1,0,1]
	v_add_f32_e32 v23, v14, v15
	v_add_f32_e32 v25, v17, v16
	v_add_f32_e32 v23, v23, v25
	v_mul_f32_e32 v25, v15, v15
	v_mul_f32_e32 v26, v16, v16
	global_store_dwordx4 v[20:21], v[14:17], off
	v_fmac_f32_e32 v25, v14, v14
	v_fmac_f32_e32 v26, v17, v17
	v_add_f32_e32 v25, v25, v26
	global_load_dwordx4 v[26:29], v[160:161], off offset:16
	global_load_dwordx4 v[30:33], v[162:163], off offset:16
	v_add_f32_e32 v23, 0, v23
	v_pk_mul_f32 v[44:45], v[44:45], v[22:23] op_sel_hi:[1,0]
	v_pk_mul_f32 v[42:43], v[42:43], v[22:23] op_sel_hi:[1,0]
	s_waitcnt vmcnt(0)
	v_pk_fma_f32 v[28:29], v[44:45], v[28:29], v[32:33]
	v_pk_fma_f32 v[26:27], v[42:43], v[26:27], v[30:31]
	v_pk_fma_f32 v[12:13], v[28:29], s[30:31], v[12:13] op_sel_hi:[1,0,1]
	v_pk_fma_f32 v[10:11], v[26:27], s[30:31], v[10:11] op_sel_hi:[1,0,1]
	v_add_f32_e32 v27, v13, v12
	v_add_f32_e32 v26, v10, v11
	v_add_f32_e32 v26, v26, v27
	v_add_f32_e32 v23, v23, v26
	v_mul_f32_e32 v26, v11, v11
	v_mul_f32_e32 v27, v12, v12
	v_fmac_f32_e32 v26, v10, v10
	v_fmac_f32_e32 v27, v13, v13
	global_store_dwordx4 v[20:21], v[10:13], off offset:16
	v_add_f32_e32 v26, v26, v27
	v_add_f32_e32 v25, v25, v26
	global_load_dwordx4 v[26:29], v[164:165], off offset:16
	global_load_dwordx4 v[30:33], v[164:165], off
	s_waitcnt vmcnt(0)
	v_pk_mul_f32 v[28:29], v[28:29], v[12:13]
	v_pk_mul_f32 v[16:17], v[16:17], v[32:33]
	v_pk_mul_f32 v[14:15], v[14:15], v[30:31]
	v_pk_mul_f32 v[12:13], v[26:27], v[10:11]
	v_cvt_pk_bf16_f32 v10, v14, v15
	v_cvt_pk_bf16_f32 v11, v16, v17
	v_cvt_pk_bf16_f32 v12, v12, v13
	v_cvt_pk_bf16_f32 v13, v28, v29
	global_store_dwordx4 v[18:19], v[10:13], off
	global_load_dwordx4 v[10:13], v[160:161], off offset:512
	s_nop 0
	global_load_dwordx4 v[14:17], v[162:163], off offset:512
	v_sub_f32_e32 v27, v39, v24
	v_sub_f32_e32 v26, v38, v24
	v_sub_f32_e32 v29, v41, v24
	v_sub_f32_e32 v28, v40, v24
	v_pk_mul_f32 v[28:29], v[28:29], v[22:23] op_sel_hi:[1,0]
	v_pk_mul_f32 v[26:27], v[26:27], v[22:23] op_sel_hi:[1,0]
	s_waitcnt vmcnt(0)
	v_pk_fma_f32 v[12:13], v[28:29], v[12:13], v[16:17]
	v_pk_fma_f32 v[10:11], v[26:27], v[10:11], v[14:15]
	v_pk_fma_f32 v[8:9], v[12:13], s[30:31], v[8:9] op_sel_hi:[1,0,1]
	v_pk_fma_f32 v[6:7], v[10:11], s[30:31], v[6:7] op_sel_hi:[1,0,1]
	v_add_f32_e32 v11, v9, v8
	v_add_f32_e32 v10, v6, v7
	v_add_f32_e32 v10, v10, v11
	v_add_f32_e32 v28, v23, v10
	v_mul_f32_e32 v10, v7, v7
	v_mul_f32_e32 v11, v8, v8
	v_fmac_f32_e32 v10, v6, v6
	v_fmac_f32_e32 v11, v9, v9
	global_store_dwordx4 v[20:21], v[6:9], off offset:512
	v_add_f32_e32 v10, v10, v11
	v_add_f32_e32 v29, v25, v10
	global_load_dwordx4 v[10:13], v[160:161], off offset:528
	global_load_dwordx4 v[14:17], v[162:163], off offset:528
	v_sub_f32_e32 v27, v35, v24
	v_sub_f32_e32 v26, v34, v24
	v_sub_f32_e32 v25, v37, v24
	v_sub_f32_e32 v24, v36, v24
	v_pk_mul_f32 v[24:25], v[24:25], v[22:23] op_sel_hi:[1,0]
	v_pk_mul_f32 v[22:23], v[26:27], v[22:23] op_sel_hi:[1,0]
	s_waitcnt vmcnt(0)
	v_pk_fma_f32 v[12:13], v[24:25], v[12:13], v[16:17]
	v_pk_fma_f32 v[10:11], v[22:23], v[10:11], v[14:15]
	v_pk_fma_f32 v[4:5], v[12:13], s[30:31], v[4:5] op_sel_hi:[1,0,1]
	v_pk_fma_f32 v[2:3], v[10:11], s[30:31], v[2:3] op_sel_hi:[1,0,1]
	v_add_f32_e32 v11, v5, v4
	v_add_f32_e32 v10, v2, v3
	v_add_f32_e32 v10, v10, v11
	global_store_dwordx4 v[20:21], v[2:5], off offset:528
	v_add_f32_e32 v20, v28, v10
	v_mul_f32_e32 v10, v3, v3
	v_mul_f32_e32 v11, v4, v4
	v_fmac_f32_e32 v10, v2, v2
	v_fmac_f32_e32 v11, v5, v5
	v_add_f32_e32 v10, v10, v11
	v_add_f32_e32 v21, v29, v10
	global_load_dwordx4 v[10:13], v[164:165], off offset:528
	global_load_dwordx4 v[14:17], v[164:165], off offset:512
	s_waitcnt vmcnt(0)
	v_pk_mul_f32 v[12:13], v[12:13], v[4:5]
	v_pk_mul_f32 v[8:9], v[8:9], v[16:17]
	v_pk_mul_f32 v[6:7], v[6:7], v[14:15]
	v_pk_mul_f32 v[4:5], v[10:11], v[2:3]
	v_cvt_pk_bf16_f32 v2, v6, v7
	v_cvt_pk_bf16_f32 v3, v8, v9
	v_cvt_pk_bf16_f32 v4, v4, v5
	v_cvt_pk_bf16_f32 v5, v12, v13
	global_store_dwordx4 v[18:19], v[2:5], off offset:256
	ds_bpermute_b32 v2, v183, v20
	ds_bpermute_b32 v4, v183, v21
	s_waitcnt lgkmcnt(0)
	v_add_f32_e32 v2, v20, v2
	v_add_f32_e32 v4, v21, v4
	ds_bpermute_b32 v3, v182, v2
	ds_bpermute_b32 v5, v182, v4
	s_and_saveexec_b64 s[14:15], s[40:41]
	s_cbranch_execz .LBB0_84
	s_waitcnt lgkmcnt(0)
	v_add_f32_e32 v4, v4, v5
	v_add_f32_e32 v5, v2, v3
	v_lshl_add_u64 v[2:3], v[66:67], 3, s[58:59]
	global_atomic_add_f32 v[2:3], v5, off
	global_atomic_add_f32 v[2:3], v4, off offset:4

; DI u32x4 pack8(f32x4 a, f32x4 b) { u32x4 w; w.x = pk2(a[0], a[1]); w.y = pk2(a[2], a[3]); w.z = pk2(b[0], b[1]); w.w = pk2(b[2], b[3]); return w; }
; DI float siluf_(float x) { return x * __builtin_amdgcn_rcpf(1.f + __expf(-x)); }
;     DI void operator()(AccRef acc, const Unit& u, int wr, int wc, int fr, int fq) const {
;         unsigned char* w_ = ws; asm volatile("" : "+s"(w_)); bf16_t* HID = (bf16_t*)(w_ + WS_HID); const float* ST = (const float*)(w_ + WS_ST1);
;         const int row0 = u.pm * 256 + wr * 64 + fr, c0 = u.pn * 128 + wc * 32 + 8 * fq, wrow = u.pn * 256 + wc * 32 + 8 * fq;
;         f32x4 gwv[2][2], bwv[2][2];
; #pragma unroll
;         for (int bj = 0; bj < 2; ++bj)
; #pragma unroll
;             for (int n = 0; n < 2; ++n) { gwv[bj][n] = *(const f32x4*)(GW + wrow + bj * 128 + 4 * n); bwv[bj][n] = *(const f32x4*)(GW + 5632 + wrow + bj * 128 + 4 * n); }
;         f32x2 sta[8];
; #pragma unroll
;         for (int it = 0; it < 8; ++it) sta[it] = *(const f32x2*)(ST + (size_t)(row0 + (it >> 2) * 128 + (it & 3) * 16) * 2);
; #pragma unroll
;         for (int ai = 0; ai < 2; ++ai)
; #pragma unroll
;             for (int m = 0; m < 4; ++m) { int row_ = row0 + ai * 128 + m * 16; asm volatile("" : "+v"(row_) :: "memory");
;                 const float mean_ = sta[ai * 4 + m].x * (1.f / DM); const f32x2 st = {mean_, __builtin_amdgcn_rsqf(fmaxf(sta[ai * 4 + m].y * (1.f / DM) - mean_ * mean_, 0.f) + LN_EPS)}; f32x4 o[2];
; #pragma unroll
;                 for (int n = 0; n < 2; ++n) { const f32x4 gt = (acc[ai][0][m][n] - gwv[0][n] * st.x) * st.y + bwv[0][n], up = (acc[ai][1][m][n] - gwv[1][n] * st.x) * st.y + bwv[1][n];
; #pragma unroll
;                     for (int i = 0; i < 4; ++i) o[n][i] = siluf_(gt[i]) * up[i]; }
;                 *(u32x4*)(HID + (size_t)row_ * DFF + c0) = pack8(o[0], o[1]); }
.LBB0_107:
	s_mov_b64 s[14:15], s[0:1]
	v_lshl_or_b32 v74, s87, 8, v228
	v_lshl_add_u32 v218, s88, 8, v225
	v_ashrrev_i32_e32 v75, 31, v74
	s_add_u32 s54, s14, 0x3540000
	v_lshlrev_b64 v[74:75], 2, v[74:75]
	s_addc_u32 s55, s15, 0
	v_ashrrev_i32_e32 v219, 31, v218
	v_lshl_add_u64 v[78:79], s[10:11], 0, v[74:75]
	v_lshl_add_u64 v[102:103], s[50:51], 0, v[74:75]
	v_lshl_add_u64 v[176:177], v[218:219], 3, s[54:55]
	global_load_dwordx4 v[82:85], v[78:79], off offset:16
	global_load_dwordx4 v[106:109], v[78:79], off
	global_load_dwordx4 v[86:89], v[102:103], off offset:16
	global_load_dwordx4 v[110:113], v[102:103], off
	global_load_dwordx4 v[74:77], v[78:79], off offset:528
	global_load_dwordx4 v[98:101], v[78:79], off offset:512
	s_nop 0
	global_load_dwordx4 v[78:81], v[102:103], off offset:528
	s_nop 0
	global_load_dwordx4 v[102:105], v[102:103], off offset:512
	v_or_b32_e32 v216, 16, v218
	global_load_dwordx2 v[222:223], v[176:177], off
	v_ashrrev_i32_e32 v217, 31, v216
	v_lshl_add_u64 v[176:177], v[216:217], 3, s[54:55]
	global_load_dwordx2 v[220:221], v[176:177], off
	v_or_b32_e32 v212, 32, v218
	v_ashrrev_i32_e32 v213, 31, v212
	v_or_b32_e32 v208, 48, v218
	v_lshl_add_u64 v[176:177], v[212:213], 3, s[54:55]
	v_ashrrev_i32_e32 v209, 31, v208
	v_add_u32_e32 v190, 0x80, v218
	global_load_dwordx2 v[214:215], v[176:177], off
	v_lshl_add_u64 v[176:177], v[208:209], 3, s[54:55]
	v_ashrrev_i32_e32 v191, 31, v190
	v_add_u32_e32 v186, 0x90, v218
	global_load_dwordx2 v[210:211], v[176:177], off
	v_lshl_add_u64 v[176:177], v[190:191], 3, s[54:55]
	v_ashrrev_i32_e32 v187, 31, v186
	v_add_u32_e32 v182, 0xa0, v218
	global_load_dwordx2 v[192:193], v[176:177], off
	v_lshl_add_u64 v[176:177], v[186:187], 3, s[54:55]
	v_ashrrev_i32_e32 v183, 31, v182
	global_load_dwordx2 v[188:189], v[176:177], off
	v_lshl_add_u64 v[176:177], v[182:183], 3, s[54:55]
	global_load_dwordx2 v[184:185], v[176:177], off
	v_add_u32_e32 v176, 0xb0, v218
	v_ashrrev_i32_e32 v177, 31, v176
	v_lshl_add_u64 v[178:179], v[176:177], 3, s[54:55]
	global_load_dwordx2 v[180:181], v[178:179], off
	v_lshl_or_b32 v178, s87, 7, v228
	v_ashrrev_i32_e32 v179, 31, v178
	v_lshl_add_u64 v[178:179], v[178:179], 1, s[14:15]
	v_lshl_add_u64 v[178:179], v[178:179], 0, s[72:73]
	s_movk_i32 s54, 0x1600
	s_and_b64 vcc, exec, s[40:41]
	s_waitcnt vmcnt(0) lgkmcnt(0)
	v_pk_mul_f32 v[222:223], v[222:223], s[36:37] op_sel_hi:[1,0]
	s_nop 0
	v_fma_f32 v177, -v222, v222, v223
	v_max_f32_e32 v177, 0, v177
	v_add_f32_e32 v177, 0x3727c5ac, v177
	v_rsq_f32_e32 v224, v177
	v_pk_fma_f32 v[162:163], v[106:107], v[222:223], v[162:163] op_sel_hi:[1,0,1] neg_lo:[1,0,0] neg_hi:[1,0,0]
	v_pk_fma_f32 v[158:159], v[98:99], v[222:223], v[158:159] op_sel_hi:[1,0,1] neg_lo:[1,0,0] neg_hi:[1,0,0]
	v_pk_fma_f32 v[160:161], v[100:101], v[222:223], v[160:161] op_sel_hi:[1,0,1] neg_lo:[1,0,0] neg_hi:[1,0,0]
	v_pk_fma_f32 v[162:163], v[162:163], v[224:225], v[110:111] op_sel_hi:[1,0,1]
	v_pk_fma_f32 v[158:159], v[158:159], v[224:225], v[102:103] op_sel_hi:[1,0,1]
	v_mul_f32_e32 v177, 0xbfb8aa3b, v162
	v_exp_f32_e32 v177, v177
	v_pk_fma_f32 v[154:155], v[82:83], v[222:223], v[154:155] op_sel_hi:[1,0,1] neg_lo:[1,0,0] neg_hi:[1,0,0]
	v_pk_fma_f32 v[160:161], v[160:161], v[224:225], v[104:105] op_sel_hi:[1,0,1]
	v_pk_fma_f32 v[154:155], v[154:155], v[224:225], v[86:87] op_sel_hi:[1,0,1]
	v_add_f32_e32 v177, 1.0, v177
	v_rcp_f32_e32 v198, v177
	v_mul_f32_e32 v177, 0xbfb8aa3b, v163
	v_exp_f32_e32 v177, v177
	v_pk_fma_f32 v[150:151], v[74:75], v[222:223], v[150:151] op_sel_hi:[1,0,1] neg_lo:[1,0,0] neg_hi:[1,0,0]
	v_pk_fma_f32 v[152:153], v[76:77], v[222:223], v[152:153] op_sel_hi:[1,0,1] neg_lo:[1,0,0] neg_hi:[1,0,0]
	v_pk_fma_f32 v[150:151], v[150:151], v[224:225], v[78:79] op_sel_hi:[1,0,1]
	v_add_f32_e32 v177, 1.0, v177
	v_rcp_f32_e32 v199, v177
	v_pk_fma_f32 v[152:153], v[152:153], v[224:225], v[80:81] op_sel_hi:[1,0,1]
	v_pk_mul_f32 v[162:163], v[162:163], v[198:199]
	s_nop 0
	v_pk_mul_f32 v[158:159], v[158:159], v[162:163]
	v_pk_fma_f32 v[162:163], v[108:109], v[222:223], v[164:165] op_sel_hi:[1,0,1] neg_lo:[1,0,0] neg_hi:[1,0,0]
	s_nop 0
	v_pk_fma_f32 v[162:163], v[162:163], v[224:225], v[112:113] op_sel_hi:[1,0,1]
	s_nop 0
	v_mul_f32_e32 v164, 0xbfb8aa3b, v162
	v_mul_f32_e32 v165, 0xbfb8aa3b, v163
	v_exp_f32_e32 v164, v164
	v_exp_f32_e32 v165, v165
	v_add_f32_e32 v164, 1.0, v164
	v_add_f32_e32 v165, 1.0, v165
	v_rcp_f32_e32 v164, v164
	v_rcp_f32_e32 v165, v165
	s_nop 0
	v_pk_mul_f32 v[162:163], v[162:163], v[164:165]
	s_nop 0
	v_pk_mul_f32 v[160:161], v[160:161], v[162:163]
	v_mul_f32_e32 v162, 0xbfb8aa3b, v154
	v_mul_f32_e32 v163, 0xbfb8aa3b, v155
	v_exp_f32_e32 v162, v162
	v_exp_f32_e32 v163, v163
	v_add_f32_e32 v162, 1.0, v162
	v_add_f32_e32 v163, 1.0, v163
	v_rcp_f32_e32 v162, v162
	v_rcp_f32_e32 v163, v163
	s_nop 0
	v_pk_mul_f32 v[154:155], v[154:155], v[162:163]
	s_nop 0
	v_pk_mul_f32 v[150:151], v[150:151], v[154:155]
	v_pk_fma_f32 v[154:155], v[84:85], v[222:223], v[156:157] op_sel_hi:[1,0,1] neg_lo:[1,0,0] neg_hi:[1,0,0]
	s_nop 0
	v_pk_fma_f32 v[154:155], v[154:155], v[224:225], v[88:89] op_sel_hi:[1,0,1]
	s_nop 0
	v_mul_f32_e32 v156, 0xbfb8aa3b, v154
	v_mul_f32_e32 v157, 0xbfb8aa3b, v155
	v_exp_f32_e32 v156, v156
	v_exp_f32_e32 v157, v157
	v_add_f32_e32 v156, 1.0, v156
	v_add_f32_e32 v157, 1.0, v157
	v_rcp_f32_e32 v156, v156
	v_rcp_f32_e32 v157, v157
	s_nop 0
	v_pk_mul_f32 v[154:155], v[154:155], v[156:157]
	s_nop 0
	v_pk_mul_f32 v[156:157], v[152:153], v[154:155]
	v_cvt_pk_bf16_f32 v152, v158, v159
	v_cvt_pk_bf16_f32 v153, v160, v161
	v_cvt_pk_bf16_f32 v154, v150, v151
	v_cvt_pk_bf16_f32 v155, v156, v157
; DI u32x4 pack8(f32x4 a, f32x4 b) { u32x4 w; w.x = pk2(a[0], a[1]); w.y = pk2(a[2], a[3]); w.z = pk2(b[0], b[1]); w.w = pk2(b[2], b[3]); return w; }
; DI float siluf_(float x) { return x * __builtin_amdgcn_rcpf(1.f + __expf(-x)); }
;     DI void operator()(AccRef acc, const Unit& u, int wr, int wc, int fr, int fq) const {
;     ...
;             for (int m = 0; m < 4; ++m) { int row_ = row0 + ai * 128 + m * 16; asm volatile("" : "+v"(row_) :: "memory");
;                 const float mean_ = sta[ai * 4 + m].x * (1.f / DM); const f32x2 st = {mean_, __builtin_amdgcn_rsqf(fmaxf(sta[ai * 4 + m].y * (1.f / DM) - mean_ * mean_, 0.f) + LN_EPS)}; f32x4 o[2];
; #pragma unroll
;                 for (int n = 0; n < 2; ++n) { const f32x4 gt = (acc[ai][0][m][n] - gwv[0][n] * st.x) * st.y + bwv[0][n], up = (acc[ai][1][m][n] - gwv[1][n] * st.x) * st.y + bwv[1][n];
; #pragma unroll
;                     for (int i = 0; i < 4; ++i) o[n][i] = siluf_(gt[i]) * up[i]; }
;                 *(u32x4*)(HID + (size_t)row_ * DFF + c0) = pack8(o[0], o[1]); }
	v_mad_i64_i32 v[150:151], s[14:15], v218, s54, v[178:179]
	global_store_dwordx4 v[150:151], v[152:155], off
	v_pk_mul_f32 v[150:151], v[220:221], s[36:37] op_sel_hi:[1,0]
	s_nop 0
	v_fma_f32 v152, -v150, v150, v151
	v_max_f32_e32 v152, 0, v152
	v_add_f32_e32 v152, 0x3727c5ac, v152
	v_rsq_f32_e32 v152, v152
	v_pk_fma_f32 v[146:147], v[106:107], v[150:151], v[146:147] op_sel_hi:[1,0,1] neg_lo:[1,0,0] neg_hi:[1,0,0]
	v_pk_fma_f32 v[142:143], v[98:99], v[150:151], v[142:143] op_sel_hi:[1,0,1] neg_lo:[1,0,0] neg_hi:[1,0,0]
	v_pk_fma_f32 v[144:145], v[100:101], v[150:151], v[144:145] op_sel_hi:[1,0,1] neg_lo:[1,0,0] neg_hi:[1,0,0]
	v_pk_fma_f32 v[146:147], v[146:147], v[152:153], v[110:111] op_sel_hi:[1,0,1]
	v_pk_fma_f32 v[138:139], v[82:83], v[150:151], v[138:139] op_sel_hi:[1,0,1] neg_lo:[1,0,0] neg_hi:[1,0,0]
	v_mul_f32_e32 v153, 0xbfb8aa3b, v146
	v_exp_f32_e32 v153, v153
	v_pk_fma_f32 v[134:135], v[74:75], v[150:151], v[134:135] op_sel_hi:[1,0,1] neg_lo:[1,0,0] neg_hi:[1,0,0]
	v_pk_fma_f32 v[136:137], v[76:77], v[150:151], v[136:137] op_sel_hi:[1,0,1] neg_lo:[1,0,0] neg_hi:[1,0,0]
	v_add_f32_e32 v153, 1.0, v153
	v_rcp_f32_e32 v154, v153
	v_mul_f32_e32 v153, 0xbfb8aa3b, v147
	v_exp_f32_e32 v153, v153
	s_nop 0
	v_add_f32_e32 v153, 1.0, v153
	v_rcp_f32_e32 v155, v153
	v_pk_fma_f32 v[142:143], v[142:143], v[152:153], v[102:103] op_sel_hi:[1,0,1]
	v_pk_fma_f32 v[144:145], v[144:145], v[152:153], v[104:105] op_sel_hi:[1,0,1]
	v_pk_fma_f32 v[138:139], v[138:139], v[152:153], v[86:87] op_sel_hi:[1,0,1]
	v_pk_mul_f32 v[146:147], v[146:147], v[154:155]
	v_pk_fma_f32 v[134:135], v[134:135], v[152:153], v[78:79] op_sel_hi:[1,0,1]
	v_pk_mul_f32 v[142:143], v[142:143], v[146:147]
	v_pk_fma_f32 v[146:147], v[108:109], v[150:151], v[148:149] op_sel_hi:[1,0,1] neg_lo:[1,0,0] neg_hi:[1,0,0]
	v_pk_fma_f32 v[136:137], v[136:137], v[152:153], v[80:81] op_sel_hi:[1,0,1]
	v_pk_fma_f32 v[146:147], v[146:147], v[152:153], v[112:113] op_sel_hi:[1,0,1]
	s_nop 0
	v_mul_f32_e32 v148, 0xbfb8aa3b, v146
	v_mul_f32_e32 v149, 0xbfb8aa3b, v147
	v_exp_f32_e32 v148, v148
	v_exp_f32_e32 v149, v149
	v_add_f32_e32 v148, 1.0, v148
	v_add_f32_e32 v149, 1.0, v149
	v_rcp_f32_e32 v148, v148
	v_rcp_f32_e32 v149, v149
	s_nop 0
	v_pk_mul_f32 v[146:147], v[146:147], v[148:149]
	s_nop 0
	v_pk_mul_f32 v[144:145], v[144:145], v[146:147]
	v_mul_f32_e32 v146, 0xbfb8aa3b, v138
	v_mul_f32_e32 v147, 0xbfb8aa3b, v139
	v_exp_f32_e32 v146, v146
	v_exp_f32_e32 v147, v147
	v_add_f32_e32 v146, 1.0, v146
	v_add_f32_e32 v147, 1.0, v147
	v_rcp_f32_e32 v146, v146
	v_rcp_f32_e32 v147, v147
	s_nop 0
	v_pk_mul_f32 v[138:139], v[138:139], v[146:147]
	s_nop 0
	v_pk_mul_f32 v[138:139], v[134:135], v[138:139]
	v_pk_fma_f32 v[134:135], v[84:85], v[150:151], v[140:141] op_sel_hi:[1,0,1] neg_lo:[1,0,0] neg_hi:[1,0,0]
	s_nop 0
	v_pk_fma_f32 v[134:135], v[134:135], v[152:153], v[88:89] op_sel_hi:[1,0,1]
	s_nop 0
	v_mul_f32_e32 v140, 0xbfb8aa3b, v134
	v_mul_f32_e32 v141, 0xbfb8aa3b, v135
	v_exp_f32_e32 v140, v140
	v_exp_f32_e32 v141, v141
	v_add_f32_e32 v140, 1.0, v140
	v_add_f32_e32 v141, 1.0, v141
	v_rcp_f32_e32 v140, v140
	v_rcp_f32_e32 v141, v141
	s_nop 0
	v_pk_mul_f32 v[134:135], v[134:135], v[140:141]
	s_nop 0
	v_pk_mul_f32 v[140:141], v[136:137], v[134:135]
	v_cvt_pk_bf16_f32 v134, v142, v143
	v_cvt_pk_bf16_f32 v135, v144, v145
	v_cvt_pk_bf16_f32 v136, v138, v139
	v_cvt_pk_bf16_f32 v137, v140, v141
	v_mad_i64_i32 v[138:139], s[14:15], v216, s54, v[178:179]
	global_store_dwordx4 v[138:139], v[134:137], off
	s_nop 1
	v_pk_mul_f32 v[134:135], v[214:215], s[36:37] op_sel_hi:[1,0]
	s_nop 0
	v_fma_f32 v136, -v134, v134, v135
	v_max_f32_e32 v136, 0, v136
	v_add_f32_e32 v136, 0x3727c5ac, v136
	v_rsq_f32_e32 v136, v136
	v_pk_fma_f32 v[126:127], v[106:107], v[134:135], v[126:127] op_sel_hi:[1,0,1] neg_lo:[1,0,0] neg_hi:[1,0,0]
	v_pk_fma_f32 v[122:123], v[98:99], v[134:135], v[122:123] op_sel_hi:[1,0,1] neg_lo:[1,0,0] neg_hi:[1,0,0]
	v_pk_fma_f32 v[124:125], v[100:101], v[134:135], v[124:125] op_sel_hi:[1,0,1] neg_lo:[1,0,0] neg_hi:[1,0,0]
	v_pk_fma_f32 v[126:127], v[126:127], v[136:137], v[110:111] op_sel_hi:[1,0,1]
	v_pk_fma_f32 v[118:119], v[82:83], v[134:135], v[118:119] op_sel_hi:[1,0,1] neg_lo:[1,0,0] neg_hi:[1,0,0]
	v_mul_f32_e32 v137, 0xbfb8aa3b, v126
	v_exp_f32_e32 v137, v137
	v_pk_fma_f32 v[114:115], v[74:75], v[134:135], v[114:115] op_sel_hi:[1,0,1] neg_lo:[1,0,0] neg_hi:[1,0,0]
	v_pk_fma_f32 v[116:117], v[76:77], v[134:135], v[116:117] op_sel_hi:[1,0,1] neg_lo:[1,0,0] neg_hi:[1,0,0]
	v_add_f32_e32 v137, 1.0, v137
	v_rcp_f32_e32 v138, v137
	v_mul_f32_e32 v137, 0xbfb8aa3b, v127
	v_exp_f32_e32 v137, v137
	s_nop 0
	v_add_f32_e32 v137, 1.0, v137
	v_rcp_f32_e32 v139, v137
	v_pk_fma_f32 v[122:123], v[122:123], v[136:137], v[102:103] op_sel_hi:[1,0,1]
	v_pk_fma_f32 v[124:125], v[124:125], v[136:137], v[104:105] op_sel_hi:[1,0,1]
	v_pk_fma_f32 v[118:119], v[118:119], v[136:137], v[86:87] op_sel_hi:[1,0,1]
	v_pk_mul_f32 v[126:127], v[126:127], v[138:139]
	v_pk_fma_f32 v[114:115], v[114:115], v[136:137], v[78:79] op_sel_hi:[1,0,1]
	v_pk_mul_f32 v[122:123], v[122:123], v[126:127]
	v_pk_fma_f32 v[126:127], v[108:109], v[134:135], v[128:129] op_sel_hi:[1,0,1] neg_lo:[1,0,0] neg_hi:[1,0,0]
	v_pk_fma_f32 v[116:117], v[116:117], v[136:137], v[80:81] op_sel_hi:[1,0,1]
	v_pk_fma_f32 v[126:127], v[126:127], v[136:137], v[112:113] op_sel_hi:[1,0,1]
	s_nop 0
	v_mul_f32_e32 v128, 0xbfb8aa3b, v126
	v_mul_f32_e32 v129, 0xbfb8aa3b, v127
	v_exp_f32_e32 v128, v128
	v_exp_f32_e32 v129, v129
	v_add_f32_e32 v128, 1.0, v128
	v_add_f32_e32 v129, 1.0, v129
	v_rcp_f32_e32 v128, v128
	v_rcp_f32_e32 v129, v129
	s_nop 0
; DI u32x4 pack8(f32x4 a, f32x4 b) { u32x4 w; w.x = pk2(a[0], a[1]); w.y = pk2(a[2], a[3]); w.z = pk2(b[0], b[1]); w.w = pk2(b[2], b[3]); return w; }
; DI float siluf_(float x) { return x * __builtin_amdgcn_rcpf(1.f + __expf(-x)); }
;     DI void operator()(AccRef acc, const Unit& u, int wr, int wc, int fr, int fq) const {
;     ...
;             for (int m = 0; m < 4; ++m) { int row_ = row0 + ai * 128 + m * 16; asm volatile("" : "+v"(row_) :: "memory");
;                 const float mean_ = sta[ai * 4 + m].x * (1.f / DM); const f32x2 st = {mean_, __builtin_amdgcn_rsqf(fmaxf(sta[ai * 4 + m].y * (1.f / DM) - mean_ * mean_, 0.f) + LN_EPS)}; f32x4 o[2];
; #pragma unroll
;                 for (int n = 0; n < 2; ++n) { const f32x4 gt = (acc[ai][0][m][n] - gwv[0][n] * st.x) * st.y + bwv[0][n], up = (acc[ai][1][m][n] - gwv[1][n] * st.x) * st.y + bwv[1][n];
; #pragma unroll
;                     for (int i = 0; i < 4; ++i) o[n][i] = siluf_(gt[i]) * up[i]; }
;                 *(u32x4*)(HID + (size_t)row_ * DFF + c0) = pack8(o[0], o[1]); }
	v_pk_mul_f32 v[126:127], v[126:127], v[128:129]
	s_nop 0
	v_pk_mul_f32 v[124:125], v[124:125], v[126:127]
	v_mul_f32_e32 v126, 0xbfb8aa3b, v118
	v_mul_f32_e32 v127, 0xbfb8aa3b, v119
	v_exp_f32_e32 v126, v126
	v_exp_f32_e32 v127, v127
	v_add_f32_e32 v126, 1.0, v126
	v_add_f32_e32 v127, 1.0, v127
	v_rcp_f32_e32 v126, v126
	v_rcp_f32_e32 v127, v127
	s_nop 0
	v_pk_mul_f32 v[118:119], v[118:119], v[126:127]
	s_nop 0
	v_pk_mul_f32 v[118:119], v[114:115], v[118:119]
	v_pk_fma_f32 v[114:115], v[84:85], v[134:135], v[120:121] op_sel_hi:[1,0,1] neg_lo:[1,0,0] neg_hi:[1,0,0]
	s_nop 0
	v_pk_fma_f32 v[114:115], v[114:115], v[136:137], v[88:89] op_sel_hi:[1,0,1]
	s_nop 0
	v_mul_f32_e32 v120, 0xbfb8aa3b, v114
	v_mul_f32_e32 v121, 0xbfb8aa3b, v115
	v_exp_f32_e32 v120, v120
	v_exp_f32_e32 v121, v121
	v_add_f32_e32 v120, 1.0, v120
	v_add_f32_e32 v121, 1.0, v121
	v_rcp_f32_e32 v120, v120
	v_rcp_f32_e32 v121, v121
	s_nop 0
	v_pk_mul_f32 v[114:115], v[114:115], v[120:121]
	s_nop 0
	v_pk_mul_f32 v[120:121], v[116:117], v[114:115]
	v_cvt_pk_bf16_f32 v114, v122, v123
	v_cvt_pk_bf16_f32 v115, v124, v125
	v_cvt_pk_bf16_f32 v116, v118, v119
	v_cvt_pk_bf16_f32 v117, v120, v121
	v_mad_i64_i32 v[118:119], s[14:15], v212, s54, v[178:179]
	global_store_dwordx4 v[118:119], v[114:117], off
	s_nop 1
	v_pk_mul_f32 v[114:115], v[210:211], s[36:37] op_sel_hi:[1,0]
	s_nop 0
	v_fma_f32 v116, -v114, v114, v115
	v_max_f32_e32 v116, 0, v116
	v_add_f32_e32 v116, 0x3727c5ac, v116
	v_rsq_f32_e32 v116, v116
	v_pk_fma_f32 v[94:95], v[106:107], v[114:115], v[94:95] op_sel_hi:[1,0,1] neg_lo:[1,0,0] neg_hi:[1,0,0]
	v_pk_fma_f32 v[90:91], v[98:99], v[114:115], v[90:91] op_sel_hi:[1,0,1] neg_lo:[1,0,0] neg_hi:[1,0,0]
	v_pk_fma_f32 v[92:93], v[100:101], v[114:115], v[92:93] op_sel_hi:[1,0,1] neg_lo:[1,0,0] neg_hi:[1,0,0]
	v_pk_fma_f32 v[94:95], v[94:95], v[116:117], v[110:111] op_sel_hi:[1,0,1]
	v_pk_fma_f32 v[70:71], v[82:83], v[114:115], v[70:71] op_sel_hi:[1,0,1] neg_lo:[1,0,0] neg_hi:[1,0,0]
	v_mul_f32_e32 v117, 0xbfb8aa3b, v94
	v_exp_f32_e32 v117, v117
	v_pk_fma_f32 v[66:67], v[74:75], v[114:115], v[66:67] op_sel_hi:[1,0,1] neg_lo:[1,0,0] neg_hi:[1,0,0]
	v_pk_fma_f32 v[68:69], v[76:77], v[114:115], v[68:69] op_sel_hi:[1,0,1] neg_lo:[1,0,0] neg_hi:[1,0,0]
	v_add_f32_e32 v117, 1.0, v117
	v_rcp_f32_e32 v118, v117
	v_mul_f32_e32 v117, 0xbfb8aa3b, v95
	v_exp_f32_e32 v117, v117
	s_nop 0
	v_add_f32_e32 v117, 1.0, v117
	v_rcp_f32_e32 v119, v117
	v_pk_fma_f32 v[90:91], v[90:91], v[116:117], v[102:103] op_sel_hi:[1,0,1]
	v_pk_fma_f32 v[92:93], v[92:93], v[116:117], v[104:105] op_sel_hi:[1,0,1]
	v_pk_fma_f32 v[70:71], v[70:71], v[116:117], v[86:87] op_sel_hi:[1,0,1]
	v_pk_mul_f32 v[94:95], v[94:95], v[118:119]
	v_pk_fma_f32 v[66:67], v[66:67], v[116:117], v[78:79] op_sel_hi:[1,0,1]
	v_pk_mul_f32 v[90:91], v[90:91], v[94:95]
	v_pk_fma_f32 v[94:95], v[108:109], v[114:115], v[96:97] op_sel_hi:[1,0,1] neg_lo:[1,0,0] neg_hi:[1,0,0]
	v_pk_fma_f32 v[68:69], v[68:69], v[116:117], v[80:81] op_sel_hi:[1,0,1]
	v_pk_fma_f32 v[94:95], v[94:95], v[116:117], v[112:113] op_sel_hi:[1,0,1]
	s_nop 0
	v_mul_f32_e32 v96, 0xbfb8aa3b, v94
	v_mul_f32_e32 v97, 0xbfb8aa3b, v95
	v_exp_f32_e32 v96, v96
	v_exp_f32_e32 v97, v97
	v_add_f32_e32 v96, 1.0, v96
	v_add_f32_e32 v97, 1.0, v97
	v_rcp_f32_e32 v96, v96
	v_rcp_f32_e32 v97, v97
	s_nop 0
	v_pk_mul_f32 v[94:95], v[94:95], v[96:97]
	s_nop 0
	v_pk_mul_f32 v[92:93], v[92:93], v[94:95]
	v_mul_f32_e32 v94, 0xbfb8aa3b, v70
	v_mul_f32_e32 v95, 0xbfb8aa3b, v71
	v_exp_f32_e32 v94, v94
	v_exp_f32_e32 v95, v95
	v_add_f32_e32 v94, 1.0, v94
	v_add_f32_e32 v95, 1.0, v95
	v_rcp_f32_e32 v94, v94
	v_rcp_f32_e32 v95, v95
	s_nop 0
	v_pk_mul_f32 v[70:71], v[70:71], v[94:95]
	s_nop 0
	v_pk_mul_f32 v[70:71], v[66:67], v[70:71]
	v_pk_fma_f32 v[66:67], v[84:85], v[114:115], v[72:73] op_sel_hi:[1,0,1] neg_lo:[1,0,0] neg_hi:[1,0,0]
	s_nop 0
	v_pk_fma_f32 v[66:67], v[66:67], v[116:117], v[88:89] op_sel_hi:[1,0,1]
	s_nop 0
	v_mul_f32_e32 v72, 0xbfb8aa3b, v66
	v_mul_f32_e32 v73, 0xbfb8aa3b, v67
	v_exp_f32_e32 v72, v72
	v_exp_f32_e32 v73, v73
	v_add_f32_e32 v72, 1.0, v72
	v_add_f32_e32 v73, 1.0, v73
	v_rcp_f32_e32 v72, v72
	v_rcp_f32_e32 v73, v73
	s_nop 0
	v_pk_mul_f32 v[66:67], v[66:67], v[72:73]
	s_nop 0
	v_pk_mul_f32 v[72:73], v[68:69], v[66:67]
	v_cvt_pk_bf16_f32 v66, v90, v91
	v_cvt_pk_bf16_f32 v67, v92, v93
	v_cvt_pk_bf16_f32 v68, v70, v71
	v_cvt_pk_bf16_f32 v69, v72, v73
	v_mad_i64_i32 v[70:71], s[14:15], v208, s54, v[178:179]
	global_store_dwordx4 v[70:71], v[66:69], off
	s_nop 1
	v_pk_mul_f32 v[66:67], v[192:193], s[36:37] op_sel_hi:[1,0]
	s_nop 0
	v_fma_f32 v68, -v66, v66, v67
	v_max_f32_e32 v68, 0, v68
	v_add_f32_e32 v68, 0x3727c5ac, v68
	v_rsq_f32_e32 v68, v68
	v_pk_fma_f32 v[62:63], v[106:107], v[66:67], v[62:63] op_sel_hi:[1,0,1] neg_lo:[1,0,0] neg_hi:[1,0,0]
	v_pk_fma_f32 v[58:59], v[98:99], v[66:67], v[58:59] op_sel_hi:[1,0,1] neg_lo:[1,0,0] neg_hi:[1,0,0]
	v_pk_fma_f32 v[60:61], v[100:101], v[66:67], v[60:61] op_sel_hi:[1,0,1] neg_lo:[1,0,0] neg_hi:[1,0,0]
	v_pk_fma_f32 v[62:63], v[62:63], v[68:69], v[110:111] op_sel_hi:[1,0,1]
	v_pk_fma_f32 v[54:55], v[82:83], v[66:67], v[54:55] op_sel_hi:[1,0,1] neg_lo:[1,0,0] neg_hi:[1,0,0]
	v_mul_f32_e32 v69, 0xbfb8aa3b, v62
	v_exp_f32_e32 v69, v69
	v_pk_fma_f32 v[50:51], v[74:75], v[66:67], v[50:51] op_sel_hi:[1,0,1] neg_lo:[1,0,0] neg_hi:[1,0,0]
	v_pk_fma_f32 v[52:53], v[76:77], v[66:67], v[52:53] op_sel_hi:[1,0,1] neg_lo:[1,0,0] neg_hi:[1,0,0]
	v_add_f32_e32 v69, 1.0, v69
	v_rcp_f32_e32 v70, v69
	v_mul_f32_e32 v69, 0xbfb8aa3b, v63
	v_exp_f32_e32 v69, v69
	s_nop 0
	v_add_f32_e32 v69, 1.0, v69
	v_rcp_f32_e32 v71, v69
; DI u32x4 pack8(f32x4 a, f32x4 b) { u32x4 w; w.x = pk2(a[0], a[1]); w.y = pk2(a[2], a[3]); w.z = pk2(b[0], b[1]); w.w = pk2(b[2], b[3]); return w; }
; DI float siluf_(float x) { return x * __builtin_amdgcn_rcpf(1.f + __expf(-x)); }
;     DI void operator()(AccRef acc, const Unit& u, int wr, int wc, int fr, int fq) const {
;     ...
;             for (int m = 0; m < 4; ++m) { int row_ = row0 + ai * 128 + m * 16; asm volatile("" : "+v"(row_) :: "memory");
;                 const float mean_ = sta[ai * 4 + m].x * (1.f / DM); const f32x2 st = {mean_, __builtin_amdgcn_rsqf(fmaxf(sta[ai * 4 + m].y * (1.f / DM) - mean_ * mean_, 0.f) + LN_EPS)}; f32x4 o[2];
; #pragma unroll
;                 for (int n = 0; n < 2; ++n) { const f32x4 gt = (acc[ai][0][m][n] - gwv[0][n] * st.x) * st.y + bwv[0][n], up = (acc[ai][1][m][n] - gwv[1][n] * st.x) * st.y + bwv[1][n];
; #pragma unroll
;                     for (int i = 0; i < 4; ++i) o[n][i] = siluf_(gt[i]) * up[i]; }
;                 *(u32x4*)(HID + (size_t)row_ * DFF + c0) = pack8(o[0], o[1]); }
	v_pk_fma_f32 v[58:59], v[58:59], v[68:69], v[102:103] op_sel_hi:[1,0,1]
	v_pk_fma_f32 v[60:61], v[60:61], v[68:69], v[104:105] op_sel_hi:[1,0,1]
	v_pk_fma_f32 v[54:55], v[54:55], v[68:69], v[86:87] op_sel_hi:[1,0,1]
	v_pk_mul_f32 v[62:63], v[62:63], v[70:71]
	v_pk_fma_f32 v[50:51], v[50:51], v[68:69], v[78:79] op_sel_hi:[1,0,1]
	v_pk_mul_f32 v[58:59], v[58:59], v[62:63]
	v_pk_fma_f32 v[62:63], v[108:109], v[66:67], v[64:65] op_sel_hi:[1,0,1] neg_lo:[1,0,0] neg_hi:[1,0,0]
	v_pk_fma_f32 v[52:53], v[52:53], v[68:69], v[80:81] op_sel_hi:[1,0,1]
	v_pk_fma_f32 v[62:63], v[62:63], v[68:69], v[112:113] op_sel_hi:[1,0,1]
	s_nop 0
	v_mul_f32_e32 v64, 0xbfb8aa3b, v62
	v_mul_f32_e32 v65, 0xbfb8aa3b, v63
	v_exp_f32_e32 v64, v64
	v_exp_f32_e32 v65, v65
	v_add_f32_e32 v64, 1.0, v64
	v_add_f32_e32 v65, 1.0, v65
	v_rcp_f32_e32 v64, v64
	v_rcp_f32_e32 v65, v65
	s_nop 0
	v_pk_mul_f32 v[62:63], v[62:63], v[64:65]
	s_nop 0
	v_pk_mul_f32 v[60:61], v[60:61], v[62:63]
	v_mul_f32_e32 v62, 0xbfb8aa3b, v54
	v_mul_f32_e32 v63, 0xbfb8aa3b, v55
	v_exp_f32_e32 v62, v62
	v_exp_f32_e32 v63, v63
	v_add_f32_e32 v62, 1.0, v62
	v_add_f32_e32 v63, 1.0, v63
	v_rcp_f32_e32 v62, v62
	v_rcp_f32_e32 v63, v63
	s_nop 0
	v_pk_mul_f32 v[54:55], v[54:55], v[62:63]
	s_nop 0
	v_pk_mul_f32 v[54:55], v[50:51], v[54:55]
	v_pk_fma_f32 v[50:51], v[84:85], v[66:67], v[56:57] op_sel_hi:[1,0,1] neg_lo:[1,0,0] neg_hi:[1,0,0]
	s_nop 0
	v_pk_fma_f32 v[50:51], v[50:51], v[68:69], v[88:89] op_sel_hi:[1,0,1]
	s_nop 0
	v_mul_f32_e32 v56, 0xbfb8aa3b, v50
	v_mul_f32_e32 v57, 0xbfb8aa3b, v51
	v_exp_f32_e32 v56, v56
	v_exp_f32_e32 v57, v57
	v_add_f32_e32 v56, 1.0, v56
	v_add_f32_e32 v57, 1.0, v57
	v_rcp_f32_e32 v56, v56
	v_rcp_f32_e32 v57, v57
	s_nop 0
	v_pk_mul_f32 v[50:51], v[50:51], v[56:57]
	s_nop 0
	v_pk_mul_f32 v[56:57], v[52:53], v[50:51]
	v_cvt_pk_bf16_f32 v50, v58, v59
	v_cvt_pk_bf16_f32 v51, v60, v61
	v_cvt_pk_bf16_f32 v52, v54, v55
	v_cvt_pk_bf16_f32 v53, v56, v57
	v_mad_i64_i32 v[54:55], s[14:15], v190, s54, v[178:179]
	global_store_dwordx4 v[54:55], v[50:53], off
	s_nop 1
	v_pk_mul_f32 v[50:51], v[188:189], s[36:37] op_sel_hi:[1,0]
	s_nop 0
	v_fma_f32 v52, -v50, v50, v51
	v_max_f32_e32 v52, 0, v52
	v_add_f32_e32 v52, 0x3727c5ac, v52
	v_rsq_f32_e32 v52, v52
	v_pk_fma_f32 v[46:47], v[106:107], v[50:51], v[46:47] op_sel_hi:[1,0,1] neg_lo:[1,0,0] neg_hi:[1,0,0]
	v_pk_fma_f32 v[42:43], v[98:99], v[50:51], v[42:43] op_sel_hi:[1,0,1] neg_lo:[1,0,0] neg_hi:[1,0,0]
	v_pk_fma_f32 v[44:45], v[100:101], v[50:51], v[44:45] op_sel_hi:[1,0,1] neg_lo:[1,0,0] neg_hi:[1,0,0]
	v_pk_fma_f32 v[46:47], v[46:47], v[52:53], v[110:111] op_sel_hi:[1,0,1]
	v_pk_fma_f32 v[38:39], v[82:83], v[50:51], v[38:39] op_sel_hi:[1,0,1] neg_lo:[1,0,0] neg_hi:[1,0,0]
	v_mul_f32_e32 v53, 0xbfb8aa3b, v46
	v_exp_f32_e32 v53, v53
	v_pk_fma_f32 v[34:35], v[74:75], v[50:51], v[34:35] op_sel_hi:[1,0,1] neg_lo:[1,0,0] neg_hi:[1,0,0]
	v_pk_fma_f32 v[36:37], v[76:77], v[50:51], v[36:37] op_sel_hi:[1,0,1] neg_lo:[1,0,0] neg_hi:[1,0,0]
	v_add_f32_e32 v53, 1.0, v53
	v_rcp_f32_e32 v54, v53
	v_mul_f32_e32 v53, 0xbfb8aa3b, v47
	v_exp_f32_e32 v53, v53
	s_nop 0
	v_add_f32_e32 v53, 1.0, v53
	v_rcp_f32_e32 v55, v53
	v_pk_fma_f32 v[42:43], v[42:43], v[52:53], v[102:103] op_sel_hi:[1,0,1]
	v_pk_fma_f32 v[44:45], v[44:45], v[52:53], v[104:105] op_sel_hi:[1,0,1]
	v_pk_fma_f32 v[38:39], v[38:39], v[52:53], v[86:87] op_sel_hi:[1,0,1]
	v_pk_mul_f32 v[46:47], v[46:47], v[54:55]
	v_pk_fma_f32 v[34:35], v[34:35], v[52:53], v[78:79] op_sel_hi:[1,0,1]
	v_pk_mul_f32 v[42:43], v[42:43], v[46:47]
	v_pk_fma_f32 v[46:47], v[108:109], v[50:51], v[48:49] op_sel_hi:[1,0,1] neg_lo:[1,0,0] neg_hi:[1,0,0]
	v_pk_fma_f32 v[36:37], v[36:37], v[52:53], v[80:81] op_sel_hi:[1,0,1]
	v_pk_fma_f32 v[46:47], v[46:47], v[52:53], v[112:113] op_sel_hi:[1,0,1]
	s_nop 0
	v_mul_f32_e32 v48, 0xbfb8aa3b, v46
	v_mul_f32_e32 v49, 0xbfb8aa3b, v47
	v_exp_f32_e32 v48, v48
	v_exp_f32_e32 v49, v49
	v_add_f32_e32 v48, 1.0, v48
	v_add_f32_e32 v49, 1.0, v49
	v_rcp_f32_e32 v48, v48
	v_rcp_f32_e32 v49, v49
	s_nop 0
	v_pk_mul_f32 v[46:47], v[46:47], v[48:49]
	s_nop 0
	v_pk_mul_f32 v[44:45], v[44:45], v[46:47]
	v_mul_f32_e32 v46, 0xbfb8aa3b, v38
	v_mul_f32_e32 v47, 0xbfb8aa3b, v39
	v_exp_f32_e32 v46, v46
	v_exp_f32_e32 v47, v47
	v_add_f32_e32 v46, 1.0, v46
	v_add_f32_e32 v47, 1.0, v47
	v_rcp_f32_e32 v46, v46
	v_rcp_f32_e32 v47, v47
	s_nop 0
	v_pk_mul_f32 v[38:39], v[38:39], v[46:47]
	s_nop 0
	v_pk_mul_f32 v[38:39], v[34:35], v[38:39]
	v_pk_fma_f32 v[34:35], v[84:85], v[50:51], v[40:41] op_sel_hi:[1,0,1] neg_lo:[1,0,0] neg_hi:[1,0,0]
	s_nop 0
	v_pk_fma_f32 v[34:35], v[34:35], v[52:53], v[88:89] op_sel_hi:[1,0,1]
	s_nop 0
	v_mul_f32_e32 v40, 0xbfb8aa3b, v34
	v_mul_f32_e32 v41, 0xbfb8aa3b, v35
	v_exp_f32_e32 v40, v40
	v_exp_f32_e32 v41, v41
	v_add_f32_e32 v40, 1.0, v40
	v_add_f32_e32 v41, 1.0, v41
	v_rcp_f32_e32 v40, v40
	v_rcp_f32_e32 v41, v41
	s_nop 0
	v_pk_mul_f32 v[34:35], v[34:35], v[40:41]
	s_nop 0
	v_pk_mul_f32 v[40:41], v[36:37], v[34:35]
	v_cvt_pk_bf16_f32 v34, v42, v43
	v_cvt_pk_bf16_f32 v35, v44, v45
	v_cvt_pk_bf16_f32 v36, v38, v39
	v_cvt_pk_bf16_f32 v37, v40, v41
	v_mad_i64_i32 v[38:39], s[14:15], v186, s54, v[178:179]
	global_store_dwordx4 v[38:39], v[34:37], off
	s_nop 1
	v_pk_mul_f32 v[34:35], v[184:185], s[36:37] op_sel_hi:[1,0]
	s_nop 0
	v_fma_f32 v36, -v34, v34, v35
	v_max_f32_e32 v36, 0, v36
	v_add_f32_e32 v36, 0x3727c5ac, v36
	v_rsq_f32_e32 v36, v36
	v_pk_fma_f32 v[30:31], v[106:107], v[34:35], v[30:31] op_sel_hi:[1,0,1] neg_lo:[1,0,0] neg_hi:[1,0,0]
	v_pk_fma_f32 v[26:27], v[98:99], v[34:35], v[26:27] op_sel_hi:[1,0,1] neg_lo:[1,0,0] neg_hi:[1,0,0]
; #define PG8_BAR __builtin_amdgcn_s_barrier()
; DI u32x4 pack8(f32x4 a, f32x4 b) { u32x4 w; w.x = pk2(a[0], a[1]); w.y = pk2(a[2], a[3]); w.z = pk2(b[0], b[1]); w.w = pk2(b[2], b[3]); return w; }
; DI float siluf_(float x) { return x * __builtin_amdgcn_rcpf(1.f + __expf(-x)); }
; template <class Epi, class Sched, bool ALIGN_EPI = false, bool SP2 = false>
; __device__ __forceinline__ void gemm_phase(PG8_LAS unsigned char* lds, const Gemm g, const Sched& S, const Epi& E) {
;     ...
;         if (!has_next) break;
; #pragma unroll
;         for (int a = 0; a < 2; ++a)
; #pragma unroll
;             for (int b = 0; b < 2; ++b)
; #pragma unroll
;                 for (int m = 0; m < 4; ++m)
; #pragma unroll
;                     for (int n = 0; n < 2; ++n) acc[a][b][m][n] = (f32x4){0.f, 0.f, 0.f, 0.f};
;         cur = nxt; cA = nA; cB = nB; ++ui;
;         if constexpr (ALIGN_EPI) { if (wr == 1) PG8_BAR; }
;     DI void operator()(AccRef acc, const Unit& u, int wr, int wc, int fr, int fq) const {
;     ...
;             for (int m = 0; m < 4; ++m) { int row_ = row0 + ai * 128 + m * 16; asm volatile("" : "+v"(row_) :: "memory");
;                 const float mean_ = sta[ai * 4 + m].x * (1.f / DM); const f32x2 st = {mean_, __builtin_amdgcn_rsqf(fmaxf(sta[ai * 4 + m].y * (1.f / DM) - mean_ * mean_, 0.f) + LN_EPS)}; f32x4 o[2];
; #pragma unroll
;                 for (int n = 0; n < 2; ++n) { const f32x4 gt = (acc[ai][0][m][n] - gwv[0][n] * st.x) * st.y + bwv[0][n], up = (acc[ai][1][m][n] - gwv[1][n] * st.x) * st.y + bwv[1][n];
; #pragma unroll
;                     for (int i = 0; i < 4; ++i) o[n][i] = siluf_(gt[i]) * up[i]; }
;                 *(u32x4*)(HID + (size_t)row_ * DFF + c0) = pack8(o[0], o[1]); }
	v_pk_fma_f32 v[28:29], v[100:101], v[34:35], v[28:29] op_sel_hi:[1,0,1] neg_lo:[1,0,0] neg_hi:[1,0,0]
	v_pk_fma_f32 v[30:31], v[30:31], v[36:37], v[110:111] op_sel_hi:[1,0,1]
	v_pk_fma_f32 v[22:23], v[82:83], v[34:35], v[22:23] op_sel_hi:[1,0,1] neg_lo:[1,0,0] neg_hi:[1,0,0]
	v_mul_f32_e32 v37, 0xbfb8aa3b, v30
	v_exp_f32_e32 v37, v37
	v_pk_fma_f32 v[18:19], v[74:75], v[34:35], v[18:19] op_sel_hi:[1,0,1] neg_lo:[1,0,0] neg_hi:[1,0,0]
	v_pk_fma_f32 v[20:21], v[76:77], v[34:35], v[20:21] op_sel_hi:[1,0,1] neg_lo:[1,0,0] neg_hi:[1,0,0]
	v_add_f32_e32 v37, 1.0, v37
	v_rcp_f32_e32 v38, v37
	v_mul_f32_e32 v37, 0xbfb8aa3b, v31
	v_exp_f32_e32 v37, v37
	s_nop 0
	v_add_f32_e32 v37, 1.0, v37
	v_rcp_f32_e32 v39, v37
	v_pk_fma_f32 v[26:27], v[26:27], v[36:37], v[102:103] op_sel_hi:[1,0,1]
	v_pk_fma_f32 v[28:29], v[28:29], v[36:37], v[104:105] op_sel_hi:[1,0,1]
	v_pk_fma_f32 v[22:23], v[22:23], v[36:37], v[86:87] op_sel_hi:[1,0,1]
	v_pk_mul_f32 v[30:31], v[30:31], v[38:39]
	v_pk_fma_f32 v[18:19], v[18:19], v[36:37], v[78:79] op_sel_hi:[1,0,1]
	v_pk_mul_f32 v[26:27], v[26:27], v[30:31]
	v_pk_fma_f32 v[30:31], v[108:109], v[34:35], v[32:33] op_sel_hi:[1,0,1] neg_lo:[1,0,0] neg_hi:[1,0,0]
	v_pk_fma_f32 v[20:21], v[20:21], v[36:37], v[80:81] op_sel_hi:[1,0,1]
	v_pk_fma_f32 v[30:31], v[30:31], v[36:37], v[112:113] op_sel_hi:[1,0,1]
	s_nop 0
	v_mul_f32_e32 v32, 0xbfb8aa3b, v30
	v_mul_f32_e32 v33, 0xbfb8aa3b, v31
	v_exp_f32_e32 v32, v32
	v_exp_f32_e32 v33, v33
	v_add_f32_e32 v32, 1.0, v32
	v_add_f32_e32 v33, 1.0, v33
	v_rcp_f32_e32 v32, v32
	v_rcp_f32_e32 v33, v33
	s_nop 0
	v_pk_mul_f32 v[30:31], v[30:31], v[32:33]
	s_nop 0
	v_pk_mul_f32 v[28:29], v[28:29], v[30:31]
	v_mul_f32_e32 v30, 0xbfb8aa3b, v22
	v_mul_f32_e32 v31, 0xbfb8aa3b, v23
	v_exp_f32_e32 v30, v30
	v_exp_f32_e32 v31, v31
	v_add_f32_e32 v30, 1.0, v30
	v_add_f32_e32 v31, 1.0, v31
	v_rcp_f32_e32 v30, v30
	v_rcp_f32_e32 v31, v31
	s_nop 0
	v_pk_mul_f32 v[22:23], v[22:23], v[30:31]
	s_nop 0
	v_pk_mul_f32 v[22:23], v[18:19], v[22:23]
	v_pk_fma_f32 v[18:19], v[84:85], v[34:35], v[24:25] op_sel_hi:[1,0,1] neg_lo:[1,0,0] neg_hi:[1,0,0]
	s_nop 0
	v_pk_fma_f32 v[18:19], v[18:19], v[36:37], v[88:89] op_sel_hi:[1,0,1]
	s_nop 0
	v_mul_f32_e32 v24, 0xbfb8aa3b, v18
	v_mul_f32_e32 v25, 0xbfb8aa3b, v19
	v_exp_f32_e32 v24, v24
	v_exp_f32_e32 v25, v25
	v_add_f32_e32 v24, 1.0, v24
	v_add_f32_e32 v25, 1.0, v25
	v_rcp_f32_e32 v24, v24
	v_rcp_f32_e32 v25, v25
	s_nop 0
	v_pk_mul_f32 v[18:19], v[18:19], v[24:25]
	s_nop 0
	v_pk_mul_f32 v[24:25], v[20:21], v[18:19]
	v_cvt_pk_bf16_f32 v18, v26, v27
	v_cvt_pk_bf16_f32 v19, v28, v29
	v_cvt_pk_bf16_f32 v20, v22, v23
	v_cvt_pk_bf16_f32 v21, v24, v25
	v_mad_i64_i32 v[22:23], s[14:15], v182, s54, v[178:179]
	global_store_dwordx4 v[22:23], v[18:21], off
	s_nop 1
	v_pk_mul_f32 v[18:19], v[180:181], s[36:37] op_sel_hi:[1,0]
	s_nop 0
	v_fma_f32 v20, -v18, v18, v19
	v_max_f32_e32 v20, 0, v20
	v_add_f32_e32 v20, 0x3727c5ac, v20
	v_rsq_f32_e32 v20, v20
	v_pk_fma_f32 v[14:15], v[106:107], v[18:19], v[14:15] op_sel_hi:[1,0,1] neg_lo:[1,0,0] neg_hi:[1,0,0]
	v_pk_fma_f32 v[10:11], v[98:99], v[18:19], v[10:11] op_sel_hi:[1,0,1] neg_lo:[1,0,0] neg_hi:[1,0,0]
	v_pk_fma_f32 v[12:13], v[100:101], v[18:19], v[12:13] op_sel_hi:[1,0,1] neg_lo:[1,0,0] neg_hi:[1,0,0]
	v_pk_fma_f32 v[14:15], v[14:15], v[20:21], v[110:111] op_sel_hi:[1,0,1]
	v_pk_fma_f32 v[6:7], v[82:83], v[18:19], v[6:7] op_sel_hi:[1,0,1] neg_lo:[1,0,0] neg_hi:[1,0,0]
	v_mul_f32_e32 v21, 0xbfb8aa3b, v14
	v_exp_f32_e32 v21, v21
	v_pk_fma_f32 v[2:3], v[74:75], v[18:19], v[2:3] op_sel_hi:[1,0,1] neg_lo:[1,0,0] neg_hi:[1,0,0]
	v_pk_fma_f32 v[4:5], v[76:77], v[18:19], v[4:5] op_sel_hi:[1,0,1] neg_lo:[1,0,0] neg_hi:[1,0,0]
	v_add_f32_e32 v21, 1.0, v21
	v_rcp_f32_e32 v22, v21
	v_mul_f32_e32 v21, 0xbfb8aa3b, v15
	v_exp_f32_e32 v21, v21
	s_nop 0
	v_add_f32_e32 v21, 1.0, v21
	v_rcp_f32_e32 v23, v21
	v_pk_fma_f32 v[10:11], v[10:11], v[20:21], v[102:103] op_sel_hi:[1,0,1]
	v_pk_fma_f32 v[12:13], v[12:13], v[20:21], v[104:105] op_sel_hi:[1,0,1]
	v_pk_fma_f32 v[6:7], v[6:7], v[20:21], v[86:87] op_sel_hi:[1,0,1]
	v_pk_mul_f32 v[14:15], v[14:15], v[22:23]
	v_pk_fma_f32 v[2:3], v[2:3], v[20:21], v[78:79] op_sel_hi:[1,0,1]
	v_pk_mul_f32 v[10:11], v[10:11], v[14:15]
	v_pk_fma_f32 v[14:15], v[108:109], v[18:19], v[16:17] op_sel_hi:[1,0,1] neg_lo:[1,0,0] neg_hi:[1,0,0]
	v_pk_fma_f32 v[4:5], v[4:5], v[20:21], v[80:81] op_sel_hi:[1,0,1]
	v_pk_fma_f32 v[14:15], v[14:15], v[20:21], v[112:113] op_sel_hi:[1,0,1]
	s_nop 0
	v_mul_f32_e32 v16, 0xbfb8aa3b, v14
	v_mul_f32_e32 v17, 0xbfb8aa3b, v15
	v_exp_f32_e32 v16, v16
	v_exp_f32_e32 v17, v17
	v_add_f32_e32 v16, 1.0, v16
	v_add_f32_e32 v17, 1.0, v17
	v_rcp_f32_e32 v16, v16
	v_rcp_f32_e32 v17, v17
	s_nop 0
	v_pk_mul_f32 v[14:15], v[14:15], v[16:17]
	s_nop 0
	v_pk_mul_f32 v[12:13], v[12:13], v[14:15]
	v_mul_f32_e32 v14, 0xbfb8aa3b, v6
	v_mul_f32_e32 v15, 0xbfb8aa3b, v7
	v_exp_f32_e32 v14, v14
	v_exp_f32_e32 v15, v15
	v_add_f32_e32 v14, 1.0, v14
	v_add_f32_e32 v15, 1.0, v15
	v_rcp_f32_e32 v14, v14
	v_rcp_f32_e32 v15, v15
	s_nop 0
	v_pk_mul_f32 v[6:7], v[6:7], v[14:15]
	s_nop 0
	v_pk_mul_f32 v[6:7], v[2:3], v[6:7]
	v_pk_fma_f32 v[2:3], v[84:85], v[18:19], v[8:9] op_sel_hi:[1,0,1] neg_lo:[1,0,0] neg_hi:[1,0,0]
	s_nop 0
	v_pk_fma_f32 v[2:3], v[2:3], v[20:21], v[88:89] op_sel_hi:[1,0,1]
	s_nop 0
	v_mul_f32_e32 v8, 0xbfb8aa3b, v2
	v_mul_f32_e32 v9, 0xbfb8aa3b, v3
	v_exp_f32_e32 v8, v8
	v_exp_f32_e32 v9, v9
	v_add_f32_e32 v8, 1.0, v8
	v_add_f32_e32 v9, 1.0, v9
	v_rcp_f32_e32 v8, v8
	v_rcp_f32_e32 v9, v9
	s_nop 0
	v_pk_mul_f32 v[2:3], v[2:3], v[8:9]
	s_nop 0
	v_pk_mul_f32 v[8:9], v[4:5], v[2:3]
	v_cvt_pk_bf16_f32 v4, v6, v7
	v_mad_i64_i32 v[6:7], s[14:15], v176, s54, v[178:179]
	v_cvt_pk_bf16_f32 v2, v10, v11
	v_cvt_pk_bf16_f32 v3, v12, v13
	v_cvt_pk_bf16_f32 v5, v8, v9
	s_mov_b64 s[14:15], -1
	global_store_dwordx4 v[6:7], v[2:5], off
	s_cbranch_vccnz .LBB0_95
	s_andn2_b64 vcc, exec, s[8:9]
	s_cbranch_vccnz .LBB0_94
	s_barrier
	s_branch .LBB0_94

; DI u32x4 pack8(f32x4 a, f32x4 b) { u32x4 w; w.x = pk2(a[0], a[1]); w.y = pk2(a[2], a[3]); w.z = pk2(b[0], b[1]); w.w = pk2(b[2], b[3]); return w; }
;     DI void operator()(AccRef acc, const Unit& u, int wr, int wc, int fr, int fq) const {
;         unsigned char* w_ = ws; asm volatile("" : "+s"(w_)); float* Y = (float*)(w_ + WS_Y); bf16_t* YG = (bf16_t*)(w_ + WS_X1B); float* ST = (float*)(w_ + WS_ST1);
;         const int row0 = u.pm * 256 + wr * 64 + fr, c0 = u.pn * 256 + wc * 32 + 8 * fq;
;         f32x4 xb[2][2][2];
;         { int r0_ = row0; asm volatile("" : "+v"(r0_) :: "memory"); const size_t o0 = (size_t)r0_ * DM + c0;
; #pragma unroll
;           for (int bj = 0; bj < 2; ++bj)
; #pragma unroll
;             for (int n = 0; n < 2; ++n) xb[0][bj][n] = *(const f32x4*)(X + o0 + bj * 128 + 4 * n); }
; #pragma unroll
;         for (int it = 0; it < 8; ++it) { const int ai = it >> 2, m = it & 3, cur = it & 1;
;             if (it + 1 < 8) { int rn_ = row0 + ((it + 1) >> 2) * 128 + ((it + 1) & 3) * 16; asm volatile("" : "+v"(rn_) :: "memory"); const size_t on = (size_t)rn_ * DM + c0;
; #pragma unroll
;                 for (int bj = 0; bj < 2; ++bj)
; #pragma unroll
;                     for (int n = 0; n < 2; ++n) xb[cur ^ 1][bj][n] = *(const f32x4*)(X + on + bj * 128 + 4 * n); }
;             int row_ = row0 + ai * 128 + m * 16; asm volatile("" : "+v"(row_)); const size_t off = (size_t)row_ * DM + c0; float s1 = 0.f, s2 = 0.f;
; #pragma unroll
;             for (int bj = 0; bj < 2; ++bj) { f32x4 y[2];
; #pragma unroll
;                 for (int n = 0; n < 2; ++n) { y[n] = xb[cur][bj][n] * ALPHA + acc[ai][bj][m][n]; *(f32x4*)(Y + off + bj * 128 + 4 * n) = y[n];
;                     s1 += (y[n][0] + y[n][1]) + (y[n][2] + y[n][3]); s2 += (y[n][0] * y[n][0] + y[n][1] * y[n][1]) + (y[n][2] * y[n][2] + y[n][3] * y[n][3]); }
;                 const f32x4 g0 = *(const f32x4*)(G + c0 + bj * 128), g1 = *(const f32x4*)(G + c0 + bj * 128 + 4);
;                 *(u32x4*)(YG + off + bj * 128) = pack8(y[0] * g0, y[1] * g1); }
;             s1 += __shfl_xor(s1, 16); s1 += __shfl_xor(s1, 32); s2 += __shfl_xor(s2, 16); s2 += __shfl_xor(s2, 32);
;             if (fq == 0) { unsafeAtomicAdd(ST + (size_t)row_ * 2, s1); unsafeAtomicAdd(ST + (size_t)row_ * 2 + 1, s2); } }
.LBB0_135:
	v_lshl_add_u32 v184, s61, 8, v180
	s_mov_b64 s[14:15], s[0:1]
	v_mov_b32_e32 v134, v184
	v_lshl_or_b32 v168, s60, 8, v182
	v_ashrrev_i32_e32 v169, 31, v168
	v_ashrrev_i32_e32 v135, 31, v134
	v_lshlrev_b64 v[134:135], 12, v[134:135]
	v_lshl_add_u64 v[134:135], s[10:11], 0, v[134:135]
	v_lshlrev_b64 v[170:171], 2, v[168:169]
	v_lshl_add_u64 v[134:135], v[134:135], 0, v[170:171]
	global_load_dwordx4 v[186:189], v[134:135], off offset:16
	global_load_dwordx4 v[190:193], v[134:135], off
	global_load_dwordx4 v[150:153], v[134:135], off offset:528
	global_load_dwordx4 v[154:157], v[134:135], off offset:512
	v_or_b32_e32 v172, 16, v184
	v_mov_b32_e32 v134, v172
	s_add_u32 s58, s14, 0x17600000
	v_ashrrev_i32_e32 v135, 31, v134
	v_lshlrev_b64 v[134:135], 12, v[134:135]
	v_lshl_add_u64 v[134:135], s[10:11], 0, v[134:135]
	v_lshl_add_u64 v[138:139], v[134:135], 0, v[170:171]
	v_mov_b32_e32 v174, v184
	s_addc_u32 s59, s15, 0
	global_load_dwordx4 v[142:145], v[138:139], off offset:16
	global_load_dwordx4 v[146:149], v[138:139], off
	global_load_dwordx4 v[134:137], v[138:139], off offset:528
	s_nop 0
	global_load_dwordx4 v[138:141], v[138:139], off offset:512
	s_add_u32 s60, s14, 0xe600000
	v_ashrrev_i32_e32 v175, 31, v174
	v_lshlrev_b64 v[176:177], 10, v[174:175]
	s_addc_u32 s61, s15, 0
	v_lshl_add_u64 v[176:177], v[176:177], 0, v[168:169]
	v_lshl_add_u64 v[178:179], v[176:177], 2, s[60:61]
	v_lshl_add_u64 v[170:171], s[48:49], 0, v[170:171]
	v_lshl_add_u64 v[176:177], v[176:177], 1, s[58:59]
	s_add_u32 s56, s14, 0x3540000
	s_addc_u32 s57, s15, 0
	s_waitcnt vmcnt(0)
	v_pk_fma_f32 v[124:125], v[188:189], s[30:31], v[124:125] op_sel_hi:[1,0,1]
	v_pk_fma_f32 v[128:129], v[192:193], s[30:31], v[128:129] op_sel_hi:[1,0,1]
	v_pk_fma_f32 v[126:127], v[190:191], s[30:31], v[126:127] op_sel_hi:[1,0,1]
	v_add_f32_e32 v185, v129, v128
	v_add_f32_e32 v173, v126, v127
	v_pk_fma_f32 v[122:123], v[186:187], s[30:31], v[122:123] op_sel_hi:[1,0,1]
	v_add_f32_e32 v173, v173, v185
	v_add_f32_e32 v186, v122, v123
	v_add_f32_e32 v187, v125, v124
	v_add_f32_e32 v173, 0, v173
	v_add_f32_e32 v186, v186, v187
	v_mul_f32_e32 v185, v127, v127
	v_mul_f32_e32 v190, v128, v128
	v_add_f32_e32 v173, v173, v186
	v_mul_f32_e32 v186, v123, v123
	v_mul_f32_e32 v187, v124, v124
	v_fmac_f32_e32 v185, v126, v126
	v_fmac_f32_e32 v190, v129, v129
	v_fmac_f32_e32 v186, v122, v122
	v_fmac_f32_e32 v187, v125, v125
	global_store_dwordx4 v[178:179], v[126:129], off
	v_add_f32_e32 v185, v185, v190
	global_store_dwordx4 v[178:179], v[122:125], off offset:16
	v_add_f32_e32 v186, v186, v187
	v_add_f32_e32 v185, v185, v186
	global_load_dwordx4 v[186:189], v[170:171], off offset:16
	global_load_dwordx4 v[190:193], v[170:171], off
	v_pk_fma_f32 v[120:121], v[156:157], s[30:31], v[120:121] op_sel_hi:[1,0,1]
	v_pk_fma_f32 v[118:119], v[154:155], s[30:31], v[118:119] op_sel_hi:[1,0,1]
	v_pk_fma_f32 v[116:117], v[152:153], s[30:31], v[116:117] op_sel_hi:[1,0,1]
	v_pk_fma_f32 v[114:115], v[150:151], s[30:31], v[114:115] op_sel_hi:[1,0,1]
	s_waitcnt vmcnt(0)
	v_pk_mul_f32 v[188:189], v[124:125], v[188:189]
	v_pk_mul_f32 v[128:129], v[128:129], v[192:193]
	v_pk_mul_f32 v[126:127], v[126:127], v[190:191]
	v_pk_mul_f32 v[124:125], v[122:123], v[186:187]
	v_cvt_pk_bf16_f32 v122, v126, v127
	v_cvt_pk_bf16_f32 v123, v128, v129
	v_cvt_pk_bf16_f32 v124, v124, v125
	v_cvt_pk_bf16_f32 v125, v188, v189
	global_store_dwordx4 v[176:177], v[122:125], off
	global_store_dwordx4 v[178:179], v[118:121], off offset:512
	global_store_dwordx4 v[178:179], v[114:117], off offset:528
	v_add_f32_e32 v122, v118, v119
	v_add_f32_e32 v123, v121, v120
	v_add_f32_e32 v122, v122, v123
	v_mul_f32_e32 v123, v119, v119
	v_mul_f32_e32 v124, v120, v120
	v_fmac_f32_e32 v123, v118, v118
	v_fmac_f32_e32 v124, v121, v121
	v_add_f32_e32 v123, v123, v124
	v_add_f32_e32 v124, v114, v115
	v_add_f32_e32 v125, v117, v116
	v_add_f32_e32 v122, v173, v122
	v_add_f32_e32 v124, v124, v125
	v_add_f32_e32 v150, v122, v124
	v_mul_f32_e32 v122, v115, v115
	v_mul_f32_e32 v124, v116, v116
	v_fmac_f32_e32 v122, v114, v114
	v_fmac_f32_e32 v124, v117, v117
	v_add_f32_e32 v123, v185, v123
	v_add_f32_e32 v122, v122, v124
	v_add_f32_e32 v151, v123, v122
	global_load_dwordx4 v[122:125], v[170:171], off offset:528
	global_load_dwordx4 v[126:129], v[170:171], off offset:512
	s_waitcnt vmcnt(0)
	v_pk_mul_f32 v[124:125], v[116:117], v[124:125]
	v_pk_mul_f32 v[120:121], v[120:121], v[128:129]
	v_pk_mul_f32 v[118:119], v[118:119], v[126:127]
	v_pk_mul_f32 v[116:117], v[114:115], v[122:123]
	v_cvt_pk_bf16_f32 v114, v118, v119
	v_cvt_pk_bf16_f32 v115, v120, v121
	v_cvt_pk_bf16_f32 v116, v116, v117
	v_cvt_pk_bf16_f32 v117, v124, v125
	global_store_dwordx4 v[176:177], v[114:117], off offset:256
	s_nop 1
	v_and_b32_e32 v115, 64, v230
	v_xor_b32_e32 v114, 16, v230
	v_add_u32_e32 v115, 64, v115
	v_cmp_lt_i32_e32 vcc, v114, v115
	v_xor_b32_e32 v116, 32, v230
	s_nop 0
	v_cndmask_b32_e32 v114, v230, v114, vcc
	v_lshlrev_b32_e32 v152, 2, v114
	v_cmp_lt_i32_e32 vcc, v116, v115
	ds_bpermute_b32 v114, v152, v150
	s_waitcnt lgkmcnt(0)
	v_add_f32_e32 v114, v150, v114
	v_cndmask_b32_e32 v115, v230, v116, vcc
	ds_bpermute_b32 v116, v152, v151
	v_lshlrev_b32_e32 v153, 2, v115
	ds_bpermute_b32 v115, v153, v114
	s_waitcnt lgkmcnt(0)
	v_add_f32_e32 v116, v151, v116
	ds_bpermute_b32 v117, v153, v116
	s_and_saveexec_b64 s[14:15], s[40:41]
	s_cbranch_execz .LBB0_137
	s_waitcnt lgkmcnt(0)
	v_add_f32_e32 v116, v116, v117
	v_add_f32_e32 v117, v114, v115
	v_lshl_add_u64 v[114:115], v[174:175], 3, s[56:57]
	global_atomic_add_f32 v[114:115], v117, off
	global_atomic_add_f32 v[114:115], v116, off offset:4
; DI u32x4 pack8(f32x4 a, f32x4 b) { u32x4 w; w.x = pk2(a[0], a[1]); w.y = pk2(a[2], a[3]); w.z = pk2(b[0], b[1]); w.w = pk2(b[2], b[3]); return w; }
;     DI void operator()(AccRef acc, const Unit& u, int wr, int wc, int fr, int fq) const {
;     ...
;         for (int it = 0; it < 8; ++it) { const int ai = it >> 2, m = it & 3, cur = it & 1;
;             if (it + 1 < 8) { int rn_ = row0 + ((it + 1) >> 2) * 128 + ((it + 1) & 3) * 16; asm volatile("" : "+v"(rn_) :: "memory"); const size_t on = (size_t)rn_ * DM + c0;
; #pragma unroll
;                 for (int bj = 0; bj < 2; ++bj)
; #pragma unroll
;                     for (int n = 0; n < 2; ++n) xb[cur ^ 1][bj][n] = *(const f32x4*)(X + on + bj * 128 + 4 * n); }
;             int row_ = row0 + ai * 128 + m * 16; asm volatile("" : "+v"(row_)); const size_t off = (size_t)row_ * DM + c0; float s1 = 0.f, s2 = 0.f;
; #pragma unroll
;             for (int bj = 0; bj < 2; ++bj) { f32x4 y[2];
; #pragma unroll
;                 for (int n = 0; n < 2; ++n) { y[n] = xb[cur][bj][n] * ALPHA + acc[ai][bj][m][n]; *(f32x4*)(Y + off + bj * 128 + 4 * n) = y[n];
;                     s1 += (y[n][0] + y[n][1]) + (y[n][2] + y[n][3]); s2 += (y[n][0] * y[n][0] + y[n][1] * y[n][1]) + (y[n][2] * y[n][2] + y[n][3] * y[n][3]); }
;                 const f32x4 g0 = *(const f32x4*)(G + c0 + bj * 128), g1 = *(const f32x4*)(G + c0 + bj * 128 + 4);
;                 *(u32x4*)(YG + off + bj * 128) = pack8(y[0] * g0, y[1] * g1); }
;             s1 += __shfl_xor(s1, 16); s1 += __shfl_xor(s1, 32); s2 += __shfl_xor(s2, 16); s2 += __shfl_xor(s2, 32);
;             if (fq == 0) { unsafeAtomicAdd(ST + (size_t)row_ * 2, s1); unsafeAtomicAdd(ST + (size_t)row_ * 2 + 1, s2); } }
.LBB0_137:
	s_or_b64 exec, exec, s[14:15]
	v_or_b32_e32 v150, 32, v184
	v_mov_b32_e32 v114, v150
	v_pk_fma_f32 v[112:113], v[148:149], s[30:31], v[112:113] op_sel_hi:[1,0,1]
	v_ashrrev_i32_e32 v115, 31, v114
	v_lshlrev_b64 v[114:115], 12, v[114:115]
	v_lshl_add_u64 v[114:115], s[10:11], 0, v[114:115]
	v_lshl_add_u64 v[118:119], v[168:169], 2, v[114:115]
	global_load_dwordx4 v[122:125], v[118:119], off offset:16
	global_load_dwordx4 v[126:129], v[118:119], off
	s_waitcnt lgkmcnt(0)
	global_load_dwordx4 v[114:117], v[118:119], off offset:528
	s_nop 0
	global_load_dwordx4 v[118:121], v[118:119], off offset:512
	v_pk_fma_f32 v[110:111], v[146:147], s[30:31], v[110:111] op_sel_hi:[1,0,1]
	v_ashrrev_i32_e32 v173, 31, v172
	v_lshlrev_b64 v[154:155], 10, v[172:173]
	v_lshl_add_u64 v[154:155], v[154:155], 0, v[168:169]
	v_lshl_add_u64 v[156:157], v[154:155], 2, s[60:61]
	v_pk_fma_f32 v[108:109], v[144:145], s[30:31], v[108:109] op_sel_hi:[1,0,1]
	v_pk_fma_f32 v[106:107], v[142:143], s[30:31], v[106:107] op_sel_hi:[1,0,1]
	global_store_dwordx4 v[156:157], v[110:113], off
	global_store_dwordx4 v[156:157], v[106:109], off offset:16
	global_load_dwordx4 v[142:145], v[170:171], off
	global_load_dwordx4 v[146:149], v[170:171], off offset:16
	v_pk_fma_f32 v[104:105], v[140:141], s[30:31], v[104:105] op_sel_hi:[1,0,1]
	v_pk_fma_f32 v[102:103], v[138:139], s[30:31], v[102:103] op_sel_hi:[1,0,1]
	v_pk_fma_f32 v[136:137], v[136:137], s[30:31], v[100:101] op_sel_hi:[1,0,1]
	v_pk_fma_f32 v[134:135], v[134:135], s[30:31], v[98:99] op_sel_hi:[1,0,1]
	v_lshl_add_u64 v[154:155], v[154:155], 1, s[58:59]
	v_mul_f32_e32 v174, v136, v136
	v_add_f32_e32 v151, v134, v135
	v_fmac_f32_e32 v174, v137, v137
	s_waitcnt vmcnt(0)
	v_pk_mul_f32 v[100:101], v[112:113], v[144:145]
	v_pk_mul_f32 v[98:99], v[110:111], v[142:143]
	v_pk_mul_f32 v[138:139], v[108:109], v[148:149]
	v_pk_mul_f32 v[140:141], v[106:107], v[146:147]
	v_cvt_pk_bf16_f32 v98, v98, v99
	v_cvt_pk_bf16_f32 v99, v100, v101
	v_cvt_pk_bf16_f32 v100, v140, v141
	v_cvt_pk_bf16_f32 v101, v138, v139
	global_store_dwordx4 v[154:155], v[98:101], off
	global_store_dwordx4 v[156:157], v[102:105], off offset:512
	global_store_dwordx4 v[156:157], v[134:137], off offset:528
	global_load_dwordx4 v[138:141], v[170:171], off offset:512
	global_load_dwordx4 v[142:145], v[170:171], off offset:528
	v_add_f32_e32 v98, v110, v111
	v_add_f32_e32 v99, v113, v112
	v_mul_f32_e32 v100, v111, v111
	v_mul_f32_e32 v101, v112, v112
	v_add_f32_e32 v111, v106, v107
	v_add_f32_e32 v112, v109, v108
	v_mul_f32_e32 v107, v107, v107
	v_mul_f32_e32 v108, v108, v108
	v_mul_f32_e32 v148, v103, v103
	v_mul_f32_e32 v149, v104, v104
	v_add_f32_e32 v98, v98, v99
	v_fmac_f32_e32 v100, v110, v110
	v_fmac_f32_e32 v101, v113, v113
	v_fmac_f32_e32 v107, v106, v106
	v_fmac_f32_e32 v108, v109, v109
	v_add_f32_e32 v146, v102, v103
	v_add_f32_e32 v147, v105, v104
	v_mul_f32_e32 v157, v135, v135
	v_add_f32_e32 v99, v111, v112
	v_fmac_f32_e32 v148, v102, v102
	v_fmac_f32_e32 v149, v105, v105
	v_add_f32_e32 v98, 0, v98
	v_add_f32_e32 v100, v100, v101
	v_add_f32_e32 v101, v107, v108
	v_add_f32_e32 v156, v137, v136
	v_add_f32_e32 v106, v146, v147
	v_fmac_f32_e32 v157, v134, v134
	v_add_f32_e32 v107, v148, v149
	v_add_f32_e32 v98, v98, v99
	v_add_f32_e32 v99, v100, v101
	v_add_f32_e32 v109, v151, v156
	v_add_f32_e32 v108, v157, v174
	v_add_f32_e32 v98, v98, v106
	v_add_f32_e32 v99, v99, v107
	v_add_f32_e32 v98, v98, v109
	v_add_f32_e32 v99, v99, v108
	ds_bpermute_b32 v100, v152, v98
	ds_bpermute_b32 v101, v152, v99
	s_waitcnt lgkmcnt(0)
	v_add_f32_e32 v98, v98, v100
	v_add_f32_e32 v100, v99, v101
	ds_bpermute_b32 v99, v153, v98
	ds_bpermute_b32 v101, v153, v100
	s_waitcnt vmcnt(0)
	v_pk_mul_f32 v[104:105], v[104:105], v[140:141]
	v_pk_mul_f32 v[102:103], v[102:103], v[138:139]
	v_pk_mul_f32 v[106:107], v[136:137], v[144:145]
	v_pk_mul_f32 v[108:109], v[134:135], v[142:143]
	v_cvt_pk_bf16_f32 v102, v102, v103
	v_cvt_pk_bf16_f32 v103, v104, v105
	v_cvt_pk_bf16_f32 v104, v108, v109
	v_cvt_pk_bf16_f32 v105, v106, v107
	global_store_dwordx4 v[154:155], v[102:105], off offset:256
	s_and_saveexec_b64 s[14:15], s[40:41]
	s_cbranch_execz .LBB0_139
	s_waitcnt lgkmcnt(0)
	v_add_f32_e32 v100, v100, v101
	v_add_f32_e32 v101, v98, v99
	v_lshl_add_u64 v[98:99], v[172:173], 3, s[56:57]
	global_atomic_add_f32 v[98:99], v101, off
	global_atomic_add_f32 v[98:99], v100, off offset:4
; DI u32x4 pack8(f32x4 a, f32x4 b) { u32x4 w; w.x = pk2(a[0], a[1]); w.y = pk2(a[2], a[3]); w.z = pk2(b[0], b[1]); w.w = pk2(b[2], b[3]); return w; }
;     DI void operator()(AccRef acc, const Unit& u, int wr, int wc, int fr, int fq) const {
;     ...
;         for (int it = 0; it < 8; ++it) { const int ai = it >> 2, m = it & 3, cur = it & 1;
;             if (it + 1 < 8) { int rn_ = row0 + ((it + 1) >> 2) * 128 + ((it + 1) & 3) * 16; asm volatile("" : "+v"(rn_) :: "memory"); const size_t on = (size_t)rn_ * DM + c0;
; #pragma unroll
;                 for (int bj = 0; bj < 2; ++bj)
; #pragma unroll
;                     for (int n = 0; n < 2; ++n) xb[cur ^ 1][bj][n] = *(const f32x4*)(X + on + bj * 128 + 4 * n); }
;             int row_ = row0 + ai * 128 + m * 16; asm volatile("" : "+v"(row_)); const size_t off = (size_t)row_ * DM + c0; float s1 = 0.f, s2 = 0.f;
; #pragma unroll
;             for (int bj = 0; bj < 2; ++bj) { f32x4 y[2];
; #pragma unroll
;                 for (int n = 0; n < 2; ++n) { y[n] = xb[cur][bj][n] * ALPHA + acc[ai][bj][m][n]; *(f32x4*)(Y + off + bj * 128 + 4 * n) = y[n];
;                     s1 += (y[n][0] + y[n][1]) + (y[n][2] + y[n][3]); s2 += (y[n][0] * y[n][0] + y[n][1] * y[n][1]) + (y[n][2] * y[n][2] + y[n][3] * y[n][3]); }
;                 const f32x4 g0 = *(const f32x4*)(G + c0 + bj * 128), g1 = *(const f32x4*)(G + c0 + bj * 128 + 4);
;                 *(u32x4*)(YG + off + bj * 128) = pack8(y[0] * g0, y[1] * g1); }
;             s1 += __shfl_xor(s1, 16); s1 += __shfl_xor(s1, 32); s2 += __shfl_xor(s2, 16); s2 += __shfl_xor(s2, 32);
;             if (fq == 0) { unsafeAtomicAdd(ST + (size_t)row_ * 2, s1); unsafeAtomicAdd(ST + (size_t)row_ * 2 + 1, s2); } }
.LBB0_139:
	s_or_b64 exec, exec, s[14:15]
	v_or_b32_e32 v134, 48, v184
	v_mov_b32_e32 v98, v134
	v_pk_fma_f32 v[96:97], v[128:129], s[30:31], v[96:97] op_sel_hi:[1,0,1]
	s_waitcnt lgkmcnt(0)
	v_ashrrev_i32_e32 v99, 31, v98
	v_lshlrev_b64 v[98:99], 12, v[98:99]
	v_lshl_add_u64 v[98:99], s[10:11], 0, v[98:99]
	v_lshl_add_u64 v[102:103], v[168:169], 2, v[98:99]
	global_load_dwordx4 v[106:109], v[102:103], off offset:16
	global_load_dwordx4 v[110:113], v[102:103], off
	global_load_dwordx4 v[98:101], v[102:103], off offset:528
	s_nop 0
	global_load_dwordx4 v[102:105], v[102:103], off offset:512
	v_pk_fma_f32 v[94:95], v[126:127], s[30:31], v[94:95] op_sel_hi:[1,0,1]
	v_ashrrev_i32_e32 v151, 31, v150
	v_lshlrev_b64 v[136:137], 10, v[150:151]
	v_lshl_add_u64 v[136:137], v[136:137], 0, v[168:169]
	v_lshl_add_u64 v[138:139], v[136:137], 2, s[60:61]
	v_pk_fma_f32 v[92:93], v[124:125], s[30:31], v[92:93] op_sel_hi:[1,0,1]
	v_pk_fma_f32 v[90:91], v[122:123], s[30:31], v[90:91] op_sel_hi:[1,0,1]
	global_store_dwordx4 v[138:139], v[94:97], off
	global_store_dwordx4 v[138:139], v[90:93], off offset:16
	global_load_dwordx4 v[122:125], v[170:171], off
	global_load_dwordx4 v[126:129], v[170:171], off offset:16
	v_pk_fma_f32 v[88:89], v[120:121], s[30:31], v[88:89] op_sel_hi:[1,0,1]
	v_pk_fma_f32 v[86:87], v[118:119], s[30:31], v[86:87] op_sel_hi:[1,0,1]
	v_pk_fma_f32 v[116:117], v[116:117], s[30:31], v[84:85] op_sel_hi:[1,0,1]
	v_pk_fma_f32 v[114:115], v[114:115], s[30:31], v[82:83] op_sel_hi:[1,0,1]
	v_lshl_add_u64 v[136:137], v[136:137], 1, s[58:59]
	v_mul_f32_e32 v140, v116, v116
	v_add_f32_e32 v135, v114, v115
	v_fmac_f32_e32 v140, v117, v117
	s_waitcnt vmcnt(0)
	v_pk_mul_f32 v[84:85], v[96:97], v[124:125]
	v_pk_mul_f32 v[82:83], v[94:95], v[122:123]
	v_pk_mul_f32 v[118:119], v[92:93], v[128:129]
	v_pk_mul_f32 v[120:121], v[90:91], v[126:127]
	v_cvt_pk_bf16_f32 v82, v82, v83
	v_cvt_pk_bf16_f32 v83, v84, v85
	v_cvt_pk_bf16_f32 v84, v120, v121
	v_cvt_pk_bf16_f32 v85, v118, v119
	global_store_dwordx4 v[136:137], v[82:85], off
	global_store_dwordx4 v[138:139], v[86:89], off offset:512
	global_store_dwordx4 v[138:139], v[114:117], off offset:528
	global_load_dwordx4 v[118:121], v[170:171], off offset:512
	global_load_dwordx4 v[122:125], v[170:171], off offset:528
	v_add_f32_e32 v82, v94, v95
	v_add_f32_e32 v83, v97, v96
	v_mul_f32_e32 v84, v95, v95
	v_mul_f32_e32 v85, v96, v96
	v_add_f32_e32 v95, v90, v91
	v_add_f32_e32 v96, v93, v92
	v_mul_f32_e32 v91, v91, v91
	v_mul_f32_e32 v92, v92, v92
	v_mul_f32_e32 v128, v87, v87
	v_mul_f32_e32 v129, v88, v88
	v_add_f32_e32 v82, v82, v83
	v_fmac_f32_e32 v84, v94, v94
	v_fmac_f32_e32 v85, v97, v97
	v_fmac_f32_e32 v91, v90, v90
	v_fmac_f32_e32 v92, v93, v93
	v_add_f32_e32 v126, v86, v87
	v_add_f32_e32 v127, v89, v88
	v_mul_f32_e32 v139, v115, v115
	v_add_f32_e32 v83, v95, v96
	v_fmac_f32_e32 v128, v86, v86
	v_fmac_f32_e32 v129, v89, v89
	v_add_f32_e32 v82, 0, v82
	v_add_f32_e32 v84, v84, v85
	v_add_f32_e32 v85, v91, v92
	v_add_f32_e32 v138, v117, v116
	v_add_f32_e32 v90, v126, v127
	v_fmac_f32_e32 v139, v114, v114
	v_add_f32_e32 v91, v128, v129
	v_add_f32_e32 v82, v82, v83
	v_add_f32_e32 v83, v84, v85
	v_add_f32_e32 v93, v135, v138
	v_add_f32_e32 v92, v139, v140
	v_add_f32_e32 v82, v82, v90
	v_add_f32_e32 v83, v83, v91
	v_add_f32_e32 v82, v82, v93
	v_add_f32_e32 v83, v83, v92
	ds_bpermute_b32 v84, v152, v82
	ds_bpermute_b32 v85, v152, v83
	s_waitcnt lgkmcnt(0)
	v_add_f32_e32 v82, v82, v84
	v_add_f32_e32 v84, v83, v85
	ds_bpermute_b32 v83, v153, v82
	ds_bpermute_b32 v85, v153, v84
	s_waitcnt vmcnt(0)
	v_pk_mul_f32 v[88:89], v[88:89], v[120:121]
	v_pk_mul_f32 v[86:87], v[86:87], v[118:119]
	v_pk_mul_f32 v[90:91], v[116:117], v[124:125]
	v_pk_mul_f32 v[92:93], v[114:115], v[122:123]
	v_cvt_pk_bf16_f32 v86, v86, v87
	v_cvt_pk_bf16_f32 v87, v88, v89
	v_cvt_pk_bf16_f32 v88, v92, v93
	v_cvt_pk_bf16_f32 v89, v90, v91
	global_store_dwordx4 v[136:137], v[86:89], off offset:256
	s_and_saveexec_b64 s[14:15], s[40:41]
	s_cbranch_execz .LBB0_141
	s_waitcnt lgkmcnt(0)
	v_add_f32_e32 v84, v84, v85
	v_add_f32_e32 v85, v82, v83
	v_lshl_add_u64 v[82:83], v[150:151], 3, s[56:57]
	global_atomic_add_f32 v[82:83], v85, off
	global_atomic_add_f32 v[82:83], v84, off offset:4
; DI u32x4 pack8(f32x4 a, f32x4 b) { u32x4 w; w.x = pk2(a[0], a[1]); w.y = pk2(a[2], a[3]); w.z = pk2(b[0], b[1]); w.w = pk2(b[2], b[3]); return w; }
;     DI void operator()(AccRef acc, const Unit& u, int wr, int wc, int fr, int fq) const {
;     ...
;         for (int it = 0; it < 8; ++it) { const int ai = it >> 2, m = it & 3, cur = it & 1;
;             if (it + 1 < 8) { int rn_ = row0 + ((it + 1) >> 2) * 128 + ((it + 1) & 3) * 16; asm volatile("" : "+v"(rn_) :: "memory"); const size_t on = (size_t)rn_ * DM + c0;
; #pragma unroll
;                 for (int bj = 0; bj < 2; ++bj)
; #pragma unroll
;                     for (int n = 0; n < 2; ++n) xb[cur ^ 1][bj][n] = *(const f32x4*)(X + on + bj * 128 + 4 * n); }
;             int row_ = row0 + ai * 128 + m * 16; asm volatile("" : "+v"(row_)); const size_t off = (size_t)row_ * DM + c0; float s1 = 0.f, s2 = 0.f;
; #pragma unroll
;             for (int bj = 0; bj < 2; ++bj) { f32x4 y[2];
; #pragma unroll
;                 for (int n = 0; n < 2; ++n) { y[n] = xb[cur][bj][n] * ALPHA + acc[ai][bj][m][n]; *(f32x4*)(Y + off + bj * 128 + 4 * n) = y[n];
;                     s1 += (y[n][0] + y[n][1]) + (y[n][2] + y[n][3]); s2 += (y[n][0] * y[n][0] + y[n][1] * y[n][1]) + (y[n][2] * y[n][2] + y[n][3] * y[n][3]); }
;                 const f32x4 g0 = *(const f32x4*)(G + c0 + bj * 128), g1 = *(const f32x4*)(G + c0 + bj * 128 + 4);
;                 *(u32x4*)(YG + off + bj * 128) = pack8(y[0] * g0, y[1] * g1); }
;             s1 += __shfl_xor(s1, 16); s1 += __shfl_xor(s1, 32); s2 += __shfl_xor(s2, 16); s2 += __shfl_xor(s2, 32);
;             if (fq == 0) { unsafeAtomicAdd(ST + (size_t)row_ * 2, s1); unsafeAtomicAdd(ST + (size_t)row_ * 2 + 1, s2); } }
.LBB0_141:
	s_or_b64 exec, exec, s[14:15]
	v_add_u32_e32 v114, 0x80, v184
	v_mov_b32_e32 v82, v114
	v_pk_fma_f32 v[80:81], v[112:113], s[30:31], v[80:81] op_sel_hi:[1,0,1]
	s_waitcnt lgkmcnt(0)
	v_ashrrev_i32_e32 v83, 31, v82
	v_lshlrev_b64 v[82:83], 12, v[82:83]
	v_lshl_add_u64 v[82:83], s[10:11], 0, v[82:83]
	v_lshl_add_u64 v[86:87], v[168:169], 2, v[82:83]
	global_load_dwordx4 v[90:93], v[86:87], off offset:16
	global_load_dwordx4 v[94:97], v[86:87], off
	global_load_dwordx4 v[82:85], v[86:87], off offset:528
	s_nop 0
	global_load_dwordx4 v[86:89], v[86:87], off offset:512
	v_pk_fma_f32 v[78:79], v[110:111], s[30:31], v[78:79] op_sel_hi:[1,0,1]
	v_ashrrev_i32_e32 v135, 31, v134
	v_lshlrev_b64 v[116:117], 10, v[134:135]
	v_lshl_add_u64 v[116:117], v[116:117], 0, v[168:169]
	v_lshl_add_u64 v[118:119], v[116:117], 2, s[60:61]
	v_pk_fma_f32 v[76:77], v[108:109], s[30:31], v[76:77] op_sel_hi:[1,0,1]
	v_pk_fma_f32 v[74:75], v[106:107], s[30:31], v[74:75] op_sel_hi:[1,0,1]
	global_store_dwordx4 v[118:119], v[78:81], off
	global_store_dwordx4 v[118:119], v[74:77], off offset:16
	global_load_dwordx4 v[106:109], v[170:171], off
	global_load_dwordx4 v[110:113], v[170:171], off offset:16
	v_pk_fma_f32 v[72:73], v[104:105], s[30:31], v[72:73] op_sel_hi:[1,0,1]
	v_pk_fma_f32 v[70:71], v[102:103], s[30:31], v[70:71] op_sel_hi:[1,0,1]
	v_pk_fma_f32 v[100:101], v[100:101], s[30:31], v[68:69] op_sel_hi:[1,0,1]
	v_pk_fma_f32 v[98:99], v[98:99], s[30:31], v[66:67] op_sel_hi:[1,0,1]
	v_lshl_add_u64 v[116:117], v[116:117], 1, s[58:59]
	v_mul_f32_e32 v120, v100, v100
	v_add_f32_e32 v115, v98, v99
	v_fmac_f32_e32 v120, v101, v101
	s_waitcnt vmcnt(0)
	v_pk_mul_f32 v[68:69], v[80:81], v[108:109]
	v_pk_mul_f32 v[66:67], v[78:79], v[106:107]
	v_pk_mul_f32 v[102:103], v[76:77], v[112:113]
	v_pk_mul_f32 v[104:105], v[74:75], v[110:111]
	v_cvt_pk_bf16_f32 v66, v66, v67
	v_cvt_pk_bf16_f32 v67, v68, v69
	v_cvt_pk_bf16_f32 v68, v104, v105
	v_cvt_pk_bf16_f32 v69, v102, v103
	global_store_dwordx4 v[116:117], v[66:69], off
	global_store_dwordx4 v[118:119], v[70:73], off offset:512
	global_store_dwordx4 v[118:119], v[98:101], off offset:528
	global_load_dwordx4 v[102:105], v[170:171], off offset:512
	global_load_dwordx4 v[106:109], v[170:171], off offset:528
	v_add_f32_e32 v66, v78, v79
	v_add_f32_e32 v67, v81, v80
	v_mul_f32_e32 v68, v79, v79
	v_mul_f32_e32 v69, v80, v80
	v_add_f32_e32 v79, v74, v75
	v_add_f32_e32 v80, v77, v76
	v_mul_f32_e32 v75, v75, v75
	v_mul_f32_e32 v76, v76, v76
	v_mul_f32_e32 v112, v71, v71
	v_mul_f32_e32 v113, v72, v72
	v_add_f32_e32 v66, v66, v67
	v_fmac_f32_e32 v68, v78, v78
	v_fmac_f32_e32 v69, v81, v81
	v_fmac_f32_e32 v75, v74, v74
	v_fmac_f32_e32 v76, v77, v77
	v_add_f32_e32 v110, v70, v71
	v_add_f32_e32 v111, v73, v72
	v_mul_f32_e32 v119, v99, v99
	v_add_f32_e32 v67, v79, v80
	v_fmac_f32_e32 v112, v70, v70
	v_fmac_f32_e32 v113, v73, v73
	v_add_f32_e32 v66, 0, v66
	v_add_f32_e32 v68, v68, v69
	v_add_f32_e32 v69, v75, v76
	v_add_f32_e32 v118, v101, v100
	v_add_f32_e32 v74, v110, v111
	v_fmac_f32_e32 v119, v98, v98
	v_add_f32_e32 v75, v112, v113
	v_add_f32_e32 v66, v66, v67
	v_add_f32_e32 v67, v68, v69
	v_add_f32_e32 v77, v115, v118
	v_add_f32_e32 v76, v119, v120
	v_add_f32_e32 v66, v66, v74
	v_add_f32_e32 v67, v67, v75
	v_add_f32_e32 v66, v66, v77
	v_add_f32_e32 v67, v67, v76
	ds_bpermute_b32 v68, v152, v66
	ds_bpermute_b32 v69, v152, v67
	s_waitcnt lgkmcnt(0)
	v_add_f32_e32 v66, v66, v68
	v_add_f32_e32 v68, v67, v69
	ds_bpermute_b32 v67, v153, v66
	ds_bpermute_b32 v69, v153, v68
	s_waitcnt vmcnt(0)
	v_pk_mul_f32 v[72:73], v[72:73], v[104:105]
	v_pk_mul_f32 v[70:71], v[70:71], v[102:103]
	v_pk_mul_f32 v[74:75], v[100:101], v[108:109]
	v_pk_mul_f32 v[76:77], v[98:99], v[106:107]
	v_cvt_pk_bf16_f32 v70, v70, v71
	v_cvt_pk_bf16_f32 v71, v72, v73
	v_cvt_pk_bf16_f32 v72, v76, v77
	v_cvt_pk_bf16_f32 v73, v74, v75
	global_store_dwordx4 v[116:117], v[70:73], off offset:256
	s_and_saveexec_b64 s[14:15], s[40:41]
	s_cbranch_execz .LBB0_143
	s_waitcnt lgkmcnt(0)
	v_add_f32_e32 v68, v68, v69
	v_add_f32_e32 v69, v66, v67
	v_lshl_add_u64 v[66:67], v[134:135], 3, s[56:57]
	global_atomic_add_f32 v[66:67], v69, off
	global_atomic_add_f32 v[66:67], v68, off offset:4
.LBB0_143:
	s_or_b64 exec, exec, s[14:15]
	v_or_b32_e32 v98, 16, v114
	v_mov_b32_e32 v66, v98
	v_mov_b32_e32 v100, v114
	s_waitcnt lgkmcnt(0)
	v_ashrrev_i32_e32 v67, 31, v66
	v_lshlrev_b64 v[66:67], 12, v[66:67]
	v_lshl_add_u64 v[66:67], s[10:11], 0, v[66:67]
	v_lshl_add_u64 v[70:71], v[168:169], 2, v[66:67]
	global_load_dwordx4 v[74:77], v[70:71], off offset:16
	global_load_dwordx4 v[78:81], v[70:71], off
	global_load_dwordx4 v[66:69], v[70:71], off offset:528
	s_nop 0
	global_load_dwordx4 v[70:73], v[70:71], off offset:512
	v_pk_fma_f32 v[64:65], v[96:97], s[30:31], v[64:65] op_sel_hi:[1,0,1]
	v_ashrrev_i32_e32 v101, 31, v100
	v_lshlrev_b64 v[102:103], 10, v[100:101]
	v_lshl_add_u64 v[102:103], v[102:103], 0, v[168:169]
	v_lshl_add_u64 v[104:105], v[102:103], 2, s[60:61]
	v_pk_fma_f32 v[62:63], v[94:95], s[30:31], v[62:63] op_sel_hi:[1,0,1]
	v_pk_fma_f32 v[60:61], v[92:93], s[30:31], v[60:61] op_sel_hi:[1,0,1]
	v_pk_fma_f32 v[58:59], v[90:91], s[30:31], v[58:59] op_sel_hi:[1,0,1]
	global_store_dwordx4 v[104:105], v[62:65], off
	global_store_dwordx4 v[104:105], v[58:61], off offset:16
	global_load_dwordx4 v[90:93], v[170:171], off
	global_load_dwordx4 v[94:97], v[170:171], off offset:16
	v_pk_fma_f32 v[56:57], v[88:89], s[30:31], v[56:57] op_sel_hi:[1,0,1]
	v_pk_fma_f32 v[54:55], v[86:87], s[30:31], v[54:55] op_sel_hi:[1,0,1]
	v_pk_fma_f32 v[84:85], v[84:85], s[30:31], v[52:53] op_sel_hi:[1,0,1]
	v_pk_fma_f32 v[82:83], v[82:83], s[30:31], v[50:51] op_sel_hi:[1,0,1]
	v_lshl_add_u64 v[102:103], v[102:103], 1, s[58:59]
	v_mul_f32_e32 v106, v84, v84
	v_add_f32_e32 v99, v82, v83
	v_fmac_f32_e32 v106, v85, v85
	s_waitcnt vmcnt(0)
; DI u32x4 pack8(f32x4 a, f32x4 b) { u32x4 w; w.x = pk2(a[0], a[1]); w.y = pk2(a[2], a[3]); w.z = pk2(b[0], b[1]); w.w = pk2(b[2], b[3]); return w; }
;     DI void operator()(AccRef acc, const Unit& u, int wr, int wc, int fr, int fq) const {
;     ...
;         for (int it = 0; it < 8; ++it) { const int ai = it >> 2, m = it & 3, cur = it & 1;
;             if (it + 1 < 8) { int rn_ = row0 + ((it + 1) >> 2) * 128 + ((it + 1) & 3) * 16; asm volatile("" : "+v"(rn_) :: "memory"); const size_t on = (size_t)rn_ * DM + c0;
; #pragma unroll
;                 for (int bj = 0; bj < 2; ++bj)
; #pragma unroll
;                     for (int n = 0; n < 2; ++n) xb[cur ^ 1][bj][n] = *(const f32x4*)(X + on + bj * 128 + 4 * n); }
;             int row_ = row0 + ai * 128 + m * 16; asm volatile("" : "+v"(row_)); const size_t off = (size_t)row_ * DM + c0; float s1 = 0.f, s2 = 0.f;
; #pragma unroll
;             for (int bj = 0; bj < 2; ++bj) { f32x4 y[2];
; #pragma unroll
;                 for (int n = 0; n < 2; ++n) { y[n] = xb[cur][bj][n] * ALPHA + acc[ai][bj][m][n]; *(f32x4*)(Y + off + bj * 128 + 4 * n) = y[n];
;                     s1 += (y[n][0] + y[n][1]) + (y[n][2] + y[n][3]); s2 += (y[n][0] * y[n][0] + y[n][1] * y[n][1]) + (y[n][2] * y[n][2] + y[n][3] * y[n][3]); }
;                 const f32x4 g0 = *(const f32x4*)(G + c0 + bj * 128), g1 = *(const f32x4*)(G + c0 + bj * 128 + 4);
;                 *(u32x4*)(YG + off + bj * 128) = pack8(y[0] * g0, y[1] * g1); }
;             s1 += __shfl_xor(s1, 16); s1 += __shfl_xor(s1, 32); s2 += __shfl_xor(s2, 16); s2 += __shfl_xor(s2, 32);
;             if (fq == 0) { unsafeAtomicAdd(ST + (size_t)row_ * 2, s1); unsafeAtomicAdd(ST + (size_t)row_ * 2 + 1, s2); } }
	v_pk_mul_f32 v[52:53], v[64:65], v[92:93]
	v_pk_mul_f32 v[50:51], v[62:63], v[90:91]
	v_pk_mul_f32 v[86:87], v[60:61], v[96:97]
	v_pk_mul_f32 v[88:89], v[58:59], v[94:95]
	v_cvt_pk_bf16_f32 v50, v50, v51
	v_cvt_pk_bf16_f32 v51, v52, v53
	v_cvt_pk_bf16_f32 v52, v88, v89
	v_cvt_pk_bf16_f32 v53, v86, v87
	global_store_dwordx4 v[102:103], v[50:53], off
	global_store_dwordx4 v[104:105], v[54:57], off offset:512
	global_store_dwordx4 v[104:105], v[82:85], off offset:528
	global_load_dwordx4 v[86:89], v[170:171], off offset:512
	global_load_dwordx4 v[90:93], v[170:171], off offset:528
	v_add_f32_e32 v50, v62, v63
	v_add_f32_e32 v51, v65, v64
	v_mul_f32_e32 v52, v63, v63
	v_mul_f32_e32 v53, v64, v64
	v_add_f32_e32 v63, v58, v59
	v_add_f32_e32 v64, v61, v60
	v_mul_f32_e32 v59, v59, v59
	v_mul_f32_e32 v60, v60, v60
	v_mul_f32_e32 v96, v55, v55
	v_mul_f32_e32 v97, v56, v56
	v_add_f32_e32 v50, v50, v51
	v_fmac_f32_e32 v52, v62, v62
	v_fmac_f32_e32 v53, v65, v65
	v_fmac_f32_e32 v59, v58, v58
	v_fmac_f32_e32 v60, v61, v61
	v_add_f32_e32 v94, v54, v55
	v_add_f32_e32 v95, v57, v56
	v_mul_f32_e32 v105, v83, v83
	v_add_f32_e32 v51, v63, v64
	v_fmac_f32_e32 v96, v54, v54
	v_fmac_f32_e32 v97, v57, v57
	v_add_f32_e32 v50, 0, v50
	v_add_f32_e32 v52, v52, v53
	v_add_f32_e32 v53, v59, v60
	v_add_f32_e32 v104, v85, v84
	v_add_f32_e32 v58, v94, v95
	v_fmac_f32_e32 v105, v82, v82
	v_add_f32_e32 v59, v96, v97
	v_add_f32_e32 v50, v50, v51
	v_add_f32_e32 v51, v52, v53
	v_add_f32_e32 v61, v99, v104
	v_add_f32_e32 v60, v105, v106
	v_add_f32_e32 v50, v50, v58
	v_add_f32_e32 v51, v51, v59
	v_add_f32_e32 v50, v50, v61
	v_add_f32_e32 v51, v51, v60
	ds_bpermute_b32 v52, v152, v50
	ds_bpermute_b32 v53, v152, v51
	s_waitcnt lgkmcnt(0)
	v_add_f32_e32 v50, v50, v52
	v_add_f32_e32 v52, v51, v53
	ds_bpermute_b32 v51, v153, v50
	ds_bpermute_b32 v53, v153, v52
	s_waitcnt vmcnt(0)
	v_pk_mul_f32 v[56:57], v[56:57], v[88:89]
	v_pk_mul_f32 v[54:55], v[54:55], v[86:87]
	v_pk_mul_f32 v[58:59], v[84:85], v[92:93]
	v_pk_mul_f32 v[60:61], v[82:83], v[90:91]
	v_cvt_pk_bf16_f32 v54, v54, v55
	v_cvt_pk_bf16_f32 v55, v56, v57
	v_cvt_pk_bf16_f32 v56, v60, v61
	v_cvt_pk_bf16_f32 v57, v58, v59
	global_store_dwordx4 v[102:103], v[54:57], off offset:256
	s_and_saveexec_b64 s[14:15], s[40:41]
	s_cbranch_execz .LBB0_145
	s_waitcnt lgkmcnt(0)
	v_add_f32_e32 v52, v52, v53
	v_add_f32_e32 v53, v50, v51
	v_lshl_add_u64 v[50:51], v[100:101], 3, s[56:57]
	global_atomic_add_f32 v[50:51], v53, off
	global_atomic_add_f32 v[50:51], v52, off offset:4
.LBB0_145:
	s_or_b64 exec, exec, s[14:15]
	v_or_b32_e32 v82, 32, v114
	v_mov_b32_e32 v50, v82
	v_pk_fma_f32 v[48:49], v[80:81], s[30:31], v[48:49] op_sel_hi:[1,0,1]
	s_waitcnt lgkmcnt(0)
	v_ashrrev_i32_e32 v51, 31, v50
	v_lshlrev_b64 v[50:51], 12, v[50:51]
	v_lshl_add_u64 v[50:51], s[10:11], 0, v[50:51]
	v_lshl_add_u64 v[54:55], v[168:169], 2, v[50:51]
	global_load_dwordx4 v[58:61], v[54:55], off offset:16
	global_load_dwordx4 v[62:65], v[54:55], off
	global_load_dwordx4 v[50:53], v[54:55], off offset:528
	s_nop 0
	global_load_dwordx4 v[54:57], v[54:55], off offset:512
	v_pk_fma_f32 v[46:47], v[78:79], s[30:31], v[46:47] op_sel_hi:[1,0,1]
	v_ashrrev_i32_e32 v99, 31, v98
	v_lshlrev_b64 v[84:85], 10, v[98:99]
	v_lshl_add_u64 v[84:85], v[84:85], 0, v[168:169]
	v_lshl_add_u64 v[86:87], v[84:85], 2, s[60:61]
	v_pk_fma_f32 v[44:45], v[76:77], s[30:31], v[44:45] op_sel_hi:[1,0,1]
	v_pk_fma_f32 v[42:43], v[74:75], s[30:31], v[42:43] op_sel_hi:[1,0,1]
	global_store_dwordx4 v[86:87], v[46:49], off
	global_store_dwordx4 v[86:87], v[42:45], off offset:16
	global_load_dwordx4 v[74:77], v[170:171], off
	global_load_dwordx4 v[78:81], v[170:171], off offset:16
	v_pk_fma_f32 v[40:41], v[72:73], s[30:31], v[40:41] op_sel_hi:[1,0,1]
	v_pk_fma_f32 v[38:39], v[70:71], s[30:31], v[38:39] op_sel_hi:[1,0,1]
	v_pk_fma_f32 v[68:69], v[68:69], s[30:31], v[36:37] op_sel_hi:[1,0,1]
	v_pk_fma_f32 v[66:67], v[66:67], s[30:31], v[34:35] op_sel_hi:[1,0,1]
	v_lshl_add_u64 v[84:85], v[84:85], 1, s[58:59]
	v_mul_f32_e32 v88, v68, v68
	v_add_f32_e32 v83, v66, v67
	v_fmac_f32_e32 v88, v69, v69
	s_waitcnt vmcnt(0)
	v_pk_mul_f32 v[36:37], v[48:49], v[76:77]
	v_pk_mul_f32 v[34:35], v[46:47], v[74:75]
	v_pk_mul_f32 v[70:71], v[44:45], v[80:81]
	v_pk_mul_f32 v[72:73], v[42:43], v[78:79]
	v_cvt_pk_bf16_f32 v34, v34, v35
	v_cvt_pk_bf16_f32 v35, v36, v37
	v_cvt_pk_bf16_f32 v36, v72, v73
	v_cvt_pk_bf16_f32 v37, v70, v71
	global_store_dwordx4 v[84:85], v[34:37], off
	global_store_dwordx4 v[86:87], v[38:41], off offset:512
	global_store_dwordx4 v[86:87], v[66:69], off offset:528
	global_load_dwordx4 v[70:73], v[170:171], off offset:512
	global_load_dwordx4 v[74:77], v[170:171], off offset:528
	v_add_f32_e32 v34, v46, v47
	v_add_f32_e32 v35, v49, v48
	v_mul_f32_e32 v36, v47, v47
	v_mul_f32_e32 v37, v48, v48
	v_add_f32_e32 v47, v42, v43
	v_add_f32_e32 v48, v45, v44
	v_mul_f32_e32 v43, v43, v43
	v_mul_f32_e32 v44, v44, v44
	v_mul_f32_e32 v80, v39, v39
	v_mul_f32_e32 v81, v40, v40
	v_add_f32_e32 v34, v34, v35
	v_fmac_f32_e32 v36, v46, v46
	v_fmac_f32_e32 v37, v49, v49
	v_fmac_f32_e32 v43, v42, v42
	v_fmac_f32_e32 v44, v45, v45
	v_add_f32_e32 v78, v38, v39
	v_add_f32_e32 v79, v41, v40
	v_mul_f32_e32 v87, v67, v67
	v_add_f32_e32 v35, v47, v48
	v_fmac_f32_e32 v80, v38, v38
	v_fmac_f32_e32 v81, v41, v41
	v_add_f32_e32 v34, 0, v34
	v_add_f32_e32 v36, v36, v37
	v_add_f32_e32 v37, v43, v44
	v_add_f32_e32 v86, v69, v68
	v_add_f32_e32 v42, v78, v79
	v_fmac_f32_e32 v87, v66, v66
	v_add_f32_e32 v43, v80, v81
	v_add_f32_e32 v34, v34, v35
	v_add_f32_e32 v35, v36, v37
	v_add_f32_e32 v45, v83, v86
	v_add_f32_e32 v44, v87, v88
	v_add_f32_e32 v34, v34, v42
	v_add_f32_e32 v35, v35, v43
	v_add_f32_e32 v34, v34, v45
	v_add_f32_e32 v35, v35, v44
	ds_bpermute_b32 v36, v152, v34
	ds_bpermute_b32 v37, v152, v35
	s_waitcnt lgkmcnt(0)
	v_add_f32_e32 v34, v34, v36
	v_add_f32_e32 v36, v35, v37
	ds_bpermute_b32 v35, v153, v34
	ds_bpermute_b32 v37, v153, v36
	s_waitcnt vmcnt(0)
	v_pk_mul_f32 v[40:41], v[40:41], v[72:73]
	v_pk_mul_f32 v[38:39], v[38:39], v[70:71]
	v_pk_mul_f32 v[42:43], v[68:69], v[76:77]
	v_pk_mul_f32 v[44:45], v[66:67], v[74:75]
	v_cvt_pk_bf16_f32 v38, v38, v39
	v_cvt_pk_bf16_f32 v39, v40, v41
	v_cvt_pk_bf16_f32 v40, v44, v45
	v_cvt_pk_bf16_f32 v41, v42, v43
	global_store_dwordx4 v[84:85], v[38:41], off offset:256
	s_and_saveexec_b64 s[14:15], s[40:41]
	s_cbranch_execz .LBB0_147
	s_waitcnt lgkmcnt(0)
	v_add_f32_e32 v36, v36, v37
	v_add_f32_e32 v37, v34, v35
	v_lshl_add_u64 v[34:35], v[98:99], 3, s[56:57]
	global_atomic_add_f32 v[34:35], v37, off
	global_atomic_add_f32 v[34:35], v36, off offset:4
; DI u32x4 pack8(f32x4 a, f32x4 b) { u32x4 w; w.x = pk2(a[0], a[1]); w.y = pk2(a[2], a[3]); w.z = pk2(b[0], b[1]); w.w = pk2(b[2], b[3]); return w; }
;     DI void operator()(AccRef acc, const Unit& u, int wr, int wc, int fr, int fq) const {
;     ...
;         for (int it = 0; it < 8; ++it) { const int ai = it >> 2, m = it & 3, cur = it & 1;
;             if (it + 1 < 8) { int rn_ = row0 + ((it + 1) >> 2) * 128 + ((it + 1) & 3) * 16; asm volatile("" : "+v"(rn_) :: "memory"); const size_t on = (size_t)rn_ * DM + c0;
; #pragma unroll
;                 for (int bj = 0; bj < 2; ++bj)
; #pragma unroll
;                     for (int n = 0; n < 2; ++n) xb[cur ^ 1][bj][n] = *(const f32x4*)(X + on + bj * 128 + 4 * n); }
;             int row_ = row0 + ai * 128 + m * 16; asm volatile("" : "+v"(row_)); const size_t off = (size_t)row_ * DM + c0; float s1 = 0.f, s2 = 0.f;
; #pragma unroll
;             for (int bj = 0; bj < 2; ++bj) { f32x4 y[2];
; #pragma unroll
;                 for (int n = 0; n < 2; ++n) { y[n] = xb[cur][bj][n] * ALPHA + acc[ai][bj][m][n]; *(f32x4*)(Y + off + bj * 128 + 4 * n) = y[n];
;                     s1 += (y[n][0] + y[n][1]) + (y[n][2] + y[n][3]); s2 += (y[n][0] * y[n][0] + y[n][1] * y[n][1]) + (y[n][2] * y[n][2] + y[n][3] * y[n][3]); }
;                 const f32x4 g0 = *(const f32x4*)(G + c0 + bj * 128), g1 = *(const f32x4*)(G + c0 + bj * 128 + 4);
;                 *(u32x4*)(YG + off + bj * 128) = pack8(y[0] * g0, y[1] * g1); }
;             s1 += __shfl_xor(s1, 16); s1 += __shfl_xor(s1, 32); s2 += __shfl_xor(s2, 16); s2 += __shfl_xor(s2, 32);
;             if (fq == 0) { unsafeAtomicAdd(ST + (size_t)row_ * 2, s1); unsafeAtomicAdd(ST + (size_t)row_ * 2 + 1, s2); } }
.LBB0_147:
	s_or_b64 exec, exec, s[14:15]
	v_or_b32_e32 v66, 48, v114
	v_mov_b32_e32 v34, v66
	v_pk_fma_f32 v[32:33], v[64:65], s[30:31], v[32:33] op_sel_hi:[1,0,1]
	s_waitcnt lgkmcnt(0)
	v_ashrrev_i32_e32 v35, 31, v34
	v_lshlrev_b64 v[34:35], 12, v[34:35]
	v_lshl_add_u64 v[34:35], s[10:11], 0, v[34:35]
	v_lshl_add_u64 v[38:39], v[168:169], 2, v[34:35]
	global_load_dwordx4 v[42:45], v[38:39], off offset:16
	global_load_dwordx4 v[46:49], v[38:39], off
	global_load_dwordx4 v[34:37], v[38:39], off offset:528
	s_nop 0
	global_load_dwordx4 v[38:41], v[38:39], off offset:512
	v_pk_fma_f32 v[30:31], v[62:63], s[30:31], v[30:31] op_sel_hi:[1,0,1]
	v_ashrrev_i32_e32 v83, 31, v82
	v_lshlrev_b64 v[68:69], 10, v[82:83]
	v_lshl_add_u64 v[68:69], v[68:69], 0, v[168:169]
	v_lshl_add_u64 v[70:71], v[68:69], 2, s[60:61]
	v_pk_fma_f32 v[28:29], v[60:61], s[30:31], v[28:29] op_sel_hi:[1,0,1]
	v_pk_fma_f32 v[26:27], v[58:59], s[30:31], v[26:27] op_sel_hi:[1,0,1]
	global_store_dwordx4 v[70:71], v[30:33], off
	global_store_dwordx4 v[70:71], v[26:29], off offset:16
	global_load_dwordx4 v[58:61], v[170:171], off
	global_load_dwordx4 v[62:65], v[170:171], off offset:16
	v_pk_fma_f32 v[24:25], v[56:57], s[30:31], v[24:25] op_sel_hi:[1,0,1]
	v_pk_fma_f32 v[22:23], v[54:55], s[30:31], v[22:23] op_sel_hi:[1,0,1]
	v_pk_fma_f32 v[52:53], v[52:53], s[30:31], v[20:21] op_sel_hi:[1,0,1]
	v_pk_fma_f32 v[50:51], v[50:51], s[30:31], v[18:19] op_sel_hi:[1,0,1]
	v_lshl_add_u64 v[68:69], v[68:69], 1, s[58:59]
	v_mul_f32_e32 v72, v52, v52
	v_add_f32_e32 v67, v50, v51
	v_fmac_f32_e32 v72, v53, v53
	s_waitcnt vmcnt(0)
	v_pk_mul_f32 v[20:21], v[32:33], v[60:61]
	v_pk_mul_f32 v[18:19], v[30:31], v[58:59]
	v_pk_mul_f32 v[54:55], v[28:29], v[64:65]
	v_pk_mul_f32 v[56:57], v[26:27], v[62:63]
	v_cvt_pk_bf16_f32 v18, v18, v19
	v_cvt_pk_bf16_f32 v19, v20, v21
	v_cvt_pk_bf16_f32 v20, v56, v57
	v_cvt_pk_bf16_f32 v21, v54, v55
	global_store_dwordx4 v[68:69], v[18:21], off
	global_store_dwordx4 v[70:71], v[22:25], off offset:512
	global_store_dwordx4 v[70:71], v[50:53], off offset:528
	global_load_dwordx4 v[54:57], v[170:171], off offset:512
	global_load_dwordx4 v[58:61], v[170:171], off offset:528
	v_add_f32_e32 v18, v30, v31
	v_add_f32_e32 v19, v33, v32
	v_mul_f32_e32 v20, v31, v31
	v_mul_f32_e32 v21, v32, v32
	v_add_f32_e32 v31, v26, v27
	v_add_f32_e32 v32, v29, v28
	v_mul_f32_e32 v27, v27, v27
	v_mul_f32_e32 v28, v28, v28
	v_mul_f32_e32 v64, v23, v23
	v_mul_f32_e32 v65, v24, v24
	v_add_f32_e32 v18, v18, v19
	v_fmac_f32_e32 v20, v30, v30
	v_fmac_f32_e32 v21, v33, v33
	v_fmac_f32_e32 v27, v26, v26
	v_fmac_f32_e32 v28, v29, v29
	v_add_f32_e32 v62, v22, v23
	v_add_f32_e32 v63, v25, v24
	v_mul_f32_e32 v71, v51, v51
	v_add_f32_e32 v19, v31, v32
	v_fmac_f32_e32 v64, v22, v22
	v_fmac_f32_e32 v65, v25, v25
	v_add_f32_e32 v18, 0, v18
	v_add_f32_e32 v20, v20, v21
	v_add_f32_e32 v21, v27, v28
	v_add_f32_e32 v70, v53, v52
	v_add_f32_e32 v26, v62, v63
	v_fmac_f32_e32 v71, v50, v50
	v_add_f32_e32 v27, v64, v65
	v_add_f32_e32 v18, v18, v19
	v_add_f32_e32 v19, v20, v21
	v_add_f32_e32 v29, v67, v70
	v_add_f32_e32 v28, v71, v72
	v_add_f32_e32 v18, v18, v26
	v_add_f32_e32 v19, v19, v27
	v_add_f32_e32 v18, v18, v29
	v_add_f32_e32 v19, v19, v28
	ds_bpermute_b32 v20, v152, v18
	ds_bpermute_b32 v21, v152, v19
	s_waitcnt lgkmcnt(0)
	v_add_f32_e32 v18, v18, v20
	v_add_f32_e32 v20, v19, v21
	ds_bpermute_b32 v19, v153, v18
	ds_bpermute_b32 v21, v153, v20
	s_waitcnt vmcnt(0)
	v_pk_mul_f32 v[24:25], v[24:25], v[56:57]
	v_pk_mul_f32 v[22:23], v[22:23], v[54:55]
	v_pk_mul_f32 v[26:27], v[52:53], v[60:61]
	v_pk_mul_f32 v[28:29], v[50:51], v[58:59]
	v_cvt_pk_bf16_f32 v22, v22, v23
	v_cvt_pk_bf16_f32 v23, v24, v25
	v_cvt_pk_bf16_f32 v24, v28, v29
	v_cvt_pk_bf16_f32 v25, v26, v27
	global_store_dwordx4 v[68:69], v[22:25], off offset:256
	s_and_saveexec_b64 s[14:15], s[40:41]
	s_cbranch_execz .LBB0_149
	s_waitcnt lgkmcnt(0)
	v_add_f32_e32 v20, v20, v21
	v_add_f32_e32 v21, v18, v19
	v_lshl_add_u64 v[18:19], v[82:83], 3, s[56:57]
	global_atomic_add_f32 v[18:19], v21, off
	global_atomic_add_f32 v[18:19], v20, off offset:4
; DI u32x4 pack8(f32x4 a, f32x4 b) { u32x4 w; w.x = pk2(a[0], a[1]); w.y = pk2(a[2], a[3]); w.z = pk2(b[0], b[1]); w.w = pk2(b[2], b[3]); return w; }
;     DI void operator()(AccRef acc, const Unit& u, int wr, int wc, int fr, int fq) const {
;     ...
;         for (int it = 0; it < 8; ++it) { const int ai = it >> 2, m = it & 3, cur = it & 1;
;             if (it + 1 < 8) { int rn_ = row0 + ((it + 1) >> 2) * 128 + ((it + 1) & 3) * 16; asm volatile("" : "+v"(rn_) :: "memory"); const size_t on = (size_t)rn_ * DM + c0;
; #pragma unroll
;                 for (int bj = 0; bj < 2; ++bj)
; #pragma unroll
;                     for (int n = 0; n < 2; ++n) xb[cur ^ 1][bj][n] = *(const f32x4*)(X + on + bj * 128 + 4 * n); }
;             int row_ = row0 + ai * 128 + m * 16; asm volatile("" : "+v"(row_)); const size_t off = (size_t)row_ * DM + c0; float s1 = 0.f, s2 = 0.f;
; #pragma unroll
;             for (int bj = 0; bj < 2; ++bj) { f32x4 y[2];
; #pragma unroll
;                 for (int n = 0; n < 2; ++n) { y[n] = xb[cur][bj][n] * ALPHA + acc[ai][bj][m][n]; *(f32x4*)(Y + off + bj * 128 + 4 * n) = y[n];
;                     s1 += (y[n][0] + y[n][1]) + (y[n][2] + y[n][3]); s2 += (y[n][0] * y[n][0] + y[n][1] * y[n][1]) + (y[n][2] * y[n][2] + y[n][3] * y[n][3]); }
;                 const f32x4 g0 = *(const f32x4*)(G + c0 + bj * 128), g1 = *(const f32x4*)(G + c0 + bj * 128 + 4);
;                 *(u32x4*)(YG + off + bj * 128) = pack8(y[0] * g0, y[1] * g1); }
;             s1 += __shfl_xor(s1, 16); s1 += __shfl_xor(s1, 32); s2 += __shfl_xor(s2, 16); s2 += __shfl_xor(s2, 32);
;             if (fq == 0) { unsafeAtomicAdd(ST + (size_t)row_ * 2, s1); unsafeAtomicAdd(ST + (size_t)row_ * 2 + 1, s2); } }
.LBB0_149:
	s_or_b64 exec, exec, s[14:15]
	v_pk_fma_f32 v[16:17], v[48:49], s[30:31], v[16:17] op_sel_hi:[1,0,1]
	v_ashrrev_i32_e32 v67, 31, v66
	s_waitcnt lgkmcnt(0)
	v_lshlrev_b64 v[18:19], 10, v[66:67]
	v_lshl_add_u64 v[30:31], v[18:19], 0, v[168:169]
	v_lshl_add_u64 v[32:33], v[30:31], 2, s[60:61]
	v_pk_fma_f32 v[14:15], v[46:47], s[30:31], v[14:15] op_sel_hi:[1,0,1]
	v_pk_fma_f32 v[12:13], v[44:45], s[30:31], v[12:13] op_sel_hi:[1,0,1]
	v_pk_fma_f32 v[10:11], v[42:43], s[30:31], v[10:11] op_sel_hi:[1,0,1]
	global_store_dwordx4 v[32:33], v[14:17], off
	global_store_dwordx4 v[32:33], v[10:13], off offset:16
	global_load_dwordx4 v[18:21], v[170:171], off
	global_load_dwordx4 v[22:25], v[170:171], off offset:16
	v_pk_fma_f32 v[28:29], v[36:37], s[30:31], v[4:5] op_sel_hi:[1,0,1]
	v_pk_fma_f32 v[26:27], v[34:35], s[30:31], v[2:3] op_sel_hi:[1,0,1]
	v_lshl_add_u64 v[30:31], v[30:31], 1, s[58:59]
	v_pk_fma_f32 v[8:9], v[40:41], s[30:31], v[8:9] op_sel_hi:[1,0,1]
	v_pk_fma_f32 v[6:7], v[38:39], s[30:31], v[6:7] op_sel_hi:[1,0,1]
	v_mul_f32_e32 v35, v8, v8
	v_mul_f32_e32 v34, v7, v7
	v_mul_f32_e32 v38, v27, v27
	v_mul_f32_e32 v39, v28, v28
	v_fmac_f32_e32 v34, v6, v6
	v_fmac_f32_e32 v35, v9, v9
	v_add_f32_e32 v36, v26, v27
	v_add_f32_e32 v37, v29, v28
	v_fmac_f32_e32 v38, v26, v26
	v_fmac_f32_e32 v39, v29, v29
	s_waitcnt vmcnt(0)
	v_pk_mul_f32 v[4:5], v[16:17], v[20:21]
	v_pk_mul_f32 v[2:3], v[14:15], v[18:19]
	v_pk_mul_f32 v[18:19], v[12:13], v[24:25]
	v_pk_mul_f32 v[20:21], v[10:11], v[22:23]
	v_cvt_pk_bf16_f32 v2, v2, v3
	v_cvt_pk_bf16_f32 v3, v4, v5
	v_cvt_pk_bf16_f32 v4, v20, v21
	v_cvt_pk_bf16_f32 v5, v18, v19
	global_store_dwordx4 v[30:31], v[2:5], off
	global_store_dwordx4 v[32:33], v[6:9], off offset:512
	global_store_dwordx4 v[32:33], v[26:29], off offset:528
	global_load_dwordx4 v[18:21], v[170:171], off offset:512
	global_load_dwordx4 v[22:25], v[170:171], off offset:528
	v_add_f32_e32 v2, v14, v15
	v_add_f32_e32 v3, v17, v16
	v_mul_f32_e32 v4, v15, v15
	v_mul_f32_e32 v5, v16, v16
	v_add_f32_e32 v15, v10, v11
	v_add_f32_e32 v16, v13, v12
	v_mul_f32_e32 v11, v11, v11
	v_mul_f32_e32 v12, v12, v12
	v_add_f32_e32 v2, v2, v3
	v_fmac_f32_e32 v4, v14, v14
	v_fmac_f32_e32 v5, v17, v17
	v_fmac_f32_e32 v11, v10, v10
	v_fmac_f32_e32 v12, v13, v13
	v_add_f32_e32 v32, v6, v7
	v_add_f32_e32 v33, v9, v8
	v_add_f32_e32 v3, v15, v16
	v_add_f32_e32 v2, 0, v2
	v_add_f32_e32 v4, v4, v5
	v_add_f32_e32 v5, v11, v12
	v_add_f32_e32 v10, v32, v33
	v_add_f32_e32 v11, v34, v35
	v_add_f32_e32 v2, v2, v3
	v_add_f32_e32 v3, v4, v5
	v_add_f32_e32 v13, v36, v37
	v_add_f32_e32 v12, v38, v39
	v_add_f32_e32 v2, v2, v10
	v_add_f32_e32 v3, v3, v11
	v_add_f32_e32 v2, v2, v13
	v_add_f32_e32 v3, v3, v12
	ds_bpermute_b32 v4, v152, v2
	ds_bpermute_b32 v5, v152, v3
	s_waitcnt lgkmcnt(0)
	v_add_f32_e32 v2, v2, v4
	v_add_f32_e32 v4, v3, v5
	ds_bpermute_b32 v3, v153, v2
	ds_bpermute_b32 v5, v153, v4
	s_waitcnt vmcnt(0)
	v_pk_mul_f32 v[8:9], v[8:9], v[20:21]
	v_pk_mul_f32 v[6:7], v[6:7], v[18:19]
	v_pk_mul_f32 v[10:11], v[28:29], v[24:25]
	v_pk_mul_f32 v[12:13], v[26:27], v[22:23]
	v_cvt_pk_bf16_f32 v6, v6, v7
	v_cvt_pk_bf16_f32 v7, v8, v9
	v_cvt_pk_bf16_f32 v8, v12, v13
	v_cvt_pk_bf16_f32 v9, v10, v11
	global_store_dwordx4 v[30:31], v[6:9], off offset:256
	s_and_saveexec_b64 s[14:15], s[40:41]
	s_cbranch_execz .LBB0_151
	s_waitcnt lgkmcnt(0)
	v_add_f32_e32 v4, v4, v5
	v_add_f32_e32 v5, v2, v3
	v_lshl_add_u64 v[2:3], v[66:67], 3, s[56:57]
	global_atomic_add_f32 v[2:3], v5, off
	global_atomic_add_f32 v[2:3], v4, off offset:4

; DI unsigned pk2(float lo, float hi) { f32x2 v = {lo, hi}; bf16x2_t b = __builtin_convertvector(v, bf16x2_t); return __builtin_bit_cast(unsigned, b); }
; DI u32x4 pack8(f32x4 a, f32x4 b) { u32x4 w; w.x = pk2(a[0], a[1]); w.y = pk2(a[2], a[3]); w.z = pk2(b[0], b[1]); w.w = pk2(b[2], b[3]); return w; }
;     DI void operator()(AccRef acc, const Unit& u, int wr, int wc, int fr, int fq) const {
;     ...
;             for (int m = 0; m < 4; ++m) { int row = row0 + ai * 128 + m * 16; asm volatile("" : "+v"(row) :: "memory"); const int b = row >> 13, s = row & 8191;
;                 const float rs = __builtin_amdgcn_rsqf(SSQ[(size_t)row * 2 + 1] * (1.f / 256.f) + RMS_EPS);
;                 *(u32x4*)(KN + ((size_t)(b * 4 + h) * SEQ + s) * 128 + cl) = pack8(acc[ai][0][m][0] * rs, acc[ai][0][m][1] * rs);
;                 bf16_t* vp = VT + ((size_t)(b * 4 + h) * 128 + cl) * SEQ + s;
; #pragma unroll
;                 for (int n = 0; n < 2; ++n)
; #pragma unroll
;                     for (int i = 0; i < 4; ++i) { *vp = (bf16_t)(pk2(acc[ai][1][m][n][i] * rs, 0.f) & 0xffffu); vp += SEQ; asm volatile("" : "+v"(vp)); } }
.LBB0_347:
	s_mov_b64 s[14:15], s[0:1]
	s_add_u32 s48, s14, 0x1a600000
	s_addc_u32 s49, s15, 0
	v_lshl_add_u32 v155, s50, 8, v152
	s_add_u32 s50, s14, 0x3500004
	v_mov_b32_e32 v156, v155
	s_addc_u32 s51, s15, 0
	v_lshl_add_u64 v[150:151], s[14:15], 0, v[142:143]
	v_ashrrev_i32_e32 v157, 31, v156
	v_lshl_add_u64 v[158:159], v[156:157], 3, s[50:51]
	global_load_dword v0, v[158:159], off
	v_and_b32_e32 v160, 0x1fff, v156
	s_mov_b64 s[14:15], 0x1c600000
	v_mov_b32_e32 v149, v1
	v_lshl_add_u64 v[150:151], v[150:151], 0, s[14:15]
	s_mov_b64 s[14:15], -1
	s_and_b64 vcc, exec, s[40:41]
	s_waitcnt vmcnt(0) lgkmcnt(0)
	v_fmamk_f32 v0, v0, 0x3b800000, v231
	v_rsq_f32_e32 v158, v0
	v_ashrrev_i32_e32 v0, 11, v156
	v_and_b32_e32 v0, -4, v0
	v_pk_mul_f32 v[124:125], v[124:125], v[158:159] op_sel_hi:[1,0]
	v_pk_mul_f32 v[122:123], v[122:123], v[158:159] op_sel_hi:[1,0]
	v_pk_mul_f32 v[126:127], v[126:127], v[158:159] op_sel_hi:[1,0]
	v_cvt_pk_bf16_f32 v122, v122, v123
	v_cvt_pk_bf16_f32 v123, v124, v125
	v_cvt_pk_bf16_f32 v124, v126, v127
	v_add_u32_e32 v126, s75, v0
	v_ashrrev_i32_e32 v127, 31, v126
	v_pk_mul_f32 v[128:129], v[128:129], v[158:159] op_sel_hi:[1,0]
	v_lshlrev_b64 v[126:127], 21, v[126:127]
	v_cvt_pk_bf16_f32 v125, v128, v129
	v_lshl_add_u64 v[128:129], s[48:49], 0, v[126:127]
	v_lshlrev_b32_e32 v0, 8, v160
	v_lshl_add_u64 v[128:129], v[128:129], 0, v[0:1]
	v_lshl_add_u64 v[128:129], v[128:129], 0, v[148:149]
	global_store_dwordx4 v[128:129], v[122:125], off
	v_lshlrev_b32_e32 v0, 1, v160
	s_nop 0
	v_lshl_add_u64 v[122:123], v[150:151], 0, v[126:127]
	v_lshl_add_u64 v[122:123], v[122:123], 0, v[0:1]
	v_mul_f32_e32 v0, v118, v158
	v_cvt_pk_bf16_f32 v0, v0, s0
	global_store_short v[122:123], v0, off
	v_mul_f32_e32 v0, v119, v158
	v_lshl_add_u64 v[122:123], v[122:123], 0, s[22:23]
	v_cvt_pk_bf16_f32 v0, v0, s0
	global_store_short v[122:123], v0, off
	v_mul_f32_e32 v0, v120, v158
	v_lshl_add_u64 v[118:119], v[122:123], 0, s[22:23]
	v_cvt_pk_bf16_f32 v0, v0, s0
	global_store_short v[118:119], v0, off
	v_mul_f32_e32 v0, v121, v158
	v_lshl_add_u64 v[118:119], v[118:119], 0, s[22:23]
	v_cvt_pk_bf16_f32 v0, v0, s0
	global_store_short v[118:119], v0, off
	v_mul_f32_e32 v0, v114, v158
	v_lshl_add_u64 v[118:119], v[118:119], 0, s[22:23]
	v_cvt_pk_bf16_f32 v0, v0, s0
	global_store_short v[118:119], v0, off
	v_mul_f32_e32 v0, v115, v158
	v_lshl_add_u64 v[118:119], v[118:119], 0, s[22:23]
	v_cvt_pk_bf16_f32 v0, v0, s0
	global_store_short v[118:119], v0, off
	v_lshl_add_u64 v[114:115], v[118:119], 0, s[22:23]
	v_mul_f32_e32 v0, v116, v158
	v_cvt_pk_bf16_f32 v0, v0, s0
	global_store_short v[114:115], v0, off
	v_lshl_add_u64 v[114:115], v[114:115], 0, s[22:23]
	v_mul_f32_e32 v0, v117, v158
	v_cvt_pk_bf16_f32 v0, v0, s0
	global_store_short v[114:115], v0, off
	v_lshl_add_u64 v[114:115], v[114:115], 0, s[22:23]
	s_nop 0
	v_or_b32_e32 v114, 16, v155
	s_nop 0
	v_ashrrev_i32_e32 v115, 31, v114
	v_lshl_add_u64 v[116:117], v[114:115], 3, s[50:51]
	global_load_dword v0, v[116:117], off
	v_and_b32_e32 v120, 0x1fff, v114
	s_waitcnt vmcnt(0) lgkmcnt(0)
	v_fmamk_f32 v0, v0, 0x3b800000, v231
	v_rsq_f32_e32 v116, v0
	v_ashrrev_i32_e32 v0, 11, v114
	v_and_b32_e32 v0, -4, v0
	v_pk_mul_f32 v[110:111], v[110:111], v[116:117] op_sel_hi:[1,0]
	v_pk_mul_f32 v[118:119], v[108:109], v[116:117] op_sel_hi:[1,0]
	v_pk_mul_f32 v[108:109], v[106:107], v[116:117] op_sel_hi:[1,0]
	v_cvt_pk_bf16_f32 v106, v110, v111
	v_add_u32_e32 v110, s75, v0
	v_ashrrev_i32_e32 v111, 31, v110
	v_pk_mul_f32 v[112:113], v[112:113], v[116:117] op_sel_hi:[1,0]
	v_lshlrev_b64 v[110:111], 21, v[110:111]
	v_cvt_pk_bf16_f32 v107, v112, v113
	v_lshl_add_u64 v[112:113], s[48:49], 0, v[110:111]
	v_lshlrev_b32_e32 v0, 8, v120
	v_lshl_add_u64 v[112:113], v[112:113], 0, v[0:1]
	v_cvt_pk_bf16_f32 v108, v108, v109
	v_cvt_pk_bf16_f32 v109, v118, v119
	v_lshl_add_u64 v[112:113], v[112:113], 0, v[148:149]
	global_store_dwordx4 v[112:113], v[106:109], off
	v_lshlrev_b32_e32 v0, 1, v120
	s_nop 0
	v_lshl_add_u64 v[106:107], v[150:151], 0, v[110:111]
	v_lshl_add_u64 v[106:107], v[106:107], 0, v[0:1]
	v_mul_f32_e32 v0, v102, v116
	v_cvt_pk_bf16_f32 v0, v0, s0
	global_store_short v[106:107], v0, off
	v_mul_f32_e32 v0, v103, v116
	v_lshl_add_u64 v[106:107], v[106:107], 0, s[22:23]
	v_cvt_pk_bf16_f32 v0, v0, s0
	global_store_short v[106:107], v0, off
	v_mul_f32_e32 v0, v104, v116
	v_lshl_add_u64 v[102:103], v[106:107], 0, s[22:23]
	v_cvt_pk_bf16_f32 v0, v0, s0
	global_store_short v[102:103], v0, off
	v_mul_f32_e32 v0, v105, v116
	v_lshl_add_u64 v[102:103], v[102:103], 0, s[22:23]
	v_cvt_pk_bf16_f32 v0, v0, s0
	global_store_short v[102:103], v0, off
	v_mul_f32_e32 v0, v98, v116
	v_lshl_add_u64 v[102:103], v[102:103], 0, s[22:23]
	v_cvt_pk_bf16_f32 v0, v0, s0
	global_store_short v[102:103], v0, off
	v_mul_f32_e32 v0, v99, v116
	v_lshl_add_u64 v[102:103], v[102:103], 0, s[22:23]
	v_cvt_pk_bf16_f32 v0, v0, s0
	global_store_short v[102:103], v0, off
	v_lshl_add_u64 v[98:99], v[102:103], 0, s[22:23]
	v_mul_f32_e32 v0, v100, v116
	v_cvt_pk_bf16_f32 v0, v0, s0
	global_store_short v[98:99], v0, off
	v_lshl_add_u64 v[98:99], v[98:99], 0, s[22:23]
	v_mul_f32_e32 v0, v101, v116
	v_cvt_pk_bf16_f32 v0, v0, s0
	global_store_short v[98:99], v0, off
	v_lshl_add_u64 v[98:99], v[98:99], 0, s[22:23]
	s_nop 0
	v_or_b32_e32 v98, 32, v155
	s_nop 0
	v_ashrrev_i32_e32 v99, 31, v98
	v_lshl_add_u64 v[100:101], v[98:99], 3, s[50:51]
	global_load_dword v0, v[100:101], off
	v_and_b32_e32 v104, 0x1fff, v98
	s_waitcnt vmcnt(0) lgkmcnt(0)
; DI unsigned pk2(float lo, float hi) { f32x2 v = {lo, hi}; bf16x2_t b = __builtin_convertvector(v, bf16x2_t); return __builtin_bit_cast(unsigned, b); }
; DI u32x4 pack8(f32x4 a, f32x4 b) { u32x4 w; w.x = pk2(a[0], a[1]); w.y = pk2(a[2], a[3]); w.z = pk2(b[0], b[1]); w.w = pk2(b[2], b[3]); return w; }
;     DI void operator()(AccRef acc, const Unit& u, int wr, int wc, int fr, int fq) const {
;     ...
;             for (int m = 0; m < 4; ++m) { int row = row0 + ai * 128 + m * 16; asm volatile("" : "+v"(row) :: "memory"); const int b = row >> 13, s = row & 8191;
;                 const float rs = __builtin_amdgcn_rsqf(SSQ[(size_t)row * 2 + 1] * (1.f / 256.f) + RMS_EPS);
;                 *(u32x4*)(KN + ((size_t)(b * 4 + h) * SEQ + s) * 128 + cl) = pack8(acc[ai][0][m][0] * rs, acc[ai][0][m][1] * rs);
;                 bf16_t* vp = VT + ((size_t)(b * 4 + h) * 128 + cl) * SEQ + s;
; #pragma unroll
;                 for (int n = 0; n < 2; ++n)
; #pragma unroll
;                     for (int i = 0; i < 4; ++i) { *vp = (bf16_t)(pk2(acc[ai][1][m][n][i] * rs, 0.f) & 0xffffu); vp += SEQ; asm volatile("" : "+v"(vp)); } }
	v_fmamk_f32 v0, v0, 0x3b800000, v231
	v_rsq_f32_e32 v100, v0
	v_ashrrev_i32_e32 v0, 11, v98
	v_and_b32_e32 v0, -4, v0
	v_pk_mul_f32 v[94:95], v[94:95], v[100:101] op_sel_hi:[1,0]
	v_pk_mul_f32 v[102:103], v[92:93], v[100:101] op_sel_hi:[1,0]
	v_pk_mul_f32 v[92:93], v[90:91], v[100:101] op_sel_hi:[1,0]
	v_cvt_pk_bf16_f32 v90, v94, v95
	v_add_u32_e32 v94, s75, v0
	v_ashrrev_i32_e32 v95, 31, v94
	v_pk_mul_f32 v[96:97], v[96:97], v[100:101] op_sel_hi:[1,0]
	v_lshlrev_b64 v[94:95], 21, v[94:95]
	v_cvt_pk_bf16_f32 v91, v96, v97
	v_lshl_add_u64 v[96:97], s[48:49], 0, v[94:95]
	v_lshlrev_b32_e32 v0, 8, v104
	v_lshl_add_u64 v[96:97], v[96:97], 0, v[0:1]
	v_cvt_pk_bf16_f32 v92, v92, v93
	v_cvt_pk_bf16_f32 v93, v102, v103
	v_lshl_add_u64 v[96:97], v[96:97], 0, v[148:149]
	global_store_dwordx4 v[96:97], v[90:93], off
	v_lshlrev_b32_e32 v0, 1, v104
	s_nop 0
	v_lshl_add_u64 v[90:91], v[150:151], 0, v[94:95]
	v_lshl_add_u64 v[90:91], v[90:91], 0, v[0:1]
	v_mul_f32_e32 v0, v86, v100
	v_cvt_pk_bf16_f32 v0, v0, s0
	global_store_short v[90:91], v0, off
	v_mul_f32_e32 v0, v87, v100
	v_lshl_add_u64 v[90:91], v[90:91], 0, s[22:23]
	v_cvt_pk_bf16_f32 v0, v0, s0
	global_store_short v[90:91], v0, off
	v_mul_f32_e32 v0, v88, v100
	v_lshl_add_u64 v[86:87], v[90:91], 0, s[22:23]
	v_cvt_pk_bf16_f32 v0, v0, s0
	global_store_short v[86:87], v0, off
	v_mul_f32_e32 v0, v89, v100
	v_lshl_add_u64 v[86:87], v[86:87], 0, s[22:23]
	v_cvt_pk_bf16_f32 v0, v0, s0
	global_store_short v[86:87], v0, off
	v_mul_f32_e32 v0, v82, v100
	v_lshl_add_u64 v[86:87], v[86:87], 0, s[22:23]
	v_cvt_pk_bf16_f32 v0, v0, s0
	global_store_short v[86:87], v0, off
	v_mul_f32_e32 v0, v83, v100
	v_lshl_add_u64 v[86:87], v[86:87], 0, s[22:23]
	v_cvt_pk_bf16_f32 v0, v0, s0
	global_store_short v[86:87], v0, off
	v_lshl_add_u64 v[82:83], v[86:87], 0, s[22:23]
	v_mul_f32_e32 v0, v84, v100
	v_cvt_pk_bf16_f32 v0, v0, s0
	global_store_short v[82:83], v0, off
	v_lshl_add_u64 v[82:83], v[82:83], 0, s[22:23]
	v_mul_f32_e32 v0, v85, v100
	v_cvt_pk_bf16_f32 v0, v0, s0
	global_store_short v[82:83], v0, off
	v_lshl_add_u64 v[82:83], v[82:83], 0, s[22:23]
	s_nop 0
	v_or_b32_e32 v82, 48, v155
	s_nop 0
	v_ashrrev_i32_e32 v83, 31, v82
	v_lshl_add_u64 v[84:85], v[82:83], 3, s[50:51]
	global_load_dword v0, v[84:85], off
	v_and_b32_e32 v88, 0x1fff, v82
	s_waitcnt vmcnt(0) lgkmcnt(0)
	v_fmamk_f32 v0, v0, 0x3b800000, v231
	v_rsq_f32_e32 v84, v0
	v_ashrrev_i32_e32 v0, 11, v82
	v_and_b32_e32 v0, -4, v0
	v_pk_mul_f32 v[78:79], v[78:79], v[84:85] op_sel_hi:[1,0]
	v_pk_mul_f32 v[86:87], v[76:77], v[84:85] op_sel_hi:[1,0]
	v_pk_mul_f32 v[76:77], v[74:75], v[84:85] op_sel_hi:[1,0]
	v_cvt_pk_bf16_f32 v74, v78, v79
	v_add_u32_e32 v78, s75, v0
	v_ashrrev_i32_e32 v79, 31, v78
	v_pk_mul_f32 v[80:81], v[80:81], v[84:85] op_sel_hi:[1,0]
	v_lshlrev_b64 v[78:79], 21, v[78:79]
	v_cvt_pk_bf16_f32 v75, v80, v81
	v_lshl_add_u64 v[80:81], s[48:49], 0, v[78:79]
	v_lshlrev_b32_e32 v0, 8, v88
	v_lshl_add_u64 v[80:81], v[80:81], 0, v[0:1]
	v_cvt_pk_bf16_f32 v76, v76, v77
	v_cvt_pk_bf16_f32 v77, v86, v87
	v_lshl_add_u64 v[80:81], v[80:81], 0, v[148:149]
	global_store_dwordx4 v[80:81], v[74:77], off
	v_lshlrev_b32_e32 v0, 1, v88
	s_nop 0
	v_lshl_add_u64 v[74:75], v[150:151], 0, v[78:79]
	v_lshl_add_u64 v[74:75], v[74:75], 0, v[0:1]
	v_mul_f32_e32 v0, v70, v84
	v_cvt_pk_bf16_f32 v0, v0, s0
	global_store_short v[74:75], v0, off
	v_mul_f32_e32 v0, v71, v84
	v_lshl_add_u64 v[74:75], v[74:75], 0, s[22:23]
	v_cvt_pk_bf16_f32 v0, v0, s0
	global_store_short v[74:75], v0, off
	v_mul_f32_e32 v0, v72, v84
	v_lshl_add_u64 v[70:71], v[74:75], 0, s[22:23]
	v_cvt_pk_bf16_f32 v0, v0, s0
	global_store_short v[70:71], v0, off
	v_mul_f32_e32 v0, v73, v84
	v_lshl_add_u64 v[70:71], v[70:71], 0, s[22:23]
	v_cvt_pk_bf16_f32 v0, v0, s0
	global_store_short v[70:71], v0, off
	v_mul_f32_e32 v0, v66, v84
	v_lshl_add_u64 v[70:71], v[70:71], 0, s[22:23]
	v_cvt_pk_bf16_f32 v0, v0, s0
	global_store_short v[70:71], v0, off
	v_mul_f32_e32 v0, v67, v84
	v_lshl_add_u64 v[70:71], v[70:71], 0, s[22:23]
	v_cvt_pk_bf16_f32 v0, v0, s0
	global_store_short v[70:71], v0, off
	v_lshl_add_u64 v[66:67], v[70:71], 0, s[22:23]
	v_mul_f32_e32 v0, v68, v84
	v_cvt_pk_bf16_f32 v0, v0, s0
	global_store_short v[66:67], v0, off
	v_lshl_add_u64 v[66:67], v[66:67], 0, s[22:23]
	v_mul_f32_e32 v0, v69, v84
	v_cvt_pk_bf16_f32 v0, v0, s0
	global_store_short v[66:67], v0, off
	v_lshl_add_u64 v[66:67], v[66:67], 0, s[22:23]
	s_nop 0
	v_add_u32_e32 v66, 0x80, v155
	s_nop 0
	v_ashrrev_i32_e32 v67, 31, v66
	v_lshl_add_u64 v[68:69], v[66:67], 3, s[50:51]
	global_load_dword v0, v[68:69], off
	v_and_b32_e32 v72, 0x1fff, v66
	s_waitcnt vmcnt(0) lgkmcnt(0)
; DI unsigned pk2(float lo, float hi) { f32x2 v = {lo, hi}; bf16x2_t b = __builtin_convertvector(v, bf16x2_t); return __builtin_bit_cast(unsigned, b); }
; DI u32x4 pack8(f32x4 a, f32x4 b) { u32x4 w; w.x = pk2(a[0], a[1]); w.y = pk2(a[2], a[3]); w.z = pk2(b[0], b[1]); w.w = pk2(b[2], b[3]); return w; }
;     DI void operator()(AccRef acc, const Unit& u, int wr, int wc, int fr, int fq) const {
;     ...
;             for (int m = 0; m < 4; ++m) { int row = row0 + ai * 128 + m * 16; asm volatile("" : "+v"(row) :: "memory"); const int b = row >> 13, s = row & 8191;
;                 const float rs = __builtin_amdgcn_rsqf(SSQ[(size_t)row * 2 + 1] * (1.f / 256.f) + RMS_EPS);
;                 *(u32x4*)(KN + ((size_t)(b * 4 + h) * SEQ + s) * 128 + cl) = pack8(acc[ai][0][m][0] * rs, acc[ai][0][m][1] * rs);
;                 bf16_t* vp = VT + ((size_t)(b * 4 + h) * 128 + cl) * SEQ + s;
; #pragma unroll
;                 for (int n = 0; n < 2; ++n)
; #pragma unroll
;                     for (int i = 0; i < 4; ++i) { *vp = (bf16_t)(pk2(acc[ai][1][m][n][i] * rs, 0.f) & 0xffffu); vp += SEQ; asm volatile("" : "+v"(vp)); } }
	v_fmamk_f32 v0, v0, 0x3b800000, v231
	v_rsq_f32_e32 v68, v0
	v_ashrrev_i32_e32 v0, 11, v66
	v_and_b32_e32 v0, -4, v0
	v_pk_mul_f32 v[62:63], v[62:63], v[68:69] op_sel_hi:[1,0]
	v_pk_mul_f32 v[70:71], v[60:61], v[68:69] op_sel_hi:[1,0]
	v_pk_mul_f32 v[60:61], v[58:59], v[68:69] op_sel_hi:[1,0]
	v_cvt_pk_bf16_f32 v58, v62, v63
	v_add_u32_e32 v62, s75, v0
	v_ashrrev_i32_e32 v63, 31, v62
	v_pk_mul_f32 v[64:65], v[64:65], v[68:69] op_sel_hi:[1,0]
	v_lshlrev_b64 v[62:63], 21, v[62:63]
	v_cvt_pk_bf16_f32 v59, v64, v65
	v_lshl_add_u64 v[64:65], s[48:49], 0, v[62:63]
	v_lshlrev_b32_e32 v0, 8, v72
	v_lshl_add_u64 v[64:65], v[64:65], 0, v[0:1]
	v_cvt_pk_bf16_f32 v60, v60, v61
	v_cvt_pk_bf16_f32 v61, v70, v71
	v_lshl_add_u64 v[64:65], v[64:65], 0, v[148:149]
	global_store_dwordx4 v[64:65], v[58:61], off
	v_lshlrev_b32_e32 v0, 1, v72
	s_nop 0
	v_lshl_add_u64 v[58:59], v[150:151], 0, v[62:63]
	v_lshl_add_u64 v[58:59], v[58:59], 0, v[0:1]
	v_mul_f32_e32 v0, v54, v68
	v_cvt_pk_bf16_f32 v0, v0, s0
	global_store_short v[58:59], v0, off
	v_mul_f32_e32 v0, v55, v68
	v_lshl_add_u64 v[58:59], v[58:59], 0, s[22:23]
	v_cvt_pk_bf16_f32 v0, v0, s0
	global_store_short v[58:59], v0, off
	v_mul_f32_e32 v0, v56, v68
	v_lshl_add_u64 v[54:55], v[58:59], 0, s[22:23]
	v_cvt_pk_bf16_f32 v0, v0, s0
	global_store_short v[54:55], v0, off
	v_mul_f32_e32 v0, v57, v68
	v_lshl_add_u64 v[54:55], v[54:55], 0, s[22:23]
	v_cvt_pk_bf16_f32 v0, v0, s0
	global_store_short v[54:55], v0, off
	v_mul_f32_e32 v0, v50, v68
	v_lshl_add_u64 v[54:55], v[54:55], 0, s[22:23]
	v_cvt_pk_bf16_f32 v0, v0, s0
	global_store_short v[54:55], v0, off
	v_mul_f32_e32 v0, v51, v68
	v_lshl_add_u64 v[54:55], v[54:55], 0, s[22:23]
	v_cvt_pk_bf16_f32 v0, v0, s0
	global_store_short v[54:55], v0, off
	v_lshl_add_u64 v[50:51], v[54:55], 0, s[22:23]
	v_mul_f32_e32 v0, v52, v68
	v_cvt_pk_bf16_f32 v0, v0, s0
	global_store_short v[50:51], v0, off
	v_lshl_add_u64 v[50:51], v[50:51], 0, s[22:23]
	v_mul_f32_e32 v0, v53, v68
	v_cvt_pk_bf16_f32 v0, v0, s0
	global_store_short v[50:51], v0, off
	v_lshl_add_u64 v[50:51], v[50:51], 0, s[22:23]
	s_nop 0
	v_add_u32_e32 v50, 0x90, v155
	s_nop 0
	v_ashrrev_i32_e32 v51, 31, v50
	v_lshl_add_u64 v[52:53], v[50:51], 3, s[50:51]
	global_load_dword v0, v[52:53], off
	v_and_b32_e32 v56, 0x1fff, v50
	s_waitcnt vmcnt(0) lgkmcnt(0)
	v_fmamk_f32 v0, v0, 0x3b800000, v231
	v_rsq_f32_e32 v52, v0
	v_ashrrev_i32_e32 v0, 11, v50
	v_and_b32_e32 v0, -4, v0
	v_pk_mul_f32 v[46:47], v[46:47], v[52:53] op_sel_hi:[1,0]
	v_pk_mul_f32 v[54:55], v[44:45], v[52:53] op_sel_hi:[1,0]
	v_pk_mul_f32 v[44:45], v[42:43], v[52:53] op_sel_hi:[1,0]
	v_cvt_pk_bf16_f32 v42, v46, v47
	v_add_u32_e32 v46, s75, v0
	v_ashrrev_i32_e32 v47, 31, v46
	v_pk_mul_f32 v[48:49], v[48:49], v[52:53] op_sel_hi:[1,0]
	v_lshlrev_b64 v[46:47], 21, v[46:47]
	v_cvt_pk_bf16_f32 v43, v48, v49
	v_lshl_add_u64 v[48:49], s[48:49], 0, v[46:47]
	v_lshlrev_b32_e32 v0, 8, v56
	v_lshl_add_u64 v[48:49], v[48:49], 0, v[0:1]
	v_cvt_pk_bf16_f32 v44, v44, v45
	v_cvt_pk_bf16_f32 v45, v54, v55
	v_lshl_add_u64 v[48:49], v[48:49], 0, v[148:149]
	global_store_dwordx4 v[48:49], v[42:45], off
	v_lshlrev_b32_e32 v0, 1, v56
	s_nop 0
	v_lshl_add_u64 v[42:43], v[150:151], 0, v[46:47]
	v_lshl_add_u64 v[42:43], v[42:43], 0, v[0:1]
	v_mul_f32_e32 v0, v38, v52
	v_cvt_pk_bf16_f32 v0, v0, s0
	global_store_short v[42:43], v0, off
	v_mul_f32_e32 v0, v39, v52
	v_lshl_add_u64 v[42:43], v[42:43], 0, s[22:23]
	v_cvt_pk_bf16_f32 v0, v0, s0
	global_store_short v[42:43], v0, off
	v_mul_f32_e32 v0, v40, v52
	v_lshl_add_u64 v[38:39], v[42:43], 0, s[22:23]
	v_cvt_pk_bf16_f32 v0, v0, s0
	global_store_short v[38:39], v0, off
	v_mul_f32_e32 v0, v41, v52
	v_lshl_add_u64 v[38:39], v[38:39], 0, s[22:23]
	v_cvt_pk_bf16_f32 v0, v0, s0
	global_store_short v[38:39], v0, off
	v_mul_f32_e32 v0, v34, v52
	v_lshl_add_u64 v[38:39], v[38:39], 0, s[22:23]
	v_cvt_pk_bf16_f32 v0, v0, s0
	global_store_short v[38:39], v0, off
	v_mul_f32_e32 v0, v35, v52
	v_lshl_add_u64 v[38:39], v[38:39], 0, s[22:23]
	v_cvt_pk_bf16_f32 v0, v0, s0
	global_store_short v[38:39], v0, off
	v_lshl_add_u64 v[34:35], v[38:39], 0, s[22:23]
	v_mul_f32_e32 v0, v36, v52
	v_cvt_pk_bf16_f32 v0, v0, s0
	global_store_short v[34:35], v0, off
	v_lshl_add_u64 v[34:35], v[34:35], 0, s[22:23]
	v_mul_f32_e32 v0, v37, v52
	v_cvt_pk_bf16_f32 v0, v0, s0
	global_store_short v[34:35], v0, off
	v_lshl_add_u64 v[34:35], v[34:35], 0, s[22:23]
	s_nop 0
	v_add_u32_e32 v34, 0xa0, v155
	s_nop 0
	v_ashrrev_i32_e32 v35, 31, v34
	v_lshl_add_u64 v[36:37], v[34:35], 3, s[50:51]
	global_load_dword v0, v[36:37], off
	v_and_b32_e32 v40, 0x1fff, v34
	s_waitcnt vmcnt(0) lgkmcnt(0)
; #define PG8_BAR __builtin_amdgcn_s_barrier()
; DI unsigned pk2(float lo, float hi) { f32x2 v = {lo, hi}; bf16x2_t b = __builtin_convertvector(v, bf16x2_t); return __builtin_bit_cast(unsigned, b); }
; DI u32x4 pack8(f32x4 a, f32x4 b) { u32x4 w; w.x = pk2(a[0], a[1]); w.y = pk2(a[2], a[3]); w.z = pk2(b[0], b[1]); w.w = pk2(b[2], b[3]); return w; }
; template <class Epi, class Sched, bool ALIGN_EPI = false, bool SP2 = false>
; __device__ __forceinline__ void gemm_phase(PG8_LAS unsigned char* lds, const Gemm g, const Sched& S, const Epi& E) {
;     ...
;         if constexpr (ALIGN_EPI) { if (wr == 0) PG8_BAR; }
;         if constexpr (!Epi::AFTER_DRAIN) { E(acc, cur, wr, wc, fr, fq); S.done(cur); }
;         if (!has_next) break;
; #pragma unroll
;         for (int a = 0; a < 2; ++a)
; #pragma unroll
;             for (int b = 0; b < 2; ++b)
; #pragma unroll
;                 for (int m = 0; m < 4; ++m)
; #pragma unroll
;                     for (int n = 0; n < 2; ++n) acc[a][b][m][n] = (f32x4){0.f, 0.f, 0.f, 0.f};
;         cur = nxt; cA = nA; cB = nB; ++ui;
;         if constexpr (ALIGN_EPI) { if (wr == 1) PG8_BAR; }
;     DI void operator()(AccRef acc, const Unit& u, int wr, int wc, int fr, int fq) const {
;     ...
;             for (int m = 0; m < 4; ++m) { int row = row0 + ai * 128 + m * 16; asm volatile("" : "+v"(row) :: "memory"); const int b = row >> 13, s = row & 8191;
;                 const float rs = __builtin_amdgcn_rsqf(SSQ[(size_t)row * 2 + 1] * (1.f / 256.f) + RMS_EPS);
;                 *(u32x4*)(KN + ((size_t)(b * 4 + h) * SEQ + s) * 128 + cl) = pack8(acc[ai][0][m][0] * rs, acc[ai][0][m][1] * rs);
;                 bf16_t* vp = VT + ((size_t)(b * 4 + h) * 128 + cl) * SEQ + s;
; #pragma unroll
;                 for (int n = 0; n < 2; ++n)
; #pragma unroll
;                     for (int i = 0; i < 4; ++i) { *vp = (bf16_t)(pk2(acc[ai][1][m][n][i] * rs, 0.f) & 0xffffu); vp += SEQ; asm volatile("" : "+v"(vp)); } }
	v_fmamk_f32 v0, v0, 0x3b800000, v231
	v_rsq_f32_e32 v36, v0
	v_ashrrev_i32_e32 v0, 11, v34
	v_and_b32_e32 v0, -4, v0
	v_pk_mul_f32 v[30:31], v[30:31], v[36:37] op_sel_hi:[1,0]
	v_pk_mul_f32 v[38:39], v[28:29], v[36:37] op_sel_hi:[1,0]
	v_pk_mul_f32 v[28:29], v[26:27], v[36:37] op_sel_hi:[1,0]
	v_cvt_pk_bf16_f32 v26, v30, v31
	v_add_u32_e32 v30, s75, v0
	v_ashrrev_i32_e32 v31, 31, v30
	v_pk_mul_f32 v[32:33], v[32:33], v[36:37] op_sel_hi:[1,0]
	v_lshlrev_b64 v[30:31], 21, v[30:31]
	v_cvt_pk_bf16_f32 v27, v32, v33
	v_lshl_add_u64 v[32:33], s[48:49], 0, v[30:31]
	v_lshlrev_b32_e32 v0, 8, v40
	v_lshl_add_u64 v[32:33], v[32:33], 0, v[0:1]
	v_cvt_pk_bf16_f32 v28, v28, v29
	v_cvt_pk_bf16_f32 v29, v38, v39
	v_lshl_add_u64 v[32:33], v[32:33], 0, v[148:149]
	global_store_dwordx4 v[32:33], v[26:29], off
	v_lshlrev_b32_e32 v0, 1, v40
	s_nop 0
	v_lshl_add_u64 v[26:27], v[150:151], 0, v[30:31]
	v_lshl_add_u64 v[26:27], v[26:27], 0, v[0:1]
	v_mul_f32_e32 v0, v22, v36
	v_cvt_pk_bf16_f32 v0, v0, s0
	global_store_short v[26:27], v0, off
	v_mul_f32_e32 v0, v23, v36
	v_lshl_add_u64 v[26:27], v[26:27], 0, s[22:23]
	v_cvt_pk_bf16_f32 v0, v0, s0
	global_store_short v[26:27], v0, off
	v_mul_f32_e32 v0, v24, v36
	v_lshl_add_u64 v[22:23], v[26:27], 0, s[22:23]
	v_cvt_pk_bf16_f32 v0, v0, s0
	global_store_short v[22:23], v0, off
	v_mul_f32_e32 v0, v25, v36
	v_lshl_add_u64 v[22:23], v[22:23], 0, s[22:23]
	v_cvt_pk_bf16_f32 v0, v0, s0
	global_store_short v[22:23], v0, off
	v_mul_f32_e32 v0, v18, v36
	v_lshl_add_u64 v[22:23], v[22:23], 0, s[22:23]
	v_cvt_pk_bf16_f32 v0, v0, s0
	global_store_short v[22:23], v0, off
	v_mul_f32_e32 v0, v19, v36
	v_lshl_add_u64 v[22:23], v[22:23], 0, s[22:23]
	v_cvt_pk_bf16_f32 v0, v0, s0
	global_store_short v[22:23], v0, off
	v_lshl_add_u64 v[18:19], v[22:23], 0, s[22:23]
	v_mul_f32_e32 v0, v20, v36
	v_cvt_pk_bf16_f32 v0, v0, s0
	global_store_short v[18:19], v0, off
	v_lshl_add_u64 v[18:19], v[18:19], 0, s[22:23]
	v_mul_f32_e32 v0, v21, v36
	v_cvt_pk_bf16_f32 v0, v0, s0
	global_store_short v[18:19], v0, off
	v_lshl_add_u64 v[18:19], v[18:19], 0, s[22:23]
	s_nop 0
	v_add_u32_e32 v18, 0xb0, v155
	s_nop 0
	v_ashrrev_i32_e32 v19, 31, v18
	v_lshl_add_u64 v[20:21], v[18:19], 3, s[50:51]
	global_load_dword v0, v[20:21], off
	v_and_b32_e32 v24, 0x1fff, v18
	s_waitcnt vmcnt(0) lgkmcnt(0)
	v_fmamk_f32 v0, v0, 0x3b800000, v231
	v_rsq_f32_e32 v20, v0
	v_ashrrev_i32_e32 v0, 11, v18
	v_and_b32_e32 v0, -4, v0
	v_pk_mul_f32 v[14:15], v[14:15], v[20:21] op_sel_hi:[1,0]
	v_pk_mul_f32 v[22:23], v[12:13], v[20:21] op_sel_hi:[1,0]
	v_pk_mul_f32 v[12:13], v[10:11], v[20:21] op_sel_hi:[1,0]
	v_cvt_pk_bf16_f32 v10, v14, v15
	v_add_u32_e32 v14, s75, v0
	v_ashrrev_i32_e32 v15, 31, v14
	v_pk_mul_f32 v[16:17], v[16:17], v[20:21] op_sel_hi:[1,0]
	v_lshlrev_b64 v[14:15], 21, v[14:15]
	v_cvt_pk_bf16_f32 v11, v16, v17
	v_lshl_add_u64 v[16:17], s[48:49], 0, v[14:15]
	v_lshlrev_b32_e32 v0, 8, v24
	v_lshl_add_u64 v[16:17], v[16:17], 0, v[0:1]
	v_cvt_pk_bf16_f32 v12, v12, v13
	v_cvt_pk_bf16_f32 v13, v22, v23
	v_lshl_add_u64 v[16:17], v[16:17], 0, v[148:149]
	global_store_dwordx4 v[16:17], v[10:13], off
	v_lshlrev_b32_e32 v0, 1, v24
	s_nop 0
	v_lshl_add_u64 v[10:11], v[150:151], 0, v[14:15]
	v_lshl_add_u64 v[10:11], v[10:11], 0, v[0:1]
	v_mul_f32_e32 v0, v6, v20
	v_cvt_pk_bf16_f32 v0, v0, s0
	global_store_short v[10:11], v0, off
	v_mul_f32_e32 v0, v7, v20
	v_lshl_add_u64 v[10:11], v[10:11], 0, s[22:23]
	v_cvt_pk_bf16_f32 v0, v0, s0
	global_store_short v[10:11], v0, off
	v_mul_f32_e32 v0, v8, v20
	v_lshl_add_u64 v[6:7], v[10:11], 0, s[22:23]
	v_cvt_pk_bf16_f32 v0, v0, s0
	global_store_short v[6:7], v0, off
	v_mul_f32_e32 v0, v9, v20
	v_lshl_add_u64 v[6:7], v[6:7], 0, s[22:23]
	v_cvt_pk_bf16_f32 v0, v0, s0
	global_store_short v[6:7], v0, off
	v_mul_f32_e32 v0, v2, v20
	v_lshl_add_u64 v[6:7], v[6:7], 0, s[22:23]
	v_cvt_pk_bf16_f32 v0, v0, s0
	global_store_short v[6:7], v0, off
	v_mul_f32_e32 v0, v3, v20
	v_lshl_add_u64 v[6:7], v[6:7], 0, s[22:23]
	v_cvt_pk_bf16_f32 v0, v0, s0
	global_store_short v[6:7], v0, off
	v_lshl_add_u64 v[2:3], v[6:7], 0, s[22:23]
	v_mul_f32_e32 v0, v4, v20
	v_cvt_pk_bf16_f32 v0, v0, s0
	global_store_short v[2:3], v0, off
	v_lshl_add_u64 v[2:3], v[2:3], 0, s[22:23]
	v_mul_f32_e32 v0, v5, v20
	v_cvt_pk_bf16_f32 v0, v0, s0
	global_store_short v[2:3], v0, off
	v_lshl_add_u64 v[2:3], v[2:3], 0, s[22:23]
	s_cbranch_vccnz .LBB0_331
	s_andn2_b64 vcc, exec, s[8:9]
	s_cbranch_vccnz .LBB0_330
	s_barrier
	s_branch .LBB0_330

; DI u32x4 pack8(f32x4 a, f32x4 b) { u32x4 w; w.x = pk2(a[0], a[1]); w.y = pk2(a[2], a[3]); w.z = pk2(b[0], b[1]); w.w = pk2(b[2], b[3]); return w; }
;     DI void operator()(AccRef acc, const Unit& u, int wr, int wc, int fr, int fq) const {
;     ...
;             for (int m = 0; m < 4; ++m) { int row = row0 + ai * 128 + m * 16; asm volatile("" : "+v"(row) :: "memory"); const int b = row >> 13, s = row & 8191;
;                 const float rs = __builtin_amdgcn_rsqf(SSQ[(size_t)row * 2] * (1.f / 384.f) + RMS_EPS) * QSCALE;
; #pragma unroll
;                 for (int bj = 0; bj < 2; ++bj) { const int cg_ = u.pn * 256 + bj * 128 + cl, h = cg_ / 192, d = cg_ % 192;
;                     f32x4 a = acc[ai][bj][m][0] * rs, bb = acc[ai][bj][m][1] * rs;
;                     if (d >= 128) { const int i0 = (d - 128) >> 1; const f32x4 cs = *(const f32x4*)(COS + (size_t)row * 32 + i0), sn = *(const f32x4*)(SIN + (size_t)row * 32 + i0); f32x4 oa, ob;
;                         oa[0] = a[0] * cs[0] - a[1] * sn[0]; oa[1] = a[1] * cs[0] + a[0] * sn[0]; oa[2] = a[2] * cs[1] - a[3] * sn[1]; oa[3] = a[3] * cs[1] + a[2] * sn[1];
;                         ob[0] = bb[0] * cs[2] - bb[1] * sn[2]; ob[1] = bb[1] * cs[2] + bb[0] * sn[2]; ob[2] = bb[2] * cs[3] - bb[3] * sn[3]; ob[3] = bb[3] * cs[3] + bb[2] * sn[3];
;                         a = oa; bb = ob; }
;                     *(u32x4*)(QM + ((size_t)(b * 4 + h) * SEQ + s) * 192 + d) = pack8(a, bb); asm volatile("" ::: "memory"); } }
.LBB0_371:
	s_mov_b64 s[14:15], s[0:1]
	v_lshl_add_u32 v162, s82, 8, v158
	s_add_u32 s56, s14, 0x3500000
	v_mov_b32_e32 v154, v162
	s_addc_u32 s57, s15, 0
	s_add_u32 s52, s14, 0x2c00000
	v_ashrrev_i32_e32 v155, 31, v154
	v_lshl_add_u64 v[146:147], v[154:155], 3, s[56:57]
	global_load_dword v0, v[146:147], off
	s_addc_u32 s53, s15, 0
	s_add_u32 s54, s14, 0x3000000
	v_lshl_or_b32 v163, s81, 8, v160
	s_mov_b32 s42, 0x2aaaaaab
	s_addc_u32 s55, s15, 0
	v_lshlrev_b64 v[146:147], 7, v[154:155]
	v_lshl_add_u64 v[150:151], s[52:53], 0, v[146:147]
	v_lshl_add_u64 v[148:149], s[54:55], 0, v[146:147]
	s_waitcnt vmcnt(0) lgkmcnt(0)
	v_fmamk_f32 v0, v0, 0x3b2aaaab, v231
	v_rsq_f32_e32 v0, v0
	s_nop 0
	v_mul_f32_e32 v152, 0x3dd53b94, v0
	v_mul_hi_i32 v0, v163, s42
	v_lshrrev_b32_e32 v146, 31, v0
	v_ashrrev_i32_e32 v0, 5, v0
	v_add_u32_e32 v155, v0, v146
	v_mul_lo_u32 v0, v155, s91
	v_sub_u32_e32 v146, v163, v0
	s_movk_i32 s42, 0x7f
	v_add_u32_e32 v0, 0xffffff80, v146
	v_pk_mul_f32 v[156:157], v[124:125], v[152:153] op_sel_hi:[1,0]
	v_pk_mul_f32 v[124:125], v[122:123], v[152:153] op_sel_hi:[1,0]
	v_pk_mul_f32 v[128:129], v[128:129], v[152:153] op_sel_hi:[1,0]
	v_pk_mul_f32 v[122:123], v[126:127], v[152:153] op_sel_hi:[1,0]
	v_cmp_lt_i32_e32 vcc, s42, v146
	v_lshrrev_b32_e32 v0, 1, v0
	s_and_saveexec_b64 s[42:43], vcc
	s_cbranch_execz .LBB0_373
	v_lshlrev_b64 v[126:127], 2, v[0:1]
	v_lshl_add_u64 v[164:165], v[150:151], 0, v[126:127]
	v_lshl_add_u64 v[126:127], v[148:149], 0, v[126:127]
	global_load_dwordx4 v[164:167], v[164:165], off
	s_nop 0
	global_load_dwordx4 v[168:171], v[126:127], off
	s_waitcnt vmcnt(0) lgkmcnt(0)
	v_pk_mul_f32 v[126:127], v[124:125], v[164:165]
	v_pk_mul_f32 v[172:173], v[124:125], v[168:169] op_sel:[1,0] op_sel_hi:[0,0]
	v_pk_fma_f32 v[124:125], v[124:125], v[164:165], v[172:173] op_sel_hi:[1,0,1]
	v_mov_b32_e32 v168, v165
	v_mul_f32_e32 v124, v157, v169
	v_pk_fma_f32 v[174:175], v[156:157], v[168:169], v[124:125] op_sel_hi:[1,1,0] neg_lo:[0,0,1] neg_hi:[0,0,1]
	v_mov_b32_e32 v164, v169
	v_mul_f32_e32 v124, v157, v165
	v_pk_mul_f32 v[168:169], v[122:123], v[170:171] op_sel:[1,0] op_sel_hi:[0,0]
	v_pk_fma_f32 v[164:165], v[156:157], v[164:165], v[124:125] op_sel_hi:[1,1,0]
	v_pk_mul_f32 v[156:157], v[122:123], v[166:167]
	v_pk_fma_f32 v[122:123], v[122:123], v[166:167], v[168:169] op_sel_hi:[1,0,1]
	v_mov_b32_e32 v170, v167
	v_mul_f32_e32 v122, v129, v171
	v_pk_fma_f32 v[176:177], v[128:129], v[170:171], v[122:123] op_sel_hi:[1,1,0] neg_lo:[0,0,1] neg_hi:[0,0,1]
	v_mov_b32_e32 v166, v171
	v_mul_f32_e32 v122, v129, v167
	v_pk_fma_f32 v[166:167], v[128:129], v[166:167], v[122:123] op_sel_hi:[1,1,0]
	v_sub_f32_e32 v124, v126, v172
	v_sub_f32_e32 v122, v156, v168
	v_mov_b32_e32 v156, v174
	v_mov_b32_e32 v157, v164
	v_mov_b32_e32 v128, v176
	v_mov_b32_e32 v129, v166
.LBB0_373:
	s_or_b64 exec, exec, s[42:43]
	v_ashrrev_i32_e32 v126, 11, v154
	v_and_b32_e32 v127, 0x1fff, v154
	v_and_b32_e32 v154, -4, v126
	v_cvt_pk_bf16_f32 v166, v122, v123
	v_add_u32_e32 v122, v154, v155
	s_add_u32 s50, s14, 0x17600000
	v_ashrrev_i32_e32 v123, 31, v122
	s_addc_u32 s51, s15, 0
	v_lshlrev_b64 v[122:123], 13, v[122:123]
	v_cvt_pk_bf16_f32 v164, v124, v125
	v_or_b32_e32 v122, v122, v127
	v_mov_b64_e32 v[124:125], s[50:51]
	v_mad_u64_u32 v[124:125], s[14:15], v122, s37, v[124:125]
	v_mad_i32_i24 v125, v123, s37, v125
	v_ashrrev_i32_e32 v147, 31, v146
	v_cvt_pk_bf16_f32 v165, v156, v157
	v_cvt_pk_bf16_f32 v167, v128, v129
	v_lshl_add_u64 v[122:123], v[146:147], 1, v[124:125]
	global_store_dwordx4 v[122:123], v[164:167], off
	v_or_b32_e32 v122, 0x80, v163
	s_mov_b32 s14, 0x2aaaaaab
	v_mul_hi_i32 v123, v122, s14
	v_lshrrev_b32_e32 v124, 31, v123
	v_ashrrev_i32_e32 v123, 5, v123
	v_add_u32_e32 v126, v123, v124
	v_mul_lo_u32 v123, v126, s91
	v_mov_b32_e32 v153, v152
	v_sub_u32_e32 v122, v122, v123
	v_mov_b32_e32 v128, v152
	v_mov_b32_e32 v129, v152
	v_pk_mul_f32 v[124:125], v[120:121], v[128:129]
	v_pk_mul_f32 v[120:121], v[116:117], v[128:129]
	v_pk_mul_f32 v[116:117], v[114:115], v[152:153]
	s_movk_i32 s14, 0x7f
	v_add_u32_e32 v114, 0xffffff80, v122
	v_pk_mul_f32 v[118:119], v[118:119], v[152:153]
	v_cmp_lt_i32_e64 s[42:43], s14, v122
	v_lshrrev_b32_e32 v114, 1, v114
	s_and_saveexec_b64 s[14:15], s[42:43]
	s_cbranch_execz .LBB0_375
	v_mov_b32_e32 v115, v1
	v_lshlrev_b64 v[128:129], 2, v[114:115]
	v_lshl_add_u64 v[150:151], v[150:151], 0, v[128:129]
	v_lshl_add_u64 v[128:129], v[148:149], 0, v[128:129]
	global_load_dwordx4 v[150:153], v[150:151], off
	s_nop 0
	global_load_dwordx4 v[164:167], v[128:129], off
	s_waitcnt vmcnt(0) lgkmcnt(0)
	v_pk_mul_f32 v[128:129], v[118:119], v[150:151]
	v_pk_mul_f32 v[148:149], v[118:119], v[164:165] op_sel:[1,0] op_sel_hi:[0,0]
	v_pk_fma_f32 v[118:119], v[118:119], v[150:151], v[148:149] op_sel_hi:[1,0,1]
	v_mov_b32_e32 v164, v151
	v_mul_f32_e32 v118, v125, v165
	v_pk_fma_f32 v[156:157], v[124:125], v[164:165], v[118:119] op_sel_hi:[1,1,0] neg_lo:[0,0,1] neg_hi:[0,0,1]
	v_mov_b32_e32 v150, v165
	v_mul_f32_e32 v118, v125, v151
	v_pk_mul_f32 v[164:165], v[116:117], v[166:167] op_sel:[1,0] op_sel_hi:[0,0]
	v_pk_fma_f32 v[150:151], v[124:125], v[150:151], v[118:119] op_sel_hi:[1,1,0]
	v_pk_mul_f32 v[124:125], v[116:117], v[152:153]
	v_pk_fma_f32 v[116:117], v[116:117], v[152:153], v[164:165] op_sel_hi:[1,0,1]
	v_mov_b32_e32 v166, v153
	v_mul_f32_e32 v116, v121, v167
	v_pk_fma_f32 v[168:169], v[120:121], v[166:167], v[116:117] op_sel_hi:[1,1,0] neg_lo:[0,0,1] neg_hi:[0,0,1]
	v_mov_b32_e32 v152, v167
	v_mul_f32_e32 v116, v121, v153
	v_pk_fma_f32 v[152:153], v[120:121], v[152:153], v[116:117] op_sel_hi:[1,1,0]
	v_sub_f32_e32 v118, v128, v148
	v_sub_f32_e32 v116, v124, v164
	v_mov_b32_e32 v124, v156
	v_mov_b32_e32 v125, v150
	v_mov_b32_e32 v120, v168
	v_mov_b32_e32 v121, v152
; DI u32x4 pack8(f32x4 a, f32x4 b) { u32x4 w; w.x = pk2(a[0], a[1]); w.y = pk2(a[2], a[3]); w.z = pk2(b[0], b[1]); w.w = pk2(b[2], b[3]); return w; }
;     DI void operator()(AccRef acc, const Unit& u, int wr, int wc, int fr, int fq) const {
;     ...
;             for (int m = 0; m < 4; ++m) { int row = row0 + ai * 128 + m * 16; asm volatile("" : "+v"(row) :: "memory"); const int b = row >> 13, s = row & 8191;
;                 const float rs = __builtin_amdgcn_rsqf(SSQ[(size_t)row * 2] * (1.f / 384.f) + RMS_EPS) * QSCALE;
; #pragma unroll
;                 for (int bj = 0; bj < 2; ++bj) { const int cg_ = u.pn * 256 + bj * 128 + cl, h = cg_ / 192, d = cg_ % 192;
;                     f32x4 a = acc[ai][bj][m][0] * rs, bb = acc[ai][bj][m][1] * rs;
;                     if (d >= 128) { const int i0 = (d - 128) >> 1; const f32x4 cs = *(const f32x4*)(COS + (size_t)row * 32 + i0), sn = *(const f32x4*)(SIN + (size_t)row * 32 + i0); f32x4 oa, ob;
;                         oa[0] = a[0] * cs[0] - a[1] * sn[0]; oa[1] = a[1] * cs[0] + a[0] * sn[0]; oa[2] = a[2] * cs[1] - a[3] * sn[1]; oa[3] = a[3] * cs[1] + a[2] * sn[1];
;                         ob[0] = bb[0] * cs[2] - bb[1] * sn[2]; ob[1] = bb[1] * cs[2] + bb[0] * sn[2]; ob[2] = bb[2] * cs[3] - bb[3] * sn[3]; ob[3] = bb[3] * cs[3] + bb[2] * sn[3];
;                         a = oa; bb = ob; }
;                     *(u32x4*)(QM + ((size_t)(b * 4 + h) * SEQ + s) * 192 + d) = pack8(a, bb); asm volatile("" ::: "memory"); } }
.LBB0_375:
	s_or_b64 exec, exec, s[14:15]
	v_cvt_pk_bf16_f32 v150, v116, v117
	v_add_u32_e32 v116, v154, v126
	v_ashrrev_i32_e32 v117, 31, v116
	v_lshlrev_b64 v[116:117], 13, v[116:117]
	v_cvt_pk_bf16_f32 v148, v118, v119
	v_or_b32_e32 v115, v116, v127
	v_mov_b64_e32 v[118:119], s[50:51]
	v_mad_u64_u32 v[118:119], s[14:15], v115, s37, v[118:119]
	v_mad_i32_i24 v119, v117, s37, v119
	v_ashrrev_i32_e32 v123, 31, v122
	v_cvt_pk_bf16_f32 v149, v124, v125
	v_cvt_pk_bf16_f32 v151, v120, v121
	v_lshl_add_u64 v[116:117], v[122:123], 1, v[118:119]
	global_store_dwordx4 v[116:117], v[148:151], off
	v_or_b32_e32 v124, 16, v162
	s_nop 0
	v_ashrrev_i32_e32 v125, 31, v124
	v_lshl_add_u64 v[116:117], v[124:125], 3, s[56:57]
	global_load_dword v115, v[116:117], off
	v_lshlrev_b64 v[116:117], 7, v[124:125]
	v_lshl_add_u64 v[118:119], s[52:53], 0, v[116:117]
	v_lshl_add_u64 v[116:117], s[54:55], 0, v[116:117]
	s_waitcnt vmcnt(0) lgkmcnt(0)
	v_fmamk_f32 v115, v115, 0x3b2aaaab, v231
	v_rsq_f32_e32 v115, v115
	s_nop 0
	v_mul_f32_e32 v120, 0x3dd53b94, v115
	v_pk_mul_f32 v[112:113], v[112:113], v[120:121] op_sel_hi:[1,0]
	v_pk_mul_f32 v[110:111], v[110:111], v[120:121] op_sel_hi:[1,0]
	v_pk_mul_f32 v[108:109], v[108:109], v[120:121] op_sel_hi:[1,0]
	v_pk_mul_f32 v[106:107], v[106:107], v[120:121] op_sel_hi:[1,0]
	s_and_saveexec_b64 s[14:15], vcc
	s_cbranch_execz .LBB0_377
	v_lshlrev_b64 v[128:129], 2, v[0:1]
	v_lshl_add_u64 v[148:149], v[118:119], 0, v[128:129]
	v_lshl_add_u64 v[128:129], v[116:117], 0, v[128:129]
	global_load_dwordx4 v[148:151], v[148:149], off
	s_nop 0
	global_load_dwordx4 v[164:167], v[128:129], off
	s_waitcnt vmcnt(0) lgkmcnt(0)
	v_pk_mul_f32 v[128:129], v[110:111], v[148:149]
	v_pk_mul_f32 v[152:153], v[110:111], v[164:165] op_sel:[1,0] op_sel_hi:[0,0]
	v_pk_fma_f32 v[110:111], v[110:111], v[148:149], v[152:153] op_sel_hi:[1,0,1]
	v_mov_b32_e32 v164, v149
	v_mul_f32_e32 v110, v113, v165
	v_pk_fma_f32 v[156:157], v[112:113], v[164:165], v[110:111] op_sel_hi:[1,1,0] neg_lo:[0,0,1] neg_hi:[0,0,1]
	v_mov_b32_e32 v148, v165
	v_mul_f32_e32 v110, v113, v149
	v_pk_mul_f32 v[164:165], v[106:107], v[166:167] op_sel:[1,0] op_sel_hi:[0,0]
	v_pk_fma_f32 v[148:149], v[112:113], v[148:149], v[110:111] op_sel_hi:[1,1,0]
	v_pk_mul_f32 v[112:113], v[106:107], v[150:151]
	v_pk_fma_f32 v[106:107], v[106:107], v[150:151], v[164:165] op_sel_hi:[1,0,1]
	v_mov_b32_e32 v166, v151
	v_mul_f32_e32 v106, v109, v167
	v_pk_fma_f32 v[168:169], v[108:109], v[166:167], v[106:107] op_sel_hi:[1,1,0] neg_lo:[0,0,1] neg_hi:[0,0,1]
	v_mov_b32_e32 v150, v167
	v_mul_f32_e32 v106, v109, v151
	v_pk_fma_f32 v[150:151], v[108:109], v[150:151], v[106:107] op_sel_hi:[1,1,0]
	v_sub_f32_e32 v110, v128, v152
	v_sub_f32_e32 v106, v112, v164
	v_mov_b32_e32 v112, v156
	v_mov_b32_e32 v113, v148
	v_mov_b32_e32 v108, v168
	v_mov_b32_e32 v109, v150
.LBB0_377:
	s_or_b64 exec, exec, s[14:15]
	v_ashrrev_i32_e32 v115, 11, v124
	v_and_b32_e32 v125, 0x1fff, v124
	v_and_b32_e32 v124, -4, v115
	v_cvt_pk_bf16_f32 v110, v110, v111
	v_cvt_pk_bf16_f32 v111, v112, v113
	v_cvt_pk_bf16_f32 v112, v106, v107
	v_add_u32_e32 v106, v124, v155
	v_ashrrev_i32_e32 v107, 31, v106
	v_lshlrev_b64 v[106:107], 13, v[106:107]
	v_cvt_pk_bf16_f32 v113, v108, v109
	v_or_b32_e32 v106, v106, v125
	v_mov_b64_e32 v[108:109], s[50:51]
	v_mad_u64_u32 v[108:109], s[14:15], v106, s37, v[108:109]
	v_mad_i32_i24 v109, v107, s37, v109
	v_lshl_add_u64 v[106:107], v[146:147], 1, v[108:109]
	global_store_dwordx4 v[106:107], v[110:113], off
	v_mov_b32_e32 v121, v120
	v_mov_b32_e32 v106, v120
	v_mov_b32_e32 v107, v120
	v_pk_mul_f32 v[104:105], v[104:105], v[106:107]
	v_pk_mul_f32 v[102:103], v[102:103], v[120:121]
	v_pk_mul_f32 v[100:101], v[100:101], v[106:107]
	v_pk_mul_f32 v[98:99], v[98:99], v[120:121]
	s_and_saveexec_b64 s[14:15], s[42:43]
	s_cbranch_execz .LBB0_379
	v_mov_b32_e32 v115, v1
	v_lshlrev_b64 v[110:111], 2, v[114:115]
	v_lshl_add_u64 v[106:107], v[118:119], 0, v[110:111]
	v_lshl_add_u64 v[110:111], v[116:117], 0, v[110:111]
	global_load_dwordx4 v[106:109], v[106:107], off
	s_nop 0
	global_load_dwordx4 v[110:113], v[110:111], off
	s_waitcnt vmcnt(0) lgkmcnt(0)
	v_pk_mul_f32 v[116:117], v[102:103], v[106:107]
	v_pk_mul_f32 v[118:119], v[102:103], v[110:111] op_sel:[1,0] op_sel_hi:[0,0]
	v_pk_fma_f32 v[102:103], v[102:103], v[106:107], v[118:119] op_sel_hi:[1,0,1]
	v_mov_b32_e32 v110, v107
	v_mul_f32_e32 v102, v105, v111
	v_pk_fma_f32 v[120:121], v[104:105], v[110:111], v[102:103] op_sel_hi:[1,1,0] neg_lo:[0,0,1] neg_hi:[0,0,1]
	v_mov_b32_e32 v106, v111
	v_mul_f32_e32 v102, v105, v107
	v_pk_mul_f32 v[110:111], v[98:99], v[112:113] op_sel:[1,0] op_sel_hi:[0,0]
	v_pk_fma_f32 v[106:107], v[104:105], v[106:107], v[102:103] op_sel_hi:[1,1,0]
	v_pk_mul_f32 v[104:105], v[98:99], v[108:109]
	v_pk_fma_f32 v[98:99], v[98:99], v[108:109], v[110:111] op_sel_hi:[1,0,1]
	v_mov_b32_e32 v112, v109
	v_mul_f32_e32 v98, v101, v113
	v_pk_fma_f32 v[128:129], v[100:101], v[112:113], v[98:99] op_sel_hi:[1,1,0] neg_lo:[0,0,1] neg_hi:[0,0,1]
	v_mov_b32_e32 v108, v113
	v_mul_f32_e32 v98, v101, v109
	v_pk_fma_f32 v[108:109], v[100:101], v[108:109], v[98:99] op_sel_hi:[1,1,0]
	v_sub_f32_e32 v102, v116, v118
	v_sub_f32_e32 v98, v104, v110
	v_mov_b32_e32 v104, v120
	v_mov_b32_e32 v105, v106
	v_mov_b32_e32 v100, v128
	v_mov_b32_e32 v101, v108
; DI u32x4 pack8(f32x4 a, f32x4 b) { u32x4 w; w.x = pk2(a[0], a[1]); w.y = pk2(a[2], a[3]); w.z = pk2(b[0], b[1]); w.w = pk2(b[2], b[3]); return w; }
;     DI void operator()(AccRef acc, const Unit& u, int wr, int wc, int fr, int fq) const {
;     ...
;             for (int m = 0; m < 4; ++m) { int row = row0 + ai * 128 + m * 16; asm volatile("" : "+v"(row) :: "memory"); const int b = row >> 13, s = row & 8191;
;                 const float rs = __builtin_amdgcn_rsqf(SSQ[(size_t)row * 2] * (1.f / 384.f) + RMS_EPS) * QSCALE;
; #pragma unroll
;                 for (int bj = 0; bj < 2; ++bj) { const int cg_ = u.pn * 256 + bj * 128 + cl, h = cg_ / 192, d = cg_ % 192;
;                     f32x4 a = acc[ai][bj][m][0] * rs, bb = acc[ai][bj][m][1] * rs;
;                     if (d >= 128) { const int i0 = (d - 128) >> 1; const f32x4 cs = *(const f32x4*)(COS + (size_t)row * 32 + i0), sn = *(const f32x4*)(SIN + (size_t)row * 32 + i0); f32x4 oa, ob;
;                         oa[0] = a[0] * cs[0] - a[1] * sn[0]; oa[1] = a[1] * cs[0] + a[0] * sn[0]; oa[2] = a[2] * cs[1] - a[3] * sn[1]; oa[3] = a[3] * cs[1] + a[2] * sn[1];
;                         ob[0] = bb[0] * cs[2] - bb[1] * sn[2]; ob[1] = bb[1] * cs[2] + bb[0] * sn[2]; ob[2] = bb[2] * cs[3] - bb[3] * sn[3]; ob[3] = bb[3] * cs[3] + bb[2] * sn[3];
;                         a = oa; bb = ob; }
;                     *(u32x4*)(QM + ((size_t)(b * 4 + h) * SEQ + s) * 192 + d) = pack8(a, bb); asm volatile("" ::: "memory"); } }
.LBB0_379:
	s_or_b64 exec, exec, s[14:15]
	v_cvt_pk_bf16_f32 v102, v102, v103
	v_cvt_pk_bf16_f32 v103, v104, v105
	v_cvt_pk_bf16_f32 v104, v98, v99
	v_add_u32_e32 v98, v124, v126
	v_ashrrev_i32_e32 v99, 31, v98
	v_lshlrev_b64 v[98:99], 13, v[98:99]
	v_cvt_pk_bf16_f32 v105, v100, v101
	v_or_b32_e32 v98, v98, v125
	v_mov_b64_e32 v[100:101], s[50:51]
	v_mad_u64_u32 v[100:101], s[14:15], v98, s37, v[100:101]
	v_mad_i32_i24 v101, v99, s37, v101
	v_lshl_add_u64 v[98:99], v[122:123], 1, v[100:101]
	global_store_dwordx4 v[98:99], v[102:105], off
	s_nop 1
	v_or_b32_e32 v104, 32, v162
	s_nop 0
	v_ashrrev_i32_e32 v105, 31, v104
	v_lshl_add_u64 v[98:99], v[104:105], 3, s[56:57]
	global_load_dword v98, v[98:99], off
	s_waitcnt vmcnt(0) lgkmcnt(0)
	v_fmamk_f32 v98, v98, 0x3b2aaaab, v231
	v_rsq_f32_e32 v102, v98
	v_lshlrev_b64 v[98:99], 7, v[104:105]
	v_lshl_add_u64 v[100:101], s[52:53], 0, v[98:99]
	v_lshl_add_u64 v[98:99], s[54:55], 0, v[98:99]
	v_mul_f32_e32 v102, 0x3dd53b94, v102
	v_pk_mul_f32 v[96:97], v[96:97], v[102:103] op_sel_hi:[1,0]
	v_pk_mul_f32 v[94:95], v[94:95], v[102:103] op_sel_hi:[1,0]
	v_pk_mul_f32 v[92:93], v[92:93], v[102:103] op_sel_hi:[1,0]
	v_pk_mul_f32 v[90:91], v[90:91], v[102:103] op_sel_hi:[1,0]
	s_and_saveexec_b64 s[14:15], vcc
	s_cbranch_execz .LBB0_381
	v_lshlrev_b64 v[110:111], 2, v[0:1]
	v_lshl_add_u64 v[106:107], v[100:101], 0, v[110:111]
	v_lshl_add_u64 v[110:111], v[98:99], 0, v[110:111]
	global_load_dwordx4 v[106:109], v[106:107], off
	s_nop 0
	global_load_dwordx4 v[110:113], v[110:111], off
	s_waitcnt vmcnt(0) lgkmcnt(0)
	v_pk_mul_f32 v[116:117], v[94:95], v[106:107]
	v_pk_mul_f32 v[118:119], v[94:95], v[110:111] op_sel:[1,0] op_sel_hi:[0,0]
	v_pk_fma_f32 v[94:95], v[94:95], v[106:107], v[118:119] op_sel_hi:[1,0,1]
	v_mov_b32_e32 v110, v107
	v_mul_f32_e32 v94, v97, v111
	v_pk_fma_f32 v[120:121], v[96:97], v[110:111], v[94:95] op_sel_hi:[1,1,0] neg_lo:[0,0,1] neg_hi:[0,0,1]
	v_mov_b32_e32 v106, v111
	v_mul_f32_e32 v94, v97, v107
	v_pk_mul_f32 v[110:111], v[90:91], v[112:113] op_sel:[1,0] op_sel_hi:[0,0]
	v_pk_fma_f32 v[106:107], v[96:97], v[106:107], v[94:95] op_sel_hi:[1,1,0]
	v_pk_mul_f32 v[96:97], v[90:91], v[108:109]
	v_pk_fma_f32 v[90:91], v[90:91], v[108:109], v[110:111] op_sel_hi:[1,0,1]
	v_mov_b32_e32 v112, v109
	v_mul_f32_e32 v90, v93, v113
	v_pk_fma_f32 v[124:125], v[92:93], v[112:113], v[90:91] op_sel_hi:[1,1,0] neg_lo:[0,0,1] neg_hi:[0,0,1]
	v_mov_b32_e32 v108, v113
	v_mul_f32_e32 v90, v93, v109
	v_pk_fma_f32 v[108:109], v[92:93], v[108:109], v[90:91] op_sel_hi:[1,1,0]
	v_sub_f32_e32 v94, v116, v118
	v_sub_f32_e32 v90, v96, v110
	v_mov_b32_e32 v96, v120
	v_mov_b32_e32 v97, v106
	v_mov_b32_e32 v92, v124
	v_mov_b32_e32 v93, v108
.LBB0_381:
	s_or_b64 exec, exec, s[14:15]
	v_and_b32_e32 v105, 0x1fff, v104
	v_ashrrev_i32_e32 v104, 11, v104
	v_and_b32_e32 v104, -4, v104
	v_cvt_pk_bf16_f32 v94, v94, v95
	v_cvt_pk_bf16_f32 v95, v96, v97
	v_cvt_pk_bf16_f32 v96, v90, v91
	v_add_u32_e32 v90, v104, v155
	v_ashrrev_i32_e32 v91, 31, v90
	v_lshlrev_b64 v[90:91], 13, v[90:91]
	v_cvt_pk_bf16_f32 v97, v92, v93
	v_or_b32_e32 v90, v90, v105
	v_mov_b64_e32 v[92:93], s[50:51]
	v_mad_u64_u32 v[92:93], s[14:15], v90, s37, v[92:93]
	v_mad_i32_i24 v93, v91, s37, v93
	v_lshl_add_u64 v[90:91], v[146:147], 1, v[92:93]
	global_store_dwordx4 v[90:91], v[94:97], off
	v_mov_b32_e32 v103, v102
	v_mov_b32_e32 v90, v102
	v_mov_b32_e32 v91, v102
	v_pk_mul_f32 v[88:89], v[88:89], v[90:91]
	v_pk_mul_f32 v[86:87], v[86:87], v[102:103]
	v_pk_mul_f32 v[84:85], v[84:85], v[90:91]
	v_pk_mul_f32 v[82:83], v[82:83], v[102:103]
	s_and_saveexec_b64 s[14:15], s[42:43]
	s_cbranch_execz .LBB0_383
	v_mov_b32_e32 v115, v1
	v_lshlrev_b64 v[94:95], 2, v[114:115]
	v_lshl_add_u64 v[90:91], v[100:101], 0, v[94:95]
	v_lshl_add_u64 v[94:95], v[98:99], 0, v[94:95]
	global_load_dwordx4 v[90:93], v[90:91], off
	s_nop 0
	global_load_dwordx4 v[94:97], v[94:95], off
	s_waitcnt vmcnt(0) lgkmcnt(0)
	v_pk_mul_f32 v[98:99], v[86:87], v[90:91]
	v_pk_mul_f32 v[100:101], v[86:87], v[94:95] op_sel:[1,0] op_sel_hi:[0,0]
	v_pk_fma_f32 v[86:87], v[86:87], v[90:91], v[100:101] op_sel_hi:[1,0,1]
	v_mov_b32_e32 v94, v91
	v_mul_f32_e32 v86, v89, v95
	v_pk_fma_f32 v[102:103], v[88:89], v[94:95], v[86:87] op_sel_hi:[1,1,0] neg_lo:[0,0,1] neg_hi:[0,0,1]
	v_mov_b32_e32 v90, v95
	v_mul_f32_e32 v86, v89, v91
	v_pk_mul_f32 v[94:95], v[82:83], v[96:97] op_sel:[1,0] op_sel_hi:[0,0]
	v_pk_fma_f32 v[90:91], v[88:89], v[90:91], v[86:87] op_sel_hi:[1,1,0]
	v_pk_mul_f32 v[88:89], v[82:83], v[92:93]
	v_pk_fma_f32 v[82:83], v[82:83], v[92:93], v[94:95] op_sel_hi:[1,0,1]
	v_mov_b32_e32 v96, v93
	v_mul_f32_e32 v82, v85, v97
	v_pk_fma_f32 v[106:107], v[84:85], v[96:97], v[82:83] op_sel_hi:[1,1,0] neg_lo:[0,0,1] neg_hi:[0,0,1]
	v_mov_b32_e32 v92, v97
	v_mul_f32_e32 v82, v85, v93
	v_pk_fma_f32 v[92:93], v[84:85], v[92:93], v[82:83] op_sel_hi:[1,1,0]
	v_sub_f32_e32 v86, v98, v100
	v_sub_f32_e32 v82, v88, v94
	v_mov_b32_e32 v88, v102
	v_mov_b32_e32 v89, v90
	v_mov_b32_e32 v84, v106
	v_mov_b32_e32 v85, v92
; DI u32x4 pack8(f32x4 a, f32x4 b) { u32x4 w; w.x = pk2(a[0], a[1]); w.y = pk2(a[2], a[3]); w.z = pk2(b[0], b[1]); w.w = pk2(b[2], b[3]); return w; }
;     DI void operator()(AccRef acc, const Unit& u, int wr, int wc, int fr, int fq) const {
;     ...
;             for (int m = 0; m < 4; ++m) { int row = row0 + ai * 128 + m * 16; asm volatile("" : "+v"(row) :: "memory"); const int b = row >> 13, s = row & 8191;
;                 const float rs = __builtin_amdgcn_rsqf(SSQ[(size_t)row * 2] * (1.f / 384.f) + RMS_EPS) * QSCALE;
; #pragma unroll
;                 for (int bj = 0; bj < 2; ++bj) { const int cg_ = u.pn * 256 + bj * 128 + cl, h = cg_ / 192, d = cg_ % 192;
;                     f32x4 a = acc[ai][bj][m][0] * rs, bb = acc[ai][bj][m][1] * rs;
;                     if (d >= 128) { const int i0 = (d - 128) >> 1; const f32x4 cs = *(const f32x4*)(COS + (size_t)row * 32 + i0), sn = *(const f32x4*)(SIN + (size_t)row * 32 + i0); f32x4 oa, ob;
;                         oa[0] = a[0] * cs[0] - a[1] * sn[0]; oa[1] = a[1] * cs[0] + a[0] * sn[0]; oa[2] = a[2] * cs[1] - a[3] * sn[1]; oa[3] = a[3] * cs[1] + a[2] * sn[1];
;                         ob[0] = bb[0] * cs[2] - bb[1] * sn[2]; ob[1] = bb[1] * cs[2] + bb[0] * sn[2]; ob[2] = bb[2] * cs[3] - bb[3] * sn[3]; ob[3] = bb[3] * cs[3] + bb[2] * sn[3];
;                         a = oa; bb = ob; }
;                     *(u32x4*)(QM + ((size_t)(b * 4 + h) * SEQ + s) * 192 + d) = pack8(a, bb); asm volatile("" ::: "memory"); } }
.LBB0_383:
	s_or_b64 exec, exec, s[14:15]
	v_cvt_pk_bf16_f32 v86, v86, v87
	v_cvt_pk_bf16_f32 v87, v88, v89
	v_cvt_pk_bf16_f32 v88, v82, v83
	v_add_u32_e32 v82, v104, v126
	v_ashrrev_i32_e32 v83, 31, v82
	v_lshlrev_b64 v[82:83], 13, v[82:83]
	v_cvt_pk_bf16_f32 v89, v84, v85
	v_or_b32_e32 v82, v82, v105
	v_mov_b64_e32 v[84:85], s[50:51]
	v_mad_u64_u32 v[84:85], s[14:15], v82, s37, v[84:85]
	v_mad_i32_i24 v85, v83, s37, v85
	v_lshl_add_u64 v[82:83], v[122:123], 1, v[84:85]
	global_store_dwordx4 v[82:83], v[86:89], off
	s_nop 1
	v_or_b32_e32 v88, 48, v162
	s_nop 0
	v_ashrrev_i32_e32 v89, 31, v88
	v_lshl_add_u64 v[82:83], v[88:89], 3, s[56:57]
	global_load_dword v82, v[82:83], off
	s_waitcnt vmcnt(0) lgkmcnt(0)
	v_fmamk_f32 v82, v82, 0x3b2aaaab, v231
	v_rsq_f32_e32 v86, v82
	v_lshlrev_b64 v[82:83], 7, v[88:89]
	v_lshl_add_u64 v[84:85], s[52:53], 0, v[82:83]
	v_lshl_add_u64 v[82:83], s[54:55], 0, v[82:83]
	v_mul_f32_e32 v86, 0x3dd53b94, v86
	v_pk_mul_f32 v[80:81], v[80:81], v[86:87] op_sel_hi:[1,0]
	v_pk_mul_f32 v[78:79], v[78:79], v[86:87] op_sel_hi:[1,0]
	v_pk_mul_f32 v[76:77], v[76:77], v[86:87] op_sel_hi:[1,0]
	v_pk_mul_f32 v[74:75], v[74:75], v[86:87] op_sel_hi:[1,0]
	s_and_saveexec_b64 s[14:15], vcc
	s_cbranch_execz .LBB0_385
	v_lshlrev_b64 v[94:95], 2, v[0:1]
	v_lshl_add_u64 v[90:91], v[84:85], 0, v[94:95]
	v_lshl_add_u64 v[94:95], v[82:83], 0, v[94:95]
	global_load_dwordx4 v[90:93], v[90:91], off
	s_nop 0
	global_load_dwordx4 v[94:97], v[94:95], off
	s_waitcnt vmcnt(0) lgkmcnt(0)
	v_pk_mul_f32 v[98:99], v[78:79], v[90:91]
	v_pk_mul_f32 v[100:101], v[78:79], v[94:95] op_sel:[1,0] op_sel_hi:[0,0]
	v_pk_fma_f32 v[78:79], v[78:79], v[90:91], v[100:101] op_sel_hi:[1,0,1]
	v_mov_b32_e32 v94, v91
	v_mul_f32_e32 v78, v81, v95
	v_pk_fma_f32 v[102:103], v[80:81], v[94:95], v[78:79] op_sel_hi:[1,1,0] neg_lo:[0,0,1] neg_hi:[0,0,1]
	v_mov_b32_e32 v90, v95
	v_mul_f32_e32 v78, v81, v91
	v_pk_mul_f32 v[94:95], v[74:75], v[96:97] op_sel:[1,0] op_sel_hi:[0,0]
	v_pk_fma_f32 v[90:91], v[80:81], v[90:91], v[78:79] op_sel_hi:[1,1,0]
	v_pk_mul_f32 v[80:81], v[74:75], v[92:93]
	v_pk_fma_f32 v[74:75], v[74:75], v[92:93], v[94:95] op_sel_hi:[1,0,1]
	v_mov_b32_e32 v96, v93
	v_mul_f32_e32 v74, v77, v97
	v_pk_fma_f32 v[104:105], v[76:77], v[96:97], v[74:75] op_sel_hi:[1,1,0] neg_lo:[0,0,1] neg_hi:[0,0,1]
	v_mov_b32_e32 v92, v97
	v_mul_f32_e32 v74, v77, v93
	v_pk_fma_f32 v[92:93], v[76:77], v[92:93], v[74:75] op_sel_hi:[1,1,0]
	v_sub_f32_e32 v78, v98, v100
	v_sub_f32_e32 v74, v80, v94
	v_mov_b32_e32 v80, v102
	v_mov_b32_e32 v81, v90
	v_mov_b32_e32 v76, v104
	v_mov_b32_e32 v77, v92
.LBB0_385:
	s_or_b64 exec, exec, s[14:15]
	v_and_b32_e32 v89, 0x1fff, v88
	v_ashrrev_i32_e32 v88, 11, v88
	v_and_b32_e32 v88, -4, v88
	v_cvt_pk_bf16_f32 v78, v78, v79
	v_cvt_pk_bf16_f32 v79, v80, v81
	v_cvt_pk_bf16_f32 v80, v74, v75
	v_add_u32_e32 v74, v88, v155
	v_ashrrev_i32_e32 v75, 31, v74
	v_lshlrev_b64 v[74:75], 13, v[74:75]
	v_cvt_pk_bf16_f32 v81, v76, v77
	v_or_b32_e32 v74, v74, v89
	v_mov_b64_e32 v[76:77], s[50:51]
	v_mad_u64_u32 v[76:77], s[14:15], v74, s37, v[76:77]
	v_mad_i32_i24 v77, v75, s37, v77
	v_lshl_add_u64 v[74:75], v[146:147], 1, v[76:77]
	global_store_dwordx4 v[74:75], v[78:81], off
	v_mov_b32_e32 v87, v86
	v_mov_b32_e32 v74, v86
	v_mov_b32_e32 v75, v86
	v_pk_mul_f32 v[72:73], v[72:73], v[74:75]
	v_pk_mul_f32 v[70:71], v[70:71], v[86:87]
	v_pk_mul_f32 v[68:69], v[68:69], v[74:75]
	v_pk_mul_f32 v[66:67], v[66:67], v[86:87]
	s_and_saveexec_b64 s[14:15], s[42:43]
	s_cbranch_execz .LBB0_387
	v_mov_b32_e32 v115, v1
	v_lshlrev_b64 v[78:79], 2, v[114:115]
	v_lshl_add_u64 v[74:75], v[84:85], 0, v[78:79]
	v_lshl_add_u64 v[78:79], v[82:83], 0, v[78:79]
	global_load_dwordx4 v[74:77], v[74:75], off
	s_nop 0
	global_load_dwordx4 v[78:81], v[78:79], off
	s_waitcnt vmcnt(0) lgkmcnt(0)
	v_pk_mul_f32 v[82:83], v[70:71], v[74:75]
	v_pk_mul_f32 v[84:85], v[70:71], v[78:79] op_sel:[1,0] op_sel_hi:[0,0]
	v_pk_fma_f32 v[70:71], v[70:71], v[74:75], v[84:85] op_sel_hi:[1,0,1]
	v_mov_b32_e32 v78, v75
	v_mul_f32_e32 v70, v73, v79
	v_pk_fma_f32 v[86:87], v[72:73], v[78:79], v[70:71] op_sel_hi:[1,1,0] neg_lo:[0,0,1] neg_hi:[0,0,1]
	v_mov_b32_e32 v74, v79
	v_mul_f32_e32 v70, v73, v75
	v_pk_mul_f32 v[78:79], v[66:67], v[80:81] op_sel:[1,0] op_sel_hi:[0,0]
	v_pk_fma_f32 v[74:75], v[72:73], v[74:75], v[70:71] op_sel_hi:[1,1,0]
	v_pk_mul_f32 v[72:73], v[66:67], v[76:77]
	v_pk_fma_f32 v[66:67], v[66:67], v[76:77], v[78:79] op_sel_hi:[1,0,1]
	v_mov_b32_e32 v80, v77
	v_mul_f32_e32 v66, v69, v81
	v_pk_fma_f32 v[90:91], v[68:69], v[80:81], v[66:67] op_sel_hi:[1,1,0] neg_lo:[0,0,1] neg_hi:[0,0,1]
	v_mov_b32_e32 v76, v81
	v_mul_f32_e32 v66, v69, v77
	v_pk_fma_f32 v[76:77], v[68:69], v[76:77], v[66:67] op_sel_hi:[1,1,0]
	v_sub_f32_e32 v70, v82, v84
	v_sub_f32_e32 v66, v72, v78
	v_mov_b32_e32 v72, v86
	v_mov_b32_e32 v73, v74
	v_mov_b32_e32 v68, v90
	v_mov_b32_e32 v69, v76
; DI u32x4 pack8(f32x4 a, f32x4 b) { u32x4 w; w.x = pk2(a[0], a[1]); w.y = pk2(a[2], a[3]); w.z = pk2(b[0], b[1]); w.w = pk2(b[2], b[3]); return w; }
;     DI void operator()(AccRef acc, const Unit& u, int wr, int wc, int fr, int fq) const {
;     ...
;             for (int m = 0; m < 4; ++m) { int row = row0 + ai * 128 + m * 16; asm volatile("" : "+v"(row) :: "memory"); const int b = row >> 13, s = row & 8191;
;                 const float rs = __builtin_amdgcn_rsqf(SSQ[(size_t)row * 2] * (1.f / 384.f) + RMS_EPS) * QSCALE;
; #pragma unroll
;                 for (int bj = 0; bj < 2; ++bj) { const int cg_ = u.pn * 256 + bj * 128 + cl, h = cg_ / 192, d = cg_ % 192;
;                     f32x4 a = acc[ai][bj][m][0] * rs, bb = acc[ai][bj][m][1] * rs;
;                     if (d >= 128) { const int i0 = (d - 128) >> 1; const f32x4 cs = *(const f32x4*)(COS + (size_t)row * 32 + i0), sn = *(const f32x4*)(SIN + (size_t)row * 32 + i0); f32x4 oa, ob;
;                         oa[0] = a[0] * cs[0] - a[1] * sn[0]; oa[1] = a[1] * cs[0] + a[0] * sn[0]; oa[2] = a[2] * cs[1] - a[3] * sn[1]; oa[3] = a[3] * cs[1] + a[2] * sn[1];
;                         ob[0] = bb[0] * cs[2] - bb[1] * sn[2]; ob[1] = bb[1] * cs[2] + bb[0] * sn[2]; ob[2] = bb[2] * cs[3] - bb[3] * sn[3]; ob[3] = bb[3] * cs[3] + bb[2] * sn[3];
;                         a = oa; bb = ob; }
;                     *(u32x4*)(QM + ((size_t)(b * 4 + h) * SEQ + s) * 192 + d) = pack8(a, bb); asm volatile("" ::: "memory"); } }
.LBB0_387:
	s_or_b64 exec, exec, s[14:15]
	v_cvt_pk_bf16_f32 v70, v70, v71
	v_cvt_pk_bf16_f32 v71, v72, v73
	v_cvt_pk_bf16_f32 v72, v66, v67
	v_add_u32_e32 v66, v88, v126
	v_ashrrev_i32_e32 v67, 31, v66
	v_lshlrev_b64 v[66:67], 13, v[66:67]
	v_cvt_pk_bf16_f32 v73, v68, v69
	v_or_b32_e32 v66, v66, v89
	v_mov_b64_e32 v[68:69], s[50:51]
	v_mad_u64_u32 v[68:69], s[14:15], v66, s37, v[68:69]
	v_mad_i32_i24 v69, v67, s37, v69
	v_lshl_add_u64 v[66:67], v[122:123], 1, v[68:69]
	global_store_dwordx4 v[66:67], v[70:73], off
	s_nop 1
	v_add_u32_e32 v72, 0x80, v162
	s_nop 0
	v_ashrrev_i32_e32 v73, 31, v72
	v_lshl_add_u64 v[66:67], v[72:73], 3, s[56:57]
	global_load_dword v66, v[66:67], off
	s_waitcnt vmcnt(0) lgkmcnt(0)
	v_fmamk_f32 v66, v66, 0x3b2aaaab, v231
	v_rsq_f32_e32 v70, v66
	v_lshlrev_b64 v[66:67], 7, v[72:73]
	v_lshl_add_u64 v[68:69], s[52:53], 0, v[66:67]
	v_lshl_add_u64 v[66:67], s[54:55], 0, v[66:67]
	v_mul_f32_e32 v70, 0x3dd53b94, v70
	v_pk_mul_f32 v[64:65], v[64:65], v[70:71] op_sel_hi:[1,0]
	v_pk_mul_f32 v[62:63], v[62:63], v[70:71] op_sel_hi:[1,0]
	v_pk_mul_f32 v[60:61], v[60:61], v[70:71] op_sel_hi:[1,0]
	v_pk_mul_f32 v[58:59], v[58:59], v[70:71] op_sel_hi:[1,0]
	s_and_saveexec_b64 s[14:15], vcc
	s_cbranch_execz .LBB0_389
	v_lshlrev_b64 v[78:79], 2, v[0:1]
	v_lshl_add_u64 v[74:75], v[68:69], 0, v[78:79]
	v_lshl_add_u64 v[78:79], v[66:67], 0, v[78:79]
	global_load_dwordx4 v[74:77], v[74:75], off
	s_nop 0
	global_load_dwordx4 v[78:81], v[78:79], off
	s_waitcnt vmcnt(0) lgkmcnt(0)
	v_pk_mul_f32 v[82:83], v[62:63], v[74:75]
	v_pk_mul_f32 v[84:85], v[62:63], v[78:79] op_sel:[1,0] op_sel_hi:[0,0]
	v_pk_fma_f32 v[62:63], v[62:63], v[74:75], v[84:85] op_sel_hi:[1,0,1]
	v_mov_b32_e32 v78, v75
	v_mul_f32_e32 v62, v65, v79
	v_pk_fma_f32 v[86:87], v[64:65], v[78:79], v[62:63] op_sel_hi:[1,1,0] neg_lo:[0,0,1] neg_hi:[0,0,1]
	v_mov_b32_e32 v74, v79
	v_mul_f32_e32 v62, v65, v75
	v_pk_mul_f32 v[78:79], v[58:59], v[80:81] op_sel:[1,0] op_sel_hi:[0,0]
	v_pk_fma_f32 v[74:75], v[64:65], v[74:75], v[62:63] op_sel_hi:[1,1,0]
	v_pk_mul_f32 v[64:65], v[58:59], v[76:77]
	v_pk_fma_f32 v[58:59], v[58:59], v[76:77], v[78:79] op_sel_hi:[1,0,1]
	v_mov_b32_e32 v80, v77
	v_mul_f32_e32 v58, v61, v81
	v_pk_fma_f32 v[88:89], v[60:61], v[80:81], v[58:59] op_sel_hi:[1,1,0] neg_lo:[0,0,1] neg_hi:[0,0,1]
	v_mov_b32_e32 v76, v81
	v_mul_f32_e32 v58, v61, v77
	v_pk_fma_f32 v[76:77], v[60:61], v[76:77], v[58:59] op_sel_hi:[1,1,0]
	v_sub_f32_e32 v62, v82, v84
	v_sub_f32_e32 v58, v64, v78
	v_mov_b32_e32 v64, v86
	v_mov_b32_e32 v65, v74
	v_mov_b32_e32 v60, v88
	v_mov_b32_e32 v61, v76
.LBB0_389:
	s_or_b64 exec, exec, s[14:15]
	v_and_b32_e32 v73, 0x1fff, v72
	v_ashrrev_i32_e32 v72, 11, v72
	v_and_b32_e32 v72, -4, v72
	v_cvt_pk_bf16_f32 v62, v62, v63
	v_cvt_pk_bf16_f32 v63, v64, v65
	v_cvt_pk_bf16_f32 v64, v58, v59
	v_add_u32_e32 v58, v72, v155
	v_ashrrev_i32_e32 v59, 31, v58
	v_lshlrev_b64 v[58:59], 13, v[58:59]
	v_cvt_pk_bf16_f32 v65, v60, v61
	v_or_b32_e32 v58, v58, v73
	v_mov_b64_e32 v[60:61], s[50:51]
	v_mad_u64_u32 v[60:61], s[14:15], v58, s37, v[60:61]
	v_mad_i32_i24 v61, v59, s37, v61
	v_lshl_add_u64 v[58:59], v[146:147], 1, v[60:61]
	global_store_dwordx4 v[58:59], v[62:65], off
	v_mov_b32_e32 v71, v70
	v_mov_b32_e32 v58, v70
	v_mov_b32_e32 v59, v70
	v_pk_mul_f32 v[56:57], v[56:57], v[58:59]
	v_pk_mul_f32 v[54:55], v[54:55], v[70:71]
	v_pk_mul_f32 v[52:53], v[52:53], v[58:59]
	v_pk_mul_f32 v[50:51], v[50:51], v[70:71]
	s_and_saveexec_b64 s[14:15], s[42:43]
	s_cbranch_execz .LBB0_391
	v_mov_b32_e32 v115, v1
	v_lshlrev_b64 v[62:63], 2, v[114:115]
	v_lshl_add_u64 v[58:59], v[68:69], 0, v[62:63]
	v_lshl_add_u64 v[62:63], v[66:67], 0, v[62:63]
	global_load_dwordx4 v[58:61], v[58:59], off
	s_nop 0
	global_load_dwordx4 v[62:65], v[62:63], off
	s_waitcnt vmcnt(0) lgkmcnt(0)
	v_pk_mul_f32 v[66:67], v[54:55], v[58:59]
	v_pk_mul_f32 v[68:69], v[54:55], v[62:63] op_sel:[1,0] op_sel_hi:[0,0]
	v_pk_fma_f32 v[54:55], v[54:55], v[58:59], v[68:69] op_sel_hi:[1,0,1]
	v_mov_b32_e32 v62, v59
	v_mul_f32_e32 v54, v57, v63
	v_pk_fma_f32 v[70:71], v[56:57], v[62:63], v[54:55] op_sel_hi:[1,1,0] neg_lo:[0,0,1] neg_hi:[0,0,1]
	v_mov_b32_e32 v58, v63
	v_mul_f32_e32 v54, v57, v59
	v_pk_mul_f32 v[62:63], v[50:51], v[64:65] op_sel:[1,0] op_sel_hi:[0,0]
	v_pk_fma_f32 v[58:59], v[56:57], v[58:59], v[54:55] op_sel_hi:[1,1,0]
	v_pk_mul_f32 v[56:57], v[50:51], v[60:61]
	v_pk_fma_f32 v[50:51], v[50:51], v[60:61], v[62:63] op_sel_hi:[1,0,1]
	v_mov_b32_e32 v64, v61
	v_mul_f32_e32 v50, v53, v65
	v_pk_fma_f32 v[74:75], v[52:53], v[64:65], v[50:51] op_sel_hi:[1,1,0] neg_lo:[0,0,1] neg_hi:[0,0,1]
	v_mov_b32_e32 v60, v65
	v_mul_f32_e32 v50, v53, v61
	v_pk_fma_f32 v[60:61], v[52:53], v[60:61], v[50:51] op_sel_hi:[1,1,0]
	v_sub_f32_e32 v54, v66, v68
	v_sub_f32_e32 v50, v56, v62
	v_mov_b32_e32 v56, v70
	v_mov_b32_e32 v57, v58
	v_mov_b32_e32 v52, v74
	v_mov_b32_e32 v53, v60
; DI u32x4 pack8(f32x4 a, f32x4 b) { u32x4 w; w.x = pk2(a[0], a[1]); w.y = pk2(a[2], a[3]); w.z = pk2(b[0], b[1]); w.w = pk2(b[2], b[3]); return w; }
;     DI void operator()(AccRef acc, const Unit& u, int wr, int wc, int fr, int fq) const {
;     ...
;             for (int m = 0; m < 4; ++m) { int row = row0 + ai * 128 + m * 16; asm volatile("" : "+v"(row) :: "memory"); const int b = row >> 13, s = row & 8191;
;                 const float rs = __builtin_amdgcn_rsqf(SSQ[(size_t)row * 2] * (1.f / 384.f) + RMS_EPS) * QSCALE;
; #pragma unroll
;                 for (int bj = 0; bj < 2; ++bj) { const int cg_ = u.pn * 256 + bj * 128 + cl, h = cg_ / 192, d = cg_ % 192;
;                     f32x4 a = acc[ai][bj][m][0] * rs, bb = acc[ai][bj][m][1] * rs;
;                     if (d >= 128) { const int i0 = (d - 128) >> 1; const f32x4 cs = *(const f32x4*)(COS + (size_t)row * 32 + i0), sn = *(const f32x4*)(SIN + (size_t)row * 32 + i0); f32x4 oa, ob;
;                         oa[0] = a[0] * cs[0] - a[1] * sn[0]; oa[1] = a[1] * cs[0] + a[0] * sn[0]; oa[2] = a[2] * cs[1] - a[3] * sn[1]; oa[3] = a[3] * cs[1] + a[2] * sn[1];
;                         ob[0] = bb[0] * cs[2] - bb[1] * sn[2]; ob[1] = bb[1] * cs[2] + bb[0] * sn[2]; ob[2] = bb[2] * cs[3] - bb[3] * sn[3]; ob[3] = bb[3] * cs[3] + bb[2] * sn[3];
;                         a = oa; bb = ob; }
;                     *(u32x4*)(QM + ((size_t)(b * 4 + h) * SEQ + s) * 192 + d) = pack8(a, bb); asm volatile("" ::: "memory"); } }
.LBB0_391:
	s_or_b64 exec, exec, s[14:15]
	v_cvt_pk_bf16_f32 v54, v54, v55
	v_cvt_pk_bf16_f32 v55, v56, v57
	v_cvt_pk_bf16_f32 v56, v50, v51
	v_add_u32_e32 v50, v72, v126
	v_ashrrev_i32_e32 v51, 31, v50
	v_lshlrev_b64 v[50:51], 13, v[50:51]
	v_cvt_pk_bf16_f32 v57, v52, v53
	v_or_b32_e32 v50, v50, v73
	v_mov_b64_e32 v[52:53], s[50:51]
	v_mad_u64_u32 v[52:53], s[14:15], v50, s37, v[52:53]
	v_mad_i32_i24 v53, v51, s37, v53
	v_lshl_add_u64 v[50:51], v[122:123], 1, v[52:53]
	global_store_dwordx4 v[50:51], v[54:57], off
	s_nop 1
	v_add_u32_e32 v56, 0x90, v162
	s_nop 0
	v_ashrrev_i32_e32 v57, 31, v56
	v_lshl_add_u64 v[50:51], v[56:57], 3, s[56:57]
	global_load_dword v50, v[50:51], off
	s_waitcnt vmcnt(0) lgkmcnt(0)
	v_fmamk_f32 v50, v50, 0x3b2aaaab, v231
	v_rsq_f32_e32 v54, v50
	v_lshlrev_b64 v[50:51], 7, v[56:57]
	v_lshl_add_u64 v[52:53], s[52:53], 0, v[50:51]
	v_lshl_add_u64 v[50:51], s[54:55], 0, v[50:51]
	v_mul_f32_e32 v54, 0x3dd53b94, v54
	v_pk_mul_f32 v[48:49], v[48:49], v[54:55] op_sel_hi:[1,0]
	v_pk_mul_f32 v[46:47], v[46:47], v[54:55] op_sel_hi:[1,0]
	v_pk_mul_f32 v[44:45], v[44:45], v[54:55] op_sel_hi:[1,0]
	v_pk_mul_f32 v[42:43], v[42:43], v[54:55] op_sel_hi:[1,0]
	s_and_saveexec_b64 s[14:15], vcc
	s_cbranch_execz .LBB0_393
	v_lshlrev_b64 v[62:63], 2, v[0:1]
	v_lshl_add_u64 v[58:59], v[52:53], 0, v[62:63]
	v_lshl_add_u64 v[62:63], v[50:51], 0, v[62:63]
	global_load_dwordx4 v[58:61], v[58:59], off
	s_nop 0
	global_load_dwordx4 v[62:65], v[62:63], off
	s_waitcnt vmcnt(0) lgkmcnt(0)
	v_pk_mul_f32 v[66:67], v[46:47], v[58:59]
	v_pk_mul_f32 v[68:69], v[46:47], v[62:63] op_sel:[1,0] op_sel_hi:[0,0]
	v_pk_fma_f32 v[46:47], v[46:47], v[58:59], v[68:69] op_sel_hi:[1,0,1]
	v_mov_b32_e32 v62, v59
	v_mul_f32_e32 v46, v49, v63
	v_pk_fma_f32 v[70:71], v[48:49], v[62:63], v[46:47] op_sel_hi:[1,1,0] neg_lo:[0,0,1] neg_hi:[0,0,1]
	v_mov_b32_e32 v58, v63
	v_mul_f32_e32 v46, v49, v59
	v_pk_mul_f32 v[62:63], v[42:43], v[64:65] op_sel:[1,0] op_sel_hi:[0,0]
	v_pk_fma_f32 v[58:59], v[48:49], v[58:59], v[46:47] op_sel_hi:[1,1,0]
	v_pk_mul_f32 v[48:49], v[42:43], v[60:61]
	v_pk_fma_f32 v[42:43], v[42:43], v[60:61], v[62:63] op_sel_hi:[1,0,1]
	v_mov_b32_e32 v64, v61
	v_mul_f32_e32 v42, v45, v65
	v_pk_fma_f32 v[72:73], v[44:45], v[64:65], v[42:43] op_sel_hi:[1,1,0] neg_lo:[0,0,1] neg_hi:[0,0,1]
	v_mov_b32_e32 v60, v65
	v_mul_f32_e32 v42, v45, v61
	v_pk_fma_f32 v[60:61], v[44:45], v[60:61], v[42:43] op_sel_hi:[1,1,0]
	v_sub_f32_e32 v46, v66, v68
	v_sub_f32_e32 v42, v48, v62
	v_mov_b32_e32 v48, v70
	v_mov_b32_e32 v49, v58
	v_mov_b32_e32 v44, v72
	v_mov_b32_e32 v45, v60
.LBB0_393:
	s_or_b64 exec, exec, s[14:15]
	v_and_b32_e32 v57, 0x1fff, v56
	v_ashrrev_i32_e32 v56, 11, v56
	v_and_b32_e32 v56, -4, v56
	v_cvt_pk_bf16_f32 v46, v46, v47
	v_cvt_pk_bf16_f32 v47, v48, v49
	v_cvt_pk_bf16_f32 v48, v42, v43
	v_add_u32_e32 v42, v56, v155
	v_ashrrev_i32_e32 v43, 31, v42
	v_lshlrev_b64 v[42:43], 13, v[42:43]
	v_cvt_pk_bf16_f32 v49, v44, v45
	v_or_b32_e32 v42, v42, v57
	v_mov_b64_e32 v[44:45], s[50:51]
	v_mad_u64_u32 v[44:45], s[14:15], v42, s37, v[44:45]
	v_mad_i32_i24 v45, v43, s37, v45
	v_lshl_add_u64 v[42:43], v[146:147], 1, v[44:45]
	global_store_dwordx4 v[42:43], v[46:49], off
	v_mov_b32_e32 v55, v54
	v_mov_b32_e32 v42, v54
	v_mov_b32_e32 v43, v54
	v_pk_mul_f32 v[40:41], v[40:41], v[42:43]
	v_pk_mul_f32 v[38:39], v[38:39], v[54:55]
	v_pk_mul_f32 v[36:37], v[36:37], v[42:43]
	v_pk_mul_f32 v[34:35], v[34:35], v[54:55]
	s_and_saveexec_b64 s[14:15], s[42:43]
	s_cbranch_execz .LBB0_395
	v_mov_b32_e32 v115, v1
	v_lshlrev_b64 v[46:47], 2, v[114:115]
	v_lshl_add_u64 v[42:43], v[52:53], 0, v[46:47]
	v_lshl_add_u64 v[46:47], v[50:51], 0, v[46:47]
	global_load_dwordx4 v[42:45], v[42:43], off
	s_nop 0
	global_load_dwordx4 v[46:49], v[46:47], off
	s_waitcnt vmcnt(0) lgkmcnt(0)
	v_pk_mul_f32 v[50:51], v[38:39], v[42:43]
	v_pk_mul_f32 v[52:53], v[38:39], v[46:47] op_sel:[1,0] op_sel_hi:[0,0]
	v_pk_fma_f32 v[38:39], v[38:39], v[42:43], v[52:53] op_sel_hi:[1,0,1]
	v_mov_b32_e32 v46, v43
	v_mul_f32_e32 v38, v41, v47
	v_pk_fma_f32 v[54:55], v[40:41], v[46:47], v[38:39] op_sel_hi:[1,1,0] neg_lo:[0,0,1] neg_hi:[0,0,1]
	v_mov_b32_e32 v42, v47
	v_mul_f32_e32 v38, v41, v43
	v_pk_mul_f32 v[46:47], v[34:35], v[48:49] op_sel:[1,0] op_sel_hi:[0,0]
	v_pk_fma_f32 v[42:43], v[40:41], v[42:43], v[38:39] op_sel_hi:[1,1,0]
	v_pk_mul_f32 v[40:41], v[34:35], v[44:45]
	v_pk_fma_f32 v[34:35], v[34:35], v[44:45], v[46:47] op_sel_hi:[1,0,1]
	v_mov_b32_e32 v48, v45
	v_mul_f32_e32 v34, v37, v49
	v_pk_fma_f32 v[58:59], v[36:37], v[48:49], v[34:35] op_sel_hi:[1,1,0] neg_lo:[0,0,1] neg_hi:[0,0,1]
	v_mov_b32_e32 v44, v49
	v_mul_f32_e32 v34, v37, v45
	v_pk_fma_f32 v[44:45], v[36:37], v[44:45], v[34:35] op_sel_hi:[1,1,0]
	v_sub_f32_e32 v38, v50, v52
	v_sub_f32_e32 v34, v40, v46
	v_mov_b32_e32 v40, v54
	v_mov_b32_e32 v41, v42
	v_mov_b32_e32 v36, v58
	v_mov_b32_e32 v37, v44
; DI u32x4 pack8(f32x4 a, f32x4 b) { u32x4 w; w.x = pk2(a[0], a[1]); w.y = pk2(a[2], a[3]); w.z = pk2(b[0], b[1]); w.w = pk2(b[2], b[3]); return w; }
;     DI void operator()(AccRef acc, const Unit& u, int wr, int wc, int fr, int fq) const {
;     ...
;             for (int m = 0; m < 4; ++m) { int row = row0 + ai * 128 + m * 16; asm volatile("" : "+v"(row) :: "memory"); const int b = row >> 13, s = row & 8191;
;                 const float rs = __builtin_amdgcn_rsqf(SSQ[(size_t)row * 2] * (1.f / 384.f) + RMS_EPS) * QSCALE;
; #pragma unroll
;                 for (int bj = 0; bj < 2; ++bj) { const int cg_ = u.pn * 256 + bj * 128 + cl, h = cg_ / 192, d = cg_ % 192;
;                     f32x4 a = acc[ai][bj][m][0] * rs, bb = acc[ai][bj][m][1] * rs;
;                     if (d >= 128) { const int i0 = (d - 128) >> 1; const f32x4 cs = *(const f32x4*)(COS + (size_t)row * 32 + i0), sn = *(const f32x4*)(SIN + (size_t)row * 32 + i0); f32x4 oa, ob;
;                         oa[0] = a[0] * cs[0] - a[1] * sn[0]; oa[1] = a[1] * cs[0] + a[0] * sn[0]; oa[2] = a[2] * cs[1] - a[3] * sn[1]; oa[3] = a[3] * cs[1] + a[2] * sn[1];
;                         ob[0] = bb[0] * cs[2] - bb[1] * sn[2]; ob[1] = bb[1] * cs[2] + bb[0] * sn[2]; ob[2] = bb[2] * cs[3] - bb[3] * sn[3]; ob[3] = bb[3] * cs[3] + bb[2] * sn[3];
;                         a = oa; bb = ob; }
;                     *(u32x4*)(QM + ((size_t)(b * 4 + h) * SEQ + s) * 192 + d) = pack8(a, bb); asm volatile("" ::: "memory"); } }
.LBB0_395:
	s_or_b64 exec, exec, s[14:15]
	v_cvt_pk_bf16_f32 v38, v38, v39
	v_cvt_pk_bf16_f32 v39, v40, v41
	v_cvt_pk_bf16_f32 v40, v34, v35
	v_add_u32_e32 v34, v56, v126
	v_ashrrev_i32_e32 v35, 31, v34
	v_lshlrev_b64 v[34:35], 13, v[34:35]
	v_cvt_pk_bf16_f32 v41, v36, v37
	v_or_b32_e32 v34, v34, v57
	v_mov_b64_e32 v[36:37], s[50:51]
	v_mad_u64_u32 v[36:37], s[14:15], v34, s37, v[36:37]
	v_mad_i32_i24 v37, v35, s37, v37
	v_lshl_add_u64 v[34:35], v[122:123], 1, v[36:37]
	global_store_dwordx4 v[34:35], v[38:41], off
	s_nop 1
	v_add_u32_e32 v40, 0xa0, v162
	s_nop 0
	v_ashrrev_i32_e32 v41, 31, v40
	v_lshl_add_u64 v[34:35], v[40:41], 3, s[56:57]
	global_load_dword v34, v[34:35], off
	s_waitcnt vmcnt(0) lgkmcnt(0)
	v_fmamk_f32 v34, v34, 0x3b2aaaab, v231
	v_rsq_f32_e32 v38, v34
	v_lshlrev_b64 v[34:35], 7, v[40:41]
	v_lshl_add_u64 v[36:37], s[52:53], 0, v[34:35]
	v_lshl_add_u64 v[34:35], s[54:55], 0, v[34:35]
	v_mul_f32_e32 v38, 0x3dd53b94, v38
	v_pk_mul_f32 v[32:33], v[32:33], v[38:39] op_sel_hi:[1,0]
	v_pk_mul_f32 v[30:31], v[30:31], v[38:39] op_sel_hi:[1,0]
	v_pk_mul_f32 v[28:29], v[28:29], v[38:39] op_sel_hi:[1,0]
	v_pk_mul_f32 v[26:27], v[26:27], v[38:39] op_sel_hi:[1,0]
	s_and_saveexec_b64 s[14:15], vcc
	s_cbranch_execz .LBB0_397
	v_lshlrev_b64 v[46:47], 2, v[0:1]
	v_lshl_add_u64 v[42:43], v[36:37], 0, v[46:47]
	v_lshl_add_u64 v[46:47], v[34:35], 0, v[46:47]
	global_load_dwordx4 v[42:45], v[42:43], off
	s_nop 0
	global_load_dwordx4 v[46:49], v[46:47], off
	s_waitcnt vmcnt(0) lgkmcnt(0)
	v_pk_mul_f32 v[50:51], v[30:31], v[42:43]
	v_pk_mul_f32 v[52:53], v[30:31], v[46:47] op_sel:[1,0] op_sel_hi:[0,0]
	v_pk_fma_f32 v[30:31], v[30:31], v[42:43], v[52:53] op_sel_hi:[1,0,1]
	v_mov_b32_e32 v46, v43
	v_mul_f32_e32 v30, v33, v47
	v_pk_fma_f32 v[54:55], v[32:33], v[46:47], v[30:31] op_sel_hi:[1,1,0] neg_lo:[0,0,1] neg_hi:[0,0,1]
	v_mov_b32_e32 v42, v47
	v_mul_f32_e32 v30, v33, v43
	v_pk_mul_f32 v[46:47], v[26:27], v[48:49] op_sel:[1,0] op_sel_hi:[0,0]
	v_pk_fma_f32 v[42:43], v[32:33], v[42:43], v[30:31] op_sel_hi:[1,1,0]
	v_pk_mul_f32 v[32:33], v[26:27], v[44:45]
	v_pk_fma_f32 v[26:27], v[26:27], v[44:45], v[46:47] op_sel_hi:[1,0,1]
	v_mov_b32_e32 v48, v45
	v_mul_f32_e32 v26, v29, v49
	v_pk_fma_f32 v[56:57], v[28:29], v[48:49], v[26:27] op_sel_hi:[1,1,0] neg_lo:[0,0,1] neg_hi:[0,0,1]
	v_mov_b32_e32 v44, v49
	v_mul_f32_e32 v26, v29, v45
	v_pk_fma_f32 v[44:45], v[28:29], v[44:45], v[26:27] op_sel_hi:[1,1,0]
	v_sub_f32_e32 v30, v50, v52
	v_sub_f32_e32 v26, v32, v46
	v_mov_b32_e32 v32, v54
	v_mov_b32_e32 v33, v42
	v_mov_b32_e32 v28, v56
	v_mov_b32_e32 v29, v44
.LBB0_397:
	s_or_b64 exec, exec, s[14:15]
	v_and_b32_e32 v41, 0x1fff, v40
	v_ashrrev_i32_e32 v40, 11, v40
	v_and_b32_e32 v40, -4, v40
	v_cvt_pk_bf16_f32 v30, v30, v31
	v_cvt_pk_bf16_f32 v31, v32, v33
	v_cvt_pk_bf16_f32 v32, v26, v27
	v_add_u32_e32 v26, v40, v155
	v_ashrrev_i32_e32 v27, 31, v26
	v_lshlrev_b64 v[26:27], 13, v[26:27]
	v_cvt_pk_bf16_f32 v33, v28, v29
	v_or_b32_e32 v26, v26, v41
	v_mov_b64_e32 v[28:29], s[50:51]
	v_mad_u64_u32 v[28:29], s[14:15], v26, s37, v[28:29]
	v_mad_i32_i24 v29, v27, s37, v29
	v_lshl_add_u64 v[26:27], v[146:147], 1, v[28:29]
	global_store_dwordx4 v[26:27], v[30:33], off
	v_mov_b32_e32 v39, v38
	v_mov_b32_e32 v26, v38
	v_mov_b32_e32 v27, v38
	v_pk_mul_f32 v[24:25], v[24:25], v[26:27]
	v_pk_mul_f32 v[22:23], v[22:23], v[38:39]
	v_pk_mul_f32 v[20:21], v[20:21], v[26:27]
	v_pk_mul_f32 v[18:19], v[18:19], v[38:39]
	s_and_saveexec_b64 s[14:15], s[42:43]
	s_cbranch_execz .LBB0_399
	v_mov_b32_e32 v115, v1
	v_lshlrev_b64 v[30:31], 2, v[114:115]
	v_lshl_add_u64 v[26:27], v[36:37], 0, v[30:31]
	v_lshl_add_u64 v[30:31], v[34:35], 0, v[30:31]
	global_load_dwordx4 v[26:29], v[26:27], off
	s_nop 0
	global_load_dwordx4 v[30:33], v[30:31], off
	s_waitcnt vmcnt(0) lgkmcnt(0)
	v_pk_mul_f32 v[34:35], v[22:23], v[26:27]
	v_pk_mul_f32 v[36:37], v[22:23], v[30:31] op_sel:[1,0] op_sel_hi:[0,0]
	v_pk_fma_f32 v[22:23], v[22:23], v[26:27], v[36:37] op_sel_hi:[1,0,1]
	v_mov_b32_e32 v30, v27
	v_mul_f32_e32 v22, v25, v31
	v_pk_fma_f32 v[38:39], v[24:25], v[30:31], v[22:23] op_sel_hi:[1,1,0] neg_lo:[0,0,1] neg_hi:[0,0,1]
	v_mov_b32_e32 v26, v31
	v_mul_f32_e32 v22, v25, v27
	v_pk_mul_f32 v[30:31], v[18:19], v[32:33] op_sel:[1,0] op_sel_hi:[0,0]
	v_pk_fma_f32 v[26:27], v[24:25], v[26:27], v[22:23] op_sel_hi:[1,1,0]
	v_pk_mul_f32 v[24:25], v[18:19], v[28:29]
	v_pk_fma_f32 v[18:19], v[18:19], v[28:29], v[30:31] op_sel_hi:[1,0,1]
	v_mov_b32_e32 v32, v29
	v_mul_f32_e32 v18, v21, v33
	v_pk_fma_f32 v[42:43], v[20:21], v[32:33], v[18:19] op_sel_hi:[1,1,0] neg_lo:[0,0,1] neg_hi:[0,0,1]
	v_mov_b32_e32 v28, v33
	v_mul_f32_e32 v18, v21, v29
	v_pk_fma_f32 v[28:29], v[20:21], v[28:29], v[18:19] op_sel_hi:[1,1,0]
	v_sub_f32_e32 v22, v34, v36
	v_sub_f32_e32 v18, v24, v30
	v_mov_b32_e32 v24, v38
	v_mov_b32_e32 v25, v26
	v_mov_b32_e32 v20, v42
	v_mov_b32_e32 v21, v28
; #define PG8_BAR __builtin_amdgcn_s_barrier()
; DI u32x4 pack8(f32x4 a, f32x4 b) { u32x4 w; w.x = pk2(a[0], a[1]); w.y = pk2(a[2], a[3]); w.z = pk2(b[0], b[1]); w.w = pk2(b[2], b[3]); return w; }
; template <class Epi, class Sched, bool ALIGN_EPI = false, bool SP2 = false>
; __device__ __forceinline__ void gemm_phase(PG8_LAS unsigned char* lds, const Gemm g, const Sched& S, const Epi& E) {
;     ...
;         if constexpr (ALIGN_EPI) { if (wr == 0) PG8_BAR; }
;         if constexpr (!Epi::AFTER_DRAIN) { E(acc, cur, wr, wc, fr, fq); S.done(cur); }
;         if (!has_next) break;
; #pragma unroll
;         for (int a = 0; a < 2; ++a)
; #pragma unroll
;             for (int b = 0; b < 2; ++b)
; #pragma unroll
;                 for (int m = 0; m < 4; ++m)
; #pragma unroll
;                     for (int n = 0; n < 2; ++n) acc[a][b][m][n] = (f32x4){0.f, 0.f, 0.f, 0.f};
;         cur = nxt; cA = nA; cB = nB; ++ui;
;         if constexpr (ALIGN_EPI) { if (wr == 1) PG8_BAR; }
;     DI void operator()(AccRef acc, const Unit& u, int wr, int wc, int fr, int fq) const {
;     ...
;             for (int m = 0; m < 4; ++m) { int row = row0 + ai * 128 + m * 16; asm volatile("" : "+v"(row) :: "memory"); const int b = row >> 13, s = row & 8191;
;                 const float rs = __builtin_amdgcn_rsqf(SSQ[(size_t)row * 2] * (1.f / 384.f) + RMS_EPS) * QSCALE;
; #pragma unroll
;                 for (int bj = 0; bj < 2; ++bj) { const int cg_ = u.pn * 256 + bj * 128 + cl, h = cg_ / 192, d = cg_ % 192;
;                     f32x4 a = acc[ai][bj][m][0] * rs, bb = acc[ai][bj][m][1] * rs;
;                     if (d >= 128) { const int i0 = (d - 128) >> 1; const f32x4 cs = *(const f32x4*)(COS + (size_t)row * 32 + i0), sn = *(const f32x4*)(SIN + (size_t)row * 32 + i0); f32x4 oa, ob;
;                         oa[0] = a[0] * cs[0] - a[1] * sn[0]; oa[1] = a[1] * cs[0] + a[0] * sn[0]; oa[2] = a[2] * cs[1] - a[3] * sn[1]; oa[3] = a[3] * cs[1] + a[2] * sn[1];
;                         ob[0] = bb[0] * cs[2] - bb[1] * sn[2]; ob[1] = bb[1] * cs[2] + bb[0] * sn[2]; ob[2] = bb[2] * cs[3] - bb[3] * sn[3]; ob[3] = bb[3] * cs[3] + bb[2] * sn[3];
;                         a = oa; bb = ob; }
;                     *(u32x4*)(QM + ((size_t)(b * 4 + h) * SEQ + s) * 192 + d) = pack8(a, bb); asm volatile("" ::: "memory"); } }
.LBB0_399:
	s_or_b64 exec, exec, s[14:15]
	v_cvt_pk_bf16_f32 v22, v22, v23
	v_cvt_pk_bf16_f32 v23, v24, v25
	v_cvt_pk_bf16_f32 v24, v18, v19
	v_add_u32_e32 v18, v40, v126
	v_ashrrev_i32_e32 v19, 31, v18
	v_lshlrev_b64 v[18:19], 13, v[18:19]
	v_cvt_pk_bf16_f32 v25, v20, v21
	v_or_b32_e32 v18, v18, v41
	v_mov_b64_e32 v[20:21], s[50:51]
	v_mad_u64_u32 v[20:21], s[14:15], v18, s37, v[20:21]
	v_mad_i32_i24 v21, v19, s37, v21
	v_lshl_add_u64 v[18:19], v[122:123], 1, v[20:21]
	global_store_dwordx4 v[18:19], v[22:25], off
	s_nop 1
	v_add_u32_e32 v24, 0xb0, v162
	s_nop 0
	v_ashrrev_i32_e32 v25, 31, v24
	v_lshl_add_u64 v[18:19], v[24:25], 3, s[56:57]
	global_load_dword v18, v[18:19], off
	s_waitcnt vmcnt(0) lgkmcnt(0)
	v_fmamk_f32 v18, v18, 0x3b2aaaab, v231
	v_rsq_f32_e32 v22, v18
	v_lshlrev_b64 v[18:19], 7, v[24:25]
	v_lshl_add_u64 v[20:21], s[52:53], 0, v[18:19]
	v_lshl_add_u64 v[18:19], s[54:55], 0, v[18:19]
	v_mul_f32_e32 v22, 0x3dd53b94, v22
	v_pk_mul_f32 v[16:17], v[16:17], v[22:23] op_sel_hi:[1,0]
	v_pk_mul_f32 v[14:15], v[14:15], v[22:23] op_sel_hi:[1,0]
	v_pk_mul_f32 v[12:13], v[12:13], v[22:23] op_sel_hi:[1,0]
	v_pk_mul_f32 v[10:11], v[10:11], v[22:23] op_sel_hi:[1,0]
	s_and_saveexec_b64 s[14:15], vcc
	s_cbranch_execz .LBB0_401
	v_lshlrev_b64 v[30:31], 2, v[0:1]
	v_lshl_add_u64 v[26:27], v[20:21], 0, v[30:31]
	v_lshl_add_u64 v[30:31], v[18:19], 0, v[30:31]
	global_load_dwordx4 v[26:29], v[26:27], off
	s_nop 0
	global_load_dwordx4 v[30:33], v[30:31], off
	s_waitcnt vmcnt(0) lgkmcnt(0)
	v_pk_mul_f32 v[34:35], v[14:15], v[26:27]
	v_pk_mul_f32 v[36:37], v[14:15], v[30:31] op_sel:[1,0] op_sel_hi:[0,0]
	v_mov_b32_e32 v30, v27
	v_mul_f32_e32 v0, v17, v31
	v_pk_fma_f32 v[14:15], v[14:15], v[26:27], v[36:37] op_sel_hi:[1,0,1]
	v_pk_fma_f32 v[38:39], v[16:17], v[30:31], v[0:1] op_sel_hi:[1,1,0] neg_lo:[0,0,1] neg_hi:[0,0,1]
	v_mov_b32_e32 v26, v31
	v_mul_f32_e32 v0, v17, v27
	v_pk_fma_f32 v[26:27], v[16:17], v[26:27], v[0:1] op_sel_hi:[1,1,0]
	v_pk_mul_f32 v[30:31], v[10:11], v[32:33] op_sel:[1,0] op_sel_hi:[0,0]
	v_mov_b32_e32 v32, v29
	v_mul_f32_e32 v0, v13, v33
	v_pk_mul_f32 v[16:17], v[10:11], v[28:29]
	v_pk_fma_f32 v[10:11], v[10:11], v[28:29], v[30:31] op_sel_hi:[1,0,1]
	v_pk_fma_f32 v[40:41], v[12:13], v[32:33], v[0:1] op_sel_hi:[1,1,0] neg_lo:[0,0,1] neg_hi:[0,0,1]
	v_mov_b32_e32 v28, v33
	v_mul_f32_e32 v0, v13, v29
	v_pk_fma_f32 v[28:29], v[12:13], v[28:29], v[0:1] op_sel_hi:[1,1,0]
	v_sub_f32_e32 v14, v34, v36
	v_sub_f32_e32 v10, v16, v30
	v_mov_b32_e32 v16, v38
	v_mov_b32_e32 v17, v26
	v_mov_b32_e32 v12, v40
	v_mov_b32_e32 v13, v28
.LBB0_401:
	s_or_b64 exec, exec, s[14:15]
	v_and_b32_e32 v0, 0x1fff, v24
	v_ashrrev_i32_e32 v24, 11, v24
	v_and_b32_e32 v24, -4, v24
	v_cvt_pk_bf16_f32 v14, v14, v15
	v_cvt_pk_bf16_f32 v15, v16, v17
	v_cvt_pk_bf16_f32 v16, v10, v11
	v_add_u32_e32 v10, v24, v155
	v_ashrrev_i32_e32 v11, 31, v10
	v_lshlrev_b64 v[10:11], 13, v[10:11]
	v_cvt_pk_bf16_f32 v17, v12, v13
	v_or_b32_e32 v10, v10, v0
	v_mov_b64_e32 v[12:13], s[50:51]
	v_mad_u64_u32 v[12:13], s[14:15], v10, s37, v[12:13]
	v_mad_i32_i24 v13, v11, s37, v13
	v_lshl_add_u64 v[10:11], v[146:147], 1, v[12:13]
	global_store_dwordx4 v[10:11], v[14:17], off
	v_mov_b32_e32 v23, v22
	v_mov_b32_e32 v10, v22
	v_mov_b32_e32 v11, v22
	v_pk_mul_f32 v[8:9], v[8:9], v[10:11]
	v_pk_mul_f32 v[6:7], v[6:7], v[22:23]
	v_pk_mul_f32 v[4:5], v[4:5], v[10:11]
	v_pk_mul_f32 v[2:3], v[2:3], v[22:23]
	s_and_saveexec_b64 s[14:15], s[42:43]
	s_cbranch_execz .LBB0_403
	v_mov_b32_e32 v115, v1
	v_lshlrev_b64 v[14:15], 2, v[114:115]
	v_lshl_add_u64 v[10:11], v[20:21], 0, v[14:15]
	v_lshl_add_u64 v[14:15], v[18:19], 0, v[14:15]
	global_load_dwordx4 v[10:13], v[10:11], off
	s_nop 0
	global_load_dwordx4 v[14:17], v[14:15], off
	s_waitcnt vmcnt(0) lgkmcnt(0)
	v_pk_mul_f32 v[18:19], v[6:7], v[10:11]
	v_pk_mul_f32 v[20:21], v[6:7], v[14:15] op_sel:[1,0] op_sel_hi:[0,0]
	v_pk_fma_f32 v[6:7], v[6:7], v[10:11], v[20:21] op_sel_hi:[1,0,1]
	v_mov_b32_e32 v14, v11
	v_mul_f32_e32 v6, v9, v15
	v_pk_fma_f32 v[22:23], v[8:9], v[14:15], v[6:7] op_sel_hi:[1,1,0] neg_lo:[0,0,1] neg_hi:[0,0,1]
	v_mov_b32_e32 v10, v15
	v_mul_f32_e32 v6, v9, v11
	v_pk_mul_f32 v[14:15], v[2:3], v[16:17] op_sel:[1,0] op_sel_hi:[0,0]
	v_pk_fma_f32 v[10:11], v[8:9], v[10:11], v[6:7] op_sel_hi:[1,1,0]
	v_pk_mul_f32 v[8:9], v[2:3], v[12:13]
	v_pk_fma_f32 v[2:3], v[2:3], v[12:13], v[14:15] op_sel_hi:[1,0,1]
	v_mov_b32_e32 v16, v13
	v_mul_f32_e32 v2, v5, v17
	v_pk_fma_f32 v[26:27], v[4:5], v[16:17], v[2:3] op_sel_hi:[1,1,0] neg_lo:[0,0,1] neg_hi:[0,0,1]
	v_mov_b32_e32 v12, v17
	v_mul_f32_e32 v2, v5, v13
	v_pk_fma_f32 v[12:13], v[4:5], v[12:13], v[2:3] op_sel_hi:[1,1,0]
	v_sub_f32_e32 v6, v18, v20
	v_sub_f32_e32 v2, v8, v14
	v_mov_b32_e32 v8, v22
	v_mov_b32_e32 v9, v10
	v_mov_b32_e32 v4, v26
	v_mov_b32_e32 v5, v12
.LBB0_403:
	s_or_b64 exec, exec, s[14:15]
	v_cvt_pk_bf16_f32 v6, v6, v7
	v_cvt_pk_bf16_f32 v7, v8, v9
	v_cvt_pk_bf16_f32 v8, v2, v3
	v_add_u32_e32 v2, v24, v126
	v_ashrrev_i32_e32 v3, 31, v2
	v_lshlrev_b64 v[2:3], 13, v[2:3]
	v_cvt_pk_bf16_f32 v9, v4, v5
	v_or_b32_e32 v0, v2, v0
	v_mov_b64_e32 v[4:5], s[50:51]
	v_mad_u64_u32 v[4:5], s[14:15], v0, s37, v[4:5]
	v_mad_i32_i24 v5, v3, s37, v5
	v_lshl_add_u64 v[2:3], v[122:123], 1, v[4:5]
	global_store_dwordx4 v[2:3], v[6:9], off
	s_and_b64 vcc, exec, s[40:41]
	s_mov_b64 s[14:15], -1
	s_cbranch_vccnz .LBB0_359
	s_andn2_b64 vcc, exec, s[8:9]
	s_cbranch_vccnz .LBB0_358
	s_barrier
	s_branch .LBB0_358

; DI u32x4 pack8(f32x4 a, f32x4 b) { u32x4 w; w.x = pk2(a[0], a[1]); w.y = pk2(a[2], a[3]); w.z = pk2(b[0], b[1]); w.w = pk2(b[2], b[3]); return w; }
;     DI void operator()(AccRef acc, const Unit& u, int wr, int wc, int fr, int fq) const {
;     ...
;                 for (int m = 0; m < 4; ++m) { int row = row0 + ai * 128 + m * 16; asm volatile("" : "+v"(row) :: "memory");
;                     { const f32x4 a = acc[ai][0][m][0], b = acc[ai][0][m][1]; *(u32x4*)(CQ + (size_t)row * 384 + 256 + cl) = pack8(a, b);
;                       float ss = (a[0] * a[0] + a[1] * a[1]) + (a[2] * a[2] + a[3] * a[3]) + (b[0] * b[0] + b[1] * b[1]) + (b[2] * b[2] + b[3] * b[3]);
;                       ss += __shfl_xor(ss, 16); ss += __shfl_xor(ss, 32);
;                       if (fq == 0) unsafeAtomicAdd(SSQ + (size_t)row * 2, ss); }
;                     if (wc < 2) {
;                         const int i0 = 16 * wc + 4 * fq; const f32x4 cs = *(const f32x4*)(COS + (size_t)row * 32 + i0), sn = *(const f32x4*)(SIN + (size_t)row * 32 + i0);
;                         const f32x4 a = acc[ai][1][m][0], b = acc[ai][1][m][1]; f32x4 oa, ob;
;                         oa[0] = a[0] * cs[0] - a[1] * sn[0]; oa[1] = a[1] * cs[0] + a[0] * sn[0]; oa[2] = a[2] * cs[1] - a[3] * sn[1]; oa[3] = a[3] * cs[1] + a[2] * sn[1];
;                         ob[0] = b[0] * cs[2] - b[1] * sn[2]; ob[1] = b[1] * cs[2] + b[0] * sn[2]; ob[2] = b[2] * cs[3] - b[3] * sn[3]; ob[3] = b[3] * cs[3] + b[2] * sn[3];
;                         *(u32x4*)(KR + (size_t)row * 64 + cl) = pack8(oa, ob);
;                     } else if (wc == 2 && fq == 0) {
;                         *(f32x4*)(AB + (size_t)row * 8) = acc[ai][1][m][0]; *(f32x4*)(AB + (size_t)row * 8 + 4) = acc[ai][1][m][1];
.LBB0_436:
	s_andn2_b64 vcc, exec, s[44:45]
	v_cvt_pk_bf16_f32 v134, v126, v127
	v_cvt_pk_bf16_f32 v135, v128, v129
	v_cvt_pk_bf16_f32 v136, v122, v123
	v_cvt_pk_bf16_f32 v137, v124, v125
	v_mul_f32_e32 v168, v127, v127
	v_mul_f32_e32 v169, v129, v129
	v_mul_f32_e32 v167, v123, v123
	v_mul_f32_e32 v166, v125, v125
	v_xor_b32_e32 v165, 16, v230
	s_cbranch_vccnz .LBB0_478
	v_mov_b32_e32 v160, v164
	v_mov_b64_e32 v[154:155], s[60:61]
	v_lshlrev_b32_e32 v0, 1, v146
	v_mad_i64_i32 v[154:155], s[14:15], v160, s92, v[154:155]
	v_lshl_add_u64 v[154:155], v[154:155], 0, v[0:1]
	global_store_dwordx4 v[154:155], v[134:137], off offset:512
	v_fma_f32 v153, v126, v126, v168
	v_fma_f32 v154, v128, v128, v169
	v_add_f32_e32 v153, v153, v154
	v_fma_f32 v154, v122, v122, v167
	v_add_f32_e32 v153, v154, v153
	v_fma_f32 v154, v124, v124, v166
	v_add_f32_e32 v153, v154, v153
	v_and_b32_e32 v154, 64, v230
	v_add_u32_e32 v154, 64, v154
	v_cmp_lt_i32_e32 vcc, v165, v154
	v_ashrrev_i32_e32 v161, 31, v160
	s_nop 0
	v_cndmask_b32_e32 v155, v230, v165, vcc
	v_lshlrev_b32_e32 v170, 2, v155
	ds_bpermute_b32 v155, v170, v153
	s_waitcnt lgkmcnt(0)
	v_add_f32_e32 v153, v153, v155
	v_xor_b32_e32 v155, 32, v230
	v_cmp_lt_i32_e32 vcc, v155, v154
	s_nop 1
	v_cndmask_b32_e32 v154, v230, v155, vcc
	v_lshlrev_b32_e32 v171, 2, v154
	ds_bpermute_b32 v154, v171, v153
	s_and_saveexec_b64 s[14:15], s[40:41]
	s_cbranch_execz .LBB0_439
	s_waitcnt lgkmcnt(0)
	v_add_f32_e32 v153, v153, v154
	v_lshl_add_u64 v[154:155], v[160:161], 3, s[58:59]
	s_waitcnt vmcnt(0)
	global_atomic_add_f32 v[154:155], v153, off
.LBB0_439:
	s_or_b64 exec, exec, s[14:15]
	s_add_u32 s14, s56, 0x3400000
	s_addc_u32 s15, s57, 0
	s_mov_b64 s[44:45], -1
	s_and_b64 vcc, exec, s[48:49]
	s_cbranch_vccz .LBB0_443
	s_and_saveexec_b64 s[44:45], s[50:51]
	s_cbranch_execz .LBB0_442
	s_waitcnt lgkmcnt(0)
	v_lshlrev_b64 v[154:155], 5, v[160:161]
	v_lshl_add_u64 v[154:155], s[14:15], 0, v[154:155]
	global_store_dwordx4 v[154:155], v[118:121], off
	global_store_dwordx4 v[154:155], v[114:117], off offset:16

; DI u32x4 pack8(f32x4 a, f32x4 b) { u32x4 w; w.x = pk2(a[0], a[1]); w.y = pk2(a[2], a[3]); w.z = pk2(b[0], b[1]); w.w = pk2(b[2], b[3]); return w; }
;     DI void operator()(AccRef acc, const Unit& u, int wr, int wc, int fr, int fq) const {
;     ...
;                     { const f32x4 a = acc[ai][0][m][0], b = acc[ai][0][m][1]; *(u32x4*)(CQ + (size_t)row * 384 + 256 + cl) = pack8(a, b);
;                       float ss = (a[0] * a[0] + a[1] * a[1]) + (a[2] * a[2] + a[3] * a[3]) + (b[0] * b[0] + b[1] * b[1]) + (b[2] * b[2] + b[3] * b[3]);
;                       ss += __shfl_xor(ss, 16); ss += __shfl_xor(ss, 32);
;                       if (fq == 0) unsafeAtomicAdd(SSQ + (size_t)row * 2, ss); }
;                     if (wc < 2) {
;                         const int i0 = 16 * wc + 4 * fq; const f32x4 cs = *(const f32x4*)(COS + (size_t)row * 32 + i0), sn = *(const f32x4*)(SIN + (size_t)row * 32 + i0);
;                         const f32x4 a = acc[ai][1][m][0], b = acc[ai][1][m][1]; f32x4 oa, ob;
;                         oa[0] = a[0] * cs[0] - a[1] * sn[0]; oa[1] = a[1] * cs[0] + a[0] * sn[0]; oa[2] = a[2] * cs[1] - a[3] * sn[1]; oa[3] = a[3] * cs[1] + a[2] * sn[1];
;                         ob[0] = b[0] * cs[2] - b[1] * sn[2]; ob[1] = b[1] * cs[2] + b[0] * sn[2]; ob[2] = b[2] * cs[3] - b[3] * sn[3]; ob[3] = b[3] * cs[3] + b[2] * sn[3];
;                         *(u32x4*)(KR + (size_t)row * 64 + cl) = pack8(oa, ob);
;                     } else if (wc == 2 && fq == 0) {
;                         *(f32x4*)(AB + (size_t)row * 8) = acc[ai][1][m][0]; *(f32x4*)(AB + (size_t)row * 8 + 4) = acc[ai][1][m][1];
;                     }
.LBB0_443:
	v_mov_b32_e32 v153, v1
	s_waitcnt lgkmcnt(0)
	v_lshl_add_u64 v[154:155], s[56:57], 0, v[152:153]
	s_mov_b64 s[64:65], 0x2c00000
	v_lshl_add_u64 v[158:159], v[154:155], 0, s[64:65]
	s_mov_b64 s[64:65], 0x3000000
	v_lshl_add_u64 v[156:157], v[154:155], 0, s[64:65]
	v_lshl_add_u64 v[154:155], s[56:57], 0, v[0:1]
	s_andn2_b64 vcc, exec, s[44:45]
	s_mov_b64 s[44:45], 0xde00000
	v_lshl_add_u64 v[154:155], v[154:155], 0, s[44:45]
	s_cbranch_vccnz .LBB0_445
	v_lshlrev_b64 v[160:161], 7, v[160:161]
	v_lshl_add_u64 v[172:173], v[158:159], 0, v[160:161]
	v_lshl_add_u64 v[176:177], v[156:157], 0, v[160:161]
	global_load_dwordx4 v[172:175], v[172:173], off
	v_lshl_add_u64 v[160:161], v[154:155], 0, v[160:161]
	global_load_dwordx4 v[176:179], v[176:177], off
	s_waitcnt vmcnt(0) lgkmcnt(0)
	v_pk_mul_f32 v[180:181], v[118:119], v[176:177] op_sel:[1,0] op_sel_hi:[0,0]
	v_pk_mul_f32 v[176:177], v[120:121], v[176:177] op_sel:[1,1] op_sel_hi:[0,1]
	v_pk_fma_f32 v[182:183], v[118:119], v[172:173], v[180:181] neg_lo:[0,0,1] neg_hi:[0,0,1]
	v_pk_fma_f32 v[180:181], v[118:119], v[172:173], v[180:181] op_sel_hi:[1,0,1]
	v_pk_fma_f32 v[184:185], v[120:121], v[172:173], v[176:177] op_sel:[0,1,0] neg_lo:[0,0,1] neg_hi:[0,0,1]
	v_pk_fma_f32 v[172:173], v[120:121], v[172:173], v[176:177] op_sel:[0,1,0]
	v_pk_mul_f32 v[176:177], v[114:115], v[178:179] op_sel:[1,0] op_sel_hi:[0,0]
	v_pk_fma_f32 v[186:187], v[114:115], v[174:175], v[176:177] neg_lo:[0,0,1] neg_hi:[0,0,1]
	v_pk_fma_f32 v[176:177], v[114:115], v[174:175], v[176:177] op_sel_hi:[1,0,1]
	v_mov_b32_e32 v174, v179
	v_mov_b32_e32 v172, v175
	v_pk_mul_f32 v[174:175], v[116:117], v[174:175] op_sel:[1,0] op_sel_hi:[0,0]
	v_pk_fma_f32 v[178:179], v[116:117], v[172:173], v[174:175] op_sel_hi:[1,0,1] neg_lo:[0,0,1] neg_hi:[0,0,1]
	v_pk_fma_f32 v[174:175], v[116:117], v[172:173], v[174:175] op_sel_hi:[1,0,1]
	v_cvt_pk_bf16_f32 v172, v182, v181
	v_cvt_pk_bf16_f32 v173, v184, v173
	v_cvt_pk_bf16_f32 v174, v186, v177
	v_cvt_pk_bf16_f32 v175, v178, v175
	global_store_dwordx4 v[160:161], v[172:175], off
.LBB0_445:
	v_or_b32_e32 v160, 16, v164
	v_mov_b64_e32 v[176:177], s[60:61]
	v_cvt_pk_bf16_f32 v172, v110, v111
	v_mad_i64_i32 v[176:177], s[44:45], v160, s92, v[176:177]
	v_cvt_pk_bf16_f32 v173, v112, v113
	v_cvt_pk_bf16_f32 v174, v106, v107
	v_cvt_pk_bf16_f32 v175, v108, v109
	v_lshl_add_u64 v[176:177], v[176:177], 0, v[0:1]
	global_store_dwordx4 v[176:177], v[172:175], off offset:512
	v_mul_f32_e32 v153, v111, v111
	v_fmac_f32_e32 v153, v110, v110
	v_mul_f32_e32 v172, v113, v113
	v_fmac_f32_e32 v172, v112, v112
	v_add_f32_e32 v153, v153, v172
	v_mul_f32_e32 v172, v107, v107
	v_fmac_f32_e32 v172, v106, v106
	v_add_f32_e32 v153, v172, v153
	v_mul_f32_e32 v172, v109, v109
	v_fmac_f32_e32 v172, v108, v108
	v_add_f32_e32 v153, v172, v153
	ds_bpermute_b32 v172, v170, v153
	v_ashrrev_i32_e32 v161, 31, v160
	s_waitcnt lgkmcnt(0)
	v_add_f32_e32 v153, v153, v172
	ds_bpermute_b32 v172, v171, v153
	s_and_saveexec_b64 s[44:45], s[40:41]
	s_cbranch_execz .LBB0_447
	s_waitcnt lgkmcnt(0)
	v_add_f32_e32 v153, v153, v172
	v_lshl_add_u64 v[172:173], v[160:161], 3, s[58:59]
	s_waitcnt vmcnt(0)
	global_atomic_add_f32 v[172:173], v153, off
.LBB0_447:
	s_or_b64 exec, exec, s[44:45]
	v_cndmask_b32_e64 v153, 0, 1, s[48:49]
	v_cmp_ne_u32_e64 s[44:45], 1, v153
	s_andn2_b64 vcc, exec, s[48:49]
	s_mov_b64 s[72:73], -1
	s_cbranch_vccnz .LBB0_451
	s_and_saveexec_b64 s[72:73], s[50:51]
	s_cbranch_execz .LBB0_450
	s_waitcnt lgkmcnt(0)
	v_lshlrev_b64 v[172:173], 5, v[160:161]
	v_lshl_add_u64 v[172:173], s[14:15], 0, v[172:173]
	global_store_dwordx4 v[172:173], v[102:105], off
	global_store_dwordx4 v[172:173], v[98:101], off offset:16

; DI u32x4 pack8(f32x4 a, f32x4 b) { u32x4 w; w.x = pk2(a[0], a[1]); w.y = pk2(a[2], a[3]); w.z = pk2(b[0], b[1]); w.w = pk2(b[2], b[3]); return w; }
;     DI void operator()(AccRef acc, const Unit& u, int wr, int wc, int fr, int fq) const {
;     ...
;                 for (int m = 0; m < 4; ++m) { int row = row0 + ai * 128 + m * 16; asm volatile("" : "+v"(row) :: "memory");
;                     { const f32x4 a = acc[ai][0][m][0], b = acc[ai][0][m][1]; *(u32x4*)(CQ + (size_t)row * 384 + 256 + cl) = pack8(a, b);
;                       float ss = (a[0] * a[0] + a[1] * a[1]) + (a[2] * a[2] + a[3] * a[3]) + (b[0] * b[0] + b[1] * b[1]) + (b[2] * b[2] + b[3] * b[3]);
;                       ss += __shfl_xor(ss, 16); ss += __shfl_xor(ss, 32);
;                       if (fq == 0) unsafeAtomicAdd(SSQ + (size_t)row * 2, ss); }
;                     if (wc < 2) {
;                         const int i0 = 16 * wc + 4 * fq; const f32x4 cs = *(const f32x4*)(COS + (size_t)row * 32 + i0), sn = *(const f32x4*)(SIN + (size_t)row * 32 + i0);
;                         const f32x4 a = acc[ai][1][m][0], b = acc[ai][1][m][1]; f32x4 oa, ob;
;                         oa[0] = a[0] * cs[0] - a[1] * sn[0]; oa[1] = a[1] * cs[0] + a[0] * sn[0]; oa[2] = a[2] * cs[1] - a[3] * sn[1]; oa[3] = a[3] * cs[1] + a[2] * sn[1];
;                         ob[0] = b[0] * cs[2] - b[1] * sn[2]; ob[1] = b[1] * cs[2] + b[0] * sn[2]; ob[2] = b[2] * cs[3] - b[3] * sn[3]; ob[3] = b[3] * cs[3] + b[2] * sn[3];
;                         *(u32x4*)(KR + (size_t)row * 64 + cl) = pack8(oa, ob);
;                     } else if (wc == 2 && fq == 0) {
;                         *(f32x4*)(AB + (size_t)row * 8) = acc[ai][1][m][0]; *(f32x4*)(AB + (size_t)row * 8 + 4) = acc[ai][1][m][1];
;                     }
.LBB0_451:
	s_andn2_b64 vcc, exec, s[72:73]
	s_cbranch_vccnz .LBB0_453
	v_lshlrev_b64 v[160:161], 7, v[160:161]
	s_waitcnt lgkmcnt(0)
	v_lshl_add_u64 v[172:173], v[158:159], 0, v[160:161]
	v_lshl_add_u64 v[176:177], v[156:157], 0, v[160:161]
	global_load_dwordx4 v[172:175], v[172:173], off
	v_lshl_add_u64 v[160:161], v[154:155], 0, v[160:161]
	global_load_dwordx4 v[176:179], v[176:177], off
	s_waitcnt vmcnt(0) lgkmcnt(0)
	v_pk_mul_f32 v[180:181], v[102:103], v[176:177] op_sel:[1,0] op_sel_hi:[0,0]
	v_pk_mul_f32 v[176:177], v[104:105], v[176:177] op_sel:[1,1] op_sel_hi:[0,1]
	v_pk_fma_f32 v[182:183], v[102:103], v[172:173], v[180:181] neg_lo:[0,0,1] neg_hi:[0,0,1]
	v_pk_fma_f32 v[180:181], v[102:103], v[172:173], v[180:181] op_sel_hi:[1,0,1]
	v_pk_fma_f32 v[184:185], v[104:105], v[172:173], v[176:177] op_sel:[0,1,0] neg_lo:[0,0,1] neg_hi:[0,0,1]
	v_pk_fma_f32 v[172:173], v[104:105], v[172:173], v[176:177] op_sel:[0,1,0]
	v_pk_mul_f32 v[176:177], v[98:99], v[178:179] op_sel:[1,0] op_sel_hi:[0,0]
	v_pk_fma_f32 v[186:187], v[98:99], v[174:175], v[176:177] neg_lo:[0,0,1] neg_hi:[0,0,1]
	v_pk_fma_f32 v[176:177], v[98:99], v[174:175], v[176:177] op_sel_hi:[1,0,1]
	v_mov_b32_e32 v174, v179
	v_mov_b32_e32 v172, v175
	v_pk_mul_f32 v[174:175], v[100:101], v[174:175] op_sel:[1,0] op_sel_hi:[0,0]
	v_pk_fma_f32 v[178:179], v[100:101], v[172:173], v[174:175] op_sel_hi:[1,0,1] neg_lo:[0,0,1] neg_hi:[0,0,1]
	v_pk_fma_f32 v[174:175], v[100:101], v[172:173], v[174:175] op_sel_hi:[1,0,1]
	v_cvt_pk_bf16_f32 v172, v182, v181
	v_cvt_pk_bf16_f32 v173, v184, v173
	v_cvt_pk_bf16_f32 v174, v186, v177
	v_cvt_pk_bf16_f32 v175, v178, v175
	global_store_dwordx4 v[160:161], v[172:175], off
.LBB0_453:
	v_or_b32_e32 v160, 32, v164
	v_mov_b64_e32 v[176:177], s[60:61]
	s_waitcnt lgkmcnt(0)
	v_cvt_pk_bf16_f32 v172, v94, v95
	v_mad_i64_i32 v[176:177], s[64:65], v160, s92, v[176:177]
	v_cvt_pk_bf16_f32 v173, v96, v97
	v_cvt_pk_bf16_f32 v174, v90, v91
	v_cvt_pk_bf16_f32 v175, v92, v93
	v_lshl_add_u64 v[176:177], v[176:177], 0, v[0:1]
	global_store_dwordx4 v[176:177], v[172:175], off offset:512
	v_mul_f32_e32 v153, v95, v95
	v_fmac_f32_e32 v153, v94, v94
	v_mul_f32_e32 v172, v97, v97
	v_fmac_f32_e32 v172, v96, v96
	v_add_f32_e32 v153, v153, v172
	v_mul_f32_e32 v172, v91, v91
	v_fmac_f32_e32 v172, v90, v90
	v_add_f32_e32 v153, v172, v153
	v_mul_f32_e32 v172, v93, v93
	v_fmac_f32_e32 v172, v92, v92
	v_add_f32_e32 v153, v172, v153
	ds_bpermute_b32 v172, v170, v153
	v_ashrrev_i32_e32 v161, 31, v160
	s_waitcnt lgkmcnt(0)
	v_add_f32_e32 v153, v153, v172
	ds_bpermute_b32 v172, v171, v153
	s_and_saveexec_b64 s[72:73], s[40:41]
	s_cbranch_execnz .LBB0_532
	s_or_b64 exec, exec, s[72:73]
	s_and_b64 vcc, exec, s[44:45]
	s_mov_b64 s[72:73], -1
	s_cbranch_vccz .LBB0_533

; DI u32x4 pack8(f32x4 a, f32x4 b) { u32x4 w; w.x = pk2(a[0], a[1]); w.y = pk2(a[2], a[3]); w.z = pk2(b[0], b[1]); w.w = pk2(b[2], b[3]); return w; }
;     DI void operator()(AccRef acc, const Unit& u, int wr, int wc, int fr, int fq) const {
;     ...
;                 for (int m = 0; m < 4; ++m) { int row = row0 + ai * 128 + m * 16; asm volatile("" : "+v"(row) :: "memory");
;                     { const f32x4 a = acc[ai][0][m][0], b = acc[ai][0][m][1]; *(u32x4*)(CQ + (size_t)row * 384 + 256 + cl) = pack8(a, b);
;                       float ss = (a[0] * a[0] + a[1] * a[1]) + (a[2] * a[2] + a[3] * a[3]) + (b[0] * b[0] + b[1] * b[1]) + (b[2] * b[2] + b[3] * b[3]);
;                       ss += __shfl_xor(ss, 16); ss += __shfl_xor(ss, 32);
;                       if (fq == 0) unsafeAtomicAdd(SSQ + (size_t)row * 2, ss); }
;                     if (wc < 2) {
;                         const int i0 = 16 * wc + 4 * fq; const f32x4 cs = *(const f32x4*)(COS + (size_t)row * 32 + i0), sn = *(const f32x4*)(SIN + (size_t)row * 32 + i0);
;                         const f32x4 a = acc[ai][1][m][0], b = acc[ai][1][m][1]; f32x4 oa, ob;
;                         oa[0] = a[0] * cs[0] - a[1] * sn[0]; oa[1] = a[1] * cs[0] + a[0] * sn[0]; oa[2] = a[2] * cs[1] - a[3] * sn[1]; oa[3] = a[3] * cs[1] + a[2] * sn[1];
;                         ob[0] = b[0] * cs[2] - b[1] * sn[2]; ob[1] = b[1] * cs[2] + b[0] * sn[2]; ob[2] = b[2] * cs[3] - b[3] * sn[3]; ob[3] = b[3] * cs[3] + b[2] * sn[3];
;                         *(u32x4*)(KR + (size_t)row * 64 + cl) = pack8(oa, ob);
;                     } else if (wc == 2 && fq == 0) {
;                         *(f32x4*)(AB + (size_t)row * 8) = acc[ai][1][m][0]; *(f32x4*)(AB + (size_t)row * 8 + 4) = acc[ai][1][m][1];
;                     }
.LBB0_456:
	v_lshlrev_b64 v[160:161], 7, v[160:161]
	s_waitcnt lgkmcnt(0)
	v_lshl_add_u64 v[172:173], v[158:159], 0, v[160:161]
	v_lshl_add_u64 v[176:177], v[156:157], 0, v[160:161]
	global_load_dwordx4 v[172:175], v[172:173], off
	v_lshl_add_u64 v[160:161], v[154:155], 0, v[160:161]
	global_load_dwordx4 v[176:179], v[176:177], off
	s_waitcnt vmcnt(0) lgkmcnt(0)
	v_pk_mul_f32 v[180:181], v[86:87], v[176:177] op_sel:[1,0] op_sel_hi:[0,0]
	v_pk_mul_f32 v[176:177], v[88:89], v[176:177] op_sel:[1,1] op_sel_hi:[0,1]
	v_pk_fma_f32 v[182:183], v[86:87], v[172:173], v[180:181] neg_lo:[0,0,1] neg_hi:[0,0,1]
	v_pk_fma_f32 v[180:181], v[86:87], v[172:173], v[180:181] op_sel_hi:[1,0,1]
	v_pk_fma_f32 v[184:185], v[88:89], v[172:173], v[176:177] op_sel:[0,1,0] neg_lo:[0,0,1] neg_hi:[0,0,1]
	v_pk_fma_f32 v[172:173], v[88:89], v[172:173], v[176:177] op_sel:[0,1,0]
	v_pk_mul_f32 v[176:177], v[82:83], v[178:179] op_sel:[1,0] op_sel_hi:[0,0]
	v_pk_fma_f32 v[186:187], v[82:83], v[174:175], v[176:177] neg_lo:[0,0,1] neg_hi:[0,0,1]
	v_pk_fma_f32 v[176:177], v[82:83], v[174:175], v[176:177] op_sel_hi:[1,0,1]
	v_mov_b32_e32 v174, v179
	v_mov_b32_e32 v172, v175
	v_pk_mul_f32 v[174:175], v[84:85], v[174:175] op_sel:[1,0] op_sel_hi:[0,0]
	v_pk_fma_f32 v[178:179], v[84:85], v[172:173], v[174:175] op_sel_hi:[1,0,1] neg_lo:[0,0,1] neg_hi:[0,0,1]
	v_pk_fma_f32 v[174:175], v[84:85], v[172:173], v[174:175] op_sel_hi:[1,0,1]
	v_cvt_pk_bf16_f32 v172, v182, v181
	v_cvt_pk_bf16_f32 v173, v184, v173
	v_cvt_pk_bf16_f32 v174, v186, v177
	v_cvt_pk_bf16_f32 v175, v178, v175
	global_store_dwordx4 v[160:161], v[172:175], off
.LBB0_457:
	v_or_b32_e32 v160, 48, v164
	v_mov_b64_e32 v[176:177], s[60:61]
	s_waitcnt lgkmcnt(0)
	v_cvt_pk_bf16_f32 v172, v78, v79
	v_mad_i64_i32 v[176:177], s[64:65], v160, s92, v[176:177]
	v_cvt_pk_bf16_f32 v173, v80, v81
	v_cvt_pk_bf16_f32 v174, v74, v75
	v_cvt_pk_bf16_f32 v175, v76, v77
	v_lshl_add_u64 v[176:177], v[176:177], 0, v[0:1]
	global_store_dwordx4 v[176:177], v[172:175], off offset:512
	v_mul_f32_e32 v153, v79, v79
	v_fmac_f32_e32 v153, v78, v78
	v_mul_f32_e32 v172, v81, v81
	v_fmac_f32_e32 v172, v80, v80
	v_add_f32_e32 v153, v153, v172
	v_mul_f32_e32 v172, v75, v75
	v_fmac_f32_e32 v172, v74, v74
	v_add_f32_e32 v153, v172, v153
	v_mul_f32_e32 v172, v77, v77
	v_fmac_f32_e32 v172, v76, v76
	v_add_f32_e32 v153, v172, v153
	ds_bpermute_b32 v172, v170, v153
	v_ashrrev_i32_e32 v161, 31, v160
	s_waitcnt lgkmcnt(0)
	v_add_f32_e32 v153, v153, v172
	ds_bpermute_b32 v172, v171, v153
	s_and_saveexec_b64 s[72:73], s[40:41]
	s_cbranch_execnz .LBB0_536
	s_or_b64 exec, exec, s[72:73]
	s_and_b64 vcc, exec, s[44:45]
	s_mov_b64 s[72:73], -1
	s_cbranch_vccz .LBB0_537

; DI u32x4 pack8(f32x4 a, f32x4 b) { u32x4 w; w.x = pk2(a[0], a[1]); w.y = pk2(a[2], a[3]); w.z = pk2(b[0], b[1]); w.w = pk2(b[2], b[3]); return w; }
;     DI void operator()(AccRef acc, const Unit& u, int wr, int wc, int fr, int fq) const {
;     ...
;                 for (int m = 0; m < 4; ++m) { int row = row0 + ai * 128 + m * 16; asm volatile("" : "+v"(row) :: "memory");
;                     { const f32x4 a = acc[ai][0][m][0], b = acc[ai][0][m][1]; *(u32x4*)(CQ + (size_t)row * 384 + 256 + cl) = pack8(a, b);
;                       float ss = (a[0] * a[0] + a[1] * a[1]) + (a[2] * a[2] + a[3] * a[3]) + (b[0] * b[0] + b[1] * b[1]) + (b[2] * b[2] + b[3] * b[3]);
;                       ss += __shfl_xor(ss, 16); ss += __shfl_xor(ss, 32);
;                       if (fq == 0) unsafeAtomicAdd(SSQ + (size_t)row * 2, ss); }
;                     if (wc < 2) {
;                         const int i0 = 16 * wc + 4 * fq; const f32x4 cs = *(const f32x4*)(COS + (size_t)row * 32 + i0), sn = *(const f32x4*)(SIN + (size_t)row * 32 + i0);
;                         const f32x4 a = acc[ai][1][m][0], b = acc[ai][1][m][1]; f32x4 oa, ob;
;                         oa[0] = a[0] * cs[0] - a[1] * sn[0]; oa[1] = a[1] * cs[0] + a[0] * sn[0]; oa[2] = a[2] * cs[1] - a[3] * sn[1]; oa[3] = a[3] * cs[1] + a[2] * sn[1];
;                         ob[0] = b[0] * cs[2] - b[1] * sn[2]; ob[1] = b[1] * cs[2] + b[0] * sn[2]; ob[2] = b[2] * cs[3] - b[3] * sn[3]; ob[3] = b[3] * cs[3] + b[2] * sn[3];
;                         *(u32x4*)(KR + (size_t)row * 64 + cl) = pack8(oa, ob);
;                     } else if (wc == 2 && fq == 0) {
;                         *(f32x4*)(AB + (size_t)row * 8) = acc[ai][1][m][0]; *(f32x4*)(AB + (size_t)row * 8 + 4) = acc[ai][1][m][1];
;                     }
.LBB0_460:
	v_lshlrev_b64 v[160:161], 7, v[160:161]
	s_waitcnt lgkmcnt(0)
	v_lshl_add_u64 v[172:173], v[158:159], 0, v[160:161]
	v_lshl_add_u64 v[176:177], v[156:157], 0, v[160:161]
	global_load_dwordx4 v[172:175], v[172:173], off
	v_lshl_add_u64 v[160:161], v[154:155], 0, v[160:161]
	global_load_dwordx4 v[176:179], v[176:177], off
	s_waitcnt vmcnt(0) lgkmcnt(0)
	v_pk_mul_f32 v[180:181], v[70:71], v[176:177] op_sel:[1,0] op_sel_hi:[0,0]
	v_pk_mul_f32 v[176:177], v[72:73], v[176:177] op_sel:[1,1] op_sel_hi:[0,1]
	v_pk_fma_f32 v[182:183], v[70:71], v[172:173], v[180:181] neg_lo:[0,0,1] neg_hi:[0,0,1]
	v_pk_fma_f32 v[180:181], v[70:71], v[172:173], v[180:181] op_sel_hi:[1,0,1]
	v_pk_fma_f32 v[184:185], v[72:73], v[172:173], v[176:177] op_sel:[0,1,0] neg_lo:[0,0,1] neg_hi:[0,0,1]
	v_pk_fma_f32 v[172:173], v[72:73], v[172:173], v[176:177] op_sel:[0,1,0]
	v_pk_mul_f32 v[176:177], v[66:67], v[178:179] op_sel:[1,0] op_sel_hi:[0,0]
	v_pk_fma_f32 v[186:187], v[66:67], v[174:175], v[176:177] neg_lo:[0,0,1] neg_hi:[0,0,1]
	v_pk_fma_f32 v[176:177], v[66:67], v[174:175], v[176:177] op_sel_hi:[1,0,1]
	v_mov_b32_e32 v174, v179
	v_mov_b32_e32 v172, v175
	v_pk_mul_f32 v[174:175], v[68:69], v[174:175] op_sel:[1,0] op_sel_hi:[0,0]
	v_pk_fma_f32 v[178:179], v[68:69], v[172:173], v[174:175] op_sel_hi:[1,0,1] neg_lo:[0,0,1] neg_hi:[0,0,1]
	v_pk_fma_f32 v[174:175], v[68:69], v[172:173], v[174:175] op_sel_hi:[1,0,1]
	v_cvt_pk_bf16_f32 v172, v182, v181
	v_cvt_pk_bf16_f32 v173, v184, v173
	v_cvt_pk_bf16_f32 v174, v186, v177
	v_cvt_pk_bf16_f32 v175, v178, v175
	global_store_dwordx4 v[160:161], v[172:175], off
.LBB0_461:
	v_add_u32_e32 v160, 0x80, v164
	v_mov_b64_e32 v[176:177], s[60:61]
	s_waitcnt lgkmcnt(0)
	v_cvt_pk_bf16_f32 v172, v62, v63
	v_mad_i64_i32 v[176:177], s[64:65], v160, s92, v[176:177]
	v_cvt_pk_bf16_f32 v173, v64, v65
	v_cvt_pk_bf16_f32 v174, v58, v59
	v_cvt_pk_bf16_f32 v175, v60, v61
	v_lshl_add_u64 v[176:177], v[176:177], 0, v[0:1]
	global_store_dwordx4 v[176:177], v[172:175], off offset:512
	v_mul_f32_e32 v153, v63, v63
	v_fmac_f32_e32 v153, v62, v62
	v_mul_f32_e32 v172, v65, v65
	v_fmac_f32_e32 v172, v64, v64
	v_add_f32_e32 v153, v153, v172
	v_mul_f32_e32 v172, v59, v59
	v_fmac_f32_e32 v172, v58, v58
	v_add_f32_e32 v153, v172, v153
	v_mul_f32_e32 v172, v61, v61
	v_fmac_f32_e32 v172, v60, v60
	v_add_f32_e32 v153, v172, v153
	ds_bpermute_b32 v172, v170, v153
	v_ashrrev_i32_e32 v161, 31, v160
	s_waitcnt lgkmcnt(0)
	v_add_f32_e32 v153, v153, v172
	ds_bpermute_b32 v172, v171, v153
	s_and_saveexec_b64 s[72:73], s[40:41]
	s_cbranch_execnz .LBB0_540
	s_or_b64 exec, exec, s[72:73]
	s_and_b64 vcc, exec, s[44:45]
	s_mov_b64 s[72:73], -1
	s_cbranch_vccz .LBB0_541

; DI u32x4 pack8(f32x4 a, f32x4 b) { u32x4 w; w.x = pk2(a[0], a[1]); w.y = pk2(a[2], a[3]); w.z = pk2(b[0], b[1]); w.w = pk2(b[2], b[3]); return w; }
;     DI void operator()(AccRef acc, const Unit& u, int wr, int wc, int fr, int fq) const {
;     ...
;                 for (int m = 0; m < 4; ++m) { int row = row0 + ai * 128 + m * 16; asm volatile("" : "+v"(row) :: "memory");
;                     { const f32x4 a = acc[ai][0][m][0], b = acc[ai][0][m][1]; *(u32x4*)(CQ + (size_t)row * 384 + 256 + cl) = pack8(a, b);
;                       float ss = (a[0] * a[0] + a[1] * a[1]) + (a[2] * a[2] + a[3] * a[3]) + (b[0] * b[0] + b[1] * b[1]) + (b[2] * b[2] + b[3] * b[3]);
;                       ss += __shfl_xor(ss, 16); ss += __shfl_xor(ss, 32);
;                       if (fq == 0) unsafeAtomicAdd(SSQ + (size_t)row * 2, ss); }
;                     if (wc < 2) {
;                         const int i0 = 16 * wc + 4 * fq; const f32x4 cs = *(const f32x4*)(COS + (size_t)row * 32 + i0), sn = *(const f32x4*)(SIN + (size_t)row * 32 + i0);
;                         const f32x4 a = acc[ai][1][m][0], b = acc[ai][1][m][1]; f32x4 oa, ob;
;                         oa[0] = a[0] * cs[0] - a[1] * sn[0]; oa[1] = a[1] * cs[0] + a[0] * sn[0]; oa[2] = a[2] * cs[1] - a[3] * sn[1]; oa[3] = a[3] * cs[1] + a[2] * sn[1];
;                         ob[0] = b[0] * cs[2] - b[1] * sn[2]; ob[1] = b[1] * cs[2] + b[0] * sn[2]; ob[2] = b[2] * cs[3] - b[3] * sn[3]; ob[3] = b[3] * cs[3] + b[2] * sn[3];
;                         *(u32x4*)(KR + (size_t)row * 64 + cl) = pack8(oa, ob);
;                     } else if (wc == 2 && fq == 0) {
;                         *(f32x4*)(AB + (size_t)row * 8) = acc[ai][1][m][0]; *(f32x4*)(AB + (size_t)row * 8 + 4) = acc[ai][1][m][1];
;                     }
.LBB0_464:
	v_lshlrev_b64 v[160:161], 7, v[160:161]
	s_waitcnt lgkmcnt(0)
	v_lshl_add_u64 v[172:173], v[158:159], 0, v[160:161]
	v_lshl_add_u64 v[176:177], v[156:157], 0, v[160:161]
	global_load_dwordx4 v[172:175], v[172:173], off
	v_lshl_add_u64 v[160:161], v[154:155], 0, v[160:161]
	global_load_dwordx4 v[176:179], v[176:177], off
	s_waitcnt vmcnt(0) lgkmcnt(0)
	v_pk_mul_f32 v[180:181], v[54:55], v[176:177] op_sel:[1,0] op_sel_hi:[0,0]
	v_pk_mul_f32 v[176:177], v[56:57], v[176:177] op_sel:[1,1] op_sel_hi:[0,1]
	v_pk_fma_f32 v[182:183], v[54:55], v[172:173], v[180:181] neg_lo:[0,0,1] neg_hi:[0,0,1]
	v_pk_fma_f32 v[180:181], v[54:55], v[172:173], v[180:181] op_sel_hi:[1,0,1]
	v_pk_fma_f32 v[184:185], v[56:57], v[172:173], v[176:177] op_sel:[0,1,0] neg_lo:[0,0,1] neg_hi:[0,0,1]
	v_pk_fma_f32 v[172:173], v[56:57], v[172:173], v[176:177] op_sel:[0,1,0]
	v_pk_mul_f32 v[176:177], v[50:51], v[178:179] op_sel:[1,0] op_sel_hi:[0,0]
	v_pk_fma_f32 v[186:187], v[50:51], v[174:175], v[176:177] neg_lo:[0,0,1] neg_hi:[0,0,1]
	v_pk_fma_f32 v[176:177], v[50:51], v[174:175], v[176:177] op_sel_hi:[1,0,1]
	v_mov_b32_e32 v174, v179
	v_mov_b32_e32 v172, v175
	v_pk_mul_f32 v[174:175], v[52:53], v[174:175] op_sel:[1,0] op_sel_hi:[0,0]
	v_pk_fma_f32 v[178:179], v[52:53], v[172:173], v[174:175] op_sel_hi:[1,0,1] neg_lo:[0,0,1] neg_hi:[0,0,1]
	v_pk_fma_f32 v[174:175], v[52:53], v[172:173], v[174:175] op_sel_hi:[1,0,1]
	v_cvt_pk_bf16_f32 v172, v182, v181
	v_cvt_pk_bf16_f32 v173, v184, v173
	v_cvt_pk_bf16_f32 v174, v186, v177
	v_cvt_pk_bf16_f32 v175, v178, v175
	global_store_dwordx4 v[160:161], v[172:175], off
.LBB0_465:
	v_add_u32_e32 v160, 0x90, v164
	v_mov_b64_e32 v[176:177], s[60:61]
	s_waitcnt lgkmcnt(0)
	v_cvt_pk_bf16_f32 v172, v46, v47
	v_mad_i64_i32 v[176:177], s[64:65], v160, s92, v[176:177]
	v_cvt_pk_bf16_f32 v173, v48, v49
	v_cvt_pk_bf16_f32 v174, v42, v43
	v_cvt_pk_bf16_f32 v175, v44, v45
	v_lshl_add_u64 v[176:177], v[176:177], 0, v[0:1]
	global_store_dwordx4 v[176:177], v[172:175], off offset:512
	v_mul_f32_e32 v153, v47, v47
	v_fmac_f32_e32 v153, v46, v46
	v_mul_f32_e32 v172, v49, v49
	v_fmac_f32_e32 v172, v48, v48
	v_add_f32_e32 v153, v153, v172
	v_mul_f32_e32 v172, v43, v43
	v_fmac_f32_e32 v172, v42, v42
	v_add_f32_e32 v153, v172, v153
	v_mul_f32_e32 v172, v45, v45
	v_fmac_f32_e32 v172, v44, v44
	v_add_f32_e32 v153, v172, v153
	ds_bpermute_b32 v172, v170, v153
	v_ashrrev_i32_e32 v161, 31, v160
	s_waitcnt lgkmcnt(0)
	v_add_f32_e32 v153, v153, v172
	ds_bpermute_b32 v172, v171, v153
	s_and_saveexec_b64 s[72:73], s[40:41]
	s_cbranch_execnz .LBB0_544
	s_or_b64 exec, exec, s[72:73]
	s_and_b64 vcc, exec, s[44:45]
	s_mov_b64 s[72:73], -1
	s_cbranch_vccz .LBB0_545

; DI u32x4 pack8(f32x4 a, f32x4 b) { u32x4 w; w.x = pk2(a[0], a[1]); w.y = pk2(a[2], a[3]); w.z = pk2(b[0], b[1]); w.w = pk2(b[2], b[3]); return w; }
;     DI void operator()(AccRef acc, const Unit& u, int wr, int wc, int fr, int fq) const {
;     ...
;                 for (int m = 0; m < 4; ++m) { int row = row0 + ai * 128 + m * 16; asm volatile("" : "+v"(row) :: "memory");
;                     { const f32x4 a = acc[ai][0][m][0], b = acc[ai][0][m][1]; *(u32x4*)(CQ + (size_t)row * 384 + 256 + cl) = pack8(a, b);
;                       float ss = (a[0] * a[0] + a[1] * a[1]) + (a[2] * a[2] + a[3] * a[3]) + (b[0] * b[0] + b[1] * b[1]) + (b[2] * b[2] + b[3] * b[3]);
;                       ss += __shfl_xor(ss, 16); ss += __shfl_xor(ss, 32);
;                       if (fq == 0) unsafeAtomicAdd(SSQ + (size_t)row * 2, ss); }
;                     if (wc < 2) {
;                         const int i0 = 16 * wc + 4 * fq; const f32x4 cs = *(const f32x4*)(COS + (size_t)row * 32 + i0), sn = *(const f32x4*)(SIN + (size_t)row * 32 + i0);
;                         const f32x4 a = acc[ai][1][m][0], b = acc[ai][1][m][1]; f32x4 oa, ob;
;                         oa[0] = a[0] * cs[0] - a[1] * sn[0]; oa[1] = a[1] * cs[0] + a[0] * sn[0]; oa[2] = a[2] * cs[1] - a[3] * sn[1]; oa[3] = a[3] * cs[1] + a[2] * sn[1];
;                         ob[0] = b[0] * cs[2] - b[1] * sn[2]; ob[1] = b[1] * cs[2] + b[0] * sn[2]; ob[2] = b[2] * cs[3] - b[3] * sn[3]; ob[3] = b[3] * cs[3] + b[2] * sn[3];
;                         *(u32x4*)(KR + (size_t)row * 64 + cl) = pack8(oa, ob);
;                     } else if (wc == 2 && fq == 0) {
;                         *(f32x4*)(AB + (size_t)row * 8) = acc[ai][1][m][0]; *(f32x4*)(AB + (size_t)row * 8 + 4) = acc[ai][1][m][1];
;                     }
.LBB0_468:
	v_lshlrev_b64 v[160:161], 7, v[160:161]
	s_waitcnt lgkmcnt(0)
	v_lshl_add_u64 v[172:173], v[158:159], 0, v[160:161]
	v_lshl_add_u64 v[176:177], v[156:157], 0, v[160:161]
	global_load_dwordx4 v[172:175], v[172:173], off
	v_lshl_add_u64 v[160:161], v[154:155], 0, v[160:161]
	global_load_dwordx4 v[176:179], v[176:177], off
	s_waitcnt vmcnt(0) lgkmcnt(0)
	v_pk_mul_f32 v[180:181], v[38:39], v[176:177] op_sel:[1,0] op_sel_hi:[0,0]
	v_pk_mul_f32 v[176:177], v[40:41], v[176:177] op_sel:[1,1] op_sel_hi:[0,1]
	v_pk_fma_f32 v[182:183], v[38:39], v[172:173], v[180:181] neg_lo:[0,0,1] neg_hi:[0,0,1]
	v_pk_fma_f32 v[180:181], v[38:39], v[172:173], v[180:181] op_sel_hi:[1,0,1]
	v_pk_fma_f32 v[184:185], v[40:41], v[172:173], v[176:177] op_sel:[0,1,0] neg_lo:[0,0,1] neg_hi:[0,0,1]
	v_pk_fma_f32 v[172:173], v[40:41], v[172:173], v[176:177] op_sel:[0,1,0]
	v_pk_mul_f32 v[176:177], v[34:35], v[178:179] op_sel:[1,0] op_sel_hi:[0,0]
	v_pk_fma_f32 v[186:187], v[34:35], v[174:175], v[176:177] neg_lo:[0,0,1] neg_hi:[0,0,1]
	v_pk_fma_f32 v[176:177], v[34:35], v[174:175], v[176:177] op_sel_hi:[1,0,1]
	v_mov_b32_e32 v174, v179
	v_mov_b32_e32 v172, v175
	v_pk_mul_f32 v[174:175], v[36:37], v[174:175] op_sel:[1,0] op_sel_hi:[0,0]
	v_pk_fma_f32 v[178:179], v[36:37], v[172:173], v[174:175] op_sel_hi:[1,0,1] neg_lo:[0,0,1] neg_hi:[0,0,1]
	v_pk_fma_f32 v[174:175], v[36:37], v[172:173], v[174:175] op_sel_hi:[1,0,1]
	v_cvt_pk_bf16_f32 v172, v182, v181
	v_cvt_pk_bf16_f32 v173, v184, v173
	v_cvt_pk_bf16_f32 v174, v186, v177
	v_cvt_pk_bf16_f32 v175, v178, v175
	global_store_dwordx4 v[160:161], v[172:175], off
.LBB0_469:
	v_add_u32_e32 v160, 0xa0, v164
	v_mov_b64_e32 v[176:177], s[60:61]
	s_waitcnt lgkmcnt(0)
	v_cvt_pk_bf16_f32 v172, v30, v31
	v_mad_i64_i32 v[176:177], s[64:65], v160, s92, v[176:177]
	v_cvt_pk_bf16_f32 v173, v32, v33
	v_cvt_pk_bf16_f32 v174, v26, v27
	v_cvt_pk_bf16_f32 v175, v28, v29
	v_lshl_add_u64 v[176:177], v[176:177], 0, v[0:1]
	global_store_dwordx4 v[176:177], v[172:175], off offset:512
	v_mul_f32_e32 v153, v31, v31
	v_fmac_f32_e32 v153, v30, v30
	v_mul_f32_e32 v172, v33, v33
	v_fmac_f32_e32 v172, v32, v32
	v_add_f32_e32 v153, v153, v172
	v_mul_f32_e32 v172, v27, v27
	v_fmac_f32_e32 v172, v26, v26
	v_add_f32_e32 v153, v172, v153
	v_mul_f32_e32 v172, v29, v29
	v_fmac_f32_e32 v172, v28, v28
	v_add_f32_e32 v153, v172, v153
	ds_bpermute_b32 v172, v170, v153
	v_ashrrev_i32_e32 v161, 31, v160
	s_waitcnt lgkmcnt(0)
	v_add_f32_e32 v153, v153, v172
	ds_bpermute_b32 v172, v171, v153
	s_and_saveexec_b64 s[72:73], s[40:41]
	s_cbranch_execnz .LBB0_548
	s_or_b64 exec, exec, s[72:73]
	s_and_b64 vcc, exec, s[44:45]
	s_mov_b64 s[72:73], -1
	s_cbranch_vccz .LBB0_549

; DI u32x4 pack8(f32x4 a, f32x4 b) { u32x4 w; w.x = pk2(a[0], a[1]); w.y = pk2(a[2], a[3]); w.z = pk2(b[0], b[1]); w.w = pk2(b[2], b[3]); return w; }
;     DI void operator()(AccRef acc, const Unit& u, int wr, int wc, int fr, int fq) const {
;     ...
;                 for (int m = 0; m < 4; ++m) { int row = row0 + ai * 128 + m * 16; asm volatile("" : "+v"(row) :: "memory");
;                     { const f32x4 a = acc[ai][0][m][0], b = acc[ai][0][m][1]; *(u32x4*)(CQ + (size_t)row * 384 + 256 + cl) = pack8(a, b);
;                       float ss = (a[0] * a[0] + a[1] * a[1]) + (a[2] * a[2] + a[3] * a[3]) + (b[0] * b[0] + b[1] * b[1]) + (b[2] * b[2] + b[3] * b[3]);
;                       ss += __shfl_xor(ss, 16); ss += __shfl_xor(ss, 32);
;                       if (fq == 0) unsafeAtomicAdd(SSQ + (size_t)row * 2, ss); }
;                     if (wc < 2) {
;                         const int i0 = 16 * wc + 4 * fq; const f32x4 cs = *(const f32x4*)(COS + (size_t)row * 32 + i0), sn = *(const f32x4*)(SIN + (size_t)row * 32 + i0);
;                         const f32x4 a = acc[ai][1][m][0], b = acc[ai][1][m][1]; f32x4 oa, ob;
;                         oa[0] = a[0] * cs[0] - a[1] * sn[0]; oa[1] = a[1] * cs[0] + a[0] * sn[0]; oa[2] = a[2] * cs[1] - a[3] * sn[1]; oa[3] = a[3] * cs[1] + a[2] * sn[1];
;                         ob[0] = b[0] * cs[2] - b[1] * sn[2]; ob[1] = b[1] * cs[2] + b[0] * sn[2]; ob[2] = b[2] * cs[3] - b[3] * sn[3]; ob[3] = b[3] * cs[3] + b[2] * sn[3];
;                         *(u32x4*)(KR + (size_t)row * 64 + cl) = pack8(oa, ob);
;                     } else if (wc == 2 && fq == 0) {
;                         *(f32x4*)(AB + (size_t)row * 8) = acc[ai][1][m][0]; *(f32x4*)(AB + (size_t)row * 8 + 4) = acc[ai][1][m][1];
;                     }
.LBB0_472:
	v_lshlrev_b64 v[160:161], 7, v[160:161]
	s_waitcnt lgkmcnt(0)
	v_lshl_add_u64 v[172:173], v[158:159], 0, v[160:161]
	v_lshl_add_u64 v[176:177], v[156:157], 0, v[160:161]
	global_load_dwordx4 v[172:175], v[172:173], off
	v_lshl_add_u64 v[160:161], v[154:155], 0, v[160:161]
	global_load_dwordx4 v[176:179], v[176:177], off
	s_waitcnt vmcnt(0) lgkmcnt(0)
	v_pk_mul_f32 v[180:181], v[22:23], v[176:177] op_sel:[1,0] op_sel_hi:[0,0]
	v_pk_mul_f32 v[176:177], v[24:25], v[176:177] op_sel:[1,1] op_sel_hi:[0,1]
	v_pk_fma_f32 v[182:183], v[22:23], v[172:173], v[180:181] neg_lo:[0,0,1] neg_hi:[0,0,1]
	v_pk_fma_f32 v[180:181], v[22:23], v[172:173], v[180:181] op_sel_hi:[1,0,1]
	v_pk_fma_f32 v[184:185], v[24:25], v[172:173], v[176:177] op_sel:[0,1,0] neg_lo:[0,0,1] neg_hi:[0,0,1]
	v_pk_fma_f32 v[172:173], v[24:25], v[172:173], v[176:177] op_sel:[0,1,0]
	v_pk_mul_f32 v[176:177], v[18:19], v[178:179] op_sel:[1,0] op_sel_hi:[0,0]
	v_pk_fma_f32 v[186:187], v[18:19], v[174:175], v[176:177] neg_lo:[0,0,1] neg_hi:[0,0,1]
	v_pk_fma_f32 v[176:177], v[18:19], v[174:175], v[176:177] op_sel_hi:[1,0,1]
	v_mov_b32_e32 v174, v179
	v_mov_b32_e32 v172, v175
	v_pk_mul_f32 v[174:175], v[20:21], v[174:175] op_sel:[1,0] op_sel_hi:[0,0]
	v_pk_fma_f32 v[178:179], v[20:21], v[172:173], v[174:175] op_sel_hi:[1,0,1] neg_lo:[0,0,1] neg_hi:[0,0,1]
	v_pk_fma_f32 v[174:175], v[20:21], v[172:173], v[174:175] op_sel_hi:[1,0,1]
	v_cvt_pk_bf16_f32 v172, v182, v181
	v_cvt_pk_bf16_f32 v173, v184, v173
	v_cvt_pk_bf16_f32 v174, v186, v177
	v_cvt_pk_bf16_f32 v175, v178, v175
	global_store_dwordx4 v[160:161], v[172:175], off
.LBB0_473:
	v_mul_f32_e32 v153, v15, v15
	v_mul_f32_e32 v161, v17, v17
	v_fmac_f32_e32 v153, v14, v14
	v_fmac_f32_e32 v161, v16, v16
	v_add_f32_e32 v153, v153, v161
	v_mul_f32_e32 v161, v11, v11
	v_fmac_f32_e32 v161, v10, v10
	v_add_f32_e32 v153, v161, v153
	v_mul_f32_e32 v161, v13, v13
	v_fmac_f32_e32 v161, v12, v12
	v_add_f32_e32 v153, v161, v153
	ds_bpermute_b32 v170, v170, v153
	v_add_u32_e32 v160, 0xb0, v164
	v_mov_b64_e32 v[176:177], s[60:61]
	s_waitcnt lgkmcnt(0)
	v_add_f32_e32 v153, v153, v170
	ds_bpermute_b32 v170, v171, v153
	v_mad_i64_i32 v[176:177], s[64:65], v160, s92, v[176:177]
	v_cvt_pk_bf16_f32 v172, v14, v15
	v_cvt_pk_bf16_f32 v173, v16, v17
	v_cvt_pk_bf16_f32 v174, v10, v11
	v_cvt_pk_bf16_f32 v175, v12, v13
	v_ashrrev_i32_e32 v161, 31, v160
	v_lshl_add_u64 v[176:177], v[176:177], 0, v[0:1]
	global_store_dwordx4 v[176:177], v[172:175], off offset:512
	s_and_saveexec_b64 s[72:73], s[40:41]
	s_cbranch_execnz .LBB0_552
	s_or_b64 exec, exec, s[72:73]
	s_and_b64 vcc, exec, s[44:45]
	s_mov_b64 s[44:45], -1
	s_cbranch_vccz .LBB0_553

; DI u32x4 pack8(f32x4 a, f32x4 b) { u32x4 w; w.x = pk2(a[0], a[1]); w.y = pk2(a[2], a[3]); w.z = pk2(b[0], b[1]); w.w = pk2(b[2], b[3]); return w; }
;     DI void operator()(AccRef acc, const Unit& u, int wr, int wc, int fr, int fq) const {
;     ...
;                         const int i0 = 16 * wc + 4 * fq; const f32x4 cs = *(const f32x4*)(COS + (size_t)row * 32 + i0), sn = *(const f32x4*)(SIN + (size_t)row * 32 + i0);
;                         const f32x4 a = acc[ai][1][m][0], b = acc[ai][1][m][1]; f32x4 oa, ob;
;                         oa[0] = a[0] * cs[0] - a[1] * sn[0]; oa[1] = a[1] * cs[0] + a[0] * sn[0]; oa[2] = a[2] * cs[1] - a[3] * sn[1]; oa[3] = a[3] * cs[1] + a[2] * sn[1];
;                         ob[0] = b[0] * cs[2] - b[1] * sn[2]; ob[1] = b[1] * cs[2] + b[0] * sn[2]; ob[2] = b[2] * cs[3] - b[3] * sn[3]; ob[3] = b[3] * cs[3] + b[2] * sn[3];
;                         *(u32x4*)(KR + (size_t)row * 64 + cl) = pack8(oa, ob);
.LBB0_476:
	v_lshlrev_b64 v[174:175], 7, v[160:161]
	v_lshl_add_u64 v[158:159], v[158:159], 0, v[174:175]
	v_lshl_add_u64 v[156:157], v[156:157], 0, v[174:175]
	global_load_dwordx4 v[158:161], v[158:159], off
	v_lshl_add_u64 v[154:155], v[154:155], 0, v[174:175]
	s_waitcnt lgkmcnt(0)
	global_load_dwordx4 v[170:173], v[156:157], off
	s_waitcnt vmcnt(0)
	v_mov_b32_e32 v0, v161
	s_waitcnt lgkmcnt(0)
	v_pk_mul_f32 v[156:157], v[6:7], v[170:171] op_sel:[1,0] op_sel_hi:[0,0]
	v_pk_fma_f32 v[176:177], v[6:7], v[158:159], v[156:157] neg_lo:[0,0,1] neg_hi:[0,0,1]
	v_pk_fma_f32 v[156:157], v[6:7], v[158:159], v[156:157] op_sel_hi:[1,0,1]
	v_pk_mul_f32 v[170:171], v[8:9], v[170:171] op_sel:[1,1] op_sel_hi:[0,1]
	v_pk_fma_f32 v[178:179], v[8:9], v[158:159], v[170:171] op_sel:[0,1,0] neg_lo:[0,0,1] neg_hi:[0,0,1]
	v_pk_fma_f32 v[158:159], v[8:9], v[158:159], v[170:171] op_sel:[0,1,0]
	v_pk_mul_f32 v[170:171], v[2:3], v[172:173] op_sel:[1,0] op_sel_hi:[0,0]
	v_mov_b32_e32 v156, v173
	v_pk_fma_f32 v[180:181], v[2:3], v[160:161], v[170:171] neg_lo:[0,0,1] neg_hi:[0,0,1]
	v_pk_fma_f32 v[170:171], v[2:3], v[160:161], v[170:171] op_sel_hi:[1,0,1]
	v_pk_mul_f32 v[160:161], v[4:5], v[156:157] op_sel:[1,0] op_sel_hi:[0,0]
	v_pk_fma_f32 v[172:173], v[4:5], v[0:1], v[160:161] op_sel_hi:[1,0,1] neg_lo:[0,0,1] neg_hi:[0,0,1]
	v_pk_fma_f32 v[160:161], v[4:5], v[0:1], v[160:161] op_sel_hi:[1,0,1]
	v_cvt_pk_bf16_f32 v156, v176, v157
	v_cvt_pk_bf16_f32 v157, v178, v159
	v_cvt_pk_bf16_f32 v158, v180, v171
	v_cvt_pk_bf16_f32 v159, v172, v161
	global_store_dwordx4 v[154:155], v[156:159], off

; DI u32x4 pack8(f32x4 a, f32x4 b) { u32x4 w; w.x = pk2(a[0], a[1]); w.y = pk2(a[2], a[3]); w.z = pk2(b[0], b[1]); w.w = pk2(b[2], b[3]); return w; }
;     DI void operator()(AccRef acc, const Unit& u, int wr, int wc, int fr, int fq) const {
;     ...
;             bf16_t* base = pn == 8 ? CQ : CKV; const int ld = pn == 8 ? 384 : 256, which = pn == 8 ? 0 : 1;
; #pragma unroll
;             for (int ai = 0; ai < 2; ++ai)
; #pragma unroll
;                 for (int m = 0; m < 4; ++m) { int row = row0 + ai * 128 + m * 16; asm volatile("" : "+v"(row) :: "memory"); bf16_t* rp = base + (size_t)row * ld + cl; float ss = 0.f;
; #pragma unroll
;                     for (int bj = 0; bj < 2; ++bj) { const f32x4 a = acc[ai][bj][m][0], b = acc[ai][bj][m][1]; *(u32x4*)(rp + bj * 128) = pack8(a, b);
;                         ss += (a[0] * a[0] + a[1] * a[1]) + (a[2] * a[2] + a[3] * a[3]) + (b[0] * b[0] + b[1] * b[1]) + (b[2] * b[2] + b[3] * b[3]); }
;                     ss += __shfl_xor(ss, 16); ss += __shfl_xor(ss, 32);
;                     if (fq == 0) unsafeAtomicAdd(SSQ + (size_t)row * 2 + which, ss); }
.LBB0_478:
	s_and_b64 vcc, exec, s[14:15]
	s_cbranch_vccz .LBB0_496
	s_add_u32 s44, s56, 0xce00000
	s_addc_u32 s45, s57, 0
	s_cmp_lg_u32 s85, 8
	s_cselect_b64 s[14:15], -1, 0
	v_cndmask_b32_e64 v153, 0, 1, s[14:15]
	s_and_b64 s[14:15], s[14:15], exec
	s_cselect_b32 s15, s45, s61
	s_cselect_b32 s14, s44, s60
	v_lshlrev_b32_e32 v0, 1, v146
	v_lshl_add_u64 v[156:157], s[14:15], 0, v[0:1]
	v_lshlrev_b32_e32 v0, 2, v153
	v_mul_f32_e32 v153, v119, v119
	v_mul_f32_e32 v159, v121, v121
	v_fmac_f32_e32 v153, v118, v118
	v_fmac_f32_e32 v159, v120, v120
	v_add_f32_e32 v153, v153, v159
	v_mul_f32_e32 v159, v115, v115
	v_fmac_f32_e32 v168, v126, v126
	v_fmac_f32_e32 v169, v128, v128
	v_fmac_f32_e32 v159, v114, v114
	v_lshl_add_u64 v[154:155], s[58:59], 0, v[0:1]
	v_add_f32_e32 v0, v168, v169
	v_fmac_f32_e32 v167, v122, v122
	v_add_f32_e32 v153, v159, v153
	v_mul_f32_e32 v159, v117, v117
	v_add_f32_e32 v0, v167, v0
	v_fmac_f32_e32 v166, v124, v124
	v_fmac_f32_e32 v159, v116, v116
	v_add_f32_e32 v0, v166, v0
	v_add_f32_e32 v153, v159, v153
	v_add_f32_e32 v0, v153, v0
	v_and_b32_e32 v153, 64, v230
	v_add_u32_e32 v159, 64, v153
	v_cmp_lt_i32_e32 vcc, v165, v159
	s_movk_i32 s44, 0x100
	s_cselect_b32 s44, s44, 0x180
	v_cndmask_b32_e32 v153, v230, v165, vcc
	v_lshlrev_b32_e32 v153, 2, v153
	ds_bpermute_b32 v165, v153, v0
	v_mov_b32_e32 v158, v164
	v_cvt_pk_bf16_f32 v166, v118, v119
	v_mad_i64_i32 v[160:161], s[14:15], s44, v158, 0
	v_lshl_add_u64 v[160:161], v[160:161], 1, v[156:157]
	global_store_dwordx4 v[160:161], v[134:137], off
	v_cvt_pk_bf16_f32 v167, v120, v121
	v_cvt_pk_bf16_f32 v168, v114, v115
	s_waitcnt lgkmcnt(0)
	v_add_f32_e32 v134, v0, v165
	v_xor_b32_e32 v0, 32, v230
	v_cmp_lt_i32_e32 vcc, v0, v159
	v_cvt_pk_bf16_f32 v169, v116, v117
	global_store_dwordx4 v[160:161], v[166:169], off offset:256
	v_cndmask_b32_e32 v0, v230, v0, vcc
	v_lshlrev_b32_e32 v0, 2, v0
	ds_bpermute_b32 v135, v0, v134
	s_and_saveexec_b64 s[14:15], s[40:41]
	s_cbranch_execz .LBB0_481
	v_ashrrev_i32_e32 v159, 31, v158
	s_waitcnt lgkmcnt(0)
	v_add_f32_e32 v136, v134, v135
	v_lshl_add_u64 v[134:135], v[158:159], 3, v[154:155]
	s_waitcnt vmcnt(0)
	global_atomic_add_f32 v[134:135], v136, off
.LBB0_481:
	s_or_b64 exec, exec, s[14:15]
	v_or_b32_e32 v134, 16, v164
	v_cvt_pk_bf16_f32 v158, v110, v111
	v_mad_i64_i32 v[136:137], s[14:15], s44, v134, 0
	v_lshl_add_u64 v[136:137], v[136:137], 1, v[156:157]
	v_cvt_pk_bf16_f32 v159, v112, v113
	v_cvt_pk_bf16_f32 v160, v106, v107
	v_cvt_pk_bf16_f32 v161, v108, v109
	global_store_dwordx4 v[136:137], v[158:161], off
	s_waitcnt lgkmcnt(0)
	v_mul_f32_e32 v135, v111, v111
	v_fmac_f32_e32 v135, v110, v110
	v_mul_f32_e32 v158, v113, v113
	v_fmac_f32_e32 v158, v112, v112
	v_add_f32_e32 v135, v135, v158
	v_mul_f32_e32 v158, v107, v107
	v_fmac_f32_e32 v158, v106, v106
	v_add_f32_e32 v135, v158, v135
	v_mul_f32_e32 v158, v109, v109
	v_fmac_f32_e32 v158, v108, v108
	v_add_f32_e32 v135, v158, v135
	v_cvt_pk_bf16_f32 v158, v102, v103
	v_cvt_pk_bf16_f32 v159, v104, v105
	v_cvt_pk_bf16_f32 v160, v98, v99
	v_cvt_pk_bf16_f32 v161, v100, v101
	global_store_dwordx4 v[136:137], v[158:161], off offset:256
	v_mul_f32_e32 v136, v103, v103
	v_mul_f32_e32 v137, v105, v105
	v_fmac_f32_e32 v136, v102, v102
	v_fmac_f32_e32 v137, v104, v104
	v_add_f32_e32 v136, v136, v137
	v_mul_f32_e32 v137, v99, v99
	v_fmac_f32_e32 v137, v98, v98
	v_add_f32_e32 v136, v137, v136
	v_mul_f32_e32 v137, v101, v101
	v_fmac_f32_e32 v137, v100, v100
	v_add_f32_e32 v136, v137, v136
	v_add_f32_e32 v135, v136, v135
	ds_bpermute_b32 v136, v153, v135
	s_waitcnt lgkmcnt(0)
	v_add_f32_e32 v136, v135, v136
	ds_bpermute_b32 v137, v0, v136
	s_and_saveexec_b64 s[14:15], s[40:41]
	s_cbranch_execz .LBB0_483
	v_ashrrev_i32_e32 v135, 31, v134
	s_waitcnt lgkmcnt(0)
	v_add_f32_e32 v136, v136, v137
	v_lshl_add_u64 v[134:135], v[134:135], 3, v[154:155]
	s_waitcnt vmcnt(0)
	global_atomic_add_f32 v[134:135], v136, off
.LBB0_483:
	s_or_b64 exec, exec, s[14:15]
	v_or_b32_e32 v134, 32, v164
	v_cvt_pk_bf16_f32 v158, v94, v95
	s_waitcnt lgkmcnt(0)
	v_mad_i64_i32 v[136:137], s[14:15], s44, v134, 0
	v_lshl_add_u64 v[136:137], v[136:137], 1, v[156:157]
	v_cvt_pk_bf16_f32 v159, v96, v97
	v_cvt_pk_bf16_f32 v160, v90, v91
	v_cvt_pk_bf16_f32 v161, v92, v93
	global_store_dwordx4 v[136:137], v[158:161], off
	v_mul_f32_e32 v135, v95, v95
	v_fmac_f32_e32 v135, v94, v94
	v_mul_f32_e32 v158, v97, v97
	v_fmac_f32_e32 v158, v96, v96
	v_add_f32_e32 v135, v135, v158
	v_mul_f32_e32 v158, v91, v91
	v_fmac_f32_e32 v158, v90, v90
	v_add_f32_e32 v135, v158, v135
	v_mul_f32_e32 v158, v93, v93
	v_fmac_f32_e32 v158, v92, v92
	v_add_f32_e32 v135, v158, v135
	v_cvt_pk_bf16_f32 v158, v86, v87
	v_cvt_pk_bf16_f32 v159, v88, v89
	v_cvt_pk_bf16_f32 v160, v82, v83
	v_cvt_pk_bf16_f32 v161, v84, v85
	global_store_dwordx4 v[136:137], v[158:161], off offset:256
	v_mul_f32_e32 v136, v87, v87
	v_mul_f32_e32 v137, v89, v89
	v_fmac_f32_e32 v136, v86, v86
	v_fmac_f32_e32 v137, v88, v88
	v_add_f32_e32 v136, v136, v137
	v_mul_f32_e32 v137, v83, v83
	v_fmac_f32_e32 v137, v82, v82
	v_add_f32_e32 v136, v137, v136
	v_mul_f32_e32 v137, v85, v85
	v_fmac_f32_e32 v137, v84, v84
	v_add_f32_e32 v136, v137, v136
	v_add_f32_e32 v135, v136, v135
	ds_bpermute_b32 v136, v153, v135
	s_waitcnt lgkmcnt(0)
	v_add_f32_e32 v136, v135, v136
	ds_bpermute_b32 v137, v0, v136
	s_and_saveexec_b64 s[14:15], s[40:41]
	s_cbranch_execz .LBB0_485
	v_ashrrev_i32_e32 v135, 31, v134
	s_waitcnt lgkmcnt(0)
	v_add_f32_e32 v136, v136, v137
	v_lshl_add_u64 v[134:135], v[134:135], 3, v[154:155]
	s_waitcnt vmcnt(0)
	global_atomic_add_f32 v[134:135], v136, off
; DI u32x4 pack8(f32x4 a, f32x4 b) { u32x4 w; w.x = pk2(a[0], a[1]); w.y = pk2(a[2], a[3]); w.z = pk2(b[0], b[1]); w.w = pk2(b[2], b[3]); return w; }
;     DI void operator()(AccRef acc, const Unit& u, int wr, int wc, int fr, int fq) const {
;     ...
;             bf16_t* base = pn == 8 ? CQ : CKV; const int ld = pn == 8 ? 384 : 256, which = pn == 8 ? 0 : 1;
; #pragma unroll
;             for (int ai = 0; ai < 2; ++ai)
; #pragma unroll
;                 for (int m = 0; m < 4; ++m) { int row = row0 + ai * 128 + m * 16; asm volatile("" : "+v"(row) :: "memory"); bf16_t* rp = base + (size_t)row * ld + cl; float ss = 0.f;
; #pragma unroll
;                     for (int bj = 0; bj < 2; ++bj) { const f32x4 a = acc[ai][bj][m][0], b = acc[ai][bj][m][1]; *(u32x4*)(rp + bj * 128) = pack8(a, b);
;                         ss += (a[0] * a[0] + a[1] * a[1]) + (a[2] * a[2] + a[3] * a[3]) + (b[0] * b[0] + b[1] * b[1]) + (b[2] * b[2] + b[3] * b[3]); }
;                     ss += __shfl_xor(ss, 16); ss += __shfl_xor(ss, 32);
;                     if (fq == 0) unsafeAtomicAdd(SSQ + (size_t)row * 2 + which, ss); }
.LBB0_485:
	s_or_b64 exec, exec, s[14:15]
	v_or_b32_e32 v134, 48, v164
	v_cvt_pk_bf16_f32 v158, v78, v79
	s_waitcnt lgkmcnt(0)
	v_mad_i64_i32 v[136:137], s[14:15], s44, v134, 0
	v_lshl_add_u64 v[136:137], v[136:137], 1, v[156:157]
	v_cvt_pk_bf16_f32 v159, v80, v81
	v_cvt_pk_bf16_f32 v160, v74, v75
	v_cvt_pk_bf16_f32 v161, v76, v77
	global_store_dwordx4 v[136:137], v[158:161], off
	v_mul_f32_e32 v135, v79, v79
	v_fmac_f32_e32 v135, v78, v78
	v_mul_f32_e32 v158, v81, v81
	v_fmac_f32_e32 v158, v80, v80
	v_add_f32_e32 v135, v135, v158
	v_mul_f32_e32 v158, v75, v75
	v_fmac_f32_e32 v158, v74, v74
	v_add_f32_e32 v135, v158, v135
	v_mul_f32_e32 v158, v77, v77
	v_fmac_f32_e32 v158, v76, v76
	v_add_f32_e32 v135, v158, v135
	v_cvt_pk_bf16_f32 v158, v70, v71
	v_cvt_pk_bf16_f32 v159, v72, v73
	v_cvt_pk_bf16_f32 v160, v66, v67
	v_cvt_pk_bf16_f32 v161, v68, v69
	global_store_dwordx4 v[136:137], v[158:161], off offset:256
	v_mul_f32_e32 v136, v71, v71
	v_mul_f32_e32 v137, v73, v73
	v_fmac_f32_e32 v136, v70, v70
	v_fmac_f32_e32 v137, v72, v72
	v_add_f32_e32 v136, v136, v137
	v_mul_f32_e32 v137, v67, v67
	v_fmac_f32_e32 v137, v66, v66
	v_add_f32_e32 v136, v137, v136
	v_mul_f32_e32 v137, v69, v69
	v_fmac_f32_e32 v137, v68, v68
	v_add_f32_e32 v136, v137, v136
	v_add_f32_e32 v135, v136, v135
	ds_bpermute_b32 v136, v153, v135
	s_waitcnt lgkmcnt(0)
	v_add_f32_e32 v136, v135, v136
	ds_bpermute_b32 v137, v0, v136
	s_and_saveexec_b64 s[14:15], s[40:41]
	s_cbranch_execz .LBB0_487
	v_ashrrev_i32_e32 v135, 31, v134
	s_waitcnt lgkmcnt(0)
	v_add_f32_e32 v136, v136, v137
	v_lshl_add_u64 v[134:135], v[134:135], 3, v[154:155]
	s_waitcnt vmcnt(0)
	global_atomic_add_f32 v[134:135], v136, off
.LBB0_487:
	s_or_b64 exec, exec, s[14:15]
	v_add_u32_e32 v134, 0x80, v164
	v_cvt_pk_bf16_f32 v158, v62, v63
	s_waitcnt lgkmcnt(0)
	v_mad_i64_i32 v[136:137], s[14:15], s44, v134, 0
	v_lshl_add_u64 v[136:137], v[136:137], 1, v[156:157]
	v_cvt_pk_bf16_f32 v159, v64, v65
	v_cvt_pk_bf16_f32 v160, v58, v59
	v_cvt_pk_bf16_f32 v161, v60, v61
	global_store_dwordx4 v[136:137], v[158:161], off
	v_mul_f32_e32 v135, v63, v63
	v_fmac_f32_e32 v135, v62, v62
	v_mul_f32_e32 v158, v65, v65
	v_fmac_f32_e32 v158, v64, v64
	v_add_f32_e32 v135, v135, v158
	v_mul_f32_e32 v158, v59, v59
	v_fmac_f32_e32 v158, v58, v58
	v_add_f32_e32 v135, v158, v135
	v_mul_f32_e32 v158, v61, v61
	v_fmac_f32_e32 v158, v60, v60
	v_add_f32_e32 v135, v158, v135
	v_cvt_pk_bf16_f32 v158, v54, v55
	v_cvt_pk_bf16_f32 v159, v56, v57
	v_cvt_pk_bf16_f32 v160, v50, v51
	v_cvt_pk_bf16_f32 v161, v52, v53
	global_store_dwordx4 v[136:137], v[158:161], off offset:256
	v_mul_f32_e32 v136, v55, v55
	v_mul_f32_e32 v137, v57, v57
	v_fmac_f32_e32 v136, v54, v54
	v_fmac_f32_e32 v137, v56, v56
	v_add_f32_e32 v136, v136, v137
	v_mul_f32_e32 v137, v51, v51
	v_fmac_f32_e32 v137, v50, v50
	v_add_f32_e32 v136, v137, v136
	v_mul_f32_e32 v137, v53, v53
	v_fmac_f32_e32 v137, v52, v52
	v_add_f32_e32 v136, v137, v136
	v_add_f32_e32 v135, v136, v135
	ds_bpermute_b32 v136, v153, v135
	s_waitcnt lgkmcnt(0)
	v_add_f32_e32 v136, v135, v136
	ds_bpermute_b32 v137, v0, v136
	s_and_saveexec_b64 s[14:15], s[40:41]
	s_cbranch_execz .LBB0_489
	v_ashrrev_i32_e32 v135, 31, v134
	s_waitcnt lgkmcnt(0)
	v_add_f32_e32 v136, v136, v137
	v_lshl_add_u64 v[134:135], v[134:135], 3, v[154:155]
	s_waitcnt vmcnt(0)
	global_atomic_add_f32 v[134:135], v136, off
; DI u32x4 pack8(f32x4 a, f32x4 b) { u32x4 w; w.x = pk2(a[0], a[1]); w.y = pk2(a[2], a[3]); w.z = pk2(b[0], b[1]); w.w = pk2(b[2], b[3]); return w; }
;     DI void operator()(AccRef acc, const Unit& u, int wr, int wc, int fr, int fq) const {
;     ...
;             bf16_t* base = pn == 8 ? CQ : CKV; const int ld = pn == 8 ? 384 : 256, which = pn == 8 ? 0 : 1;
; #pragma unroll
;             for (int ai = 0; ai < 2; ++ai)
; #pragma unroll
;                 for (int m = 0; m < 4; ++m) { int row = row0 + ai * 128 + m * 16; asm volatile("" : "+v"(row) :: "memory"); bf16_t* rp = base + (size_t)row * ld + cl; float ss = 0.f;
; #pragma unroll
;                     for (int bj = 0; bj < 2; ++bj) { const f32x4 a = acc[ai][bj][m][0], b = acc[ai][bj][m][1]; *(u32x4*)(rp + bj * 128) = pack8(a, b);
;                         ss += (a[0] * a[0] + a[1] * a[1]) + (a[2] * a[2] + a[3] * a[3]) + (b[0] * b[0] + b[1] * b[1]) + (b[2] * b[2] + b[3] * b[3]); }
;                     ss += __shfl_xor(ss, 16); ss += __shfl_xor(ss, 32);
;                     if (fq == 0) unsafeAtomicAdd(SSQ + (size_t)row * 2 + which, ss); }
.LBB0_489:
	s_or_b64 exec, exec, s[14:15]
	v_add_u32_e32 v134, 0x90, v164
	v_cvt_pk_bf16_f32 v158, v46, v47
	s_waitcnt lgkmcnt(0)
	v_mad_i64_i32 v[136:137], s[14:15], s44, v134, 0
	v_lshl_add_u64 v[136:137], v[136:137], 1, v[156:157]
	v_cvt_pk_bf16_f32 v159, v48, v49
	v_cvt_pk_bf16_f32 v160, v42, v43
	v_cvt_pk_bf16_f32 v161, v44, v45
	global_store_dwordx4 v[136:137], v[158:161], off
	v_mul_f32_e32 v135, v47, v47
	v_fmac_f32_e32 v135, v46, v46
	v_mul_f32_e32 v158, v49, v49
	v_fmac_f32_e32 v158, v48, v48
	v_add_f32_e32 v135, v135, v158
	v_mul_f32_e32 v158, v43, v43
	v_fmac_f32_e32 v158, v42, v42
	v_add_f32_e32 v135, v158, v135
	v_mul_f32_e32 v158, v45, v45
	v_fmac_f32_e32 v158, v44, v44
	v_add_f32_e32 v135, v158, v135
	v_cvt_pk_bf16_f32 v158, v38, v39
	v_cvt_pk_bf16_f32 v159, v40, v41
	v_cvt_pk_bf16_f32 v160, v34, v35
	v_cvt_pk_bf16_f32 v161, v36, v37
	global_store_dwordx4 v[136:137], v[158:161], off offset:256
	v_mul_f32_e32 v136, v39, v39
	v_mul_f32_e32 v137, v41, v41
	v_fmac_f32_e32 v136, v38, v38
	v_fmac_f32_e32 v137, v40, v40
	v_add_f32_e32 v136, v136, v137
	v_mul_f32_e32 v137, v35, v35
	v_fmac_f32_e32 v137, v34, v34
	v_add_f32_e32 v136, v137, v136
	v_mul_f32_e32 v137, v37, v37
	v_fmac_f32_e32 v137, v36, v36
	v_add_f32_e32 v136, v137, v136
	v_add_f32_e32 v135, v136, v135
	ds_bpermute_b32 v136, v153, v135
	s_waitcnt lgkmcnt(0)
	v_add_f32_e32 v136, v135, v136
	ds_bpermute_b32 v137, v0, v136
	s_and_saveexec_b64 s[14:15], s[40:41]
	s_cbranch_execz .LBB0_491
	v_ashrrev_i32_e32 v135, 31, v134
	s_waitcnt lgkmcnt(0)
	v_add_f32_e32 v136, v136, v137
	v_lshl_add_u64 v[134:135], v[134:135], 3, v[154:155]
	s_waitcnt vmcnt(0)
	global_atomic_add_f32 v[134:135], v136, off
.LBB0_491:
	s_or_b64 exec, exec, s[14:15]
	v_add_u32_e32 v134, 0xa0, v164
	v_cvt_pk_bf16_f32 v158, v30, v31
	s_waitcnt lgkmcnt(0)
	v_mad_i64_i32 v[136:137], s[14:15], s44, v134, 0
	v_lshl_add_u64 v[136:137], v[136:137], 1, v[156:157]
	v_cvt_pk_bf16_f32 v159, v32, v33
	v_cvt_pk_bf16_f32 v160, v26, v27
	v_cvt_pk_bf16_f32 v161, v28, v29
	global_store_dwordx4 v[136:137], v[158:161], off
	v_mul_f32_e32 v135, v31, v31
	v_fmac_f32_e32 v135, v30, v30
	v_mul_f32_e32 v158, v33, v33
	v_fmac_f32_e32 v158, v32, v32
	v_add_f32_e32 v135, v135, v158
	v_mul_f32_e32 v158, v27, v27
	v_fmac_f32_e32 v158, v26, v26
	v_add_f32_e32 v135, v158, v135
	v_mul_f32_e32 v158, v29, v29
	v_fmac_f32_e32 v158, v28, v28
	v_add_f32_e32 v135, v158, v135
	v_cvt_pk_bf16_f32 v158, v22, v23
	v_cvt_pk_bf16_f32 v159, v24, v25
	v_cvt_pk_bf16_f32 v160, v18, v19
	v_cvt_pk_bf16_f32 v161, v20, v21
	global_store_dwordx4 v[136:137], v[158:161], off offset:256
	v_mul_f32_e32 v136, v23, v23
	v_mul_f32_e32 v137, v25, v25
	v_fmac_f32_e32 v136, v22, v22
	v_fmac_f32_e32 v137, v24, v24
	v_add_f32_e32 v136, v136, v137
	v_mul_f32_e32 v137, v19, v19
	v_fmac_f32_e32 v137, v18, v18
	v_add_f32_e32 v136, v137, v136
	v_mul_f32_e32 v137, v21, v21
	v_fmac_f32_e32 v137, v20, v20
	v_add_f32_e32 v136, v137, v136
	v_add_f32_e32 v135, v136, v135
	ds_bpermute_b32 v136, v153, v135
	s_waitcnt lgkmcnt(0)
	v_add_f32_e32 v136, v135, v136
	ds_bpermute_b32 v137, v0, v136
	s_and_saveexec_b64 s[14:15], s[40:41]
	s_cbranch_execz .LBB0_493
	v_ashrrev_i32_e32 v135, 31, v134
	s_waitcnt lgkmcnt(0)
	v_add_f32_e32 v136, v136, v137
	v_lshl_add_u64 v[134:135], v[134:135], 3, v[154:155]
	s_waitcnt vmcnt(0)
	global_atomic_add_f32 v[134:135], v136, off
.LBB0_493:
	s_or_b64 exec, exec, s[14:15]
	v_add_u32_e32 v134, 0xb0, v164
	v_cvt_pk_bf16_f32 v158, v10, v11
	s_waitcnt lgkmcnt(0)
	v_mad_i64_i32 v[136:137], s[14:15], s44, v134, 0
	v_lshl_add_u64 v[136:137], v[136:137], 1, v[156:157]
	v_cvt_pk_bf16_f32 v156, v14, v15
	v_cvt_pk_bf16_f32 v157, v16, v17
	v_cvt_pk_bf16_f32 v159, v12, v13
	global_store_dwordx4 v[136:137], v[156:159], off
	v_mul_f32_e32 v135, v15, v15
	v_fmac_f32_e32 v135, v14, v14
	v_mul_f32_e32 v156, v17, v17
	v_fmac_f32_e32 v156, v16, v16
	v_add_f32_e32 v135, v135, v156
	v_mul_f32_e32 v156, v11, v11
	v_fmac_f32_e32 v156, v10, v10
	v_add_f32_e32 v135, v156, v135
	v_mul_f32_e32 v156, v13, v13
	v_fmac_f32_e32 v156, v12, v12
	v_add_f32_e32 v135, v156, v135
	v_cvt_pk_bf16_f32 v156, v6, v7
	v_cvt_pk_bf16_f32 v157, v8, v9
	v_cvt_pk_bf16_f32 v158, v2, v3
	v_cvt_pk_bf16_f32 v159, v4, v5
	global_store_dwordx4 v[136:137], v[156:159], off offset:256
	v_mul_f32_e32 v136, v7, v7
	v_mul_f32_e32 v137, v9, v9
	v_fmac_f32_e32 v136, v6, v6
	v_fmac_f32_e32 v137, v8, v8
	v_add_f32_e32 v136, v136, v137
	v_mul_f32_e32 v137, v3, v3
	v_fmac_f32_e32 v137, v2, v2
	v_add_f32_e32 v136, v137, v136
	v_mul_f32_e32 v137, v5, v5
	v_fmac_f32_e32 v137, v4, v4
	v_add_f32_e32 v136, v137, v136
	v_add_f32_e32 v135, v136, v135
	ds_bpermute_b32 v136, v153, v135
	s_waitcnt lgkmcnt(0)
	v_add_f32_e32 v136, v135, v136
	ds_bpermute_b32 v0, v0, v136
	s_and_saveexec_b64 s[14:15], s[40:41]
	s_cbranch_execz .LBB0_495
	v_ashrrev_i32_e32 v135, 31, v134
	s_waitcnt lgkmcnt(0)
	v_add_f32_e32 v0, v136, v0
	v_lshl_add_u64 v[134:135], v[134:135], 3, v[154:155]
	s_waitcnt vmcnt(0)
	global_atomic_add_f32 v[134:135], v0, off

; DI u32x4 pack8(f32x4 a, f32x4 b) { u32x4 w; w.x = pk2(a[0], a[1]); w.y = pk2(a[2], a[3]); w.z = pk2(b[0], b[1]); w.w = pk2(b[2], b[3]); return w; }
; DI float siluf_(float x) { return x * __builtin_amdgcn_rcpf(1.f + __expf(-x)); }
;     DI void operator()(AccRef acc, const Unit& u, int wr, int wc, int fr, int fq) const {
;     ...
;         if (pn < 8) {
;             bf16_t* base; int ld, c0;
;             if (pn < 6) { base = QKV; ld = 1536; c0 = pn * 256; } else { base = Z; ld = 512; c0 = (pn - 6) * 256; }
; #pragma unroll
;             for (int ai = 0; ai < 2; ++ai)
; #pragma unroll
;                 for (int m = 0; m < 4; ++m) { int row_ = row0 + ai * 128 + m * 16; asm volatile("" : "+v"(row_) :: "memory"); bf16_t* rp = base + (size_t)row_ * ld + c0 + cl;
; #pragma unroll
;                     for (int bj = 0; bj < 2; ++bj) { f32x4 a = acc[ai][bj][m][0], b = acc[ai][bj][m][1];
;                         if (pn >= 6) {
; #pragma unroll
;                             for (int i = 0; i < 4; ++i) { a[i] = siluf_(a[i]); b[i] = siluf_(b[i]); } }
;                         *(u32x4*)(rp + bj * 128) = pack8(a, b); } }
.LBB0_499:
	s_lshl_b32 s44, s85, 8
	s_add_i32 s45, s44, 0xfffffa00
	s_cmp_lt_i32 s85, 6
	s_cselect_b32 s44, s44, s45
	s_movk_i32 s45, 0x600
	s_cselect_b32 s58, s45, 0x200
	s_mov_b32 s45, 0x9600000
	s_cselect_b32 s45, 0x3600000, s45
	s_add_u32 s56, s56, s45
	s_addc_u32 s57, s57, 0
	s_ashr_i32 s45, s44, 31
	s_lshl_b64 s[44:45], s[44:45], 1
	s_add_u32 s44, s56, s44
	s_addc_u32 s45, s57, s45
	s_waitcnt lgkmcnt(0)
	v_lshlrev_b32_e32 v0, 1, v146
	v_lshl_add_u64 v[134:135], s[44:45], 0, v[0:1]
	v_mad_i64_i32 v[136:137], s[44:45], s58, v136, 0
	v_cndmask_b32_e64 v0, 0, 1, s[14:15]
	v_lshl_add_u64 v[136:137], v[136:137], 1, v[134:135]
	v_cvt_pk_bf16_f32 v126, v126, v127
	v_cvt_pk_bf16_f32 v127, v128, v129
	v_cvt_pk_bf16_f32 v128, v122, v123
	v_cvt_pk_bf16_f32 v129, v124, v125
	v_cmp_ne_u32_e64 s[44:45], 1, v0
	s_andn2_b64 vcc, exec, s[14:15]
	global_store_dwordx4 v[136:137], v[126:129], off
	s_cbranch_vccnz .LBB0_501
	v_mul_f32_e32 v0, 0xbfb8aa3b, v118
	v_exp_f32_e32 v0, v0
	s_nop 0
	v_add_f32_e32 v0, 1.0, v0
	v_rcp_f32_e32 v122, v0
	v_mul_f32_e32 v0, 0xbfb8aa3b, v114
	v_exp_f32_e32 v0, v0
	s_nop 0
	v_add_f32_e32 v0, 1.0, v0
	v_rcp_f32_e32 v124, v0
	v_mul_f32_e32 v0, 0xbfb8aa3b, v119
	v_exp_f32_e32 v0, v0
	s_nop 0
	v_add_f32_e32 v0, 1.0, v0
	v_rcp_f32_e32 v123, v0
	v_mul_f32_e32 v0, 0xbfb8aa3b, v115
	v_exp_f32_e32 v0, v0
	v_pk_mul_f32 v[118:119], v[118:119], v[122:123]
	v_add_f32_e32 v0, 1.0, v0
	v_rcp_f32_e32 v125, v0
	v_mul_f32_e32 v0, 0xbfb8aa3b, v120
	v_exp_f32_e32 v0, v0
	v_pk_mul_f32 v[114:115], v[114:115], v[124:125]
	v_add_f32_e32 v0, 1.0, v0
	v_rcp_f32_e32 v126, v0
	v_mul_f32_e32 v0, 0xbfb8aa3b, v116
	v_exp_f32_e32 v0, v0
	s_nop 0
	v_add_f32_e32 v0, 1.0, v0
	v_rcp_f32_e32 v128, v0
	v_mul_f32_e32 v0, 0xbfb8aa3b, v121
	v_exp_f32_e32 v0, v0
	s_nop 0
	v_add_f32_e32 v0, 1.0, v0
	v_rcp_f32_e32 v127, v0
	v_mul_f32_e32 v0, 0xbfb8aa3b, v117
	v_exp_f32_e32 v0, v0
	v_pk_mul_f32 v[120:121], v[120:121], v[126:127]
	v_add_f32_e32 v0, 1.0, v0
	v_rcp_f32_e32 v129, v0
	s_nop 0
	v_pk_mul_f32 v[116:117], v[116:117], v[128:129]
.LBB0_501:
	v_cvt_pk_bf16_f32 v118, v118, v119
	v_cvt_pk_bf16_f32 v119, v120, v121
	v_cvt_pk_bf16_f32 v120, v114, v115
	v_cvt_pk_bf16_f32 v121, v116, v117
	global_store_dwordx4 v[136:137], v[118:121], off offset:256
	v_or_b32_e32 v0, 16, v164
	s_and_b64 vcc, exec, s[44:45]
	s_cbranch_vccnz .LBB0_503
	v_mul_f32_e32 v115, 0xbfb8aa3b, v106
	v_exp_f32_e32 v115, v115
	v_mul_f32_e32 v114, 0xbfb8aa3b, v110
	v_exp_f32_e32 v114, v114
	v_mul_f32_e32 v119, 0xbfb8aa3b, v108
	v_add_f32_e32 v115, 1.0, v115
	v_rcp_f32_e32 v116, v115
	v_mul_f32_e32 v115, 0xbfb8aa3b, v111
	v_exp_f32_e32 v115, v115
	v_add_f32_e32 v114, 1.0, v114
	v_exp_f32_e32 v119, v119
	v_rcp_f32_e32 v114, v114
	v_add_f32_e32 v115, 1.0, v115
	v_rcp_f32_e32 v115, v115
	v_add_f32_e32 v119, 1.0, v119
	v_mul_f32_e32 v117, 0xbfb8aa3b, v107
	v_mul_f32_e32 v118, 0xbfb8aa3b, v112
	v_rcp_f32_e32 v120, v119
	v_mul_f32_e32 v119, 0xbfb8aa3b, v113
	v_pk_mul_f32 v[110:111], v[110:111], v[114:115]
	v_mul_f32_e32 v114, 0xbfb8aa3b, v109
	v_exp_f32_e32 v117, v117
	v_exp_f32_e32 v118, v118
	v_exp_f32_e32 v119, v119
	v_exp_f32_e32 v114, v114
	v_add_f32_e32 v117, 1.0, v117
	v_add_f32_e32 v118, 1.0, v118
	v_add_f32_e32 v119, 1.0, v119
	v_add_f32_e32 v114, 1.0, v114
	v_rcp_f32_e32 v117, v117
	v_rcp_f32_e32 v118, v118
	v_rcp_f32_e32 v119, v119
	v_rcp_f32_e32 v121, v114
	v_pk_mul_f32 v[106:107], v[106:107], v[116:117]
	v_pk_mul_f32 v[112:113], v[112:113], v[118:119]
	v_pk_mul_f32 v[108:109], v[108:109], v[120:121]
.LBB0_503:
	v_mad_i64_i32 v[114:115], s[14:15], s58, v0, 0
	v_lshl_add_u64 v[114:115], v[114:115], 1, v[134:135]
	v_cvt_pk_bf16_f32 v110, v110, v111
	v_cvt_pk_bf16_f32 v111, v112, v113
	v_cvt_pk_bf16_f32 v112, v106, v107
	v_cvt_pk_bf16_f32 v113, v108, v109
	s_and_b64 vcc, exec, s[44:45]
	global_store_dwordx4 v[114:115], v[110:113], off
	s_cbranch_vccnz .LBB0_505
	v_mul_f32_e32 v0, 0xbfb8aa3b, v102
	v_exp_f32_e32 v0, v0
	s_nop 0
	v_add_f32_e32 v0, 1.0, v0
	v_rcp_f32_e32 v106, v0
	v_mul_f32_e32 v0, 0xbfb8aa3b, v98
	v_exp_f32_e32 v0, v0
	s_nop 0
	v_add_f32_e32 v0, 1.0, v0
	v_rcp_f32_e32 v108, v0
	v_mul_f32_e32 v0, 0xbfb8aa3b, v103
	v_exp_f32_e32 v0, v0
	s_nop 0
	v_add_f32_e32 v0, 1.0, v0
	v_rcp_f32_e32 v107, v0
	v_mul_f32_e32 v0, 0xbfb8aa3b, v99
	v_exp_f32_e32 v0, v0
	v_pk_mul_f32 v[102:103], v[102:103], v[106:107]
	v_add_f32_e32 v0, 1.0, v0
	v_rcp_f32_e32 v109, v0
	v_mul_f32_e32 v0, 0xbfb8aa3b, v104
	v_exp_f32_e32 v0, v0
	v_pk_mul_f32 v[98:99], v[98:99], v[108:109]
	v_add_f32_e32 v0, 1.0, v0
	v_rcp_f32_e32 v110, v0
	v_mul_f32_e32 v0, 0xbfb8aa3b, v100
	v_exp_f32_e32 v0, v0
	s_nop 0
	v_add_f32_e32 v0, 1.0, v0
	v_rcp_f32_e32 v112, v0
	v_mul_f32_e32 v0, 0xbfb8aa3b, v105
	v_exp_f32_e32 v0, v0
	s_nop 0
	v_add_f32_e32 v0, 1.0, v0
	v_rcp_f32_e32 v111, v0
	v_mul_f32_e32 v0, 0xbfb8aa3b, v101
	v_exp_f32_e32 v0, v0
	v_pk_mul_f32 v[104:105], v[104:105], v[110:111]
	v_add_f32_e32 v0, 1.0, v0
	v_rcp_f32_e32 v113, v0
	s_nop 0
	v_pk_mul_f32 v[100:101], v[100:101], v[112:113]
; DI u32x4 pack8(f32x4 a, f32x4 b) { u32x4 w; w.x = pk2(a[0], a[1]); w.y = pk2(a[2], a[3]); w.z = pk2(b[0], b[1]); w.w = pk2(b[2], b[3]); return w; }
; DI float siluf_(float x) { return x * __builtin_amdgcn_rcpf(1.f + __expf(-x)); }
;     DI void operator()(AccRef acc, const Unit& u, int wr, int wc, int fr, int fq) const {
;     ...
;         if (pn < 8) {
;             bf16_t* base; int ld, c0;
;             if (pn < 6) { base = QKV; ld = 1536; c0 = pn * 256; } else { base = Z; ld = 512; c0 = (pn - 6) * 256; }
; #pragma unroll
;             for (int ai = 0; ai < 2; ++ai)
; #pragma unroll
;                 for (int m = 0; m < 4; ++m) { int row_ = row0 + ai * 128 + m * 16; asm volatile("" : "+v"(row_) :: "memory"); bf16_t* rp = base + (size_t)row_ * ld + c0 + cl;
; #pragma unroll
;                     for (int bj = 0; bj < 2; ++bj) { f32x4 a = acc[ai][bj][m][0], b = acc[ai][bj][m][1];
;                         if (pn >= 6) {
; #pragma unroll
;                             for (int i = 0; i < 4; ++i) { a[i] = siluf_(a[i]); b[i] = siluf_(b[i]); } }
;                         *(u32x4*)(rp + bj * 128) = pack8(a, b); } }
.LBB0_505:
	v_cvt_pk_bf16_f32 v102, v102, v103
	v_cvt_pk_bf16_f32 v103, v104, v105
	v_cvt_pk_bf16_f32 v104, v98, v99
	v_cvt_pk_bf16_f32 v105, v100, v101
	global_store_dwordx4 v[114:115], v[102:105], off offset:256
	v_or_b32_e32 v0, 32, v164
	s_and_b64 vcc, exec, s[44:45]
	s_cbranch_vccnz .LBB0_507
	v_mul_f32_e32 v99, 0xbfb8aa3b, v90
	v_exp_f32_e32 v99, v99
	v_mul_f32_e32 v98, 0xbfb8aa3b, v94
	v_exp_f32_e32 v98, v98
	v_mul_f32_e32 v103, 0xbfb8aa3b, v92
	v_add_f32_e32 v99, 1.0, v99
	v_rcp_f32_e32 v100, v99
	v_mul_f32_e32 v99, 0xbfb8aa3b, v95
	v_exp_f32_e32 v99, v99
	v_add_f32_e32 v98, 1.0, v98
	v_exp_f32_e32 v103, v103
	v_rcp_f32_e32 v98, v98
	v_add_f32_e32 v99, 1.0, v99
	v_rcp_f32_e32 v99, v99
	v_add_f32_e32 v103, 1.0, v103
	v_mul_f32_e32 v101, 0xbfb8aa3b, v91
	v_mul_f32_e32 v102, 0xbfb8aa3b, v96
	v_rcp_f32_e32 v104, v103
	v_mul_f32_e32 v103, 0xbfb8aa3b, v97
	v_pk_mul_f32 v[94:95], v[94:95], v[98:99]
	v_mul_f32_e32 v98, 0xbfb8aa3b, v93
	v_exp_f32_e32 v101, v101
	v_exp_f32_e32 v102, v102
	v_exp_f32_e32 v103, v103
	v_exp_f32_e32 v98, v98
	v_add_f32_e32 v101, 1.0, v101
	v_add_f32_e32 v102, 1.0, v102
	v_add_f32_e32 v103, 1.0, v103
	v_add_f32_e32 v98, 1.0, v98
	v_rcp_f32_e32 v101, v101
	v_rcp_f32_e32 v102, v102
	v_rcp_f32_e32 v103, v103
	v_rcp_f32_e32 v105, v98
	v_pk_mul_f32 v[90:91], v[90:91], v[100:101]
	v_pk_mul_f32 v[96:97], v[96:97], v[102:103]
	v_pk_mul_f32 v[92:93], v[92:93], v[104:105]
.LBB0_507:
	v_mad_i64_i32 v[98:99], s[14:15], s58, v0, 0
	v_lshl_add_u64 v[98:99], v[98:99], 1, v[134:135]
	v_cvt_pk_bf16_f32 v94, v94, v95
	v_cvt_pk_bf16_f32 v95, v96, v97
	v_cvt_pk_bf16_f32 v96, v90, v91
	v_cvt_pk_bf16_f32 v97, v92, v93
	s_and_b64 vcc, exec, s[44:45]
	global_store_dwordx4 v[98:99], v[94:97], off
	s_cbranch_vccnz .LBB0_509
	v_mul_f32_e32 v0, 0xbfb8aa3b, v86
	v_exp_f32_e32 v0, v0
	s_nop 0
	v_add_f32_e32 v0, 1.0, v0
	v_rcp_f32_e32 v90, v0
	v_mul_f32_e32 v0, 0xbfb8aa3b, v82
	v_exp_f32_e32 v0, v0
	s_nop 0
	v_add_f32_e32 v0, 1.0, v0
	v_rcp_f32_e32 v92, v0
	v_mul_f32_e32 v0, 0xbfb8aa3b, v87
	v_exp_f32_e32 v0, v0
	s_nop 0
	v_add_f32_e32 v0, 1.0, v0
	v_rcp_f32_e32 v91, v0
	v_mul_f32_e32 v0, 0xbfb8aa3b, v83
	v_exp_f32_e32 v0, v0
	v_pk_mul_f32 v[86:87], v[86:87], v[90:91]
	v_add_f32_e32 v0, 1.0, v0
	v_rcp_f32_e32 v93, v0
	v_mul_f32_e32 v0, 0xbfb8aa3b, v88
	v_exp_f32_e32 v0, v0
	v_pk_mul_f32 v[82:83], v[82:83], v[92:93]
	v_add_f32_e32 v0, 1.0, v0
	v_rcp_f32_e32 v94, v0
	v_mul_f32_e32 v0, 0xbfb8aa3b, v84
	v_exp_f32_e32 v0, v0
	s_nop 0
	v_add_f32_e32 v0, 1.0, v0
	v_rcp_f32_e32 v96, v0
	v_mul_f32_e32 v0, 0xbfb8aa3b, v89
	v_exp_f32_e32 v0, v0
	s_nop 0
	v_add_f32_e32 v0, 1.0, v0
	v_rcp_f32_e32 v95, v0
	v_mul_f32_e32 v0, 0xbfb8aa3b, v85
	v_exp_f32_e32 v0, v0
	v_pk_mul_f32 v[88:89], v[88:89], v[94:95]
	v_add_f32_e32 v0, 1.0, v0
	v_rcp_f32_e32 v97, v0
	s_nop 0
	v_pk_mul_f32 v[84:85], v[84:85], v[96:97]
.LBB0_509:
	v_cvt_pk_bf16_f32 v86, v86, v87
	v_cvt_pk_bf16_f32 v87, v88, v89
	v_cvt_pk_bf16_f32 v88, v82, v83
	v_cvt_pk_bf16_f32 v89, v84, v85
	global_store_dwordx4 v[98:99], v[86:89], off offset:256
	v_or_b32_e32 v0, 48, v164
	s_and_b64 vcc, exec, s[44:45]
	s_cbranch_vccnz .LBB0_511
	v_mul_f32_e32 v83, 0xbfb8aa3b, v74
	v_exp_f32_e32 v83, v83
	v_mul_f32_e32 v82, 0xbfb8aa3b, v78
	v_exp_f32_e32 v82, v82
	v_mul_f32_e32 v87, 0xbfb8aa3b, v76
	v_add_f32_e32 v83, 1.0, v83
	v_rcp_f32_e32 v84, v83
	v_mul_f32_e32 v83, 0xbfb8aa3b, v79
	v_exp_f32_e32 v83, v83
	v_add_f32_e32 v82, 1.0, v82
	v_exp_f32_e32 v87, v87
	v_rcp_f32_e32 v82, v82
	v_add_f32_e32 v83, 1.0, v83
	v_rcp_f32_e32 v83, v83
	v_add_f32_e32 v87, 1.0, v87
	v_mul_f32_e32 v85, 0xbfb8aa3b, v75
	v_mul_f32_e32 v86, 0xbfb8aa3b, v80
	v_rcp_f32_e32 v88, v87
	v_mul_f32_e32 v87, 0xbfb8aa3b, v81
	v_pk_mul_f32 v[78:79], v[78:79], v[82:83]
	v_mul_f32_e32 v82, 0xbfb8aa3b, v77
	v_exp_f32_e32 v85, v85
	v_exp_f32_e32 v86, v86
	v_exp_f32_e32 v87, v87
	v_exp_f32_e32 v82, v82
	v_add_f32_e32 v85, 1.0, v85
	v_add_f32_e32 v86, 1.0, v86
	v_add_f32_e32 v87, 1.0, v87
	v_add_f32_e32 v82, 1.0, v82
	v_rcp_f32_e32 v85, v85
	v_rcp_f32_e32 v86, v86
	v_rcp_f32_e32 v87, v87
	v_rcp_f32_e32 v89, v82
	v_pk_mul_f32 v[74:75], v[74:75], v[84:85]
	v_pk_mul_f32 v[80:81], v[80:81], v[86:87]
	v_pk_mul_f32 v[76:77], v[76:77], v[88:89]
.LBB0_511:
	v_mad_i64_i32 v[82:83], s[14:15], s58, v0, 0
	v_lshl_add_u64 v[82:83], v[82:83], 1, v[134:135]
	v_cvt_pk_bf16_f32 v78, v78, v79
	v_cvt_pk_bf16_f32 v79, v80, v81
	v_cvt_pk_bf16_f32 v80, v74, v75
	v_cvt_pk_bf16_f32 v81, v76, v77
	s_and_b64 vcc, exec, s[44:45]
	global_store_dwordx4 v[82:83], v[78:81], off
	s_cbranch_vccnz .LBB0_513
	v_mul_f32_e32 v0, 0xbfb8aa3b, v70
	v_exp_f32_e32 v0, v0
	s_nop 0
	v_add_f32_e32 v0, 1.0, v0
	v_rcp_f32_e32 v74, v0
	v_mul_f32_e32 v0, 0xbfb8aa3b, v66
	v_exp_f32_e32 v0, v0
	s_nop 0
	v_add_f32_e32 v0, 1.0, v0
	v_rcp_f32_e32 v76, v0
	v_mul_f32_e32 v0, 0xbfb8aa3b, v71
	v_exp_f32_e32 v0, v0
	s_nop 0
	v_add_f32_e32 v0, 1.0, v0
	v_rcp_f32_e32 v75, v0
	v_mul_f32_e32 v0, 0xbfb8aa3b, v67
	v_exp_f32_e32 v0, v0
	v_pk_mul_f32 v[70:71], v[70:71], v[74:75]
	v_add_f32_e32 v0, 1.0, v0
	v_rcp_f32_e32 v77, v0
	v_mul_f32_e32 v0, 0xbfb8aa3b, v72
	v_exp_f32_e32 v0, v0
	v_pk_mul_f32 v[66:67], v[66:67], v[76:77]
	v_add_f32_e32 v0, 1.0, v0
	v_rcp_f32_e32 v78, v0
	v_mul_f32_e32 v0, 0xbfb8aa3b, v68
	v_exp_f32_e32 v0, v0
	s_nop 0
	v_add_f32_e32 v0, 1.0, v0
	v_rcp_f32_e32 v80, v0
	v_mul_f32_e32 v0, 0xbfb8aa3b, v73
	v_exp_f32_e32 v0, v0
	s_nop 0
	v_add_f32_e32 v0, 1.0, v0
	v_rcp_f32_e32 v79, v0
	v_mul_f32_e32 v0, 0xbfb8aa3b, v69
	v_exp_f32_e32 v0, v0
	v_pk_mul_f32 v[72:73], v[72:73], v[78:79]
	v_add_f32_e32 v0, 1.0, v0
	v_rcp_f32_e32 v81, v0
	s_nop 0
	v_pk_mul_f32 v[68:69], v[68:69], v[80:81]
; DI u32x4 pack8(f32x4 a, f32x4 b) { u32x4 w; w.x = pk2(a[0], a[1]); w.y = pk2(a[2], a[3]); w.z = pk2(b[0], b[1]); w.w = pk2(b[2], b[3]); return w; }
; DI float siluf_(float x) { return x * __builtin_amdgcn_rcpf(1.f + __expf(-x)); }
;     DI void operator()(AccRef acc, const Unit& u, int wr, int wc, int fr, int fq) const {
;     ...
;         if (pn < 8) {
;             bf16_t* base; int ld, c0;
;             if (pn < 6) { base = QKV; ld = 1536; c0 = pn * 256; } else { base = Z; ld = 512; c0 = (pn - 6) * 256; }
; #pragma unroll
;             for (int ai = 0; ai < 2; ++ai)
; #pragma unroll
;                 for (int m = 0; m < 4; ++m) { int row_ = row0 + ai * 128 + m * 16; asm volatile("" : "+v"(row_) :: "memory"); bf16_t* rp = base + (size_t)row_ * ld + c0 + cl;
; #pragma unroll
;                     for (int bj = 0; bj < 2; ++bj) { f32x4 a = acc[ai][bj][m][0], b = acc[ai][bj][m][1];
;                         if (pn >= 6) {
; #pragma unroll
;                             for (int i = 0; i < 4; ++i) { a[i] = siluf_(a[i]); b[i] = siluf_(b[i]); } }
;                         *(u32x4*)(rp + bj * 128) = pack8(a, b); } }
.LBB0_513:
	v_cvt_pk_bf16_f32 v70, v70, v71
	v_cvt_pk_bf16_f32 v71, v72, v73
	v_cvt_pk_bf16_f32 v72, v66, v67
	v_cvt_pk_bf16_f32 v73, v68, v69
	global_store_dwordx4 v[82:83], v[70:73], off offset:256
	v_add_u32_e32 v0, 0x80, v164
	s_and_b64 vcc, exec, s[44:45]
	s_cbranch_vccnz .LBB0_515
	v_mul_f32_e32 v67, 0xbfb8aa3b, v58
	v_exp_f32_e32 v67, v67
	v_mul_f32_e32 v66, 0xbfb8aa3b, v62
	v_exp_f32_e32 v66, v66
	v_mul_f32_e32 v71, 0xbfb8aa3b, v60
	v_add_f32_e32 v67, 1.0, v67
	v_rcp_f32_e32 v68, v67
	v_mul_f32_e32 v67, 0xbfb8aa3b, v63
	v_exp_f32_e32 v67, v67
	v_add_f32_e32 v66, 1.0, v66
	v_exp_f32_e32 v71, v71
	v_rcp_f32_e32 v66, v66
	v_add_f32_e32 v67, 1.0, v67
	v_rcp_f32_e32 v67, v67
	v_add_f32_e32 v71, 1.0, v71
	v_mul_f32_e32 v69, 0xbfb8aa3b, v59
	v_mul_f32_e32 v70, 0xbfb8aa3b, v64
	v_rcp_f32_e32 v72, v71
	v_mul_f32_e32 v71, 0xbfb8aa3b, v65
	v_pk_mul_f32 v[62:63], v[62:63], v[66:67]
	v_mul_f32_e32 v66, 0xbfb8aa3b, v61
	v_exp_f32_e32 v69, v69
	v_exp_f32_e32 v70, v70
	v_exp_f32_e32 v71, v71
	v_exp_f32_e32 v66, v66
	v_add_f32_e32 v69, 1.0, v69
	v_add_f32_e32 v70, 1.0, v70
	v_add_f32_e32 v71, 1.0, v71
	v_add_f32_e32 v66, 1.0, v66
	v_rcp_f32_e32 v69, v69
	v_rcp_f32_e32 v70, v70
	v_rcp_f32_e32 v71, v71
	v_rcp_f32_e32 v73, v66
	v_pk_mul_f32 v[58:59], v[58:59], v[68:69]
	v_pk_mul_f32 v[64:65], v[64:65], v[70:71]
	v_pk_mul_f32 v[60:61], v[60:61], v[72:73]
.LBB0_515:
	v_mad_i64_i32 v[66:67], s[14:15], s58, v0, 0
	v_lshl_add_u64 v[66:67], v[66:67], 1, v[134:135]
	v_cvt_pk_bf16_f32 v62, v62, v63
	v_cvt_pk_bf16_f32 v63, v64, v65
	v_cvt_pk_bf16_f32 v64, v58, v59
	v_cvt_pk_bf16_f32 v65, v60, v61
	s_and_b64 vcc, exec, s[44:45]
	global_store_dwordx4 v[66:67], v[62:65], off
	s_cbranch_vccnz .LBB0_517
	v_mul_f32_e32 v0, 0xbfb8aa3b, v54
	v_exp_f32_e32 v0, v0
	s_nop 0
	v_add_f32_e32 v0, 1.0, v0
	v_rcp_f32_e32 v58, v0
	v_mul_f32_e32 v0, 0xbfb8aa3b, v50
	v_exp_f32_e32 v0, v0
	s_nop 0
	v_add_f32_e32 v0, 1.0, v0
	v_rcp_f32_e32 v60, v0
	v_mul_f32_e32 v0, 0xbfb8aa3b, v55
	v_exp_f32_e32 v0, v0
	s_nop 0
	v_add_f32_e32 v0, 1.0, v0
	v_rcp_f32_e32 v59, v0
	v_mul_f32_e32 v0, 0xbfb8aa3b, v51
	v_exp_f32_e32 v0, v0
	v_pk_mul_f32 v[54:55], v[54:55], v[58:59]
	v_add_f32_e32 v0, 1.0, v0
	v_rcp_f32_e32 v61, v0
	v_mul_f32_e32 v0, 0xbfb8aa3b, v56
	v_exp_f32_e32 v0, v0
	v_pk_mul_f32 v[50:51], v[50:51], v[60:61]
	v_add_f32_e32 v0, 1.0, v0
	v_rcp_f32_e32 v62, v0
	v_mul_f32_e32 v0, 0xbfb8aa3b, v52
	v_exp_f32_e32 v0, v0
	s_nop 0
	v_add_f32_e32 v0, 1.0, v0
	v_rcp_f32_e32 v64, v0
	v_mul_f32_e32 v0, 0xbfb8aa3b, v57
	v_exp_f32_e32 v0, v0
	s_nop 0
	v_add_f32_e32 v0, 1.0, v0
	v_rcp_f32_e32 v63, v0
	v_mul_f32_e32 v0, 0xbfb8aa3b, v53
	v_exp_f32_e32 v0, v0
	v_pk_mul_f32 v[56:57], v[56:57], v[62:63]
	v_add_f32_e32 v0, 1.0, v0
	v_rcp_f32_e32 v65, v0
	s_nop 0
	v_pk_mul_f32 v[52:53], v[52:53], v[64:65]
.LBB0_517:
	v_cvt_pk_bf16_f32 v54, v54, v55
	v_cvt_pk_bf16_f32 v55, v56, v57
	v_cvt_pk_bf16_f32 v56, v50, v51
	v_cvt_pk_bf16_f32 v57, v52, v53
	global_store_dwordx4 v[66:67], v[54:57], off offset:256
	v_add_u32_e32 v0, 0x90, v164
	s_and_b64 vcc, exec, s[44:45]
	s_cbranch_vccnz .LBB0_519
	v_mul_f32_e32 v51, 0xbfb8aa3b, v42
	v_exp_f32_e32 v51, v51
	v_mul_f32_e32 v50, 0xbfb8aa3b, v46
	v_exp_f32_e32 v50, v50
	v_mul_f32_e32 v55, 0xbfb8aa3b, v44
	v_add_f32_e32 v51, 1.0, v51
	v_rcp_f32_e32 v52, v51
	v_mul_f32_e32 v51, 0xbfb8aa3b, v47
	v_exp_f32_e32 v51, v51
	v_add_f32_e32 v50, 1.0, v50
	v_exp_f32_e32 v55, v55
	v_rcp_f32_e32 v50, v50
	v_add_f32_e32 v51, 1.0, v51
	v_rcp_f32_e32 v51, v51
	v_add_f32_e32 v55, 1.0, v55
	v_mul_f32_e32 v53, 0xbfb8aa3b, v43
	v_mul_f32_e32 v54, 0xbfb8aa3b, v48
	v_rcp_f32_e32 v56, v55
	v_mul_f32_e32 v55, 0xbfb8aa3b, v49
	v_pk_mul_f32 v[46:47], v[46:47], v[50:51]
	v_mul_f32_e32 v50, 0xbfb8aa3b, v45
	v_exp_f32_e32 v53, v53
	v_exp_f32_e32 v54, v54
	v_exp_f32_e32 v55, v55
	v_exp_f32_e32 v50, v50
	v_add_f32_e32 v53, 1.0, v53
	v_add_f32_e32 v54, 1.0, v54
	v_add_f32_e32 v55, 1.0, v55
	v_add_f32_e32 v50, 1.0, v50
	v_rcp_f32_e32 v53, v53
	v_rcp_f32_e32 v54, v54
	v_rcp_f32_e32 v55, v55
	v_rcp_f32_e32 v57, v50
	v_pk_mul_f32 v[42:43], v[42:43], v[52:53]
	v_pk_mul_f32 v[48:49], v[48:49], v[54:55]
	v_pk_mul_f32 v[44:45], v[44:45], v[56:57]
.LBB0_519:
	v_mad_i64_i32 v[50:51], s[14:15], s58, v0, 0
	v_lshl_add_u64 v[50:51], v[50:51], 1, v[134:135]
	v_cvt_pk_bf16_f32 v46, v46, v47
	v_cvt_pk_bf16_f32 v47, v48, v49
	v_cvt_pk_bf16_f32 v48, v42, v43
	v_cvt_pk_bf16_f32 v49, v44, v45
	s_and_b64 vcc, exec, s[44:45]
	global_store_dwordx4 v[50:51], v[46:49], off
	s_cbranch_vccnz .LBB0_521
	v_mul_f32_e32 v0, 0xbfb8aa3b, v38
	v_exp_f32_e32 v0, v0
	s_nop 0
	v_add_f32_e32 v0, 1.0, v0
	v_rcp_f32_e32 v42, v0
	v_mul_f32_e32 v0, 0xbfb8aa3b, v34
	v_exp_f32_e32 v0, v0
	s_nop 0
	v_add_f32_e32 v0, 1.0, v0
	v_rcp_f32_e32 v44, v0
	v_mul_f32_e32 v0, 0xbfb8aa3b, v39
	v_exp_f32_e32 v0, v0
	s_nop 0
	v_add_f32_e32 v0, 1.0, v0
	v_rcp_f32_e32 v43, v0
	v_mul_f32_e32 v0, 0xbfb8aa3b, v35
	v_exp_f32_e32 v0, v0
	v_pk_mul_f32 v[38:39], v[38:39], v[42:43]
	v_add_f32_e32 v0, 1.0, v0
	v_rcp_f32_e32 v45, v0
	v_mul_f32_e32 v0, 0xbfb8aa3b, v40
	v_exp_f32_e32 v0, v0
	v_pk_mul_f32 v[34:35], v[34:35], v[44:45]
	v_add_f32_e32 v0, 1.0, v0
	v_rcp_f32_e32 v46, v0
	v_mul_f32_e32 v0, 0xbfb8aa3b, v36
	v_exp_f32_e32 v0, v0
	s_nop 0
	v_add_f32_e32 v0, 1.0, v0
	v_rcp_f32_e32 v48, v0
	v_mul_f32_e32 v0, 0xbfb8aa3b, v41
	v_exp_f32_e32 v0, v0
	s_nop 0
	v_add_f32_e32 v0, 1.0, v0
	v_rcp_f32_e32 v47, v0
	v_mul_f32_e32 v0, 0xbfb8aa3b, v37
	v_exp_f32_e32 v0, v0
	v_pk_mul_f32 v[40:41], v[40:41], v[46:47]
	v_add_f32_e32 v0, 1.0, v0
	v_rcp_f32_e32 v49, v0
	s_nop 0
	v_pk_mul_f32 v[36:37], v[36:37], v[48:49]
; DI u32x4 pack8(f32x4 a, f32x4 b) { u32x4 w; w.x = pk2(a[0], a[1]); w.y = pk2(a[2], a[3]); w.z = pk2(b[0], b[1]); w.w = pk2(b[2], b[3]); return w; }
; DI float siluf_(float x) { return x * __builtin_amdgcn_rcpf(1.f + __expf(-x)); }
;     DI void operator()(AccRef acc, const Unit& u, int wr, int wc, int fr, int fq) const {
;     ...
;         if (pn < 8) {
;             bf16_t* base; int ld, c0;
;             if (pn < 6) { base = QKV; ld = 1536; c0 = pn * 256; } else { base = Z; ld = 512; c0 = (pn - 6) * 256; }
; #pragma unroll
;             for (int ai = 0; ai < 2; ++ai)
; #pragma unroll
;                 for (int m = 0; m < 4; ++m) { int row_ = row0 + ai * 128 + m * 16; asm volatile("" : "+v"(row_) :: "memory"); bf16_t* rp = base + (size_t)row_ * ld + c0 + cl;
; #pragma unroll
;                     for (int bj = 0; bj < 2; ++bj) { f32x4 a = acc[ai][bj][m][0], b = acc[ai][bj][m][1];
;                         if (pn >= 6) {
; #pragma unroll
;                             for (int i = 0; i < 4; ++i) { a[i] = siluf_(a[i]); b[i] = siluf_(b[i]); } }
;                         *(u32x4*)(rp + bj * 128) = pack8(a, b); } }
.LBB0_521:
	v_cvt_pk_bf16_f32 v38, v38, v39
	v_cvt_pk_bf16_f32 v39, v40, v41
	v_cvt_pk_bf16_f32 v40, v34, v35
	v_cvt_pk_bf16_f32 v41, v36, v37
	global_store_dwordx4 v[50:51], v[38:41], off offset:256
	v_add_u32_e32 v0, 0xa0, v164
	s_and_b64 vcc, exec, s[44:45]
	s_cbranch_vccnz .LBB0_523
	v_mul_f32_e32 v35, 0xbfb8aa3b, v26
	v_exp_f32_e32 v35, v35
	v_mul_f32_e32 v34, 0xbfb8aa3b, v30
	v_exp_f32_e32 v34, v34
	v_mul_f32_e32 v39, 0xbfb8aa3b, v28
	v_add_f32_e32 v35, 1.0, v35
	v_rcp_f32_e32 v36, v35
	v_mul_f32_e32 v35, 0xbfb8aa3b, v31
	v_exp_f32_e32 v35, v35
	v_add_f32_e32 v34, 1.0, v34
	v_exp_f32_e32 v39, v39
	v_rcp_f32_e32 v34, v34
	v_add_f32_e32 v35, 1.0, v35
	v_rcp_f32_e32 v35, v35
	v_add_f32_e32 v39, 1.0, v39
	v_mul_f32_e32 v37, 0xbfb8aa3b, v27
	v_mul_f32_e32 v38, 0xbfb8aa3b, v32
	v_rcp_f32_e32 v40, v39
	v_mul_f32_e32 v39, 0xbfb8aa3b, v33
	v_pk_mul_f32 v[30:31], v[30:31], v[34:35]
	v_mul_f32_e32 v34, 0xbfb8aa3b, v29
	v_exp_f32_e32 v37, v37
	v_exp_f32_e32 v38, v38
	v_exp_f32_e32 v39, v39
	v_exp_f32_e32 v34, v34
	v_add_f32_e32 v37, 1.0, v37
	v_add_f32_e32 v38, 1.0, v38
	v_add_f32_e32 v39, 1.0, v39
	v_add_f32_e32 v34, 1.0, v34
	v_rcp_f32_e32 v37, v37
	v_rcp_f32_e32 v38, v38
	v_rcp_f32_e32 v39, v39
	v_rcp_f32_e32 v41, v34
	v_pk_mul_f32 v[26:27], v[26:27], v[36:37]
	v_pk_mul_f32 v[32:33], v[32:33], v[38:39]
	v_pk_mul_f32 v[28:29], v[28:29], v[40:41]
.LBB0_523:
	v_mad_i64_i32 v[34:35], s[14:15], s58, v0, 0
	v_lshl_add_u64 v[34:35], v[34:35], 1, v[134:135]
	v_cvt_pk_bf16_f32 v30, v30, v31
	v_cvt_pk_bf16_f32 v31, v32, v33
	v_cvt_pk_bf16_f32 v32, v26, v27
	v_cvt_pk_bf16_f32 v33, v28, v29
	s_and_b64 vcc, exec, s[44:45]
	global_store_dwordx4 v[34:35], v[30:33], off
	s_cbranch_vccnz .LBB0_525
	v_mul_f32_e32 v0, 0xbfb8aa3b, v22
	v_exp_f32_e32 v0, v0
	s_nop 0
	v_add_f32_e32 v0, 1.0, v0
	v_rcp_f32_e32 v26, v0
	v_mul_f32_e32 v0, 0xbfb8aa3b, v18
	v_exp_f32_e32 v0, v0
	s_nop 0
	v_add_f32_e32 v0, 1.0, v0
	v_rcp_f32_e32 v28, v0
	v_mul_f32_e32 v0, 0xbfb8aa3b, v23
	v_exp_f32_e32 v0, v0
	s_nop 0
	v_add_f32_e32 v0, 1.0, v0
	v_rcp_f32_e32 v27, v0
	v_mul_f32_e32 v0, 0xbfb8aa3b, v19
	v_exp_f32_e32 v0, v0
	v_pk_mul_f32 v[22:23], v[22:23], v[26:27]
	v_add_f32_e32 v0, 1.0, v0
	v_rcp_f32_e32 v29, v0
	v_mul_f32_e32 v0, 0xbfb8aa3b, v24
	v_exp_f32_e32 v0, v0
	v_pk_mul_f32 v[18:19], v[18:19], v[28:29]
	v_add_f32_e32 v0, 1.0, v0
	v_rcp_f32_e32 v30, v0
	v_mul_f32_e32 v0, 0xbfb8aa3b, v20
	v_exp_f32_e32 v0, v0
	s_nop 0
	v_add_f32_e32 v0, 1.0, v0
	v_rcp_f32_e32 v32, v0
	v_mul_f32_e32 v0, 0xbfb8aa3b, v25
	v_exp_f32_e32 v0, v0
	s_nop 0
	v_add_f32_e32 v0, 1.0, v0
	v_rcp_f32_e32 v31, v0
	v_mul_f32_e32 v0, 0xbfb8aa3b, v21
	v_exp_f32_e32 v0, v0
	v_pk_mul_f32 v[24:25], v[24:25], v[30:31]
	v_add_f32_e32 v0, 1.0, v0
	v_rcp_f32_e32 v33, v0
	s_nop 0
	v_pk_mul_f32 v[20:21], v[20:21], v[32:33]
.LBB0_525:
	v_cvt_pk_bf16_f32 v22, v22, v23
	v_cvt_pk_bf16_f32 v23, v24, v25
	v_cvt_pk_bf16_f32 v24, v18, v19
	v_cvt_pk_bf16_f32 v25, v20, v21
	global_store_dwordx4 v[34:35], v[22:25], off offset:256
	v_add_u32_e32 v0, 0xb0, v164
	s_and_b64 vcc, exec, s[44:45]
	s_cbranch_vccnz .LBB0_527
	v_mul_f32_e32 v19, 0xbfb8aa3b, v10
	v_exp_f32_e32 v19, v19
	v_mul_f32_e32 v18, 0xbfb8aa3b, v14
	v_exp_f32_e32 v18, v18
	v_mul_f32_e32 v23, 0xbfb8aa3b, v12
	v_add_f32_e32 v19, 1.0, v19
	v_rcp_f32_e32 v20, v19
	v_mul_f32_e32 v19, 0xbfb8aa3b, v15
	v_exp_f32_e32 v19, v19
	v_add_f32_e32 v18, 1.0, v18
	v_exp_f32_e32 v23, v23
	v_rcp_f32_e32 v18, v18
	v_add_f32_e32 v19, 1.0, v19
	v_rcp_f32_e32 v19, v19
	v_add_f32_e32 v23, 1.0, v23
	v_mul_f32_e32 v21, 0xbfb8aa3b, v11
	v_mul_f32_e32 v22, 0xbfb8aa3b, v16
	v_rcp_f32_e32 v24, v23
	v_mul_f32_e32 v23, 0xbfb8aa3b, v17
	v_pk_mul_f32 v[14:15], v[14:15], v[18:19]
	v_mul_f32_e32 v18, 0xbfb8aa3b, v13
	v_exp_f32_e32 v21, v21
	v_exp_f32_e32 v22, v22
	v_exp_f32_e32 v23, v23
	v_exp_f32_e32 v18, v18
	v_add_f32_e32 v21, 1.0, v21
	v_add_f32_e32 v22, 1.0, v22
	v_add_f32_e32 v23, 1.0, v23
	v_add_f32_e32 v18, 1.0, v18
	v_rcp_f32_e32 v21, v21
	v_rcp_f32_e32 v22, v22
	v_rcp_f32_e32 v23, v23
	v_rcp_f32_e32 v25, v18
	v_pk_mul_f32 v[10:11], v[10:11], v[20:21]
	v_pk_mul_f32 v[16:17], v[16:17], v[22:23]
	v_pk_mul_f32 v[12:13], v[12:13], v[24:25]
.LBB0_527:
	v_mad_i64_i32 v[18:19], s[14:15], s58, v0, 0
	v_lshl_add_u64 v[18:19], v[18:19], 1, v[134:135]
	v_cvt_pk_bf16_f32 v14, v14, v15
	v_cvt_pk_bf16_f32 v15, v16, v17
	v_cvt_pk_bf16_f32 v16, v10, v11
	v_cvt_pk_bf16_f32 v17, v12, v13
	s_and_b64 vcc, exec, s[44:45]
	global_store_dwordx4 v[18:19], v[14:17], off
	s_cbranch_vccnz .LBB0_529
	v_mul_f32_e32 v0, 0xbfb8aa3b, v6
	v_exp_f32_e32 v0, v0
	s_nop 0
	v_add_f32_e32 v0, 1.0, v0
	v_rcp_f32_e32 v10, v0
	v_mul_f32_e32 v0, 0xbfb8aa3b, v2
	v_exp_f32_e32 v0, v0
	s_nop 0
	v_add_f32_e32 v0, 1.0, v0
	v_rcp_f32_e32 v12, v0
	v_mul_f32_e32 v0, 0xbfb8aa3b, v7
	v_exp_f32_e32 v0, v0
	s_nop 0
	v_add_f32_e32 v0, 1.0, v0
	v_rcp_f32_e32 v11, v0
	v_mul_f32_e32 v0, 0xbfb8aa3b, v3
	v_exp_f32_e32 v0, v0
	v_pk_mul_f32 v[6:7], v[6:7], v[10:11]
	v_add_f32_e32 v0, 1.0, v0
	v_rcp_f32_e32 v13, v0
	v_mul_f32_e32 v0, 0xbfb8aa3b, v8
	v_exp_f32_e32 v0, v0
	v_pk_mul_f32 v[2:3], v[2:3], v[12:13]
	v_add_f32_e32 v0, 1.0, v0
	v_rcp_f32_e32 v14, v0
	v_mul_f32_e32 v0, 0xbfb8aa3b, v4
	v_exp_f32_e32 v0, v0
	s_nop 0
	v_add_f32_e32 v0, 1.0, v0
	v_rcp_f32_e32 v16, v0
	v_mul_f32_e32 v0, 0xbfb8aa3b, v9
	v_exp_f32_e32 v0, v0
	s_nop 0
	v_add_f32_e32 v0, 1.0, v0
	v_rcp_f32_e32 v15, v0
	v_mul_f32_e32 v0, 0xbfb8aa3b, v5
	v_exp_f32_e32 v0, v0
	v_pk_mul_f32 v[8:9], v[8:9], v[14:15]
	v_add_f32_e32 v0, 1.0, v0
	v_rcp_f32_e32 v17, v0
	s_nop 0
	v_pk_mul_f32 v[4:5], v[4:5], v[16:17]
.LBB0_529:
	v_cvt_pk_bf16_f32 v6, v6, v7
	v_cvt_pk_bf16_f32 v7, v8, v9
	v_cvt_pk_bf16_f32 v8, v2, v3
	v_cvt_pk_bf16_f32 v9, v4, v5
	global_store_dwordx4 v[18:19], v[6:9], off offset:256
	s_and_b64 vcc, exec, s[42:43]
	s_mov_b64 s[14:15], -1
	s_cbranch_vccnz .LBB0_416

; DI u32x4 pack8(f32x4 a, f32x4 b) { u32x4 w; w.x = pk2(a[0], a[1]); w.y = pk2(a[2], a[3]); w.z = pk2(b[0], b[1]); w.w = pk2(b[2], b[3]); return w; }
;     DI void operator()(AccRef acc, const Unit& u, int wr, int wc, int fr, int fq) const {
;     ...
;                 for (int m = 0; m < 4; ++m) { int row = row0 + ai * 128 + m * 16; asm volatile("" : "+v"(row) :: "memory");
;                     { const f32x4 a = acc[ai][0][m][0], b = acc[ai][0][m][1]; *(u32x4*)(CQ + (size_t)row * 384 + 256 + cl) = pack8(a, b);
;                       float ss = (a[0] * a[0] + a[1] * a[1]) + (a[2] * a[2] + a[3] * a[3]) + (b[0] * b[0] + b[1] * b[1]) + (b[2] * b[2] + b[3] * b[3]);
;                       ss += __shfl_xor(ss, 16); ss += __shfl_xor(ss, 32);
;                       if (fq == 0) unsafeAtomicAdd(SSQ + (size_t)row * 2, ss); }
;                     if (wc < 2) {
;                         const int i0 = 16 * wc + 4 * fq; const f32x4 cs = *(const f32x4*)(COS + (size_t)row * 32 + i0), sn = *(const f32x4*)(SIN + (size_t)row * 32 + i0);
;                         const f32x4 a = acc[ai][1][m][0], b = acc[ai][1][m][1]; f32x4 oa, ob;
;                         oa[0] = a[0] * cs[0] - a[1] * sn[0]; oa[1] = a[1] * cs[0] + a[0] * sn[0]; oa[2] = a[2] * cs[1] - a[3] * sn[1]; oa[3] = a[3] * cs[1] + a[2] * sn[1];
;                         ob[0] = b[0] * cs[2] - b[1] * sn[2]; ob[1] = b[1] * cs[2] + b[0] * sn[2]; ob[2] = b[2] * cs[3] - b[3] * sn[3]; ob[3] = b[3] * cs[3] + b[2] * sn[3];
;                         *(u32x4*)(KR + (size_t)row * 64 + cl) = pack8(oa, ob);
;                     } else if (wc == 2 && fq == 0) {
;                         *(f32x4*)(AB + (size_t)row * 8) = acc[ai][1][m][0]; *(f32x4*)(AB + (size_t)row * 8 + 4) = acc[ai][1][m][1];
;                     }
.LBB0_532:
	s_waitcnt lgkmcnt(0)
	v_add_f32_e32 v153, v153, v172
	v_lshl_add_u64 v[172:173], v[160:161], 3, s[58:59]
	s_waitcnt vmcnt(0)
	global_atomic_add_f32 v[172:173], v153, off
	s_or_b64 exec, exec, s[72:73]
	s_and_b64 vcc, exec, s[44:45]
	s_mov_b64 s[72:73], -1
	s_cbranch_vccnz .LBB0_455
.LBB0_533:
	s_and_saveexec_b64 s[72:73], s[50:51]
	s_cbranch_execz .LBB0_535
	s_waitcnt lgkmcnt(0)
	v_lshlrev_b64 v[172:173], 5, v[160:161]
	v_lshl_add_u64 v[172:173], s[14:15], 0, v[172:173]
	global_store_dwordx4 v[172:173], v[86:89], off
	global_store_dwordx4 v[172:173], v[82:85], off offset:16

;     DI void operator()(AccRef acc, const Unit& u, int wr, int wc, int fr, int fq) const {
;     ...
;                     } else if (wc == 2 && fq == 0) {
;                         *(f32x4*)(AB + (size_t)row * 8) = acc[ai][1][m][0]; *(f32x4*)(AB + (size_t)row * 8 + 4) = acc[ai][1][m][1];
;                     }
.LBB0_537:
	s_and_saveexec_b64 s[72:73], s[50:51]
	s_cbranch_execz .LBB0_539
	s_waitcnt lgkmcnt(0)
	v_lshlrev_b64 v[172:173], 5, v[160:161]
	v_lshl_add_u64 v[172:173], s[14:15], 0, v[172:173]
	global_store_dwordx4 v[172:173], v[70:73], off
	global_store_dwordx4 v[172:173], v[66:69], off offset:16

;     DI void operator()(AccRef acc, const Unit& u, int wr, int wc, int fr, int fq) const {
;     ...
;                     } else if (wc == 2 && fq == 0) {
;                         *(f32x4*)(AB + (size_t)row * 8) = acc[ai][1][m][0]; *(f32x4*)(AB + (size_t)row * 8 + 4) = acc[ai][1][m][1];
;                     }
.LBB0_541:
	s_and_saveexec_b64 s[72:73], s[50:51]
	s_cbranch_execz .LBB0_543
	s_waitcnt lgkmcnt(0)
	v_lshlrev_b64 v[172:173], 5, v[160:161]
	v_lshl_add_u64 v[172:173], s[14:15], 0, v[172:173]
	global_store_dwordx4 v[172:173], v[54:57], off
	global_store_dwordx4 v[172:173], v[50:53], off offset:16

;     DI void operator()(AccRef acc, const Unit& u, int wr, int wc, int fr, int fq) const {
;     ...
;                     } else if (wc == 2 && fq == 0) {
;                         *(f32x4*)(AB + (size_t)row * 8) = acc[ai][1][m][0]; *(f32x4*)(AB + (size_t)row * 8 + 4) = acc[ai][1][m][1];
;                     }
.LBB0_545:
	s_and_saveexec_b64 s[72:73], s[50:51]
	s_cbranch_execz .LBB0_547
	s_waitcnt lgkmcnt(0)
	v_lshlrev_b64 v[172:173], 5, v[160:161]
	v_lshl_add_u64 v[172:173], s[14:15], 0, v[172:173]
	global_store_dwordx4 v[172:173], v[38:41], off
	global_store_dwordx4 v[172:173], v[34:37], off offset:16

;     DI void operator()(AccRef acc, const Unit& u, int wr, int wc, int fr, int fq) const {
;     ...
;                     } else if (wc == 2 && fq == 0) {
;                         *(f32x4*)(AB + (size_t)row * 8) = acc[ai][1][m][0]; *(f32x4*)(AB + (size_t)row * 8 + 4) = acc[ai][1][m][1];
;                     }
.LBB0_549:
	s_and_saveexec_b64 s[72:73], s[50:51]
	s_cbranch_execz .LBB0_551
	s_waitcnt lgkmcnt(0)
	v_lshlrev_b64 v[172:173], 5, v[160:161]
	v_lshl_add_u64 v[172:173], s[14:15], 0, v[172:173]
	global_store_dwordx4 v[172:173], v[22:25], off
	global_store_dwordx4 v[172:173], v[18:21], off offset:16

; DI u32x4 pack8(f32x4 a, f32x4 b) { u32x4 w; w.x = pk2(a[0], a[1]); w.y = pk2(a[2], a[3]); w.z = pk2(b[0], b[1]); w.w = pk2(b[2], b[3]); return w; }
;     DI void operator()(AccRef acc, const Unit& u, int wr, int wc, int fr, int fq) const {
;     ...
;                 for (int m = 0; m < 4; ++m) { int row = row0 + ai * 128 + m * 16; asm volatile("" : "+v"(row) :: "memory");
;                     { const f32x4 a = acc[ai][0][m][0], b = acc[ai][0][m][1]; *(u32x4*)(CQ + (size_t)row * 384 + 256 + cl) = pack8(a, b);
;                       float ss = (a[0] * a[0] + a[1] * a[1]) + (a[2] * a[2] + a[3] * a[3]) + (b[0] * b[0] + b[1] * b[1]) + (b[2] * b[2] + b[3] * b[3]);
;                       ss += __shfl_xor(ss, 16); ss += __shfl_xor(ss, 32);
;                       if (fq == 0) unsafeAtomicAdd(SSQ + (size_t)row * 2, ss); }
;                     if (wc < 2) {
;                         const int i0 = 16 * wc + 4 * fq; const f32x4 cs = *(const f32x4*)(COS + (size_t)row * 32 + i0), sn = *(const f32x4*)(SIN + (size_t)row * 32 + i0);
;                         const f32x4 a = acc[ai][1][m][0], b = acc[ai][1][m][1]; f32x4 oa, ob;
;                         oa[0] = a[0] * cs[0] - a[1] * sn[0]; oa[1] = a[1] * cs[0] + a[0] * sn[0]; oa[2] = a[2] * cs[1] - a[3] * sn[1]; oa[3] = a[3] * cs[1] + a[2] * sn[1];
;                         ob[0] = b[0] * cs[2] - b[1] * sn[2]; ob[1] = b[1] * cs[2] + b[0] * sn[2]; ob[2] = b[2] * cs[3] - b[3] * sn[3]; ob[3] = b[3] * cs[3] + b[2] * sn[3];
;                         *(u32x4*)(KR + (size_t)row * 64 + cl) = pack8(oa, ob);
;                     } else if (wc == 2 && fq == 0) {
;                         *(f32x4*)(AB + (size_t)row * 8) = acc[ai][1][m][0]; *(f32x4*)(AB + (size_t)row * 8 + 4) = acc[ai][1][m][1];
;                     }
.LBB0_552:
	s_waitcnt lgkmcnt(0)
	v_add_f32_e32 v0, v153, v170
	v_lshl_add_u64 v[170:171], v[160:161], 3, s[58:59]
	s_waitcnt vmcnt(0)
	global_atomic_add_f32 v[170:171], v0, off
	s_or_b64 exec, exec, s[72:73]
	s_and_b64 vcc, exec, s[44:45]
	s_mov_b64 s[44:45], -1
	s_cbranch_vccnz .LBB0_475
.LBB0_553:
	s_and_saveexec_b64 s[44:45], s[50:51]
	s_cbranch_execz .LBB0_555
	s_waitcnt lgkmcnt(0)
	v_lshlrev_b64 v[170:171], 5, v[160:161]
	v_lshl_add_u64 v[170:171], s[14:15], 0, v[170:171]
	global_store_dwordx4 v[170:171], v[6:9], off
	global_store_dwordx4 v[170:171], v[2:5], off offset:16

; DI unsigned pk2(float lo, float hi) { f32x2 v = {lo, hi}; bf16x2_t b = __builtin_convertvector(v, bf16x2_t); return __builtin_bit_cast(unsigned, b); }
; DI float lo_bf(unsigned u) { return __uint_as_float(u << 16); }
; DI float hi_bf(unsigned u) { return __uint_as_float(u & 0xffff0000u); }
; DI float sigmoidf_(float x) { return __builtin_amdgcn_rcpf(1.f + __expf(-x)); }
;     DI void operator()(AccRef acc, const Unit& u, int wr, int wc, int fr, int fq) const {
;     ...
;         for (int it = 0; it < 8; ++it) { const int ai = it >> 2, m = it & 3, cur = it & 1;
;             if (it + 1 < 8) { int rn_ = row0 + ((it + 1) >> 2) * 128 + ((it + 1) & 3) * 16; asm volatile("" : "+v"(rn_) :: "memory"); const size_t on = (size_t)rn_ * DM + c0; sb[cur ^ 1] = *(const f32x2*)(ST + (size_t)rn_ * 2);
; #pragma unroll
;                 for (int bj = 0; bj < 2; ++bj) { eb[cur ^ 1][bj] = *(const u32x4*)(E + on + bj * 128);
; #pragma unroll
;                     for (int n = 0; n < 2; ++n) yb[cur ^ 1][bj][n] = *(const f32x4*)(Y + on + bj * 128 + 4 * n); } }
;             int row = row0 + ai * 128 + m * 16; asm volatile("" : "+v"(row)); const size_t off = (size_t)row * DM + c0;
;             const float mean = sb[cur].x * (1.f / DM); const float rstd = __builtin_amdgcn_rsqf(fmaxf(sb[cur].y * (1.f / DM) - mean * mean, 0.f) + LN_EPS);
; #pragma unroll
;             for (int bj = 0; bj < 2; ++bj)
; #pragma unroll
;                 for (int n = 0; n < 2; ++n) { const int cc = c0 + bj * 128 + 4 * n; const f32x4 gv = *(const f32x4*)(G + cc), bv = *(const f32x4*)(Bv + cc), gw = *(const f32x4*)(GW + cc), bw = *(const f32x4*)(GW + 1024 + cc);
;                     const unsigned e0 = eb[cur][bj][2 * n], e1 = eb[cur][bj][2 * n + 1]; const f32x4 ev = {lo_bf(e0), hi_bf(e0), lo_bf(e1), hi_bf(e1)};
;                     const f32x4 x2 = (yb[cur][bj][n] - mean) * rstd * gv + bv; const f32x4 a = (acc[ai][bj][m][n] - gw * mean) * rstd + bw; f32x4 o;
; #pragma unroll
;                     for (int i = 0; i < 4; ++i) o[i] = x2[i] + sigmoidf_(a[i]) * ev[i];
;                     *(f32x4*)(OUT + off + bj * 128 + 4 * n) = o; u32x2 w2; w2.x = pk2(o[0], o[1]); w2.y = pk2(o[2], o[3]);
;                     *(u32x2*)(XB + off + bj * 128 + 4 * n) = w2; } }
.LBB0_582:
	s_mov_b64 s[6:7], s[0:1]
	s_add_u32 s78, s6, 0xe600000
	s_addc_u32 s79, s7, 0
	v_lshl_add_u32 v240, s77, 8, v236
	s_add_u32 s4, s6, 0x3580000
	v_mov_b32_e32 v114, v240
	s_addc_u32 s5, s7, 0
	v_lshl_or_b32 v210, s76, 8, v238
	s_add_u32 vcc_lo, s6, 0x3600000
	v_ashrrev_i32_e32 v115, 31, v114
	v_lshlrev_b64 v[116:117], 10, v[114:115]
	v_ashrrev_i32_e32 v211, 31, v210
	s_addc_u32 vcc_hi, s7, 0
	v_lshl_add_u64 v[116:117], v[116:117], 0, v[210:211]
	v_lshl_add_u64 v[118:119], v[116:117], 1, vcc
	v_lshl_add_u64 v[114:115], v[114:115], 3, s[4:5]
	v_lshl_add_u64 v[116:117], v[116:117], 2, s[78:79]
	global_load_dwordx4 v[170:173], v[118:119], off
	global_load_dwordx4 v[178:181], v[116:117], off
	global_load_dwordx4 v[174:177], v[116:117], off offset:16
	global_load_dwordx4 v[154:157], v[118:119], off offset:256
	global_load_dwordx4 v[166:169], v[116:117], off offset:512
	global_load_dwordx4 v[158:161], v[116:117], off offset:528
	global_load_dwordx2 v[192:193], v[114:115], off
	v_or_b32_e32 v218, 16, v240
	v_mov_b32_e32 v114, v218
	v_mov_b32_e32 v198, v240
	v_ashrrev_i32_e32 v115, 31, v114
	v_lshlrev_b64 v[116:117], 10, v[114:115]
	v_lshl_add_u64 v[116:117], v[116:117], 0, v[210:211]
	v_lshl_add_u64 v[114:115], v[114:115], 3, s[4:5]
	global_load_dwordx2 v[220:221], v[114:115], off
	v_lshl_add_u64 v[114:115], v[116:117], 1, vcc
	v_lshl_add_u64 v[118:119], v[116:117], 2, s[78:79]
	global_load_dwordx4 v[142:145], v[114:115], off
	global_load_dwordx4 v[150:153], v[118:119], off
	global_load_dwordx4 v[138:141], v[118:119], off offset:16
	s_nop 0
	global_load_dwordx4 v[114:117], v[114:115], off offset:256
	s_nop 0
	global_load_dwordx4 v[122:125], v[118:119], off offset:512
	s_nop 0
	global_load_dwordx4 v[118:121], v[118:119], off offset:528
	v_lshlrev_b64 v[202:203], 2, v[210:211]
	v_ashrrev_i32_e32 v199, 31, v198
	v_lshlrev_b64 v[198:199], 10, v[198:199]
	v_lshl_add_u64 v[212:213], s[54:55], 0, v[202:203]
	v_lshl_add_u64 v[216:217], v[198:199], 0, v[210:211]
	global_load_dwordx4 v[198:201], v[212:213], off
	v_lshl_add_u64 v[214:215], s[72:73], 0, v[202:203]
	v_lshl_add_u64 v[208:209], s[52:53], 0, v[202:203]
	global_load_dwordx4 v[246:249], v[208:209], off
	s_add_u32 s76, s6, 0x1b600000
	s_addc_u32 s77, s7, 0
	v_lshl_add_u64 v[228:229], v[216:217], 2, s[18:19]
	v_lshl_add_u64 v[222:223], v[216:217], 1, s[76:77]
	s_waitcnt vmcnt(0) lgkmcnt(0)
	v_pk_mul_f32 v[224:225], v[192:193], s[36:37] op_sel_hi:[1,0]
	s_nop 0
	v_fma_f32 v192, -v224, v224, v225
	v_max_f32_e32 v192, 0, v192
	v_add_f32_e32 v192, 0x3727c5ac, v192
	v_rsq_f32_e32 v226, v192
	v_lshl_add_u64 v[192:193], s[50:51], 0, v[202:203]
	global_load_dwordx4 v[202:205], v[214:215], off
	global_load_dwordx4 v[242:245], v[192:193], off
	v_pk_add_f32 v[178:179], v[178:179], v[224:225] op_sel_hi:[1,0] neg_lo:[0,1] neg_hi:[0,1]
	v_pk_add_f32 v[174:175], v[174:175], v[224:225] op_sel_hi:[1,0] neg_lo:[0,1] neg_hi:[0,1]
	v_pk_mul_f32 v[178:179], v[178:179], v[226:227] op_sel_hi:[1,0]
	v_pk_mul_f32 v[174:175], v[174:175], v[226:227] op_sel_hi:[1,0]
	v_pk_add_f32 v[166:167], v[166:167], v[224:225] op_sel_hi:[1,0] neg_lo:[0,1] neg_hi:[0,1]
	v_pk_add_f32 v[158:159], v[158:159], v[224:225] op_sel_hi:[1,0] neg_lo:[0,1] neg_hi:[0,1]
	v_pk_mul_f32 v[166:167], v[166:167], v[226:227] op_sel_hi:[1,0]
	v_pk_mul_f32 v[158:159], v[158:159], v[226:227] op_sel_hi:[1,0]
	v_fma_f32 v162, -v224, v198, v162
	v_fma_f32 v163, -v224, v199, v163
	v_fma_f32 v164, -v224, v200, v164
	v_fma_f32 v165, -v224, v201, v165
	v_lshlrev_b32_e32 v198, 16, v170
	v_and_b32_e32 v199, 0xffff0000, v170
	v_lshlrev_b32_e32 v170, 16, v171
	v_and_b32_e32 v171, 0xffff0000, v171
	s_waitcnt vmcnt(1)
	v_fma_f32 v162, v226, v162, v202
	v_fma_f32 v163, v226, v163, v203
	v_mul_f32_e32 v162, 0xbfb8aa3b, v162
	v_mul_f32_e32 v163, 0xbfb8aa3b, v163
	v_exp_f32_e32 v162, v162
	v_exp_f32_e32 v163, v163
	v_fma_f32 v164, v226, v164, v204
	v_fmac_f32_e32 v205, v226, v165
	v_mul_f32_e32 v164, 0xbfb8aa3b, v164
	v_mul_f32_e32 v165, 0xbfb8aa3b, v205
	v_exp_f32_e32 v164, v164
	v_exp_f32_e32 v165, v165
	v_add_f32_e32 v162, 1.0, v162
	v_add_f32_e32 v163, 1.0, v163
	v_rcp_f32_e32 v162, v162
	v_rcp_f32_e32 v163, v163
	v_add_f32_e32 v164, 1.0, v164
	v_add_f32_e32 v165, 1.0, v165
	s_waitcnt vmcnt(0)
	v_pk_fma_f32 v[178:179], v[178:179], v[242:243], v[246:247]
	v_rcp_f32_e32 v164, v164
	v_rcp_f32_e32 v165, v165
	v_pk_fma_f32 v[162:163], v[162:163], v[198:199], v[178:179]
	v_pk_add_f32 v[178:179], v[180:181], v[224:225] op_sel_hi:[1,0] neg_lo:[0,1] neg_hi:[0,1]
	s_nop 0
	v_pk_mul_f32 v[178:179], v[178:179], v[226:227] op_sel_hi:[1,0]
	s_nop 0
	v_pk_fma_f32 v[178:179], v[178:179], v[244:245], v[248:249]
	s_nop 0
	v_pk_fma_f32 v[164:165], v[164:165], v[170:171], v[178:179]
	v_or_b32_e32 v170, 4, v210
	v_ashrrev_i32_e32 v171, 31, v170
	global_store_dwordx4 v[228:229], v[162:165], off
	v_lshlrev_b64 v[202:203], 2, v[170:171]
	v_lshl_add_u64 v[170:171], s[54:55], 0, v[202:203]
	v_cvt_pk_bf16_f32 v162, v162, v163
	v_cvt_pk_bf16_f32 v163, v164, v165
	global_store_dwordx2 v[222:223], v[162:163], off
	global_load_dwordx4 v[162:165], v[192:193], off offset:16
	s_nop 0
	global_load_dwordx4 v[178:181], v[208:209], off offset:16
	global_load_dwordx4 v[198:201], v[170:171], off
	v_lshl_add_u64 v[216:217], s[72:73], 0, v[202:203]
	global_load_dwordx4 v[202:205], v[216:217], off
	s_waitcnt vmcnt(0)
; DI unsigned pk2(float lo, float hi) { f32x2 v = {lo, hi}; bf16x2_t b = __builtin_convertvector(v, bf16x2_t); return __builtin_bit_cast(unsigned, b); }
; DI float lo_bf(unsigned u) { return __uint_as_float(u << 16); }
; DI float hi_bf(unsigned u) { return __uint_as_float(u & 0xffff0000u); }
; DI float sigmoidf_(float x) { return __builtin_amdgcn_rcpf(1.f + __expf(-x)); }
;     DI void operator()(AccRef acc, const Unit& u, int wr, int wc, int fr, int fq) const {
;     ...
;             int row = row0 + ai * 128 + m * 16; asm volatile("" : "+v"(row)); const size_t off = (size_t)row * DM + c0;
;             const float mean = sb[cur].x * (1.f / DM); const float rstd = __builtin_amdgcn_rsqf(fmaxf(sb[cur].y * (1.f / DM) - mean * mean, 0.f) + LN_EPS);
; #pragma unroll
;             for (int bj = 0; bj < 2; ++bj)
; #pragma unroll
;                 for (int n = 0; n < 2; ++n) { const int cc = c0 + bj * 128 + 4 * n; const f32x4 gv = *(const f32x4*)(G + cc), bv = *(const f32x4*)(Bv + cc), gw = *(const f32x4*)(GW + cc), bw = *(const f32x4*)(GW + 1024 + cc);
;                     const unsigned e0 = eb[cur][bj][2 * n], e1 = eb[cur][bj][2 * n + 1]; const f32x4 ev = {lo_bf(e0), hi_bf(e0), lo_bf(e1), hi_bf(e1)};
;                     const f32x4 x2 = (yb[cur][bj][n] - mean) * rstd * gv + bv; const f32x4 a = (acc[ai][bj][m][n] - gw * mean) * rstd + bw; f32x4 o;
; #pragma unroll
;                     for (int i = 0; i < 4; ++i) o[i] = x2[i] + sigmoidf_(a[i]) * ev[i];
;                     *(f32x4*)(OUT + off + bj * 128 + 4 * n) = o; u32x2 w2; w2.x = pk2(o[0], o[1]); w2.y = pk2(o[2], o[3]);
;                     *(u32x2*)(XB + off + bj * 128 + 4 * n) = w2; } }
	v_pk_fma_f32 v[162:163], v[174:175], v[162:163], v[178:179]
	v_fma_f32 v146, -v224, v198, v146
	v_fma_f32 v147, -v224, v199, v147
	v_fma_f32 v146, v226, v146, v202
	v_fma_f32 v147, v226, v147, v203
	v_mul_f32_e32 v146, 0xbfb8aa3b, v146
	v_mul_f32_e32 v147, 0xbfb8aa3b, v147
	v_exp_f32_e32 v146, v146
	v_exp_f32_e32 v147, v147
	v_fma_f32 v148, -v224, v200, v148
	v_fma_f32 v149, -v224, v201, v149
	v_fma_f32 v148, v226, v148, v204
	v_fmac_f32_e32 v205, v226, v149
	v_mul_f32_e32 v148, 0xbfb8aa3b, v148
	v_mul_f32_e32 v149, 0xbfb8aa3b, v205
	v_exp_f32_e32 v148, v148
	v_exp_f32_e32 v149, v149
	v_add_f32_e32 v146, 1.0, v146
	v_add_f32_e32 v147, 1.0, v147
	v_rcp_f32_e32 v146, v146
	v_rcp_f32_e32 v147, v147
	v_add_f32_e32 v148, 1.0, v148
	v_add_f32_e32 v149, 1.0, v149
	v_lshlrev_b32_e32 v198, 16, v172
	v_and_b32_e32 v199, 0xffff0000, v172
	v_rcp_f32_e32 v148, v148
	v_rcp_f32_e32 v149, v149
	v_pk_fma_f32 v[146:147], v[146:147], v[198:199], v[162:163]
	v_lshlrev_b32_e32 v162, 16, v173
	v_and_b32_e32 v163, 0xffff0000, v173
	v_pk_add_f32 v[172:173], v[176:177], v[224:225] op_sel_hi:[1,0] neg_lo:[0,1] neg_hi:[0,1]
	s_nop 0
	v_pk_mul_f32 v[172:173], v[172:173], v[226:227] op_sel_hi:[1,0]
	s_nop 0
	v_pk_fma_f32 v[164:165], v[172:173], v[164:165], v[180:181]
	v_or_b32_e32 v172, 0x80, v210
	v_pk_fma_f32 v[148:149], v[148:149], v[162:163], v[164:165]
	v_ashrrev_i32_e32 v173, 31, v172
	global_store_dwordx4 v[228:229], v[146:149], off offset:16
	v_lshlrev_b64 v[174:175], 2, v[172:173]
	v_lshl_add_u64 v[172:173], s[54:55], 0, v[174:175]
	v_cvt_pk_bf16_f32 v146, v146, v147
	v_cvt_pk_bf16_f32 v147, v148, v149
	global_store_dwordx2 v[222:223], v[146:147], off offset:8
	global_load_dwordx4 v[146:149], v[192:193], off offset:512
	s_nop 0
	global_load_dwordx4 v[162:165], v[208:209], off offset:512
	global_load_dwordx4 v[176:179], v[172:173], off
	v_lshl_add_u64 v[174:175], s[72:73], 0, v[174:175]
	global_load_dwordx4 v[198:201], v[174:175], off
	s_waitcnt vmcnt(0)
	v_pk_fma_f32 v[146:147], v[166:167], v[146:147], v[162:163]
	v_fma_f32 v134, -v224, v176, v134
	v_fma_f32 v135, -v224, v177, v135
	v_fma_f32 v134, v226, v134, v198
	v_fma_f32 v135, v226, v135, v199
	v_mul_f32_e32 v134, 0xbfb8aa3b, v134
	v_mul_f32_e32 v135, 0xbfb8aa3b, v135
	v_exp_f32_e32 v134, v134
	v_exp_f32_e32 v135, v135
	v_fma_f32 v136, -v224, v178, v136
	v_fma_f32 v137, -v224, v179, v137
	v_fma_f32 v136, v226, v136, v200
	v_fmac_f32_e32 v201, v226, v137
	v_mul_f32_e32 v136, 0xbfb8aa3b, v136
	v_mul_f32_e32 v137, 0xbfb8aa3b, v201
	v_exp_f32_e32 v136, v136
	v_exp_f32_e32 v137, v137
	v_add_f32_e32 v134, 1.0, v134
	v_add_f32_e32 v135, 1.0, v135
	v_rcp_f32_e32 v134, v134
	v_rcp_f32_e32 v135, v135
	v_add_f32_e32 v136, 1.0, v136
	v_add_f32_e32 v137, 1.0, v137
	v_lshlrev_b32_e32 v176, 16, v154
	v_and_b32_e32 v177, 0xffff0000, v154
	v_rcp_f32_e32 v136, v136
	v_rcp_f32_e32 v137, v137
	v_pk_fma_f32 v[134:135], v[134:135], v[176:177], v[146:147]
	v_lshlrev_b32_e32 v146, 16, v155
	v_and_b32_e32 v147, 0xffff0000, v155
	v_pk_add_f32 v[154:155], v[168:169], v[224:225] op_sel_hi:[1,0] neg_lo:[0,1] neg_hi:[0,1]
	s_nop 0
	v_pk_mul_f32 v[154:155], v[154:155], v[226:227] op_sel_hi:[1,0]
	s_nop 0
	v_pk_fma_f32 v[148:149], v[154:155], v[148:149], v[164:165]
	v_or_b32_e32 v154, 0x84, v210
	v_pk_fma_f32 v[136:137], v[136:137], v[146:147], v[148:149]
	v_ashrrev_i32_e32 v155, 31, v154
	global_store_dwordx4 v[228:229], v[134:137], off offset:512
	v_lshlrev_b64 v[154:155], 2, v[154:155]
	v_lshl_add_u64 v[166:167], s[54:55], 0, v[154:155]
	v_cvt_pk_bf16_f32 v134, v134, v135
	v_cvt_pk_bf16_f32 v135, v136, v137
	global_store_dwordx2 v[222:223], v[134:135], off offset:256
	global_load_dwordx4 v[134:137], v[192:193], off offset:528
	s_nop 0
	global_load_dwordx4 v[146:149], v[208:209], off offset:528
	global_load_dwordx4 v[162:165], v[166:167], off
	v_lshl_add_u64 v[168:169], s[72:73], 0, v[154:155]
	global_load_dwordx4 v[176:179], v[168:169], off
	v_lshlrev_b32_e32 v154, 16, v156
	v_and_b32_e32 v155, 0xffff0000, v156
	s_waitcnt vmcnt(0)
	v_pk_fma_f32 v[134:135], v[158:159], v[134:135], v[146:147]
	v_fma_f32 v126, -v224, v162, v126
	v_fma_f32 v127, -v224, v163, v127
	v_fma_f32 v126, v226, v126, v176
	v_fma_f32 v127, v226, v127, v177
	v_fma_f32 v128, -v224, v164, v128
	v_fma_f32 v129, -v224, v165, v129
	v_mul_f32_e32 v126, 0xbfb8aa3b, v126
	v_mul_f32_e32 v127, 0xbfb8aa3b, v127
	v_fma_f32 v128, v226, v128, v178
	v_fmac_f32_e32 v179, v226, v129
	v_exp_f32_e32 v126, v126
	v_exp_f32_e32 v127, v127
	v_mul_f32_e32 v128, 0xbfb8aa3b, v128
	v_mul_f32_e32 v129, 0xbfb8aa3b, v179
	v_exp_f32_e32 v128, v128
	v_exp_f32_e32 v129, v129
	v_add_f32_e32 v126, 1.0, v126
	v_add_f32_e32 v127, 1.0, v127
	v_rcp_f32_e32 v126, v126
	v_rcp_f32_e32 v127, v127
	v_add_f32_e32 v128, 1.0, v128
	v_add_f32_e32 v129, 1.0, v129
	v_rcp_f32_e32 v128, v128
	v_rcp_f32_e32 v129, v129
	v_pk_add_f32 v[146:147], v[160:161], v[224:225] op_sel_hi:[1,0] neg_lo:[0,1] neg_hi:[0,1]
	v_pk_fma_f32 v[126:127], v[126:127], v[154:155], v[134:135]
	v_pk_mul_f32 v[146:147], v[146:147], v[226:227] op_sel_hi:[1,0]
	v_lshlrev_b32_e32 v134, 16, v157
	v_and_b32_e32 v135, 0xffff0000, v157
	v_pk_fma_f32 v[136:137], v[146:147], v[136:137], v[148:149]
	v_or_b32_e32 v176, 32, v240
	v_pk_fma_f32 v[128:129], v[128:129], v[134:135], v[136:137]
	global_store_dwordx4 v[228:229], v[126:129], off offset:528
	v_lshlrev_b32_e32 v224, 16, v142
	v_and_b32_e32 v225, 0xffff0000, v142
	v_cvt_pk_bf16_f32 v126, v126, v127
	v_cvt_pk_bf16_f32 v127, v128, v129
	global_store_dwordx2 v[222:223], v[126:127], off offset:264
	v_mov_b32_e32 v126, v176
	v_lshlrev_b32_e32 v142, 16, v143
	v_ashrrev_i32_e32 v127, 31, v126
; DI unsigned pk2(float lo, float hi) { f32x2 v = {lo, hi}; bf16x2_t b = __builtin_convertvector(v, bf16x2_t); return __builtin_bit_cast(unsigned, b); }
; DI float lo_bf(unsigned u) { return __uint_as_float(u << 16); }
; DI float hi_bf(unsigned u) { return __uint_as_float(u & 0xffff0000u); }
; DI float sigmoidf_(float x) { return __builtin_amdgcn_rcpf(1.f + __expf(-x)); }
;     DI void operator()(AccRef acc, const Unit& u, int wr, int wc, int fr, int fq) const {
;     ...
;         for (int it = 0; it < 8; ++it) { const int ai = it >> 2, m = it & 3, cur = it & 1;
;             if (it + 1 < 8) { int rn_ = row0 + ((it + 1) >> 2) * 128 + ((it + 1) & 3) * 16; asm volatile("" : "+v"(rn_) :: "memory"); const size_t on = (size_t)rn_ * DM + c0; sb[cur ^ 1] = *(const f32x2*)(ST + (size_t)rn_ * 2);
; #pragma unroll
;                 for (int bj = 0; bj < 2; ++bj) { eb[cur ^ 1][bj] = *(const u32x4*)(E + on + bj * 128);
; #pragma unroll
;                     for (int n = 0; n < 2; ++n) yb[cur ^ 1][bj][n] = *(const f32x4*)(Y + on + bj * 128 + 4 * n); } }
;             int row = row0 + ai * 128 + m * 16; asm volatile("" : "+v"(row)); const size_t off = (size_t)row * DM + c0;
;             const float mean = sb[cur].x * (1.f / DM); const float rstd = __builtin_amdgcn_rsqf(fmaxf(sb[cur].y * (1.f / DM) - mean * mean, 0.f) + LN_EPS);
; #pragma unroll
;             for (int bj = 0; bj < 2; ++bj)
; #pragma unroll
;                 for (int n = 0; n < 2; ++n) { const int cc = c0 + bj * 128 + 4 * n; const f32x4 gv = *(const f32x4*)(G + cc), bv = *(const f32x4*)(Bv + cc), gw = *(const f32x4*)(GW + cc), bw = *(const f32x4*)(GW + 1024 + cc);
;                     const unsigned e0 = eb[cur][bj][2 * n], e1 = eb[cur][bj][2 * n + 1]; const f32x4 ev = {lo_bf(e0), hi_bf(e0), lo_bf(e1), hi_bf(e1)};
;                     const f32x4 x2 = (yb[cur][bj][n] - mean) * rstd * gv + bv; const f32x4 a = (acc[ai][bj][m][n] - gw * mean) * rstd + bw; f32x4 o;
; #pragma unroll
;                     for (int i = 0; i < 4; ++i) o[i] = x2[i] + sigmoidf_(a[i]) * ev[i];
;                     *(f32x4*)(OUT + off + bj * 128 + 4 * n) = o; u32x2 w2; w2.x = pk2(o[0], o[1]); w2.y = pk2(o[2], o[3]);
;                     *(u32x2*)(XB + off + bj * 128 + 4 * n) = w2; } }
	v_lshlrev_b64 v[128:129], 10, v[126:127]
	v_lshl_add_u64 v[128:129], v[128:129], 0, v[210:211]
	v_lshl_add_u64 v[126:127], v[126:127], 3, s[4:5]
	global_load_dwordx2 v[178:179], v[126:127], off
	v_lshl_add_u64 v[126:127], v[128:129], 1, vcc
	v_lshl_add_u64 v[134:135], v[128:129], 2, s[78:79]
	global_load_dwordx4 v[158:161], v[126:127], off
	global_load_dwordx4 v[162:165], v[134:135], off
	global_load_dwordx4 v[154:157], v[134:135], off offset:16
	s_nop 0
	global_load_dwordx4 v[126:129], v[126:127], off offset:256
	s_nop 0
	global_load_dwordx4 v[146:149], v[134:135], off offset:512
	s_nop 0
	global_load_dwordx4 v[134:137], v[134:135], off offset:528
	global_load_dwordx4 v[198:201], v[192:193], off
	global_load_dwordx4 v[202:205], v[208:209], off
	global_load_dwordx4 v[242:245], v[212:213], off
	global_load_dwordx4 v[246:249], v[214:215], off
	v_ashrrev_i32_e32 v219, 31, v218
	v_lshlrev_b64 v[180:181], 10, v[218:219]
	v_pk_mul_f32 v[218:219], v[220:221], s[36:37] op_sel_hi:[1,0]
	v_lshl_add_u64 v[222:223], v[180:181], 0, v[210:211]
	v_fma_f32 v177, -v218, v218, v219
	v_max_f32_e32 v177, 0, v177
	v_add_f32_e32 v177, 0x3727c5ac, v177
	v_rsq_f32_e32 v220, v177
	v_pk_add_f32 v[150:151], v[150:151], v[218:219] op_sel_hi:[1,0] neg_lo:[0,1] neg_hi:[0,1]
	v_and_b32_e32 v143, 0xffff0000, v143
	v_lshl_add_u64 v[180:181], v[222:223], 1, s[76:77]
	v_pk_mul_f32 v[150:151], v[150:151], v[220:221] op_sel_hi:[1,0]
	v_pk_add_f32 v[138:139], v[138:139], v[218:219] op_sel_hi:[1,0] neg_lo:[0,1] neg_hi:[0,1]
	v_pk_add_f32 v[122:123], v[122:123], v[218:219] op_sel_hi:[1,0] neg_lo:[0,1] neg_hi:[0,1]
	v_pk_mul_f32 v[138:139], v[138:139], v[220:221] op_sel_hi:[1,0]
	v_pk_mul_f32 v[122:123], v[220:221], v[122:123] op_sel_hi:[0,1]
	s_waitcnt vmcnt(0)
	v_pk_fma_f32 v[150:151], v[150:151], v[198:199], v[202:203]
	v_fma_f32 v110, -v218, v242, v110
	v_fma_f32 v111, -v218, v243, v111
	v_fma_f32 v110, v220, v110, v246
	v_fma_f32 v111, v220, v111, v247
	v_mul_f32_e32 v110, 0xbfb8aa3b, v110
	v_mul_f32_e32 v111, 0xbfb8aa3b, v111
	v_exp_f32_e32 v110, v110
	v_exp_f32_e32 v111, v111
	v_fma_f32 v112, -v218, v244, v112
	v_fma_f32 v113, -v218, v245, v113
	v_fma_f32 v112, v220, v112, v248
	v_fmac_f32_e32 v249, v220, v113
	v_mul_f32_e32 v112, 0xbfb8aa3b, v112
	v_mul_f32_e32 v113, 0xbfb8aa3b, v249
	v_exp_f32_e32 v112, v112
	v_exp_f32_e32 v113, v113
	v_add_f32_e32 v110, 1.0, v110
	v_add_f32_e32 v111, 1.0, v111
	v_rcp_f32_e32 v110, v110
	v_rcp_f32_e32 v111, v111
	v_add_f32_e32 v112, 1.0, v112
	v_add_f32_e32 v113, 1.0, v113
	v_rcp_f32_e32 v112, v112
	v_rcp_f32_e32 v113, v113
	v_pk_fma_f32 v[110:111], v[110:111], v[224:225], v[150:151]
	v_pk_add_f32 v[150:151], v[152:153], v[218:219] op_sel_hi:[1,0] neg_lo:[0,1] neg_hi:[0,1]
	s_nop 0
	v_pk_mul_f32 v[150:151], v[150:151], v[220:221] op_sel_hi:[1,0]
	s_nop 0
	v_pk_fma_f32 v[150:151], v[150:151], v[200:201], v[204:205]
	s_nop 0
	v_pk_fma_f32 v[112:113], v[112:113], v[142:143], v[150:151]
	v_lshl_add_u64 v[142:143], v[222:223], 2, s[18:19]
	global_store_dwordx4 v[142:143], v[110:113], off
	s_nop 1
	v_cvt_pk_bf16_f32 v110, v110, v111
	v_cvt_pk_bf16_f32 v111, v112, v113
	global_store_dwordx2 v[180:181], v[110:111], off
	global_load_dwordx4 v[110:113], v[192:193], off offset:16
	s_nop 0
	global_load_dwordx4 v[150:153], v[208:209], off offset:16
	global_load_dwordx4 v[198:201], v[170:171], off
	global_load_dwordx4 v[202:205], v[216:217], off
	s_waitcnt vmcnt(0)
	v_pk_fma_f32 v[110:111], v[138:139], v[110:111], v[150:151]
	v_fma_f32 v106, -v218, v198, v106
	v_fma_f32 v107, -v218, v199, v107
	v_fma_f32 v106, v220, v106, v202
	v_fma_f32 v107, v220, v107, v203
	v_fma_f32 v108, -v218, v200, v108
	v_fma_f32 v109, -v218, v201, v109
	v_mul_f32_e32 v106, 0xbfb8aa3b, v106
	v_mul_f32_e32 v107, 0xbfb8aa3b, v107
	v_fma_f32 v108, v220, v108, v204
	v_fmac_f32_e32 v205, v220, v109
	v_exp_f32_e32 v106, v106
	v_exp_f32_e32 v107, v107
	v_mul_f32_e32 v108, 0xbfb8aa3b, v108
	v_mul_f32_e32 v109, 0xbfb8aa3b, v205
	v_exp_f32_e32 v108, v108
	v_exp_f32_e32 v109, v109
	v_add_f32_e32 v106, 1.0, v106
	v_add_f32_e32 v107, 1.0, v107
	v_rcp_f32_e32 v106, v106
	v_rcp_f32_e32 v107, v107
	v_add_f32_e32 v108, 1.0, v108
	v_add_f32_e32 v109, 1.0, v109
	v_rcp_f32_e32 v108, v108
	v_rcp_f32_e32 v109, v109
	v_pk_add_f32 v[138:139], v[140:141], v[218:219] op_sel_hi:[1,0] neg_lo:[0,1] neg_hi:[0,1]
	v_lshlrev_b32_e32 v198, 16, v144
	v_and_b32_e32 v199, 0xffff0000, v144
	v_pk_mul_f32 v[138:139], v[138:139], v[220:221] op_sel_hi:[1,0]
	v_pk_fma_f32 v[106:107], v[106:107], v[198:199], v[110:111]
	v_lshlrev_b32_e32 v110, 16, v145
	v_and_b32_e32 v111, 0xffff0000, v145
	v_pk_fma_f32 v[112:113], v[138:139], v[112:113], v[152:153]
	s_waitcnt lgkmcnt(0)
	v_pk_mul_f32 v[144:145], v[178:179], s[36:37] op_sel_hi:[1,0]
	v_pk_fma_f32 v[108:109], v[108:109], v[110:111], v[112:113]
	global_store_dwordx4 v[142:143], v[106:109], off offset:16
	v_pk_add_f32 v[154:155], v[154:155], v[144:145] op_sel_hi:[1,0] neg_lo:[0,1] neg_hi:[0,1]
	v_pk_add_f32 v[146:147], v[146:147], v[144:145] op_sel_hi:[1,0] neg_lo:[0,1] neg_hi:[0,1]
	v_cvt_pk_bf16_f32 v106, v106, v107
	v_cvt_pk_bf16_f32 v107, v108, v109
	global_store_dwordx2 v[180:181], v[106:107], off offset:8
	global_load_dwordx4 v[106:109], v[192:193], off offset:512
	s_nop 0
	global_load_dwordx4 v[110:113], v[208:209], off offset:512
	global_load_dwordx4 v[138:141], v[172:173], off
	global_load_dwordx4 v[150:153], v[174:175], off
	s_waitcnt vmcnt(0)
; DI unsigned pk2(float lo, float hi) { f32x2 v = {lo, hi}; bf16x2_t b = __builtin_convertvector(v, bf16x2_t); return __builtin_bit_cast(unsigned, b); }
; DI float lo_bf(unsigned u) { return __uint_as_float(u << 16); }
; DI float hi_bf(unsigned u) { return __uint_as_float(u & 0xffff0000u); }
; DI float sigmoidf_(float x) { return __builtin_amdgcn_rcpf(1.f + __expf(-x)); }
;     DI void operator()(AccRef acc, const Unit& u, int wr, int wc, int fr, int fq) const {
;     ...
;         for (int it = 0; it < 8; ++it) { const int ai = it >> 2, m = it & 3, cur = it & 1;
;             if (it + 1 < 8) { int rn_ = row0 + ((it + 1) >> 2) * 128 + ((it + 1) & 3) * 16; asm volatile("" : "+v"(rn_) :: "memory"); const size_t on = (size_t)rn_ * DM + c0; sb[cur ^ 1] = *(const f32x2*)(ST + (size_t)rn_ * 2);
; #pragma unroll
;                 for (int bj = 0; bj < 2; ++bj) { eb[cur ^ 1][bj] = *(const u32x4*)(E + on + bj * 128);
; #pragma unroll
;                     for (int n = 0; n < 2; ++n) yb[cur ^ 1][bj][n] = *(const f32x4*)(Y + on + bj * 128 + 4 * n); } }
;             int row = row0 + ai * 128 + m * 16; asm volatile("" : "+v"(row)); const size_t off = (size_t)row * DM + c0;
;             const float mean = sb[cur].x * (1.f / DM); const float rstd = __builtin_amdgcn_rsqf(fmaxf(sb[cur].y * (1.f / DM) - mean * mean, 0.f) + LN_EPS);
; #pragma unroll
;             for (int bj = 0; bj < 2; ++bj)
; #pragma unroll
;                 for (int n = 0; n < 2; ++n) { const int cc = c0 + bj * 128 + 4 * n; const f32x4 gv = *(const f32x4*)(G + cc), bv = *(const f32x4*)(Bv + cc), gw = *(const f32x4*)(GW + cc), bw = *(const f32x4*)(GW + 1024 + cc);
;                     const unsigned e0 = eb[cur][bj][2 * n], e1 = eb[cur][bj][2 * n + 1]; const f32x4 ev = {lo_bf(e0), hi_bf(e0), lo_bf(e1), hi_bf(e1)};
;                     const f32x4 x2 = (yb[cur][bj][n] - mean) * rstd * gv + bv; const f32x4 a = (acc[ai][bj][m][n] - gw * mean) * rstd + bw; f32x4 o;
; #pragma unroll
;                     for (int i = 0; i < 4; ++i) o[i] = x2[i] + sigmoidf_(a[i]) * ev[i];
;                     *(f32x4*)(OUT + off + bj * 128 + 4 * n) = o; u32x2 w2; w2.x = pk2(o[0], o[1]); w2.y = pk2(o[2], o[3]);
;                     *(u32x2*)(XB + off + bj * 128 + 4 * n) = w2; } }
	v_pk_fma_f32 v[106:107], v[122:123], v[106:107], v[110:111]
	v_fma_f32 v102, -v218, v138, v102
	v_fma_f32 v103, -v218, v139, v103
	v_fma_f32 v102, v220, v102, v150
	v_fma_f32 v103, v220, v103, v151
	v_fma_f32 v104, -v218, v140, v104
	v_fma_f32 v105, -v218, v141, v105
	v_mul_f32_e32 v102, 0xbfb8aa3b, v102
	v_mul_f32_e32 v103, 0xbfb8aa3b, v103
	v_fma_f32 v104, v220, v104, v152
	v_fmac_f32_e32 v153, v220, v105
	v_exp_f32_e32 v102, v102
	v_exp_f32_e32 v103, v103
	v_mul_f32_e32 v104, 0xbfb8aa3b, v104
	v_mul_f32_e32 v105, 0xbfb8aa3b, v153
	v_exp_f32_e32 v104, v104
	v_exp_f32_e32 v105, v105
	v_add_f32_e32 v102, 1.0, v102
	v_add_f32_e32 v103, 1.0, v103
	v_rcp_f32_e32 v102, v102
	v_rcp_f32_e32 v103, v103
	v_add_f32_e32 v104, 1.0, v104
	v_add_f32_e32 v105, 1.0, v105
	v_rcp_f32_e32 v104, v104
	v_rcp_f32_e32 v105, v105
	v_pk_add_f32 v[110:111], v[124:125], v[218:219] op_sel_hi:[1,0] neg_lo:[0,1] neg_hi:[0,1]
	v_lshlrev_b32_e32 v138, 16, v114
	v_and_b32_e32 v139, 0xffff0000, v114
	v_pk_mul_f32 v[110:111], v[220:221], v[110:111] op_sel_hi:[0,1]
	v_pk_fma_f32 v[102:103], v[102:103], v[138:139], v[106:107]
	v_lshlrev_b32_e32 v106, 16, v115
	v_and_b32_e32 v107, 0xffff0000, v115
	v_pk_fma_f32 v[108:109], v[110:111], v[108:109], v[112:113]
	v_pk_add_f32 v[114:115], v[118:119], v[218:219] op_sel_hi:[1,0] neg_lo:[0,1] neg_hi:[0,1]
	v_pk_fma_f32 v[104:105], v[104:105], v[106:107], v[108:109]
	global_store_dwordx4 v[142:143], v[102:105], off offset:512
	v_pk_mul_f32 v[114:115], v[220:221], v[114:115] op_sel_hi:[0,1]
	v_or_b32_e32 v138, 48, v240
	v_cvt_pk_bf16_f32 v102, v102, v103
	v_cvt_pk_bf16_f32 v103, v104, v105
	global_store_dwordx2 v[180:181], v[102:103], off offset:256
	global_load_dwordx4 v[102:105], v[192:193], off offset:528
	s_nop 0
	global_load_dwordx4 v[106:109], v[208:209], off offset:528
	global_load_dwordx4 v[110:113], v[166:167], off
	global_load_dwordx4 v[122:125], v[168:169], off
	v_pk_add_f32 v[152:153], v[162:163], v[144:145] op_sel_hi:[1,0] neg_lo:[0,1] neg_hi:[0,1]
	s_waitcnt vmcnt(0)
	v_pk_fma_f32 v[102:103], v[114:115], v[102:103], v[106:107]
	v_fma_f32 v98, -v218, v110, v98
	v_fma_f32 v99, -v218, v111, v99
	v_fma_f32 v98, v220, v98, v122
	v_fma_f32 v99, v220, v99, v123
	v_fma_f32 v100, -v218, v112, v100
	v_fma_f32 v101, -v218, v113, v101
	v_mul_f32_e32 v98, 0xbfb8aa3b, v98
	v_mul_f32_e32 v99, 0xbfb8aa3b, v99
	v_fma_f32 v100, v220, v100, v124
	v_fmac_f32_e32 v125, v220, v101
	v_exp_f32_e32 v98, v98
	v_exp_f32_e32 v99, v99
	v_mul_f32_e32 v100, 0xbfb8aa3b, v100
	v_mul_f32_e32 v101, 0xbfb8aa3b, v125
	v_exp_f32_e32 v100, v100
	v_exp_f32_e32 v101, v101
	v_add_f32_e32 v98, 1.0, v98
	v_add_f32_e32 v99, 1.0, v99
	v_rcp_f32_e32 v98, v98
	v_rcp_f32_e32 v99, v99
	v_add_f32_e32 v100, 1.0, v100
	v_add_f32_e32 v101, 1.0, v101
	v_rcp_f32_e32 v100, v100
	v_rcp_f32_e32 v101, v101
	v_pk_add_f32 v[106:107], v[120:121], v[218:219] op_sel_hi:[1,0] neg_lo:[0,1] neg_hi:[0,1]
	v_lshlrev_b32_e32 v110, 16, v116
	v_and_b32_e32 v111, 0xffff0000, v116
	v_pk_mul_f32 v[106:107], v[220:221], v[106:107] op_sel_hi:[0,1]
	v_pk_fma_f32 v[98:99], v[98:99], v[110:111], v[102:103]
	v_lshlrev_b32_e32 v102, 16, v117
	v_and_b32_e32 v103, 0xffff0000, v117
	v_pk_fma_f32 v[104:105], v[106:107], v[104:105], v[108:109]
	v_fma_f32 v120, -v144, v144, v145
	v_pk_fma_f32 v[100:101], v[100:101], v[102:103], v[104:105]
	global_store_dwordx4 v[142:143], v[98:101], off offset:528
	v_max_f32_e32 v120, 0, v120
	v_add_f32_e32 v120, 0x3727c5ac, v120
	v_cvt_pk_bf16_f32 v98, v98, v99
	v_cvt_pk_bf16_f32 v99, v100, v101
	global_store_dwordx2 v[180:181], v[98:99], off offset:264
	v_mov_b32_e32 v98, v138
	v_rsq_f32_e32 v150, v120
	v_ashrrev_i32_e32 v99, 31, v98
	v_lshlrev_b64 v[100:101], 10, v[98:99]
	v_lshl_add_u64 v[100:101], v[100:101], 0, v[210:211]
	v_lshl_add_u64 v[98:99], v[98:99], 3, s[4:5]
	global_load_dwordx2 v[140:141], v[98:99], off
	v_lshl_add_u64 v[98:99], v[100:101], 1, vcc
	v_lshl_add_u64 v[102:103], v[100:101], 2, s[78:79]
	global_load_dwordx4 v[114:117], v[98:99], off
	global_load_dwordx4 v[122:125], v[102:103], off
	global_load_dwordx4 v[110:113], v[102:103], off offset:16
	s_nop 0
	global_load_dwordx4 v[98:101], v[98:99], off offset:256
	s_nop 0
	global_load_dwordx4 v[106:109], v[102:103], off offset:512
	s_nop 0
	global_load_dwordx4 v[102:105], v[102:103], off offset:528
	v_pk_mul_f32 v[152:153], v[152:153], v[150:151] op_sel_hi:[1,0]
	v_ashrrev_i32_e32 v177, 31, v176
	v_lshlrev_b64 v[118:119], 10, v[176:177]
	global_load_dwordx4 v[176:179], v[192:193], off
	global_load_dwordx4 v[198:201], v[208:209], off
	global_load_dwordx4 v[202:205], v[212:213], off
	global_load_dwordx4 v[218:221], v[214:215], off
	v_lshlrev_b32_e32 v120, 16, v158
	v_and_b32_e32 v121, 0xffff0000, v158
	v_lshl_add_u64 v[118:119], v[118:119], 0, v[210:211]
	v_lshl_add_u64 v[142:143], v[118:119], 1, s[76:77]
	v_pk_mul_f32 v[154:155], v[154:155], v[150:151] op_sel_hi:[1,0]
	v_lshlrev_b32_e32 v158, 16, v160
	v_pk_mul_f32 v[146:147], v[150:151], v[146:147] op_sel_hi:[0,1]
	s_waitcnt vmcnt(0) lgkmcnt(0)
; DI unsigned pk2(float lo, float hi) { f32x2 v = {lo, hi}; bf16x2_t b = __builtin_convertvector(v, bf16x2_t); return __builtin_bit_cast(unsigned, b); }
; DI float lo_bf(unsigned u) { return __uint_as_float(u << 16); }
; DI float hi_bf(unsigned u) { return __uint_as_float(u & 0xffff0000u); }
; DI float sigmoidf_(float x) { return __builtin_amdgcn_rcpf(1.f + __expf(-x)); }
;     DI void operator()(AccRef acc, const Unit& u, int wr, int wc, int fr, int fq) const {
;     ...
;             int row = row0 + ai * 128 + m * 16; asm volatile("" : "+v"(row)); const size_t off = (size_t)row * DM + c0;
;             const float mean = sb[cur].x * (1.f / DM); const float rstd = __builtin_amdgcn_rsqf(fmaxf(sb[cur].y * (1.f / DM) - mean * mean, 0.f) + LN_EPS);
; #pragma unroll
;             for (int bj = 0; bj < 2; ++bj)
; #pragma unroll
;                 for (int n = 0; n < 2; ++n) { const int cc = c0 + bj * 128 + 4 * n; const f32x4 gv = *(const f32x4*)(G + cc), bv = *(const f32x4*)(Bv + cc), gw = *(const f32x4*)(GW + cc), bw = *(const f32x4*)(GW + 1024 + cc);
;                     const unsigned e0 = eb[cur][bj][2 * n], e1 = eb[cur][bj][2 * n + 1]; const f32x4 ev = {lo_bf(e0), hi_bf(e0), lo_bf(e1), hi_bf(e1)};
;                     const f32x4 x2 = (yb[cur][bj][n] - mean) * rstd * gv + bv; const f32x4 a = (acc[ai][bj][m][n] - gw * mean) * rstd + bw; f32x4 o;
; #pragma unroll
;                     for (int i = 0; i < 4; ++i) o[i] = x2[i] + sigmoidf_(a[i]) * ev[i];
;                     *(f32x4*)(OUT + off + bj * 128 + 4 * n) = o; u32x2 w2; w2.x = pk2(o[0], o[1]); w2.y = pk2(o[2], o[3]);
;                     *(u32x2*)(XB + off + bj * 128 + 4 * n) = w2; } }
	v_pk_mul_f32 v[140:141], v[140:141], s[36:37] op_sel_hi:[1,0]
	s_nop 0
	v_pk_add_f32 v[122:123], v[122:123], v[140:141] op_sel_hi:[1,0] neg_lo:[0,1] neg_hi:[0,1]
	v_pk_add_f32 v[110:111], v[110:111], v[140:141] op_sel_hi:[1,0] neg_lo:[0,1] neg_hi:[0,1]
	v_pk_add_f32 v[106:107], v[106:107], v[140:141] op_sel_hi:[1,0] neg_lo:[0,1] neg_hi:[0,1]
	v_pk_fma_f32 v[152:153], v[152:153], v[176:177], v[198:199]
	v_fma_f32 v94, -v144, v202, v94
	v_fma_f32 v95, -v144, v203, v95
	v_fma_f32 v94, v150, v94, v218
	v_fma_f32 v95, v150, v95, v219
	v_mul_f32_e32 v94, 0xbfb8aa3b, v94
	v_mul_f32_e32 v95, 0xbfb8aa3b, v95
	v_exp_f32_e32 v94, v94
	v_exp_f32_e32 v95, v95
	v_fma_f32 v96, -v144, v204, v96
	v_fma_f32 v97, -v144, v205, v97
	v_fma_f32 v96, v150, v96, v220
	v_fmac_f32_e32 v221, v150, v97
	v_mul_f32_e32 v96, 0xbfb8aa3b, v96
	v_mul_f32_e32 v97, 0xbfb8aa3b, v221
	v_exp_f32_e32 v96, v96
	v_exp_f32_e32 v97, v97
	v_add_f32_e32 v94, 1.0, v94
	v_add_f32_e32 v95, 1.0, v95
	v_rcp_f32_e32 v94, v94
	v_rcp_f32_e32 v95, v95
	v_add_f32_e32 v96, 1.0, v96
	v_add_f32_e32 v97, 1.0, v97
	v_rcp_f32_e32 v96, v96
	v_rcp_f32_e32 v97, v97
	v_pk_fma_f32 v[94:95], v[94:95], v[120:121], v[152:153]
	v_pk_add_f32 v[152:153], v[164:165], v[144:145] op_sel_hi:[1,0] neg_lo:[0,1] neg_hi:[0,1]
	v_lshlrev_b32_e32 v120, 16, v159
	v_pk_mul_f32 v[152:153], v[152:153], v[150:151] op_sel_hi:[1,0]
	v_and_b32_e32 v121, 0xffff0000, v159
	v_pk_fma_f32 v[152:153], v[152:153], v[178:179], v[200:201]
	v_and_b32_e32 v159, 0xffff0000, v160
	v_pk_fma_f32 v[96:97], v[96:97], v[120:121], v[152:153]
	v_lshl_add_u64 v[152:153], v[118:119], 2, s[18:19]
	global_store_dwordx4 v[152:153], v[94:97], off
	s_nop 1
	v_cvt_pk_bf16_f32 v94, v94, v95
	v_cvt_pk_bf16_f32 v95, v96, v97
	global_store_dwordx2 v[142:143], v[94:95], off
	global_load_dwordx4 v[94:97], v[192:193], off offset:16
	s_nop 0
	global_load_dwordx4 v[118:121], v[208:209], off offset:16
	global_load_dwordx4 v[162:165], v[170:171], off
	global_load_dwordx4 v[176:179], v[216:217], off
	s_waitcnt vmcnt(0)
	v_pk_fma_f32 v[94:95], v[154:155], v[94:95], v[118:119]
	v_fma_f32 v90, -v144, v162, v90
	v_fma_f32 v91, -v144, v163, v91
	v_fma_f32 v90, v150, v90, v176
	v_fma_f32 v91, v150, v91, v177
	v_fma_f32 v92, -v144, v164, v92
	v_fma_f32 v93, -v144, v165, v93
	v_mul_f32_e32 v90, 0xbfb8aa3b, v90
	v_mul_f32_e32 v91, 0xbfb8aa3b, v91
	v_fma_f32 v92, v150, v92, v178
	v_fmac_f32_e32 v179, v150, v93
	v_exp_f32_e32 v90, v90
	v_exp_f32_e32 v91, v91
	v_mul_f32_e32 v92, 0xbfb8aa3b, v92
	v_mul_f32_e32 v93, 0xbfb8aa3b, v179
	v_exp_f32_e32 v92, v92
	v_exp_f32_e32 v93, v93
	v_add_f32_e32 v90, 1.0, v90
	v_add_f32_e32 v91, 1.0, v91
	v_rcp_f32_e32 v90, v90
	v_rcp_f32_e32 v91, v91
	v_add_f32_e32 v92, 1.0, v92
	v_add_f32_e32 v93, 1.0, v93
	v_rcp_f32_e32 v92, v92
	v_rcp_f32_e32 v93, v93
	v_pk_add_f32 v[118:119], v[156:157], v[144:145] op_sel_hi:[1,0] neg_lo:[0,1] neg_hi:[0,1]
	v_pk_fma_f32 v[90:91], v[90:91], v[158:159], v[94:95]
	v_pk_mul_f32 v[118:119], v[118:119], v[150:151] op_sel_hi:[1,0]
	v_lshlrev_b32_e32 v94, 16, v161
	v_and_b32_e32 v95, 0xffff0000, v161
	v_pk_fma_f32 v[96:97], v[118:119], v[96:97], v[120:121]
	s_nop 0
	v_pk_fma_f32 v[92:93], v[92:93], v[94:95], v[96:97]
	global_store_dwordx4 v[152:153], v[90:93], off offset:16
	s_nop 1
	v_cvt_pk_bf16_f32 v90, v90, v91
	v_cvt_pk_bf16_f32 v91, v92, v93
	global_store_dwordx2 v[142:143], v[90:91], off offset:8
	global_load_dwordx4 v[90:93], v[192:193], off offset:512
	s_nop 0
	global_load_dwordx4 v[94:97], v[208:209], off offset:512
	global_load_dwordx4 v[118:121], v[172:173], off
	global_load_dwordx4 v[154:157], v[174:175], off
	s_waitcnt vmcnt(0)
	v_pk_fma_f32 v[90:91], v[146:147], v[90:91], v[94:95]
	v_fma_f32 v86, -v144, v118, v86
	v_fma_f32 v87, -v144, v119, v87
	v_fma_f32 v86, v150, v86, v154
	v_fma_f32 v87, v150, v87, v155
	v_fma_f32 v88, -v144, v120, v88
	v_fma_f32 v89, -v144, v121, v89
	v_mul_f32_e32 v86, 0xbfb8aa3b, v86
	v_mul_f32_e32 v87, 0xbfb8aa3b, v87
	v_fma_f32 v88, v150, v88, v156
	v_fmac_f32_e32 v157, v150, v89
	v_exp_f32_e32 v86, v86
	v_exp_f32_e32 v87, v87
	v_mul_f32_e32 v88, 0xbfb8aa3b, v88
	v_mul_f32_e32 v89, 0xbfb8aa3b, v157
	v_exp_f32_e32 v88, v88
	v_exp_f32_e32 v89, v89
	v_add_f32_e32 v86, 1.0, v86
	v_add_f32_e32 v87, 1.0, v87
	v_rcp_f32_e32 v86, v86
	v_rcp_f32_e32 v87, v87
	v_add_f32_e32 v88, 1.0, v88
	v_add_f32_e32 v89, 1.0, v89
	v_rcp_f32_e32 v88, v88
	v_rcp_f32_e32 v89, v89
	v_pk_add_f32 v[94:95], v[148:149], v[144:145] op_sel_hi:[1,0] neg_lo:[0,1] neg_hi:[0,1]
	v_lshlrev_b32_e32 v118, 16, v126
	v_and_b32_e32 v119, 0xffff0000, v126
	v_pk_mul_f32 v[94:95], v[150:151], v[94:95] op_sel_hi:[0,1]
	v_pk_fma_f32 v[86:87], v[86:87], v[118:119], v[90:91]
	v_lshlrev_b32_e32 v90, 16, v127
	v_and_b32_e32 v91, 0xffff0000, v127
	v_pk_fma_f32 v[92:93], v[94:95], v[92:93], v[96:97]
	s_nop 0
	v_pk_fma_f32 v[88:89], v[88:89], v[90:91], v[92:93]
	global_store_dwordx4 v[152:153], v[86:89], off offset:512
	s_nop 1
	v_cvt_pk_bf16_f32 v86, v86, v87
	v_cvt_pk_bf16_f32 v87, v88, v89
	global_store_dwordx2 v[142:143], v[86:87], off offset:256
	global_load_dwordx4 v[86:89], v[192:193], off offset:528
	s_nop 0
	global_load_dwordx4 v[90:93], v[208:209], off offset:528
	global_load_dwordx4 v[94:97], v[166:167], off
	global_load_dwordx4 v[118:121], v[168:169], off
	s_waitcnt vmcnt(0)
; DI unsigned pk2(float lo, float hi) { f32x2 v = {lo, hi}; bf16x2_t b = __builtin_convertvector(v, bf16x2_t); return __builtin_bit_cast(unsigned, b); }
; DI float lo_bf(unsigned u) { return __uint_as_float(u << 16); }
; DI float hi_bf(unsigned u) { return __uint_as_float(u & 0xffff0000u); }
; DI float sigmoidf_(float x) { return __builtin_amdgcn_rcpf(1.f + __expf(-x)); }
;     DI void operator()(AccRef acc, const Unit& u, int wr, int wc, int fr, int fq) const {
;     ...
;         for (int it = 0; it < 8; ++it) { const int ai = it >> 2, m = it & 3, cur = it & 1;
;             if (it + 1 < 8) { int rn_ = row0 + ((it + 1) >> 2) * 128 + ((it + 1) & 3) * 16; asm volatile("" : "+v"(rn_) :: "memory"); const size_t on = (size_t)rn_ * DM + c0; sb[cur ^ 1] = *(const f32x2*)(ST + (size_t)rn_ * 2);
; #pragma unroll
;                 for (int bj = 0; bj < 2; ++bj) { eb[cur ^ 1][bj] = *(const u32x4*)(E + on + bj * 128);
; #pragma unroll
;                     for (int n = 0; n < 2; ++n) yb[cur ^ 1][bj][n] = *(const f32x4*)(Y + on + bj * 128 + 4 * n); } }
;             int row = row0 + ai * 128 + m * 16; asm volatile("" : "+v"(row)); const size_t off = (size_t)row * DM + c0;
;             const float mean = sb[cur].x * (1.f / DM); const float rstd = __builtin_amdgcn_rsqf(fmaxf(sb[cur].y * (1.f / DM) - mean * mean, 0.f) + LN_EPS);
; #pragma unroll
;             for (int bj = 0; bj < 2; ++bj)
; #pragma unroll
;                 for (int n = 0; n < 2; ++n) { const int cc = c0 + bj * 128 + 4 * n; const f32x4 gv = *(const f32x4*)(G + cc), bv = *(const f32x4*)(Bv + cc), gw = *(const f32x4*)(GW + cc), bw = *(const f32x4*)(GW + 1024 + cc);
;                     const unsigned e0 = eb[cur][bj][2 * n], e1 = eb[cur][bj][2 * n + 1]; const f32x4 ev = {lo_bf(e0), hi_bf(e0), lo_bf(e1), hi_bf(e1)};
;                     const f32x4 x2 = (yb[cur][bj][n] - mean) * rstd * gv + bv; const f32x4 a = (acc[ai][bj][m][n] - gw * mean) * rstd + bw; f32x4 o;
; #pragma unroll
;                     for (int i = 0; i < 4; ++i) o[i] = x2[i] + sigmoidf_(a[i]) * ev[i];
;                     *(f32x4*)(OUT + off + bj * 128 + 4 * n) = o; u32x2 w2; w2.x = pk2(o[0], o[1]); w2.y = pk2(o[2], o[3]);
;                     *(u32x2*)(XB + off + bj * 128 + 4 * n) = w2; } }
	v_fma_f32 v82, -v144, v94, v82
	v_fma_f32 v83, -v144, v95, v83
	v_fma_f32 v82, v150, v82, v118
	v_fma_f32 v83, v150, v83, v119
	v_fma_f32 v84, -v144, v96, v84
	v_fma_f32 v85, -v144, v97, v85
	v_mul_f32_e32 v82, 0xbfb8aa3b, v82
	v_mul_f32_e32 v83, 0xbfb8aa3b, v83
	v_fma_f32 v84, v150, v84, v120
	v_fmac_f32_e32 v121, v150, v85
	v_exp_f32_e32 v82, v82
	v_exp_f32_e32 v83, v83
	v_mul_f32_e32 v84, 0xbfb8aa3b, v84
	v_mul_f32_e32 v85, 0xbfb8aa3b, v121
	v_exp_f32_e32 v84, v84
	v_exp_f32_e32 v85, v85
	v_add_f32_e32 v82, 1.0, v82
	v_add_f32_e32 v83, 1.0, v83
	v_rcp_f32_e32 v82, v82
	v_rcp_f32_e32 v83, v83
	v_pk_add_f32 v[118:119], v[134:135], v[144:145] op_sel_hi:[1,0] neg_lo:[0,1] neg_hi:[0,1]
	v_add_f32_e32 v84, 1.0, v84
	v_add_f32_e32 v85, 1.0, v85
	v_pk_mul_f32 v[118:119], v[150:151], v[118:119] op_sel_hi:[0,1]
	v_rcp_f32_e32 v84, v84
	v_rcp_f32_e32 v85, v85
	v_pk_fma_f32 v[86:87], v[118:119], v[86:87], v[90:91]
	v_pk_add_f32 v[90:91], v[136:137], v[144:145] op_sel_hi:[1,0] neg_lo:[0,1] neg_hi:[0,1]
	v_lshlrev_b32_e32 v94, 16, v128
	v_and_b32_e32 v95, 0xffff0000, v128
	v_pk_mul_f32 v[90:91], v[150:151], v[90:91] op_sel_hi:[0,1]
	v_pk_fma_f32 v[82:83], v[82:83], v[94:95], v[86:87]
	v_lshlrev_b32_e32 v86, 16, v129
	v_and_b32_e32 v87, 0xffff0000, v129
	v_pk_fma_f32 v[88:89], v[90:91], v[88:89], v[92:93]
	v_add_u32_e32 v134, 0x80, v240
	v_pk_fma_f32 v[84:85], v[84:85], v[86:87], v[88:89]
	global_store_dwordx4 v[152:153], v[82:85], off offset:528
	v_fma_f32 v135, -v140, v140, v141
	v_max_f32_e32 v135, 0, v135
	v_cvt_pk_bf16_f32 v82, v82, v83
	v_cvt_pk_bf16_f32 v83, v84, v85
	global_store_dwordx2 v[142:143], v[82:83], off offset:264
	v_mov_b32_e32 v82, v134
	v_add_f32_e32 v135, 0x3727c5ac, v135
	v_ashrrev_i32_e32 v83, 31, v82
	v_lshlrev_b64 v[84:85], 10, v[82:83]
	v_lshl_add_u64 v[84:85], v[84:85], 0, v[210:211]
	v_lshl_add_u64 v[82:83], v[82:83], 3, s[4:5]
	global_load_dwordx2 v[136:137], v[82:83], off
	v_lshl_add_u64 v[82:83], v[84:85], 1, vcc
	v_lshl_add_u64 v[86:87], v[84:85], 2, s[78:79]
	global_load_dwordx4 v[118:121], v[82:83], off
	global_load_dwordx4 v[126:129], v[86:87], off
	global_load_dwordx4 v[94:97], v[86:87], off offset:16
	s_nop 0
	global_load_dwordx4 v[82:85], v[82:83], off offset:256
	s_nop 0
	global_load_dwordx4 v[90:93], v[86:87], off offset:512
	s_nop 0
	global_load_dwordx4 v[86:89], v[86:87], off offset:528
	global_load_dwordx4 v[146:149], v[192:193], off
	global_load_dwordx4 v[150:153], v[208:209], off
	global_load_dwordx4 v[154:157], v[212:213], off
	global_load_dwordx4 v[158:161], v[214:215], off
	v_rsq_f32_e32 v142, v135
	v_ashrrev_i32_e32 v139, 31, v138
	v_lshlrev_b64 v[138:139], 10, v[138:139]
	v_lshl_add_u64 v[144:145], v[138:139], 0, v[210:211]
	v_pk_mul_f32 v[122:123], v[122:123], v[142:143] op_sel_hi:[1,0]
	v_lshl_add_u64 v[138:139], v[144:145], 1, s[76:77]
	v_pk_mul_f32 v[110:111], v[110:111], v[142:143] op_sel_hi:[1,0]
	v_pk_mul_f32 v[106:107], v[142:143], v[106:107] op_sel_hi:[0,1]
	s_waitcnt vmcnt(0)
	v_pk_fma_f32 v[122:123], v[122:123], v[146:147], v[150:151]
	v_fma_f32 v78, -v140, v154, v78
	v_fma_f32 v79, -v140, v155, v79
	v_fma_f32 v78, v142, v78, v158
	v_fma_f32 v79, v142, v79, v159
	v_mul_f32_e32 v78, 0xbfb8aa3b, v78
	v_mul_f32_e32 v79, 0xbfb8aa3b, v79
	v_exp_f32_e32 v78, v78
	v_exp_f32_e32 v79, v79
	v_fma_f32 v80, -v140, v156, v80
	v_fma_f32 v81, -v140, v157, v81
	v_fma_f32 v80, v142, v80, v160
	v_fmac_f32_e32 v161, v142, v81
	v_mul_f32_e32 v80, 0xbfb8aa3b, v80
	v_mul_f32_e32 v81, 0xbfb8aa3b, v161
	v_exp_f32_e32 v80, v80
	v_exp_f32_e32 v81, v81
	v_add_f32_e32 v78, 1.0, v78
	v_add_f32_e32 v79, 1.0, v79
	v_rcp_f32_e32 v78, v78
	v_rcp_f32_e32 v79, v79
	v_add_f32_e32 v80, 1.0, v80
	v_add_f32_e32 v81, 1.0, v81
	v_lshlrev_b32_e32 v154, 16, v114
	v_and_b32_e32 v155, 0xffff0000, v114
	v_rcp_f32_e32 v80, v80
	v_rcp_f32_e32 v81, v81
	v_pk_fma_f32 v[78:79], v[78:79], v[154:155], v[122:123]
	v_pk_add_f32 v[122:123], v[124:125], v[140:141] op_sel_hi:[1,0] neg_lo:[0,1] neg_hi:[0,1]
	v_lshlrev_b32_e32 v114, 16, v115
	v_pk_mul_f32 v[122:123], v[122:123], v[142:143] op_sel_hi:[1,0]
	v_and_b32_e32 v115, 0xffff0000, v115
	v_pk_fma_f32 v[122:123], v[122:123], v[148:149], v[152:153]
	s_nop 0
	v_pk_fma_f32 v[80:81], v[80:81], v[114:115], v[122:123]
	v_lshl_add_u64 v[114:115], v[144:145], 2, s[18:19]
	global_store_dwordx4 v[114:115], v[78:81], off
	s_nop 1
	v_cvt_pk_bf16_f32 v78, v78, v79
	v_cvt_pk_bf16_f32 v79, v80, v81
	global_store_dwordx2 v[138:139], v[78:79], off
	global_load_dwordx4 v[78:81], v[192:193], off offset:16
	s_nop 0
	global_load_dwordx4 v[122:125], v[208:209], off offset:16
	global_load_dwordx4 v[144:147], v[170:171], off
	global_load_dwordx4 v[148:151], v[216:217], off
	s_waitcnt vmcnt(0)
	v_pk_fma_f32 v[78:79], v[110:111], v[78:79], v[122:123]
	v_fma_f32 v74, -v140, v144, v74
	v_fma_f32 v75, -v140, v145, v75
	v_fma_f32 v74, v142, v74, v148
	v_fma_f32 v75, v142, v75, v149
	v_fma_f32 v76, -v140, v146, v76
	v_fma_f32 v77, -v140, v147, v77
	v_mul_f32_e32 v74, 0xbfb8aa3b, v74
	v_mul_f32_e32 v75, 0xbfb8aa3b, v75
	v_fma_f32 v76, v142, v76, v150
	v_fmac_f32_e32 v151, v142, v77
	v_exp_f32_e32 v74, v74
	v_exp_f32_e32 v75, v75
	v_mul_f32_e32 v76, 0xbfb8aa3b, v76
	v_mul_f32_e32 v77, 0xbfb8aa3b, v151
	v_exp_f32_e32 v76, v76
	v_exp_f32_e32 v77, v77
	v_add_f32_e32 v74, 1.0, v74
	v_add_f32_e32 v75, 1.0, v75
	v_rcp_f32_e32 v74, v74
	v_rcp_f32_e32 v75, v75
	v_add_f32_e32 v76, 1.0, v76
	v_add_f32_e32 v77, 1.0, v77
	v_rcp_f32_e32 v76, v76
	v_rcp_f32_e32 v77, v77
	v_pk_add_f32 v[110:111], v[112:113], v[140:141] op_sel_hi:[1,0] neg_lo:[0,1] neg_hi:[0,1]
	v_lshlrev_b32_e32 v144, 16, v116
	v_and_b32_e32 v145, 0xffff0000, v116
	v_pk_mul_f32 v[110:111], v[110:111], v[142:143] op_sel_hi:[1,0]
	v_pk_fma_f32 v[74:75], v[74:75], v[144:145], v[78:79]
	v_lshlrev_b32_e32 v78, 16, v117
	v_and_b32_e32 v79, 0xffff0000, v117
	v_pk_fma_f32 v[80:81], v[110:111], v[80:81], v[124:125]
	s_waitcnt lgkmcnt(0)
; DI unsigned pk2(float lo, float hi) { f32x2 v = {lo, hi}; bf16x2_t b = __builtin_convertvector(v, bf16x2_t); return __builtin_bit_cast(unsigned, b); }
; DI float lo_bf(unsigned u) { return __uint_as_float(u << 16); }
; DI float hi_bf(unsigned u) { return __uint_as_float(u & 0xffff0000u); }
; DI float sigmoidf_(float x) { return __builtin_amdgcn_rcpf(1.f + __expf(-x)); }
;     DI void operator()(AccRef acc, const Unit& u, int wr, int wc, int fr, int fq) const {
;     ...
;         for (int it = 0; it < 8; ++it) { const int ai = it >> 2, m = it & 3, cur = it & 1;
;             if (it + 1 < 8) { int rn_ = row0 + ((it + 1) >> 2) * 128 + ((it + 1) & 3) * 16; asm volatile("" : "+v"(rn_) :: "memory"); const size_t on = (size_t)rn_ * DM + c0; sb[cur ^ 1] = *(const f32x2*)(ST + (size_t)rn_ * 2);
; #pragma unroll
;                 for (int bj = 0; bj < 2; ++bj) { eb[cur ^ 1][bj] = *(const u32x4*)(E + on + bj * 128);
; #pragma unroll
;                     for (int n = 0; n < 2; ++n) yb[cur ^ 1][bj][n] = *(const f32x4*)(Y + on + bj * 128 + 4 * n); } }
;             int row = row0 + ai * 128 + m * 16; asm volatile("" : "+v"(row)); const size_t off = (size_t)row * DM + c0;
;             const float mean = sb[cur].x * (1.f / DM); const float rstd = __builtin_amdgcn_rsqf(fmaxf(sb[cur].y * (1.f / DM) - mean * mean, 0.f) + LN_EPS);
; #pragma unroll
;             for (int bj = 0; bj < 2; ++bj)
; #pragma unroll
;                 for (int n = 0; n < 2; ++n) { const int cc = c0 + bj * 128 + 4 * n; const f32x4 gv = *(const f32x4*)(G + cc), bv = *(const f32x4*)(Bv + cc), gw = *(const f32x4*)(GW + cc), bw = *(const f32x4*)(GW + 1024 + cc);
;                     const unsigned e0 = eb[cur][bj][2 * n], e1 = eb[cur][bj][2 * n + 1]; const f32x4 ev = {lo_bf(e0), hi_bf(e0), lo_bf(e1), hi_bf(e1)};
;                     const f32x4 x2 = (yb[cur][bj][n] - mean) * rstd * gv + bv; const f32x4 a = (acc[ai][bj][m][n] - gw * mean) * rstd + bw; f32x4 o;
; #pragma unroll
;                     for (int i = 0; i < 4; ++i) o[i] = x2[i] + sigmoidf_(a[i]) * ev[i];
;                     *(f32x4*)(OUT + off + bj * 128 + 4 * n) = o; u32x2 w2; w2.x = pk2(o[0], o[1]); w2.y = pk2(o[2], o[3]);
;                     *(u32x2*)(XB + off + bj * 128 + 4 * n) = w2; } }
	v_pk_mul_f32 v[116:117], v[136:137], s[36:37] op_sel_hi:[1,0]
	v_pk_fma_f32 v[76:77], v[76:77], v[78:79], v[80:81]
	global_store_dwordx4 v[114:115], v[74:77], off offset:16
	v_pk_add_f32 v[94:95], v[94:95], v[116:117] op_sel_hi:[1,0] neg_lo:[0,1] neg_hi:[0,1]
	v_pk_add_f32 v[90:91], v[90:91], v[116:117] op_sel_hi:[1,0] neg_lo:[0,1] neg_hi:[0,1]
	v_cvt_pk_bf16_f32 v74, v74, v75
	v_cvt_pk_bf16_f32 v75, v76, v77
	global_store_dwordx2 v[138:139], v[74:75], off offset:8
	global_load_dwordx4 v[74:77], v[192:193], off offset:512
	s_nop 0
	global_load_dwordx4 v[78:81], v[208:209], off offset:512
	global_load_dwordx4 v[110:113], v[172:173], off
	global_load_dwordx4 v[122:125], v[174:175], off
	s_waitcnt vmcnt(0)
	v_pk_fma_f32 v[74:75], v[106:107], v[74:75], v[78:79]
	v_fma_f32 v70, -v140, v110, v70
	v_fma_f32 v71, -v140, v111, v71
	v_fma_f32 v70, v142, v70, v122
	v_fma_f32 v71, v142, v71, v123
	v_fma_f32 v72, -v140, v112, v72
	v_fma_f32 v73, -v140, v113, v73
	v_mul_f32_e32 v70, 0xbfb8aa3b, v70
	v_mul_f32_e32 v71, 0xbfb8aa3b, v71
	v_fma_f32 v72, v142, v72, v124
	v_fmac_f32_e32 v125, v142, v73
	v_exp_f32_e32 v70, v70
	v_exp_f32_e32 v71, v71
	v_mul_f32_e32 v72, 0xbfb8aa3b, v72
	v_mul_f32_e32 v73, 0xbfb8aa3b, v125
	v_exp_f32_e32 v72, v72
	v_exp_f32_e32 v73, v73
	v_add_f32_e32 v70, 1.0, v70
	v_add_f32_e32 v71, 1.0, v71
	v_rcp_f32_e32 v70, v70
	v_rcp_f32_e32 v71, v71
	v_add_f32_e32 v72, 1.0, v72
	v_add_f32_e32 v73, 1.0, v73
	v_rcp_f32_e32 v72, v72
	v_rcp_f32_e32 v73, v73
	v_pk_add_f32 v[78:79], v[108:109], v[140:141] op_sel_hi:[1,0] neg_lo:[0,1] neg_hi:[0,1]
	v_lshlrev_b32_e32 v110, 16, v98
	v_and_b32_e32 v111, 0xffff0000, v98
	v_pk_mul_f32 v[78:79], v[142:143], v[78:79] op_sel_hi:[0,1]
	v_pk_fma_f32 v[70:71], v[70:71], v[110:111], v[74:75]
	v_lshlrev_b32_e32 v74, 16, v99
	v_and_b32_e32 v75, 0xffff0000, v99
	v_pk_fma_f32 v[76:77], v[78:79], v[76:77], v[80:81]
	v_pk_add_f32 v[98:99], v[102:103], v[140:141] op_sel_hi:[1,0] neg_lo:[0,1] neg_hi:[0,1]
	v_pk_fma_f32 v[72:73], v[72:73], v[74:75], v[76:77]
	global_store_dwordx4 v[114:115], v[70:73], off offset:512
	v_pk_mul_f32 v[98:99], v[142:143], v[98:99] op_sel_hi:[0,1]
	v_add_u32_e32 v110, 0x90, v240
	v_cvt_pk_bf16_f32 v70, v70, v71
	v_cvt_pk_bf16_f32 v71, v72, v73
	global_store_dwordx2 v[138:139], v[70:71], off offset:256
	global_load_dwordx4 v[70:73], v[192:193], off offset:528
	s_nop 0
	global_load_dwordx4 v[74:77], v[208:209], off offset:528
	global_load_dwordx4 v[78:81], v[166:167], off
	global_load_dwordx4 v[106:109], v[168:169], off
	v_pk_add_f32 v[124:125], v[126:127], v[116:117] op_sel_hi:[1,0] neg_lo:[0,1] neg_hi:[0,1]
	s_waitcnt vmcnt(0)
	v_pk_fma_f32 v[70:71], v[98:99], v[70:71], v[74:75]
	v_fma_f32 v66, -v140, v78, v66
	v_fma_f32 v67, -v140, v79, v67
	v_fma_f32 v66, v142, v66, v106
	v_fma_f32 v67, v142, v67, v107
	v_fma_f32 v68, -v140, v80, v68
	v_fma_f32 v69, -v140, v81, v69
	v_mul_f32_e32 v66, 0xbfb8aa3b, v66
	v_mul_f32_e32 v67, 0xbfb8aa3b, v67
	v_fma_f32 v68, v142, v68, v108
	v_fmac_f32_e32 v109, v142, v69
	v_exp_f32_e32 v66, v66
	v_exp_f32_e32 v67, v67
	v_mul_f32_e32 v68, 0xbfb8aa3b, v68
	v_mul_f32_e32 v69, 0xbfb8aa3b, v109
	v_exp_f32_e32 v68, v68
	v_exp_f32_e32 v69, v69
	v_add_f32_e32 v66, 1.0, v66
	v_add_f32_e32 v67, 1.0, v67
	v_rcp_f32_e32 v66, v66
	v_rcp_f32_e32 v67, v67
	v_add_f32_e32 v68, 1.0, v68
	v_add_f32_e32 v69, 1.0, v69
	v_rcp_f32_e32 v68, v68
	v_rcp_f32_e32 v69, v69
	v_pk_add_f32 v[74:75], v[104:105], v[140:141] op_sel_hi:[1,0] neg_lo:[0,1] neg_hi:[0,1]
	v_lshlrev_b32_e32 v78, 16, v100
	v_and_b32_e32 v79, 0xffff0000, v100
	v_pk_mul_f32 v[74:75], v[142:143], v[74:75] op_sel_hi:[0,1]
	v_pk_fma_f32 v[66:67], v[66:67], v[78:79], v[70:71]
	v_lshlrev_b32_e32 v70, 16, v101
	v_and_b32_e32 v71, 0xffff0000, v101
	v_pk_fma_f32 v[72:73], v[74:75], v[72:73], v[76:77]
	v_fma_f32 v108, -v116, v116, v117
	v_pk_fma_f32 v[68:69], v[68:69], v[70:71], v[72:73]
	global_store_dwordx4 v[114:115], v[66:69], off offset:528
	v_max_f32_e32 v108, 0, v108
	v_add_f32_e32 v108, 0x3727c5ac, v108
	v_cvt_pk_bf16_f32 v66, v66, v67
	v_cvt_pk_bf16_f32 v67, v68, v69
	global_store_dwordx2 v[138:139], v[66:67], off offset:264
	v_mov_b32_e32 v66, v110
	v_rsq_f32_e32 v122, v108
	v_ashrrev_i32_e32 v67, 31, v66
	v_lshlrev_b64 v[68:69], 10, v[66:67]
	v_lshl_add_u64 v[68:69], v[68:69], 0, v[210:211]
	v_lshl_add_u64 v[66:67], v[66:67], 3, s[4:5]
	global_load_dwordx2 v[112:113], v[66:67], off
	v_lshl_add_u64 v[66:67], v[68:69], 1, vcc
	v_lshl_add_u64 v[70:71], v[68:69], 2, s[78:79]
	global_load_dwordx4 v[98:101], v[66:67], off
	global_load_dwordx4 v[102:105], v[70:71], off
	global_load_dwordx4 v[78:81], v[70:71], off offset:16
	s_nop 0
	global_load_dwordx4 v[66:69], v[66:67], off offset:256
	s_nop 0
	global_load_dwordx4 v[74:77], v[70:71], off offset:512
	s_nop 0
	global_load_dwordx4 v[70:73], v[70:71], off offset:528
	v_pk_mul_f32 v[124:125], v[124:125], v[122:123] op_sel_hi:[1,0]
	v_ashrrev_i32_e32 v135, 31, v134
	v_lshlrev_b64 v[106:107], 10, v[134:135]
	global_load_dwordx4 v[134:137], v[192:193], off
	global_load_dwordx4 v[138:141], v[208:209], off
	global_load_dwordx4 v[142:145], v[212:213], off
	global_load_dwordx4 v[146:149], v[214:215], off
	v_lshlrev_b32_e32 v108, 16, v118
	v_and_b32_e32 v109, 0xffff0000, v118
	v_lshl_add_u64 v[106:107], v[106:107], 0, v[210:211]
	v_lshl_add_u64 v[114:115], v[106:107], 1, s[76:77]
	v_pk_mul_f32 v[94:95], v[94:95], v[122:123] op_sel_hi:[1,0]
	v_pk_mul_f32 v[90:91], v[122:123], v[90:91] op_sel_hi:[0,1]
	s_waitcnt vmcnt(0)
; DI unsigned pk2(float lo, float hi) { f32x2 v = {lo, hi}; bf16x2_t b = __builtin_convertvector(v, bf16x2_t); return __builtin_bit_cast(unsigned, b); }
; DI float lo_bf(unsigned u) { return __uint_as_float(u << 16); }
; DI float hi_bf(unsigned u) { return __uint_as_float(u & 0xffff0000u); }
; DI float sigmoidf_(float x) { return __builtin_amdgcn_rcpf(1.f + __expf(-x)); }
;     DI void operator()(AccRef acc, const Unit& u, int wr, int wc, int fr, int fq) const {
;     ...
;             int row = row0 + ai * 128 + m * 16; asm volatile("" : "+v"(row)); const size_t off = (size_t)row * DM + c0;
;             const float mean = sb[cur].x * (1.f / DM); const float rstd = __builtin_amdgcn_rsqf(fmaxf(sb[cur].y * (1.f / DM) - mean * mean, 0.f) + LN_EPS);
; #pragma unroll
;             for (int bj = 0; bj < 2; ++bj)
; #pragma unroll
;                 for (int n = 0; n < 2; ++n) { const int cc = c0 + bj * 128 + 4 * n; const f32x4 gv = *(const f32x4*)(G + cc), bv = *(const f32x4*)(Bv + cc), gw = *(const f32x4*)(GW + cc), bw = *(const f32x4*)(GW + 1024 + cc);
;                     const unsigned e0 = eb[cur][bj][2 * n], e1 = eb[cur][bj][2 * n + 1]; const f32x4 ev = {lo_bf(e0), hi_bf(e0), lo_bf(e1), hi_bf(e1)};
;                     const f32x4 x2 = (yb[cur][bj][n] - mean) * rstd * gv + bv; const f32x4 a = (acc[ai][bj][m][n] - gw * mean) * rstd + bw; f32x4 o;
; #pragma unroll
;                     for (int i = 0; i < 4; ++i) o[i] = x2[i] + sigmoidf_(a[i]) * ev[i];
;                     *(f32x4*)(OUT + off + bj * 128 + 4 * n) = o; u32x2 w2; w2.x = pk2(o[0], o[1]); w2.y = pk2(o[2], o[3]);
;                     *(u32x2*)(XB + off + bj * 128 + 4 * n) = w2; } }
	v_pk_fma_f32 v[124:125], v[124:125], v[134:135], v[138:139]
	v_fma_f32 v62, -v116, v142, v62
	v_fma_f32 v63, -v116, v143, v63
	v_fma_f32 v62, v122, v62, v146
	v_fma_f32 v63, v122, v63, v147
	v_mul_f32_e32 v62, 0xbfb8aa3b, v62
	v_mul_f32_e32 v63, 0xbfb8aa3b, v63
	v_exp_f32_e32 v62, v62
	v_exp_f32_e32 v63, v63
	v_fma_f32 v64, -v116, v144, v64
	v_fma_f32 v65, -v116, v145, v65
	v_fma_f32 v64, v122, v64, v148
	v_fmac_f32_e32 v149, v122, v65
	v_mul_f32_e32 v64, 0xbfb8aa3b, v64
	v_mul_f32_e32 v65, 0xbfb8aa3b, v149
	v_exp_f32_e32 v64, v64
	v_exp_f32_e32 v65, v65
	v_add_f32_e32 v62, 1.0, v62
	v_add_f32_e32 v63, 1.0, v63
	v_rcp_f32_e32 v62, v62
	v_rcp_f32_e32 v63, v63
	v_add_f32_e32 v64, 1.0, v64
	v_add_f32_e32 v65, 1.0, v65
	v_rcp_f32_e32 v64, v64
	v_rcp_f32_e32 v65, v65
	v_pk_fma_f32 v[62:63], v[62:63], v[108:109], v[124:125]
	v_lshlrev_b32_e32 v108, 16, v119
	v_and_b32_e32 v109, 0xffff0000, v119
	v_pk_add_f32 v[118:119], v[128:129], v[116:117] op_sel_hi:[1,0] neg_lo:[0,1] neg_hi:[0,1]
	s_nop 0
	v_pk_mul_f32 v[118:119], v[118:119], v[122:123] op_sel_hi:[1,0]
	s_nop 0
	v_pk_fma_f32 v[118:119], v[118:119], v[136:137], v[140:141]
	s_nop 0
	v_pk_fma_f32 v[64:65], v[64:65], v[108:109], v[118:119]
	v_lshl_add_u64 v[118:119], v[106:107], 2, s[18:19]
	global_store_dwordx4 v[118:119], v[62:65], off
	s_nop 1
	v_cvt_pk_bf16_f32 v62, v62, v63
	v_cvt_pk_bf16_f32 v63, v64, v65
	global_store_dwordx2 v[114:115], v[62:63], off
	global_load_dwordx4 v[62:65], v[192:193], off offset:16
	s_nop 0
	global_load_dwordx4 v[106:109], v[208:209], off offset:16
	global_load_dwordx4 v[124:127], v[170:171], off
	global_load_dwordx4 v[134:137], v[216:217], off
	s_waitcnt vmcnt(0)
	v_pk_fma_f32 v[62:63], v[94:95], v[62:63], v[106:107]
	v_fma_f32 v58, -v116, v124, v58
	v_fma_f32 v59, -v116, v125, v59
	v_fma_f32 v58, v122, v58, v134
	v_fma_f32 v59, v122, v59, v135
	v_fma_f32 v60, -v116, v126, v60
	v_fma_f32 v61, -v116, v127, v61
	v_mul_f32_e32 v58, 0xbfb8aa3b, v58
	v_mul_f32_e32 v59, 0xbfb8aa3b, v59
	v_fma_f32 v60, v122, v60, v136
	v_fmac_f32_e32 v137, v122, v61
	v_exp_f32_e32 v58, v58
	v_exp_f32_e32 v59, v59
	v_mul_f32_e32 v60, 0xbfb8aa3b, v60
	v_mul_f32_e32 v61, 0xbfb8aa3b, v137
	v_exp_f32_e32 v60, v60
	v_exp_f32_e32 v61, v61
	v_add_f32_e32 v58, 1.0, v58
	v_add_f32_e32 v59, 1.0, v59
	v_rcp_f32_e32 v58, v58
	v_rcp_f32_e32 v59, v59
	v_add_f32_e32 v60, 1.0, v60
	v_add_f32_e32 v61, 1.0, v61
	v_rcp_f32_e32 v60, v60
	v_rcp_f32_e32 v61, v61
	v_pk_add_f32 v[94:95], v[96:97], v[116:117] op_sel_hi:[1,0] neg_lo:[0,1] neg_hi:[0,1]
	v_lshlrev_b32_e32 v124, 16, v120
	v_and_b32_e32 v125, 0xffff0000, v120
	v_pk_mul_f32 v[94:95], v[94:95], v[122:123] op_sel_hi:[1,0]
	v_pk_fma_f32 v[58:59], v[58:59], v[124:125], v[62:63]
	v_lshlrev_b32_e32 v62, 16, v121
	v_and_b32_e32 v63, 0xffff0000, v121
	v_pk_fma_f32 v[64:65], v[94:95], v[64:65], v[108:109]
	s_nop 0
	v_pk_fma_f32 v[60:61], v[60:61], v[62:63], v[64:65]
	global_store_dwordx4 v[118:119], v[58:61], off offset:16
	s_nop 1
	v_cvt_pk_bf16_f32 v58, v58, v59
	v_cvt_pk_bf16_f32 v59, v60, v61
	global_store_dwordx2 v[114:115], v[58:59], off offset:8
	global_load_dwordx4 v[58:61], v[192:193], off offset:512
	s_nop 0
	global_load_dwordx4 v[62:65], v[208:209], off offset:512
	global_load_dwordx4 v[94:97], v[172:173], off
	global_load_dwordx4 v[106:109], v[174:175], off
	s_waitcnt vmcnt(0)
	v_pk_fma_f32 v[58:59], v[90:91], v[58:59], v[62:63]
	v_fma_f32 v54, -v116, v94, v54
	v_fma_f32 v55, -v116, v95, v55
	v_fma_f32 v54, v122, v54, v106
	v_fma_f32 v55, v122, v55, v107
	v_fma_f32 v56, -v116, v96, v56
	v_fma_f32 v57, -v116, v97, v57
	v_mul_f32_e32 v54, 0xbfb8aa3b, v54
	v_mul_f32_e32 v55, 0xbfb8aa3b, v55
	v_fma_f32 v56, v122, v56, v108
	v_fmac_f32_e32 v109, v122, v57
	v_exp_f32_e32 v54, v54
	v_exp_f32_e32 v55, v55
	v_mul_f32_e32 v56, 0xbfb8aa3b, v56
	v_mul_f32_e32 v57, 0xbfb8aa3b, v109
	v_exp_f32_e32 v56, v56
	v_exp_f32_e32 v57, v57
	v_add_f32_e32 v54, 1.0, v54
	v_add_f32_e32 v55, 1.0, v55
	v_rcp_f32_e32 v54, v54
	v_rcp_f32_e32 v55, v55
	v_add_f32_e32 v56, 1.0, v56
	v_add_f32_e32 v57, 1.0, v57
	v_rcp_f32_e32 v56, v56
	v_rcp_f32_e32 v57, v57
	v_pk_add_f32 v[62:63], v[92:93], v[116:117] op_sel_hi:[1,0] neg_lo:[0,1] neg_hi:[0,1]
	v_lshlrev_b32_e32 v94, 16, v82
	v_and_b32_e32 v95, 0xffff0000, v82
	v_pk_mul_f32 v[62:63], v[122:123], v[62:63] op_sel_hi:[0,1]
	v_pk_fma_f32 v[54:55], v[54:55], v[94:95], v[58:59]
	v_lshlrev_b32_e32 v58, 16, v83
	v_and_b32_e32 v59, 0xffff0000, v83
	v_pk_fma_f32 v[60:61], v[62:63], v[60:61], v[64:65]
	v_pk_add_f32 v[82:83], v[86:87], v[116:117] op_sel_hi:[1,0] neg_lo:[0,1] neg_hi:[0,1]
	v_pk_fma_f32 v[56:57], v[56:57], v[58:59], v[60:61]
	global_store_dwordx4 v[118:119], v[54:57], off offset:512
	v_pk_mul_f32 v[82:83], v[122:123], v[82:83] op_sel_hi:[0,1]
	v_add_u32_e32 v94, 0xa0, v240
	v_cvt_pk_bf16_f32 v54, v54, v55
	v_cvt_pk_bf16_f32 v55, v56, v57
	global_store_dwordx2 v[114:115], v[54:55], off offset:256
	global_load_dwordx4 v[54:57], v[192:193], off offset:528
	s_nop 0
	global_load_dwordx4 v[58:61], v[208:209], off offset:528
	global_load_dwordx4 v[62:65], v[166:167], off
	global_load_dwordx4 v[90:93], v[168:169], off
	s_waitcnt lgkmcnt(0)
	v_pk_mul_f32 v[108:109], v[112:113], s[36:37] op_sel_hi:[1,0]
	s_waitcnt vmcnt(0)
; DI unsigned pk2(float lo, float hi) { f32x2 v = {lo, hi}; bf16x2_t b = __builtin_convertvector(v, bf16x2_t); return __builtin_bit_cast(unsigned, b); }
; DI float lo_bf(unsigned u) { return __uint_as_float(u << 16); }
; DI float hi_bf(unsigned u) { return __uint_as_float(u & 0xffff0000u); }
; DI float sigmoidf_(float x) { return __builtin_amdgcn_rcpf(1.f + __expf(-x)); }
;     DI void operator()(AccRef acc, const Unit& u, int wr, int wc, int fr, int fq) const {
;     ...
;         for (int it = 0; it < 8; ++it) { const int ai = it >> 2, m = it & 3, cur = it & 1;
;             if (it + 1 < 8) { int rn_ = row0 + ((it + 1) >> 2) * 128 + ((it + 1) & 3) * 16; asm volatile("" : "+v"(rn_) :: "memory"); const size_t on = (size_t)rn_ * DM + c0; sb[cur ^ 1] = *(const f32x2*)(ST + (size_t)rn_ * 2);
; #pragma unroll
;                 for (int bj = 0; bj < 2; ++bj) { eb[cur ^ 1][bj] = *(const u32x4*)(E + on + bj * 128);
; #pragma unroll
;                     for (int n = 0; n < 2; ++n) yb[cur ^ 1][bj][n] = *(const f32x4*)(Y + on + bj * 128 + 4 * n); } }
;             int row = row0 + ai * 128 + m * 16; asm volatile("" : "+v"(row)); const size_t off = (size_t)row * DM + c0;
;             const float mean = sb[cur].x * (1.f / DM); const float rstd = __builtin_amdgcn_rsqf(fmaxf(sb[cur].y * (1.f / DM) - mean * mean, 0.f) + LN_EPS);
; #pragma unroll
;             for (int bj = 0; bj < 2; ++bj)
; #pragma unroll
;                 for (int n = 0; n < 2; ++n) { const int cc = c0 + bj * 128 + 4 * n; const f32x4 gv = *(const f32x4*)(G + cc), bv = *(const f32x4*)(Bv + cc), gw = *(const f32x4*)(GW + cc), bw = *(const f32x4*)(GW + 1024 + cc);
;                     const unsigned e0 = eb[cur][bj][2 * n], e1 = eb[cur][bj][2 * n + 1]; const f32x4 ev = {lo_bf(e0), hi_bf(e0), lo_bf(e1), hi_bf(e1)};
;                     const f32x4 x2 = (yb[cur][bj][n] - mean) * rstd * gv + bv; const f32x4 a = (acc[ai][bj][m][n] - gw * mean) * rstd + bw; f32x4 o;
; #pragma unroll
;                     for (int i = 0; i < 4; ++i) o[i] = x2[i] + sigmoidf_(a[i]) * ev[i];
;                     *(f32x4*)(OUT + off + bj * 128 + 4 * n) = o; u32x2 w2; w2.x = pk2(o[0], o[1]); w2.y = pk2(o[2], o[3]);
;                     *(u32x2*)(XB + off + bj * 128 + 4 * n) = w2; } }
	v_pk_fma_f32 v[54:55], v[82:83], v[54:55], v[58:59]
	v_fma_f32 v50, -v116, v62, v50
	v_fma_f32 v51, -v116, v63, v51
	v_fma_f32 v50, v122, v50, v90
	v_fma_f32 v51, v122, v51, v91
	v_fma_f32 v52, -v116, v64, v52
	v_fma_f32 v53, -v116, v65, v53
	v_mul_f32_e32 v50, 0xbfb8aa3b, v50
	v_mul_f32_e32 v51, 0xbfb8aa3b, v51
	v_fma_f32 v52, v122, v52, v92
	v_fmac_f32_e32 v93, v122, v53
	v_exp_f32_e32 v50, v50
	v_exp_f32_e32 v51, v51
	v_mul_f32_e32 v52, 0xbfb8aa3b, v52
	v_mul_f32_e32 v53, 0xbfb8aa3b, v93
	v_exp_f32_e32 v52, v52
	v_exp_f32_e32 v53, v53
	v_add_f32_e32 v50, 1.0, v50
	v_add_f32_e32 v51, 1.0, v51
	v_rcp_f32_e32 v50, v50
	v_rcp_f32_e32 v51, v51
	v_add_f32_e32 v52, 1.0, v52
	v_add_f32_e32 v53, 1.0, v53
	v_rcp_f32_e32 v52, v52
	v_rcp_f32_e32 v53, v53
	v_pk_add_f32 v[58:59], v[88:89], v[116:117] op_sel_hi:[1,0] neg_lo:[0,1] neg_hi:[0,1]
	v_lshlrev_b32_e32 v62, 16, v84
	v_and_b32_e32 v63, 0xffff0000, v84
	v_pk_mul_f32 v[58:59], v[122:123], v[58:59] op_sel_hi:[0,1]
	v_pk_fma_f32 v[50:51], v[50:51], v[62:63], v[54:55]
	v_lshlrev_b32_e32 v54, 16, v85
	v_and_b32_e32 v55, 0xffff0000, v85
	v_pk_fma_f32 v[56:57], v[58:59], v[56:57], v[60:61]
	v_fma_f32 v92, -v108, v108, v109
	v_pk_fma_f32 v[52:53], v[52:53], v[54:55], v[56:57]
	global_store_dwordx4 v[118:119], v[50:53], off offset:528
	v_max_f32_e32 v92, 0, v92
	v_add_f32_e32 v92, 0x3727c5ac, v92
	v_cvt_pk_bf16_f32 v50, v50, v51
	v_cvt_pk_bf16_f32 v51, v52, v53
	global_store_dwordx2 v[114:115], v[50:51], off offset:264
	v_mov_b32_e32 v50, v94
	v_pk_add_f32 v[102:103], v[102:103], v[108:109] op_sel_hi:[1,0] neg_lo:[0,1] neg_hi:[0,1]
	v_ashrrev_i32_e32 v51, 31, v50
	v_lshlrev_b64 v[52:53], 10, v[50:51]
	v_lshl_add_u64 v[52:53], v[52:53], 0, v[210:211]
	v_lshl_add_u64 v[50:51], v[50:51], 3, s[4:5]
	global_load_dwordx2 v[96:97], v[50:51], off
	v_lshl_add_u64 v[50:51], v[52:53], 1, vcc
	v_lshl_add_u64 v[54:55], v[52:53], 2, s[78:79]
	global_load_dwordx4 v[82:85], v[50:51], off
	global_load_dwordx4 v[86:89], v[54:55], off
	global_load_dwordx4 v[62:65], v[54:55], off offset:16
	s_nop 0
	global_load_dwordx4 v[50:53], v[50:51], off offset:256
	s_nop 0
	global_load_dwordx4 v[58:61], v[54:55], off offset:512
	s_nop 0
	global_load_dwordx4 v[54:57], v[54:55], off offset:528
	global_load_dwordx4 v[112:115], v[192:193], off
	global_load_dwordx4 v[116:119], v[208:209], off
	global_load_dwordx4 v[120:123], v[212:213], off
	global_load_dwordx4 v[124:127], v[214:215], off
	v_ashrrev_i32_e32 v111, 31, v110
	v_lshlrev_b64 v[90:91], 10, v[110:111]
	v_rsq_f32_e32 v110, v92
	v_lshlrev_b32_e32 v92, 16, v98
	v_and_b32_e32 v93, 0xffff0000, v98
	v_lshl_add_u64 v[90:91], v[90:91], 0, v[210:211]
	v_pk_mul_f32 v[102:103], v[102:103], v[110:111] op_sel_hi:[1,0]
	v_lshl_add_u64 v[106:107], v[90:91], 1, s[76:77]
	v_pk_add_f32 v[78:79], v[78:79], v[108:109] op_sel_hi:[1,0] neg_lo:[0,1] neg_hi:[0,1]
	v_pk_add_f32 v[74:75], v[74:75], v[108:109] op_sel_hi:[1,0] neg_lo:[0,1] neg_hi:[0,1]
	v_pk_mul_f32 v[78:79], v[78:79], v[110:111] op_sel_hi:[1,0]
	v_pk_mul_f32 v[74:75], v[110:111], v[74:75] op_sel_hi:[0,1]
	s_waitcnt vmcnt(0)
	v_pk_fma_f32 v[102:103], v[102:103], v[112:113], v[116:117]
	v_fma_f32 v46, -v108, v120, v46
	v_fma_f32 v47, -v108, v121, v47
	v_fma_f32 v46, v110, v46, v124
	v_fma_f32 v47, v110, v47, v125
	v_mul_f32_e32 v46, 0xbfb8aa3b, v46
	v_mul_f32_e32 v47, 0xbfb8aa3b, v47
	v_exp_f32_e32 v46, v46
	v_exp_f32_e32 v47, v47
	v_fma_f32 v48, -v108, v122, v48
	v_fma_f32 v49, -v108, v123, v49
	v_fma_f32 v48, v110, v48, v126
	v_fmac_f32_e32 v127, v110, v49
	v_mul_f32_e32 v48, 0xbfb8aa3b, v48
	v_mul_f32_e32 v49, 0xbfb8aa3b, v127
	v_exp_f32_e32 v48, v48
	v_exp_f32_e32 v49, v49
	v_add_f32_e32 v46, 1.0, v46
	v_add_f32_e32 v47, 1.0, v47
	v_rcp_f32_e32 v46, v46
	v_rcp_f32_e32 v47, v47
	v_add_f32_e32 v48, 1.0, v48
	v_add_f32_e32 v49, 1.0, v49
	v_rcp_f32_e32 v48, v48
	v_rcp_f32_e32 v49, v49
	v_pk_fma_f32 v[46:47], v[46:47], v[92:93], v[102:103]
	v_lshlrev_b32_e32 v92, 16, v99
	v_and_b32_e32 v93, 0xffff0000, v99
	v_pk_add_f32 v[98:99], v[104:105], v[108:109] op_sel_hi:[1,0] neg_lo:[0,1] neg_hi:[0,1]
	s_nop 0
	v_pk_mul_f32 v[98:99], v[98:99], v[110:111] op_sel_hi:[1,0]
	s_nop 0
	v_pk_fma_f32 v[98:99], v[98:99], v[114:115], v[118:119]
	s_nop 0
	v_pk_fma_f32 v[48:49], v[48:49], v[92:93], v[98:99]
	v_lshl_add_u64 v[98:99], v[90:91], 2, s[18:19]
	global_store_dwordx4 v[98:99], v[46:49], off
	s_nop 1
	v_cvt_pk_bf16_f32 v46, v46, v47
	v_cvt_pk_bf16_f32 v47, v48, v49
	global_store_dwordx2 v[106:107], v[46:47], off
	global_load_dwordx4 v[46:49], v[192:193], off offset:16
	s_nop 0
	global_load_dwordx4 v[90:93], v[208:209], off offset:16
	global_load_dwordx4 v[102:105], v[170:171], off
	global_load_dwordx4 v[112:115], v[216:217], off
	s_waitcnt vmcnt(0)
	v_pk_fma_f32 v[46:47], v[78:79], v[46:47], v[90:91]
	v_fma_f32 v42, -v108, v102, v42
	v_fma_f32 v43, -v108, v103, v43
	v_fma_f32 v42, v110, v42, v112
	v_fma_f32 v43, v110, v43, v113
	v_fma_f32 v44, -v108, v104, v44
	v_fma_f32 v45, -v108, v105, v45
	v_mul_f32_e32 v42, 0xbfb8aa3b, v42
	v_mul_f32_e32 v43, 0xbfb8aa3b, v43
	v_fma_f32 v44, v110, v44, v114
	v_fmac_f32_e32 v115, v110, v45
	v_exp_f32_e32 v42, v42
	v_exp_f32_e32 v43, v43
	v_mul_f32_e32 v44, 0xbfb8aa3b, v44
	v_mul_f32_e32 v45, 0xbfb8aa3b, v115
	v_exp_f32_e32 v44, v44
	v_exp_f32_e32 v45, v45
	v_add_f32_e32 v42, 1.0, v42
	v_add_f32_e32 v43, 1.0, v43
	v_rcp_f32_e32 v42, v42
	v_rcp_f32_e32 v43, v43
	v_add_f32_e32 v44, 1.0, v44
	v_add_f32_e32 v45, 1.0, v45
	v_rcp_f32_e32 v44, v44
	v_rcp_f32_e32 v45, v45
	v_pk_add_f32 v[78:79], v[80:81], v[108:109] op_sel_hi:[1,0] neg_lo:[0,1] neg_hi:[0,1]
	v_lshlrev_b32_e32 v102, 16, v100
	v_and_b32_e32 v103, 0xffff0000, v100
	v_pk_mul_f32 v[78:79], v[78:79], v[110:111] op_sel_hi:[1,0]
	v_pk_fma_f32 v[42:43], v[42:43], v[102:103], v[46:47]
	v_lshlrev_b32_e32 v46, 16, v101
	v_and_b32_e32 v47, 0xffff0000, v101
	v_pk_fma_f32 v[48:49], v[78:79], v[48:49], v[92:93]
	s_nop 0
	v_pk_fma_f32 v[44:45], v[44:45], v[46:47], v[48:49]
	global_store_dwordx4 v[98:99], v[42:45], off offset:16
	s_nop 1
	v_cvt_pk_bf16_f32 v42, v42, v43
	v_cvt_pk_bf16_f32 v43, v44, v45
	global_store_dwordx2 v[106:107], v[42:43], off offset:8
	global_load_dwordx4 v[42:45], v[192:193], off offset:512
	s_nop 0
	global_load_dwordx4 v[46:49], v[208:209], off offset:512
	global_load_dwordx4 v[78:81], v[172:173], off
	global_load_dwordx4 v[90:93], v[174:175], off
	s_waitcnt vmcnt(0)
; DI unsigned pk2(float lo, float hi) { f32x2 v = {lo, hi}; bf16x2_t b = __builtin_convertvector(v, bf16x2_t); return __builtin_bit_cast(unsigned, b); }
; DI float lo_bf(unsigned u) { return __uint_as_float(u << 16); }
; DI float hi_bf(unsigned u) { return __uint_as_float(u & 0xffff0000u); }
; DI float sigmoidf_(float x) { return __builtin_amdgcn_rcpf(1.f + __expf(-x)); }
;     DI void operator()(AccRef acc, const Unit& u, int wr, int wc, int fr, int fq) const {
;     ...
;         for (int it = 0; it < 8; ++it) { const int ai = it >> 2, m = it & 3, cur = it & 1;
;             if (it + 1 < 8) { int rn_ = row0 + ((it + 1) >> 2) * 128 + ((it + 1) & 3) * 16; asm volatile("" : "+v"(rn_) :: "memory"); const size_t on = (size_t)rn_ * DM + c0; sb[cur ^ 1] = *(const f32x2*)(ST + (size_t)rn_ * 2);
; #pragma unroll
;                 for (int bj = 0; bj < 2; ++bj) { eb[cur ^ 1][bj] = *(const u32x4*)(E + on + bj * 128);
; #pragma unroll
;                     for (int n = 0; n < 2; ++n) yb[cur ^ 1][bj][n] = *(const f32x4*)(Y + on + bj * 128 + 4 * n); } }
;             int row = row0 + ai * 128 + m * 16; asm volatile("" : "+v"(row)); const size_t off = (size_t)row * DM + c0;
;             const float mean = sb[cur].x * (1.f / DM); const float rstd = __builtin_amdgcn_rsqf(fmaxf(sb[cur].y * (1.f / DM) - mean * mean, 0.f) + LN_EPS);
; #pragma unroll
;             for (int bj = 0; bj < 2; ++bj)
; #pragma unroll
;                 for (int n = 0; n < 2; ++n) { const int cc = c0 + bj * 128 + 4 * n; const f32x4 gv = *(const f32x4*)(G + cc), bv = *(const f32x4*)(Bv + cc), gw = *(const f32x4*)(GW + cc), bw = *(const f32x4*)(GW + 1024 + cc);
;                     const unsigned e0 = eb[cur][bj][2 * n], e1 = eb[cur][bj][2 * n + 1]; const f32x4 ev = {lo_bf(e0), hi_bf(e0), lo_bf(e1), hi_bf(e1)};
;                     const f32x4 x2 = (yb[cur][bj][n] - mean) * rstd * gv + bv; const f32x4 a = (acc[ai][bj][m][n] - gw * mean) * rstd + bw; f32x4 o;
; #pragma unroll
;                     for (int i = 0; i < 4; ++i) o[i] = x2[i] + sigmoidf_(a[i]) * ev[i];
;                     *(f32x4*)(OUT + off + bj * 128 + 4 * n) = o; u32x2 w2; w2.x = pk2(o[0], o[1]); w2.y = pk2(o[2], o[3]);
;                     *(u32x2*)(XB + off + bj * 128 + 4 * n) = w2; } }
	v_pk_fma_f32 v[42:43], v[74:75], v[42:43], v[46:47]
	v_fma_f32 v38, -v108, v78, v38
	v_fma_f32 v39, -v108, v79, v39
	v_fma_f32 v38, v110, v38, v90
	v_fma_f32 v39, v110, v39, v91
	v_fma_f32 v40, -v108, v80, v40
	v_fma_f32 v41, -v108, v81, v41
	v_mul_f32_e32 v38, 0xbfb8aa3b, v38
	v_mul_f32_e32 v39, 0xbfb8aa3b, v39
	v_fma_f32 v40, v110, v40, v92
	v_fmac_f32_e32 v93, v110, v41
	v_exp_f32_e32 v38, v38
	v_exp_f32_e32 v39, v39
	v_mul_f32_e32 v40, 0xbfb8aa3b, v40
	v_mul_f32_e32 v41, 0xbfb8aa3b, v93
	v_exp_f32_e32 v40, v40
	v_exp_f32_e32 v41, v41
	v_add_f32_e32 v38, 1.0, v38
	v_add_f32_e32 v39, 1.0, v39
	v_rcp_f32_e32 v38, v38
	v_rcp_f32_e32 v39, v39
	v_add_f32_e32 v40, 1.0, v40
	v_add_f32_e32 v41, 1.0, v41
	v_rcp_f32_e32 v40, v40
	v_rcp_f32_e32 v41, v41
	v_pk_add_f32 v[46:47], v[76:77], v[108:109] op_sel_hi:[1,0] neg_lo:[0,1] neg_hi:[0,1]
	v_lshlrev_b32_e32 v78, 16, v66
	v_and_b32_e32 v79, 0xffff0000, v66
	v_pk_mul_f32 v[46:47], v[110:111], v[46:47] op_sel_hi:[0,1]
	v_pk_fma_f32 v[38:39], v[38:39], v[78:79], v[42:43]
	v_lshlrev_b32_e32 v42, 16, v67
	v_and_b32_e32 v43, 0xffff0000, v67
	v_pk_fma_f32 v[44:45], v[46:47], v[44:45], v[48:49]
	v_pk_add_f32 v[66:67], v[70:71], v[108:109] op_sel_hi:[1,0] neg_lo:[0,1] neg_hi:[0,1]
	v_pk_fma_f32 v[40:41], v[40:41], v[42:43], v[44:45]
	global_store_dwordx4 v[98:99], v[38:41], off offset:512
	v_pk_mul_f32 v[66:67], v[110:111], v[66:67] op_sel_hi:[0,1]
	v_add_u32_e32 v78, 0xb0, v240
	v_cvt_pk_bf16_f32 v38, v38, v39
	v_cvt_pk_bf16_f32 v39, v40, v41
	global_store_dwordx2 v[106:107], v[38:39], off offset:256
	global_load_dwordx4 v[38:41], v[192:193], off offset:528
	s_nop 0
	global_load_dwordx4 v[42:45], v[208:209], off offset:528
	global_load_dwordx4 v[46:49], v[166:167], off
	global_load_dwordx4 v[74:77], v[168:169], off
	s_waitcnt vmcnt(0)
	v_pk_fma_f32 v[38:39], v[66:67], v[38:39], v[42:43]
	v_fma_f32 v34, -v108, v46, v34
	v_fma_f32 v35, -v108, v47, v35
	v_fma_f32 v34, v110, v34, v74
	v_fma_f32 v35, v110, v35, v75
	v_fma_f32 v36, -v108, v48, v36
	v_fma_f32 v37, -v108, v49, v37
	v_mul_f32_e32 v34, 0xbfb8aa3b, v34
	v_mul_f32_e32 v35, 0xbfb8aa3b, v35
	v_fma_f32 v36, v110, v36, v76
	v_fmac_f32_e32 v77, v110, v37
	v_exp_f32_e32 v34, v34
	v_exp_f32_e32 v35, v35
	v_mul_f32_e32 v36, 0xbfb8aa3b, v36
	v_mul_f32_e32 v37, 0xbfb8aa3b, v77
	v_exp_f32_e32 v36, v36
	v_exp_f32_e32 v37, v37
	v_add_f32_e32 v34, 1.0, v34
	v_add_f32_e32 v35, 1.0, v35
	v_rcp_f32_e32 v34, v34
	v_rcp_f32_e32 v35, v35
	v_add_f32_e32 v36, 1.0, v36
	v_add_f32_e32 v37, 1.0, v37
	v_rcp_f32_e32 v36, v36
	v_rcp_f32_e32 v37, v37
	v_pk_add_f32 v[42:43], v[72:73], v[108:109] op_sel_hi:[1,0] neg_lo:[0,1] neg_hi:[0,1]
	v_lshlrev_b32_e32 v46, 16, v68
	v_and_b32_e32 v47, 0xffff0000, v68
	v_pk_mul_f32 v[42:43], v[110:111], v[42:43] op_sel_hi:[0,1]
	v_pk_fma_f32 v[34:35], v[34:35], v[46:47], v[38:39]
	v_lshlrev_b32_e32 v38, 16, v69
	v_and_b32_e32 v39, 0xffff0000, v69
	v_pk_fma_f32 v[40:41], v[42:43], v[40:41], v[44:45]
	s_waitcnt lgkmcnt(0)
	v_and_b32_e32 v77, 0xffff0000, v82
	v_pk_fma_f32 v[36:37], v[36:37], v[38:39], v[40:41]
	global_store_dwordx4 v[98:99], v[34:37], off offset:528
	s_nop 1
	v_cvt_pk_bf16_f32 v34, v34, v35
	v_cvt_pk_bf16_f32 v35, v36, v37
	global_store_dwordx2 v[106:107], v[34:35], off offset:264
	v_mov_b32_e32 v34, v78
	s_nop 0
	v_ashrrev_i32_e32 v35, 31, v34
	v_lshlrev_b64 v[36:37], 10, v[34:35]
	v_lshl_add_u64 v[36:37], v[36:37], 0, v[210:211]
	v_lshl_add_u64 v[34:35], v[34:35], 3, s[4:5]
	global_load_dwordx2 v[80:81], v[34:35], off
	v_lshl_add_u64 v[34:35], v[36:37], 1, vcc
	v_lshl_add_u64 v[38:39], v[36:37], 2, s[78:79]
	global_load_dwordx4 v[66:69], v[34:35], off
	global_load_dwordx4 v[70:73], v[38:39], off
	global_load_dwordx4 v[46:49], v[38:39], off offset:16
	s_nop 0
	global_load_dwordx4 v[34:37], v[34:35], off offset:256
	s_nop 0
	global_load_dwordx4 v[42:45], v[38:39], off offset:512
	s_nop 0
	global_load_dwordx4 v[38:41], v[38:39], off offset:528
	s_mov_b64 s[4:5], -1
	v_ashrrev_i32_e32 v95, 31, v94
	v_lshlrev_b64 v[74:75], 10, v[94:95]
	v_pk_mul_f32 v[94:95], v[96:97], s[36:37] op_sel_hi:[1,0]
	global_load_dwordx4 v[96:99], v[192:193], off
	global_load_dwordx4 v[100:103], v[208:209], off
	global_load_dwordx4 v[104:107], v[212:213], off
	global_load_dwordx4 v[108:111], v[214:215], off
	v_fma_f32 v76, -v94, v94, v95
	v_max_f32_e32 v76, 0, v76
	v_add_f32_e32 v76, 0x3727c5ac, v76
	v_rsq_f32_e32 v92, v76
	v_pk_add_f32 v[86:87], v[86:87], v[94:95] op_sel_hi:[1,0] neg_lo:[0,1] neg_hi:[0,1]
	v_lshlrev_b32_e32 v76, 16, v82
	v_lshl_add_u64 v[74:75], v[74:75], 0, v[210:211]
	v_pk_mul_f32 v[86:87], v[86:87], v[92:93] op_sel_hi:[1,0]
	v_lshl_add_u64 v[90:91], v[74:75], 1, s[76:77]
	v_pk_add_f32 v[62:63], v[62:63], v[94:95] op_sel_hi:[1,0] neg_lo:[0,1] neg_hi:[0,1]
	v_pk_add_f32 v[58:59], v[58:59], v[94:95] op_sel_hi:[1,0] neg_lo:[0,1] neg_hi:[0,1]
	v_pk_mul_f32 v[62:63], v[62:63], v[92:93] op_sel_hi:[1,0]
	v_pk_mul_f32 v[58:59], v[92:93], v[58:59] op_sel_hi:[0,1]
	s_and_b64 vcc, exec, s[40:41]
	s_waitcnt vmcnt(0)
; DI unsigned pk2(float lo, float hi) { f32x2 v = {lo, hi}; bf16x2_t b = __builtin_convertvector(v, bf16x2_t); return __builtin_bit_cast(unsigned, b); }
; DI float lo_bf(unsigned u) { return __uint_as_float(u << 16); }
; DI float hi_bf(unsigned u) { return __uint_as_float(u & 0xffff0000u); }
; DI float sigmoidf_(float x) { return __builtin_amdgcn_rcpf(1.f + __expf(-x)); }
;     DI void operator()(AccRef acc, const Unit& u, int wr, int wc, int fr, int fq) const {
;     ...
;             int row = row0 + ai * 128 + m * 16; asm volatile("" : "+v"(row)); const size_t off = (size_t)row * DM + c0;
;             const float mean = sb[cur].x * (1.f / DM); const float rstd = __builtin_amdgcn_rsqf(fmaxf(sb[cur].y * (1.f / DM) - mean * mean, 0.f) + LN_EPS);
; #pragma unroll
;             for (int bj = 0; bj < 2; ++bj)
; #pragma unroll
;                 for (int n = 0; n < 2; ++n) { const int cc = c0 + bj * 128 + 4 * n; const f32x4 gv = *(const f32x4*)(G + cc), bv = *(const f32x4*)(Bv + cc), gw = *(const f32x4*)(GW + cc), bw = *(const f32x4*)(GW + 1024 + cc);
;                     const unsigned e0 = eb[cur][bj][2 * n], e1 = eb[cur][bj][2 * n + 1]; const f32x4 ev = {lo_bf(e0), hi_bf(e0), lo_bf(e1), hi_bf(e1)};
;                     const f32x4 x2 = (yb[cur][bj][n] - mean) * rstd * gv + bv; const f32x4 a = (acc[ai][bj][m][n] - gw * mean) * rstd + bw; f32x4 o;
; #pragma unroll
;                     for (int i = 0; i < 4; ++i) o[i] = x2[i] + sigmoidf_(a[i]) * ev[i];
;                     *(f32x4*)(OUT + off + bj * 128 + 4 * n) = o; u32x2 w2; w2.x = pk2(o[0], o[1]); w2.y = pk2(o[2], o[3]);
;                     *(u32x2*)(XB + off + bj * 128 + 4 * n) = w2; } }
	v_pk_fma_f32 v[86:87], v[86:87], v[96:97], v[100:101]
	v_fma_f32 v30, -v94, v104, v30
	v_fma_f32 v31, -v94, v105, v31
	v_fma_f32 v30, v92, v30, v108
	v_fma_f32 v31, v92, v31, v109
	v_mul_f32_e32 v30, 0xbfb8aa3b, v30
	v_mul_f32_e32 v31, 0xbfb8aa3b, v31
	v_exp_f32_e32 v30, v30
	v_exp_f32_e32 v31, v31
	v_fma_f32 v32, -v94, v106, v32
	v_fma_f32 v33, -v94, v107, v33
	v_fma_f32 v32, v92, v32, v110
	v_fmac_f32_e32 v111, v92, v33
	v_mul_f32_e32 v32, 0xbfb8aa3b, v32
	v_mul_f32_e32 v33, 0xbfb8aa3b, v111
	v_exp_f32_e32 v32, v32
	v_exp_f32_e32 v33, v33
	v_add_f32_e32 v30, 1.0, v30
	v_add_f32_e32 v31, 1.0, v31
	v_rcp_f32_e32 v30, v30
	v_rcp_f32_e32 v31, v31
	v_add_f32_e32 v32, 1.0, v32
	v_add_f32_e32 v33, 1.0, v33
	v_rcp_f32_e32 v32, v32
	v_rcp_f32_e32 v33, v33
	v_pk_fma_f32 v[30:31], v[30:31], v[76:77], v[86:87]
	v_lshlrev_b32_e32 v76, 16, v83
	v_and_b32_e32 v77, 0xffff0000, v83
	v_pk_add_f32 v[82:83], v[88:89], v[94:95] op_sel_hi:[1,0] neg_lo:[0,1] neg_hi:[0,1]
	s_nop 0
	v_pk_mul_f32 v[82:83], v[82:83], v[92:93] op_sel_hi:[1,0]
	s_nop 0
	v_pk_fma_f32 v[82:83], v[82:83], v[98:99], v[102:103]
	s_nop 0
	v_pk_fma_f32 v[32:33], v[32:33], v[76:77], v[82:83]
	v_lshl_add_u64 v[82:83], v[74:75], 2, s[18:19]
	global_store_dwordx4 v[82:83], v[30:33], off
	s_nop 1
	v_cvt_pk_bf16_f32 v30, v30, v31
	v_cvt_pk_bf16_f32 v31, v32, v33
	global_store_dwordx2 v[90:91], v[30:31], off
	global_load_dwordx4 v[30:33], v[192:193], off offset:16
	s_nop 0
	global_load_dwordx4 v[74:77], v[208:209], off offset:16
	global_load_dwordx4 v[86:89], v[170:171], off
	global_load_dwordx4 v[96:99], v[216:217], off
	s_waitcnt vmcnt(0)
	v_pk_fma_f32 v[30:31], v[62:63], v[30:31], v[74:75]
	v_fma_f32 v26, -v94, v86, v26
	v_fma_f32 v27, -v94, v87, v27
	v_fma_f32 v26, v92, v26, v96
	v_fma_f32 v27, v92, v27, v97
	v_fma_f32 v28, -v94, v88, v28
	v_fma_f32 v29, -v94, v89, v29
	v_mul_f32_e32 v26, 0xbfb8aa3b, v26
	v_mul_f32_e32 v27, 0xbfb8aa3b, v27
	v_fma_f32 v28, v92, v28, v98
	v_fmac_f32_e32 v99, v92, v29
	v_exp_f32_e32 v26, v26
	v_exp_f32_e32 v27, v27
	v_mul_f32_e32 v28, 0xbfb8aa3b, v28
	v_mul_f32_e32 v29, 0xbfb8aa3b, v99
	v_exp_f32_e32 v28, v28
	v_exp_f32_e32 v29, v29
	v_add_f32_e32 v26, 1.0, v26
	v_add_f32_e32 v27, 1.0, v27
	v_rcp_f32_e32 v26, v26
	v_rcp_f32_e32 v27, v27
	v_add_f32_e32 v28, 1.0, v28
	v_add_f32_e32 v29, 1.0, v29
	v_rcp_f32_e32 v28, v28
	v_rcp_f32_e32 v29, v29
	v_pk_add_f32 v[62:63], v[64:65], v[94:95] op_sel_hi:[1,0] neg_lo:[0,1] neg_hi:[0,1]
	v_lshlrev_b32_e32 v86, 16, v84
	v_and_b32_e32 v87, 0xffff0000, v84
	v_pk_mul_f32 v[62:63], v[62:63], v[92:93] op_sel_hi:[1,0]
	v_pk_fma_f32 v[26:27], v[26:27], v[86:87], v[30:31]
	v_lshlrev_b32_e32 v30, 16, v85
	v_and_b32_e32 v31, 0xffff0000, v85
	v_pk_fma_f32 v[32:33], v[62:63], v[32:33], v[76:77]
	s_nop 0
	v_pk_fma_f32 v[28:29], v[28:29], v[30:31], v[32:33]
	global_store_dwordx4 v[82:83], v[26:29], off offset:16
	s_nop 1
	v_cvt_pk_bf16_f32 v26, v26, v27
	v_cvt_pk_bf16_f32 v27, v28, v29
	global_store_dwordx2 v[90:91], v[26:27], off offset:8
	global_load_dwordx4 v[26:29], v[192:193], off offset:512
	s_nop 0
	global_load_dwordx4 v[30:33], v[208:209], off offset:512
	global_load_dwordx4 v[62:65], v[172:173], off
	global_load_dwordx4 v[74:77], v[174:175], off
	s_waitcnt vmcnt(0)
	v_pk_fma_f32 v[26:27], v[58:59], v[26:27], v[30:31]
	v_fma_f32 v22, -v94, v62, v22
	v_fma_f32 v23, -v94, v63, v23
	v_fma_f32 v22, v92, v22, v74
	v_fma_f32 v23, v92, v23, v75
	v_fma_f32 v24, -v94, v64, v24
	v_fma_f32 v25, -v94, v65, v25
	v_mul_f32_e32 v22, 0xbfb8aa3b, v22
	v_mul_f32_e32 v23, 0xbfb8aa3b, v23
	v_fma_f32 v24, v92, v24, v76
	v_fmac_f32_e32 v77, v92, v25
	v_exp_f32_e32 v22, v22
	v_exp_f32_e32 v23, v23
	v_mul_f32_e32 v24, 0xbfb8aa3b, v24
	v_mul_f32_e32 v25, 0xbfb8aa3b, v77
	v_exp_f32_e32 v24, v24
	v_exp_f32_e32 v25, v25
	v_add_f32_e32 v22, 1.0, v22
	v_add_f32_e32 v23, 1.0, v23
	v_rcp_f32_e32 v22, v22
	v_rcp_f32_e32 v23, v23
	v_add_f32_e32 v24, 1.0, v24
	v_add_f32_e32 v25, 1.0, v25
	v_rcp_f32_e32 v24, v24
	v_rcp_f32_e32 v25, v25
	v_pk_add_f32 v[30:31], v[60:61], v[94:95] op_sel_hi:[1,0] neg_lo:[0,1] neg_hi:[0,1]
	v_lshlrev_b32_e32 v62, 16, v50
	v_and_b32_e32 v63, 0xffff0000, v50
	v_pk_mul_f32 v[30:31], v[92:93], v[30:31] op_sel_hi:[0,1]
	v_pk_fma_f32 v[22:23], v[22:23], v[62:63], v[26:27]
	v_lshlrev_b32_e32 v26, 16, v51
	v_and_b32_e32 v27, 0xffff0000, v51
	v_pk_fma_f32 v[28:29], v[30:31], v[28:29], v[32:33]
	v_pk_add_f32 v[50:51], v[54:55], v[94:95] op_sel_hi:[1,0] neg_lo:[0,1] neg_hi:[0,1]
	v_pk_fma_f32 v[24:25], v[24:25], v[26:27], v[28:29]
	global_store_dwordx4 v[82:83], v[22:25], off offset:512
	v_pk_mul_f32 v[50:51], v[92:93], v[50:51] op_sel_hi:[0,1]
	s_nop 0
	v_cvt_pk_bf16_f32 v22, v22, v23
	v_cvt_pk_bf16_f32 v23, v24, v25
	global_store_dwordx2 v[90:91], v[22:23], off offset:256
	global_load_dwordx4 v[22:25], v[192:193], off offset:528
	s_nop 0
	global_load_dwordx4 v[26:29], v[208:209], off offset:528
	global_load_dwordx4 v[30:33], v[166:167], off
	global_load_dwordx4 v[58:61], v[168:169], off
	s_waitcnt vmcnt(0)
	v_pk_fma_f32 v[22:23], v[50:51], v[22:23], v[26:27]
	v_fma_f32 v18, -v94, v30, v18
	v_fma_f32 v19, -v94, v31, v19
	v_fma_f32 v18, v92, v18, v58
	v_fma_f32 v19, v92, v19, v59
	v_fma_f32 v20, -v94, v32, v20
	v_fma_f32 v21, -v94, v33, v21
	v_mul_f32_e32 v18, 0xbfb8aa3b, v18
	v_mul_f32_e32 v19, 0xbfb8aa3b, v19
	v_fma_f32 v20, v92, v20, v60
	v_fmac_f32_e32 v61, v92, v21
	v_exp_f32_e32 v18, v18
	v_exp_f32_e32 v19, v19
	v_mul_f32_e32 v20, 0xbfb8aa3b, v20
	v_mul_f32_e32 v21, 0xbfb8aa3b, v61
	v_exp_f32_e32 v20, v20
	v_exp_f32_e32 v21, v21
	v_add_f32_e32 v18, 1.0, v18
	v_add_f32_e32 v19, 1.0, v19
	v_rcp_f32_e32 v18, v18
	v_rcp_f32_e32 v19, v19
	v_add_f32_e32 v20, 1.0, v20
	v_add_f32_e32 v21, 1.0, v21
	v_rcp_f32_e32 v20, v20
	v_rcp_f32_e32 v21, v21
	v_pk_add_f32 v[26:27], v[56:57], v[94:95] op_sel_hi:[1,0] neg_lo:[0,1] neg_hi:[0,1]
	v_lshlrev_b32_e32 v30, 16, v52
	v_and_b32_e32 v31, 0xffff0000, v52
	v_pk_mul_f32 v[26:27], v[92:93], v[26:27] op_sel_hi:[0,1]
	v_pk_fma_f32 v[18:19], v[18:19], v[30:31], v[22:23]
	v_lshlrev_b32_e32 v22, 16, v53
	v_and_b32_e32 v23, 0xffff0000, v53
	v_pk_fma_f32 v[24:25], v[26:27], v[24:25], v[28:29]
	s_nop 0
	v_pk_fma_f32 v[20:21], v[20:21], v[22:23], v[24:25]
	global_store_dwordx4 v[82:83], v[18:21], off offset:528
	s_waitcnt lgkmcnt(0)
; DI unsigned pk2(float lo, float hi) { f32x2 v = {lo, hi}; bf16x2_t b = __builtin_convertvector(v, bf16x2_t); return __builtin_bit_cast(unsigned, b); }
; DI float lo_bf(unsigned u) { return __uint_as_float(u << 16); }
; DI float hi_bf(unsigned u) { return __uint_as_float(u & 0xffff0000u); }
; DI float sigmoidf_(float x) { return __builtin_amdgcn_rcpf(1.f + __expf(-x)); }
;     DI void operator()(AccRef acc, const Unit& u, int wr, int wc, int fr, int fq) const {
;     ...
;             int row = row0 + ai * 128 + m * 16; asm volatile("" : "+v"(row)); const size_t off = (size_t)row * DM + c0;
;             const float mean = sb[cur].x * (1.f / DM); const float rstd = __builtin_amdgcn_rsqf(fmaxf(sb[cur].y * (1.f / DM) - mean * mean, 0.f) + LN_EPS);
; #pragma unroll
;             for (int bj = 0; bj < 2; ++bj)
; #pragma unroll
;                 for (int n = 0; n < 2; ++n) { const int cc = c0 + bj * 128 + 4 * n; const f32x4 gv = *(const f32x4*)(G + cc), bv = *(const f32x4*)(Bv + cc), gw = *(const f32x4*)(GW + cc), bw = *(const f32x4*)(GW + 1024 + cc);
;                     const unsigned e0 = eb[cur][bj][2 * n], e1 = eb[cur][bj][2 * n + 1]; const f32x4 ev = {lo_bf(e0), hi_bf(e0), lo_bf(e1), hi_bf(e1)};
;                     const f32x4 x2 = (yb[cur][bj][n] - mean) * rstd * gv + bv; const f32x4 a = (acc[ai][bj][m][n] - gw * mean) * rstd + bw; f32x4 o;
; #pragma unroll
;                     for (int i = 0; i < 4; ++i) o[i] = x2[i] + sigmoidf_(a[i]) * ev[i];
;                     *(f32x4*)(OUT + off + bj * 128 + 4 * n) = o; u32x2 w2; w2.x = pk2(o[0], o[1]); w2.y = pk2(o[2], o[3]);
;                     *(u32x2*)(XB + off + bj * 128 + 4 * n) = w2; } }
	v_pk_mul_f32 v[24:25], v[80:81], s[36:37] op_sel_hi:[1,0]
	v_cvt_pk_bf16_f32 v18, v18, v19
	v_cvt_pk_bf16_f32 v19, v20, v21
	global_store_dwordx2 v[90:91], v[18:19], off offset:264
	global_load_dwordx4 v[28:31], v[192:193], off
	global_load_dwordx4 v[50:53], v[208:209], off
	global_load_dwordx4 v[54:57], v[212:213], off
	global_load_dwordx4 v[58:61], v[214:215], off
	v_fma_f32 v20, -v24, v24, v25
	v_max_f32_e32 v20, 0, v20
	v_add_f32_e32 v20, 0x3727c5ac, v20
	v_rsq_f32_e32 v26, v20
	v_pk_add_f32 v[32:33], v[70:71], v[24:25] op_sel_hi:[1,0] neg_lo:[0,1] neg_hi:[0,1]
	v_lshlrev_b32_e32 v20, 16, v66
	v_and_b32_e32 v21, 0xffff0000, v66
	v_pk_mul_f32 v[32:33], v[32:33], v[26:27] op_sel_hi:[1,0]
	v_ashrrev_i32_e32 v79, 31, v78
	v_lshlrev_b64 v[18:19], 10, v[78:79]
	v_lshl_add_u64 v[18:19], v[18:19], 0, v[210:211]
	v_lshl_add_u64 v[22:23], v[18:19], 1, s[76:77]
	v_pk_add_f32 v[46:47], v[46:47], v[24:25] op_sel_hi:[1,0] neg_lo:[0,1] neg_hi:[0,1]
	s_waitcnt vmcnt(0)
	v_pk_fma_f32 v[28:29], v[32:33], v[28:29], v[50:51]
	v_fma_f32 v14, -v24, v54, v14
	v_fma_f32 v15, -v24, v55, v15
	v_fma_f32 v14, v26, v14, v58
	v_fma_f32 v15, v26, v15, v59
	v_mul_f32_e32 v14, 0xbfb8aa3b, v14
	v_mul_f32_e32 v15, 0xbfb8aa3b, v15
	v_exp_f32_e32 v14, v14
	v_exp_f32_e32 v15, v15
	v_fma_f32 v16, -v24, v56, v16
	v_fma_f32 v17, -v24, v57, v17
	v_fma_f32 v16, v26, v16, v60
	v_fmac_f32_e32 v61, v26, v17
	v_mul_f32_e32 v16, 0xbfb8aa3b, v16
	v_mul_f32_e32 v17, 0xbfb8aa3b, v61
	v_exp_f32_e32 v16, v16
	v_exp_f32_e32 v17, v17
	v_add_f32_e32 v14, 1.0, v14
	v_add_f32_e32 v15, 1.0, v15
	v_rcp_f32_e32 v14, v14
	v_rcp_f32_e32 v15, v15
	v_add_f32_e32 v16, 1.0, v16
	v_add_f32_e32 v17, 1.0, v17
	v_rcp_f32_e32 v16, v16
	v_rcp_f32_e32 v17, v17
	v_pk_fma_f32 v[14:15], v[14:15], v[20:21], v[28:29]
	v_pk_add_f32 v[28:29], v[72:73], v[24:25] op_sel_hi:[1,0] neg_lo:[0,1] neg_hi:[0,1]
	v_lshlrev_b32_e32 v20, 16, v67
	v_pk_mul_f32 v[28:29], v[28:29], v[26:27] op_sel_hi:[1,0]
	v_and_b32_e32 v21, 0xffff0000, v67
	v_pk_fma_f32 v[28:29], v[28:29], v[30:31], v[52:53]
	v_pk_mul_f32 v[46:47], v[46:47], v[26:27] op_sel_hi:[1,0]
	v_pk_fma_f32 v[16:17], v[16:17], v[20:21], v[28:29]
	v_lshl_add_u64 v[28:29], v[18:19], 2, s[18:19]
	global_store_dwordx4 v[28:29], v[14:17], off
	s_nop 1
	v_cvt_pk_bf16_f32 v14, v14, v15
	v_cvt_pk_bf16_f32 v15, v16, v17
	global_store_dwordx2 v[22:23], v[14:15], off
	global_load_dwordx4 v[14:17], v[192:193], off offset:16
	s_nop 0
	global_load_dwordx4 v[18:21], v[208:209], off offset:16
	global_load_dwordx4 v[30:33], v[170:171], off
	global_load_dwordx4 v[50:53], v[216:217], off
	s_waitcnt vmcnt(0)
	v_pk_fma_f32 v[14:15], v[46:47], v[14:15], v[18:19]
	v_fma_f32 v10, -v24, v30, v10
	v_fma_f32 v11, -v24, v31, v11
	v_fma_f32 v10, v26, v10, v50
	v_fma_f32 v11, v26, v11, v51
	v_fma_f32 v12, -v24, v32, v12
	v_fma_f32 v13, -v24, v33, v13
	v_mul_f32_e32 v10, 0xbfb8aa3b, v10
	v_mul_f32_e32 v11, 0xbfb8aa3b, v11
	v_fma_f32 v12, v26, v12, v52
	v_fmac_f32_e32 v53, v26, v13
	v_exp_f32_e32 v10, v10
	v_exp_f32_e32 v11, v11
	v_mul_f32_e32 v12, 0xbfb8aa3b, v12
	v_mul_f32_e32 v13, 0xbfb8aa3b, v53
	v_exp_f32_e32 v12, v12
	v_exp_f32_e32 v13, v13
	v_add_f32_e32 v10, 1.0, v10
	v_add_f32_e32 v11, 1.0, v11
	v_rcp_f32_e32 v10, v10
	v_rcp_f32_e32 v11, v11
	v_add_f32_e32 v12, 1.0, v12
	v_add_f32_e32 v13, 1.0, v13
	v_rcp_f32_e32 v12, v12
	v_rcp_f32_e32 v13, v13
	v_pk_add_f32 v[18:19], v[48:49], v[24:25] op_sel_hi:[1,0] neg_lo:[0,1] neg_hi:[0,1]
	v_lshlrev_b32_e32 v30, 16, v68
	v_and_b32_e32 v31, 0xffff0000, v68
	v_pk_mul_f32 v[18:19], v[18:19], v[26:27] op_sel_hi:[1,0]
	v_pk_fma_f32 v[10:11], v[10:11], v[30:31], v[14:15]
	v_lshlrev_b32_e32 v14, 16, v69
	v_and_b32_e32 v15, 0xffff0000, v69
	v_pk_fma_f32 v[16:17], v[18:19], v[16:17], v[20:21]
	s_nop 0
	v_pk_fma_f32 v[12:13], v[12:13], v[14:15], v[16:17]
	global_store_dwordx4 v[28:29], v[10:13], off offset:16
	s_nop 1
	v_cvt_pk_bf16_f32 v10, v10, v11
	v_cvt_pk_bf16_f32 v11, v12, v13
	global_store_dwordx2 v[22:23], v[10:11], off offset:8
	global_load_dwordx4 v[10:13], v[192:193], off offset:512
	s_nop 0
	global_load_dwordx4 v[14:17], v[208:209], off offset:512
	global_load_dwordx4 v[18:21], v[172:173], off
	global_load_dwordx4 v[30:33], v[174:175], off
	s_waitcnt vmcnt(0)
; #define PG8_BAR __builtin_amdgcn_s_barrier()
; DI unsigned pk2(float lo, float hi) { f32x2 v = {lo, hi}; bf16x2_t b = __builtin_convertvector(v, bf16x2_t); return __builtin_bit_cast(unsigned, b); }
; DI float lo_bf(unsigned u) { return __uint_as_float(u << 16); }
; DI float hi_bf(unsigned u) { return __uint_as_float(u & 0xffff0000u); }
; DI float sigmoidf_(float x) { return __builtin_amdgcn_rcpf(1.f + __expf(-x)); }
; template <class Epi, class Sched, bool ALIGN_EPI = false, bool SP2 = false>
; __device__ __forceinline__ void gemm_phase(PG8_LAS unsigned char* lds, const Gemm g, const Sched& S, const Epi& E) {
;     ...
;         if constexpr (ALIGN_EPI) { if (wr == 1) PG8_BAR; }
;     }
;     DI void operator()(AccRef acc, const Unit& u, int wr, int wc, int fr, int fq) const {
;     ...
;             int row = row0 + ai * 128 + m * 16; asm volatile("" : "+v"(row)); const size_t off = (size_t)row * DM + c0;
;             const float mean = sb[cur].x * (1.f / DM); const float rstd = __builtin_amdgcn_rsqf(fmaxf(sb[cur].y * (1.f / DM) - mean * mean, 0.f) + LN_EPS);
; #pragma unroll
;             for (int bj = 0; bj < 2; ++bj)
; #pragma unroll
;                 for (int n = 0; n < 2; ++n) { const int cc = c0 + bj * 128 + 4 * n; const f32x4 gv = *(const f32x4*)(G + cc), bv = *(const f32x4*)(Bv + cc), gw = *(const f32x4*)(GW + cc), bw = *(const f32x4*)(GW + 1024 + cc);
;                     const unsigned e0 = eb[cur][bj][2 * n], e1 = eb[cur][bj][2 * n + 1]; const f32x4 ev = {lo_bf(e0), hi_bf(e0), lo_bf(e1), hi_bf(e1)};
;                     const f32x4 x2 = (yb[cur][bj][n] - mean) * rstd * gv + bv; const f32x4 a = (acc[ai][bj][m][n] - gw * mean) * rstd + bw; f32x4 o;
; #pragma unroll
;                     for (int i = 0; i < 4; ++i) o[i] = x2[i] + sigmoidf_(a[i]) * ev[i];
;                     *(f32x4*)(OUT + off + bj * 128 + 4 * n) = o; u32x2 w2; w2.x = pk2(o[0], o[1]); w2.y = pk2(o[2], o[3]);
;                     *(u32x2*)(XB + off + bj * 128 + 4 * n) = w2; } }
	v_fma_f32 v6, -v24, v18, v6
	v_fma_f32 v7, -v24, v19, v7
	v_fma_f32 v6, v26, v6, v30
	v_fma_f32 v7, v26, v7, v31
	v_fma_f32 v8, -v24, v20, v8
	v_fma_f32 v9, -v24, v21, v9
	v_mul_f32_e32 v6, 0xbfb8aa3b, v6
	v_mul_f32_e32 v7, 0xbfb8aa3b, v7
	v_fma_f32 v8, v26, v8, v32
	v_fmac_f32_e32 v33, v26, v9
	v_exp_f32_e32 v6, v6
	v_exp_f32_e32 v7, v7
	v_mul_f32_e32 v8, 0xbfb8aa3b, v8
	v_mul_f32_e32 v9, 0xbfb8aa3b, v33
	v_exp_f32_e32 v8, v8
	v_exp_f32_e32 v9, v9
	v_add_f32_e32 v6, 1.0, v6
	v_add_f32_e32 v7, 1.0, v7
	v_rcp_f32_e32 v6, v6
	v_rcp_f32_e32 v7, v7
	v_pk_add_f32 v[30:31], v[42:43], v[24:25] op_sel_hi:[1,0] neg_lo:[0,1] neg_hi:[0,1]
	v_add_f32_e32 v8, 1.0, v8
	v_add_f32_e32 v9, 1.0, v9
	v_pk_mul_f32 v[30:31], v[26:27], v[30:31] op_sel_hi:[0,1]
	v_rcp_f32_e32 v8, v8
	v_rcp_f32_e32 v9, v9
	v_pk_fma_f32 v[10:11], v[30:31], v[10:11], v[14:15]
	v_pk_add_f32 v[14:15], v[44:45], v[24:25] op_sel_hi:[1,0] neg_lo:[0,1] neg_hi:[0,1]
	v_lshlrev_b32_e32 v18, 16, v34
	v_and_b32_e32 v19, 0xffff0000, v34
	v_pk_mul_f32 v[14:15], v[26:27], v[14:15] op_sel_hi:[0,1]
	v_pk_fma_f32 v[6:7], v[6:7], v[18:19], v[10:11]
	v_lshlrev_b32_e32 v10, 16, v35
	v_and_b32_e32 v11, 0xffff0000, v35
	v_pk_fma_f32 v[12:13], v[14:15], v[12:13], v[16:17]
	s_nop 0
	v_pk_fma_f32 v[8:9], v[8:9], v[10:11], v[12:13]
	global_store_dwordx4 v[28:29], v[6:9], off offset:512
	s_nop 1
	v_cvt_pk_bf16_f32 v6, v6, v7
	v_cvt_pk_bf16_f32 v7, v8, v9
	global_store_dwordx2 v[22:23], v[6:7], off offset:256
	global_load_dwordx4 v[6:9], v[192:193], off offset:528
	s_nop 0
	global_load_dwordx4 v[10:13], v[208:209], off offset:528
	global_load_dwordx4 v[14:17], v[166:167], off
	global_load_dwordx4 v[18:21], v[168:169], off
	s_waitcnt vmcnt(0)
	v_fma_f32 v2, -v24, v14, v2
	v_fma_f32 v3, -v24, v15, v3
	v_fma_f32 v2, v26, v2, v18
	v_fma_f32 v3, v26, v3, v19
	v_fma_f32 v4, -v24, v16, v4
	v_fma_f32 v5, -v24, v17, v5
	v_mul_f32_e32 v2, 0xbfb8aa3b, v2
	v_mul_f32_e32 v3, 0xbfb8aa3b, v3
	v_fma_f32 v4, v26, v4, v20
	v_fmac_f32_e32 v21, v26, v5
	v_exp_f32_e32 v2, v2
	v_exp_f32_e32 v3, v3
	v_mul_f32_e32 v4, 0xbfb8aa3b, v4
	v_mul_f32_e32 v5, 0xbfb8aa3b, v21
	v_exp_f32_e32 v4, v4
	v_exp_f32_e32 v5, v5
	v_add_f32_e32 v2, 1.0, v2
	v_add_f32_e32 v3, 1.0, v3
	v_rcp_f32_e32 v2, v2
	v_rcp_f32_e32 v3, v3
	v_pk_add_f32 v[18:19], v[38:39], v[24:25] op_sel_hi:[1,0] neg_lo:[0,1] neg_hi:[0,1]
	v_add_f32_e32 v4, 1.0, v4
	v_add_f32_e32 v5, 1.0, v5
	v_pk_mul_f32 v[18:19], v[26:27], v[18:19] op_sel_hi:[0,1]
	v_rcp_f32_e32 v4, v4
	v_rcp_f32_e32 v5, v5
	v_pk_fma_f32 v[6:7], v[18:19], v[6:7], v[10:11]
	v_pk_add_f32 v[10:11], v[40:41], v[24:25] op_sel_hi:[1,0] neg_lo:[0,1] neg_hi:[0,1]
	v_lshlrev_b32_e32 v14, 16, v36
	v_and_b32_e32 v15, 0xffff0000, v36
	v_pk_mul_f32 v[10:11], v[26:27], v[10:11] op_sel_hi:[0,1]
	v_pk_fma_f32 v[2:3], v[2:3], v[14:15], v[6:7]
	v_lshlrev_b32_e32 v6, 16, v37
	v_and_b32_e32 v7, 0xffff0000, v37
	v_pk_fma_f32 v[8:9], v[10:11], v[8:9], v[12:13]
	s_nop 0
	v_pk_fma_f32 v[4:5], v[4:5], v[6:7], v[8:9]
	global_store_dwordx4 v[28:29], v[2:5], off offset:528
	s_nop 1
	v_cvt_pk_bf16_f32 v2, v2, v3
	v_cvt_pk_bf16_f32 v3, v4, v5
	global_store_dwordx2 v[22:23], v[2:3], off offset:264
	s_cbranch_vccnz .LBB0_566
	s_andn2_b64 vcc, exec, s[48:49]
	s_cbranch_vccnz .LBB0_565
	s_barrier
	s_branch .LBB0_565
